# device-scope (sc1) write-through on all bulk dwordx4 stores of the GEMM epilogues and ATTN outputs so the seam's L2 writeback has little left to flush
# baseline (speedup 1.0000x reference)
.LBB0_206:
	v_mov_b32_e32 v84, v132
	v_mov_b32_e32 v85, v132
	v_mov_b32_e32 v90, v132
	v_mov_b32_e32 v91, v132
	v_pk_mul_f32 v[28:29], v[28:29], v[84:85]
	v_pk_mul_f32 v[20:21], v[20:21], v[84:85]
	v_mov_b32_e32 v132, v133
	v_mov_b32_e32 v86, v133
	v_mov_b32_e32 v87, v133
	v_pk_mul_f32 v[30:31], v[30:31], v[90:91]
	v_pk_mul_f32 v[22:23], v[22:23], v[90:91]
	v_pk_mul_f32 v[28:29], v[28:29], v[20:21]
	v_pk_mul_f32 v[20:21], v[26:27], v[132:133]
	v_pk_mul_f32 v[18:19], v[18:19], v[132:133]
	v_pk_mul_f32 v[30:31], v[30:31], v[22:23]
	v_pk_mul_f32 v[22:23], v[24:25], v[86:87]
	v_pk_mul_f32 v[16:17], v[16:17], v[86:87]
	v_pk_mul_f32 v[18:19], v[20:21], v[18:19]
	v_mov_b32_dpp v78, v108 row_shr:1 row_mask:0xf bank_mask:0xf
	v_mov_b32_dpp v79, v104 row_shr:1 row_mask:0xf bank_mask:0xf
	s_waitcnt lgkmcnt(0)
	v_mov_b32_e32 v20, v44
	v_mov_b32_e32 v21, v56
	v_pk_mul_f32 v[16:17], v[22:23], v[16:17]
	v_pk_mul_f32 v[22:23], v[20:21], v[78:79]
	v_mov_b32_e32 v78, v56
	v_fma_f32 v23, v28, v40, v23
	v_add_f32_e32 v76, v22, v23
	v_mov_b32_e32 v22, v28
	v_mov_b32_e32 v23, v44
	v_pk_mul_f32 v[22:23], v[22:23], v[78:79]
	v_mov_b32_dpp v70, v109 row_shr:1 row_mask:0xf bank_mask:0xf
	v_fma_f32 v22, v16, v40, v22
	v_add_f32_e32 v78, v22, v23
	v_mov_b32_e32 v22, v28
	v_mov_b32_e32 v23, v16
	v_pk_mul_f32 v[22:23], v[22:23], v[20:21]
	v_mov_b32_dpp v71, v105 row_shr:1 row_mask:0xf bank_mask:0xf
	v_fma_f32 v23, v108, v40, v23
	v_add_f32_e32 v79, v22, v23
	v_mov_b32_e32 v22, v16
	v_mov_b32_e32 v23, v108
	v_pk_mul_f32 v[22:23], v[22:23], v[20:21]
	v_mov_b32_e32 v108, v17
	v_fma_f32 v16, v104, v40, v23
	v_add_f32_e32 v84, v22, v16
	v_mov_b32_e32 v22, v45
	v_mov_b32_e32 v23, v57
	v_pk_mul_f32 v[24:25], v[22:23], v[70:71]
	v_mov_b32_e32 v70, v57
	v_fma_f32 v16, v29, v41, v25
	v_add_f32_e32 v28, v24, v16
	v_mov_b32_e32 v24, v29
	v_mov_b32_e32 v25, v45
	v_pk_mul_f32 v[24:25], v[24:25], v[70:71]
	v_mov_b32_dpp v54, v110 row_shr:1 row_mask:0xf bank_mask:0xf
	v_fma_f32 v16, v17, v41, v24
	v_add_f32_e32 v85, v16, v25
	v_mov_b32_e32 v16, v29
	v_pk_mul_f32 v[24:25], v[16:17], v[22:23]
	v_mov_b32_dpp v55, v106 row_shr:1 row_mask:0xf bank_mask:0xf
	v_fma_f32 v16, v109, v41, v25
	v_add_f32_e32 v86, v24, v16
	v_pk_mul_f32 v[16:17], v[108:109], v[22:23]
	v_mov_b32_e32 v24, v46
	v_fma_f32 v17, v105, v41, v17
	v_mov_b32_e32 v25, v58
	v_add_f32_e32 v87, v16, v17
	v_pk_mul_f32 v[16:17], v[24:25], v[54:55]
	v_mov_b32_e32 v54, v58
	v_fma_f32 v17, v30, v42, v17
	v_add_f32_e32 v29, v16, v17
	v_mov_b32_e32 v16, v30
	v_mov_b32_e32 v17, v46
	v_pk_mul_f32 v[16:17], v[16:17], v[54:55]
	v_mov_b32_dpp v72, v111 row_shr:1 row_mask:0xf bank_mask:0xf
	v_fma_f32 v16, v18, v42, v16
	v_add_f32_e32 v54, v16, v17
	v_mov_b32_e32 v16, v30
	v_mov_b32_e32 v17, v18
	v_pk_mul_f32 v[16:17], v[16:17], v[24:25]
	v_mov_b32_dpp v73, v107 row_shr:1 row_mask:0xf bank_mask:0xf
	v_fma_f32 v17, v110, v42, v17
	v_add_f32_e32 v30, v16, v17
	v_mov_b32_e32 v16, v18
	v_mov_b32_e32 v17, v110
	v_pk_mul_f32 v[16:17], v[16:17], v[24:25]
	v_mov_b32_e32 v26, v47
	v_fma_f32 v17, v106, v42, v17
	v_mov_b32_e32 v27, v59
	v_add_f32_e32 v55, v16, v17
	v_pk_mul_f32 v[16:17], v[26:27], v[72:73]
	v_mov_b32_e32 v72, v59
	v_fma_f32 v17, v31, v43, v17
	v_add_f32_e32 v71, v16, v17
	v_mov_b32_e32 v16, v31
	v_mov_b32_e32 v17, v47
	v_pk_mul_f32 v[16:17], v[16:17], v[72:73]
	v_mov_b32_e32 v18, v31
	v_fma_f32 v16, v19, v43, v16
	v_add_f32_e32 v72, v16, v17
	v_pk_mul_f32 v[16:17], v[18:19], v[26:27]
	v_mov_b32_e32 v110, v19
	v_fma_f32 v17, v111, v43, v17
	v_lshl_add_u32 v88, s60, 8, v157
	v_add_f32_e32 v31, v16, v17
	v_pk_mul_f32 v[16:17], v[110:111], v[26:27]
	v_lshl_or_b32 v74, s59, 7, v158
	v_fma_f32 v17, v107, v43, v17
	v_ashrrev_i32_e32 v89, 31, v88
	v_ashrrev_i32_e32 v75, 31, v74
	v_add_f32_e32 v73, v16, v17
	v_lshlrev_b64 v[16:17], 11, v[88:89]
	v_cvt_pk_bf16_f32 v70, v76, v28
	v_cvt_pk_bf16_f32 v71, v29, v71
	v_lshl_add_u64 v[28:29], s[0:1], 0, v[16:17]
	v_lshlrev_b64 v[16:17], 1, v[74:75]
	v_lshl_add_u64 v[18:19], v[28:29], 0, v[16:17]
	global_store_dwordx4 v[18:19], v[68:71], off sc1 nt
	v_or_b32_e32 v18, 1, v88
	v_ashrrev_i32_e32 v19, 31, v18
	v_lshlrev_b64 v[18:19], 11, v[18:19]
	v_lshl_add_u64 v[18:19], s[0:1], 0, v[18:19]
	v_lshl_add_u64 v[18:19], v[18:19], 0, v[16:17]
	v_cvt_pk_bf16_f32 v68, v78, v85
	v_cvt_pk_bf16_f32 v69, v54, v72
	global_store_dwordx4 v[18:19], v[66:69], off sc1 nt
	v_or_b32_e32 v18, 2, v88
	v_ashrrev_i32_e32 v19, 31, v18
	v_lshlrev_b64 v[18:19], 11, v[18:19]
	v_lshl_add_u64 v[18:19], s[0:1], 0, v[18:19]
	v_lshl_add_u64 v[18:19], v[18:19], 0, v[16:17]
	v_cvt_pk_bf16_f32 v66, v79, v86
	v_cvt_pk_bf16_f32 v67, v30, v31
	global_store_dwordx4 v[18:19], v[64:67], off sc1 nt
	v_or_b32_e32 v18, 3, v88
	v_ashrrev_i32_e32 v19, 31, v18
	v_lshlrev_b64 v[18:19], 11, v[18:19]
	v_lshl_add_u64 v[18:19], s[0:1], 0, v[18:19]
	v_lshl_add_u64 v[16:17], v[18:19], 0, v[16:17]
	v_cvt_pk_bf16_f32 v54, v84, v87
	v_cvt_pk_bf16_f32 v55, v55, v73
	global_store_dwordx4 v[16:17], v[52:55], off sc1 nt
	s_andn2_b64 vcc, exec, s[30:31]
	v_mov_b32_e32 v17, 0
	v_mov_b32_e32 v31, 0
	v_mov_b32_e32 v19, 0
	v_mov_b32_e32 v76, 0
	v_mov_b32_e32 v16, 0
	v_mov_b32_e32 v30, 0
	v_mov_b32_e32 v18, 0
	s_cbranch_vccnz .LBB0_208
	ds_read_b128 v[16:19], v102 offset:1040
	ds_read_b128 v[52:55], v102 offset:16
	s_waitcnt lgkmcnt(0)
	v_mov_b32_e32 v77, v16
	v_mov_b32_e32 v31, v18
	v_mov_b32_e32 v76, v52
	v_mov_b32_e32 v16, v53
	v_mov_b32_e32 v30, v54
	v_mov_b32_e32 v18, v55
.LBB0_208:
	v_mov_b32_e32 v52, v100
	v_mov_b32_e32 v53, v100
	v_mov_b32_e32 v54, v101
	v_mov_b32_e32 v55, v101
	v_pk_mul_f32 v[12:13], v[12:13], v[52:53]
	v_pk_mul_f32 v[4:5], v[4:5], v[52:53]
	v_pk_mul_f32 v[8:9], v[8:9], v[54:55]
	v_pk_mul_f32 v[0:1], v[0:1], v[54:55]
	v_mov_b32_dpp v76, v80 row_shr:1 row_mask:0xf bank_mask:0xf
	v_mov_b32_dpp v77, v60 row_shr:1 row_mask:0xf bank_mask:0xf
	v_mov_b32_e32 v64, v100
	v_mov_b32_e32 v65, v100
	v_pk_mul_f32 v[4:5], v[12:13], v[4:5]
	v_mov_b32_e32 v100, v101
	v_pk_mul_f32 v[0:1], v[8:9], v[0:1]
	v_pk_mul_f32 v[8:9], v[20:21], v[76:77]
	v_pk_mul_f32 v[10:11], v[10:11], v[100:101]
	v_pk_mul_f32 v[2:3], v[2:3], v[100:101]
	v_fma_f32 v9, v4, v40, v9
	v_pk_mul_f32 v[2:3], v[10:11], v[2:3]
	v_add_f32_e32 v10, v8, v9
	v_mov_b32_e32 v8, v4
	v_mov_b32_e32 v9, v44
	v_mov_b32_e32 v76, v56
	v_pk_mul_f32 v[8:9], v[8:9], v[76:77]
	v_mov_b32_dpp v16, v81 row_shr:1 row_mask:0xf bank_mask:0xf
	v_fma_f32 v8, v0, v40, v8
	v_add_f32_e32 v11, v8, v9
	v_mov_b32_e32 v8, v4
	v_mov_b32_e32 v9, v0
	v_pk_mul_f32 v[8:9], v[8:9], v[20:21]
	v_mov_b32_dpp v17, v61 row_shr:1 row_mask:0xf bank_mask:0xf
	v_fma_f32 v4, v80, v40, v9
	v_add_f32_e32 v12, v8, v4
	v_mov_b32_e32 v8, v0
	v_mov_b32_e32 v9, v80
	v_pk_mul_f32 v[8:9], v[8:9], v[20:21]
	v_pk_mul_f32 v[14:15], v[14:15], v[64:65]
	v_fma_f32 v0, v60, v40, v9
	v_add_f32_e32 v13, v8, v0
	v_pk_mul_f32 v[8:9], v[22:23], v[16:17]
	v_pk_mul_f32 v[6:7], v[6:7], v[64:65]
	v_fma_f32 v0, v5, v41, v9
	v_mov_b32_e32 v44, v5
	v_mov_b32_e32 v16, v57
	v_pk_mul_f32 v[6:7], v[14:15], v[6:7]
	v_add_f32_e32 v14, v8, v0
	v_pk_mul_f32 v[8:9], v[44:45], v[16:17]
	v_mov_b32_e32 v80, v1
	v_fma_f32 v0, v1, v41, v8
	v_add_f32_e32 v8, v0, v9
	v_mov_b32_e32 v0, v5
	v_pk_mul_f32 v[4:5], v[0:1], v[22:23]
	v_mov_b32_dpp v30, v82 row_shr:1 row_mask:0xf bank_mask:0xf
	v_fma_f32 v0, v81, v41, v5
	v_add_f32_e32 v4, v4, v0
	v_pk_mul_f32 v[0:1], v[80:81], v[22:23]
	v_mov_b32_dpp v31, v62 row_shr:1 row_mask:0xf bank_mask:0xf
	v_fma_f32 v1, v61, v41, v1
	v_add_f32_e32 v5, v0, v1
	v_pk_mul_f32 v[0:1], v[24:25], v[30:31]
	v_mov_b32_e32 v30, v58
	v_fma_f32 v1, v6, v42, v1
	v_add_f32_e32 v9, v0, v1
	v_mov_b32_e32 v0, v6
	v_mov_b32_e32 v1, v46
	v_pk_mul_f32 v[0:1], v[0:1], v[30:31]
	v_mov_b32_dpp v18, v83 row_shr:1 row_mask:0xf bank_mask:0xf
	v_fma_f32 v0, v2, v42, v0
	v_add_f32_e32 v15, v0, v1
	v_mov_b32_e32 v0, v6
	v_mov_b32_e32 v1, v2
	v_pk_mul_f32 v[0:1], v[0:1], v[24:25]
	v_mov_b32_dpp v19, v63 row_shr:1 row_mask:0xf bank_mask:0xf
	v_fma_f32 v1, v82, v42, v1
	v_add_f32_e32 v6, v0, v1
	v_mov_b32_e32 v0, v2
	v_mov_b32_e32 v1, v82
	v_pk_mul_f32 v[0:1], v[0:1], v[24:25]
	v_mov_b32_e32 v46, v7
	v_fma_f32 v1, v62, v42, v1
	v_add_f32_e32 v16, v0, v1
	v_pk_mul_f32 v[0:1], v[26:27], v[18:19]
	v_mov_b32_e32 v18, v59
	v_fma_f32 v1, v7, v43, v1
	v_add_f32_e32 v17, v0, v1
	v_pk_mul_f32 v[0:1], v[46:47], v[18:19]
	v_mov_b32_e32 v2, v7
	v_fma_f32 v0, v3, v43, v0
	v_add_f32_e32 v18, v0, v1
	v_pk_mul_f32 v[0:1], v[2:3], v[26:27]
	v_mov_b32_e32 v82, v3
	v_fma_f32 v1, v83, v43, v1
	v_add_f32_e32 v7, v0, v1
	v_pk_mul_f32 v[0:1], v[82:83], v[26:27]
	v_cvt_pk_bf16_f32 v40, v10, v14
	v_cvt_pk_bf16_f32 v41, v9, v17
	s_nop 0
	v_fma_f32 v1, v63, v43, v1
	v_add_f32_e32 v19, v0, v1
	v_lshl_add_u64 v[0:1], v[74:75], 1, v[28:29]
	v_add_co_u32_e32 v2, vcc, s56, v0
	s_nop 1
	v_addc_co_u32_e32 v3, vcc, 0, v1, vcc
	v_add_co_u32_e32 v0, vcc, 0x41000, v0
	global_store_dwordx4 v[2:3], v[38:41], off sc1 nt
	s_nop 0
	v_addc_co_u32_e32 v1, vcc, 0, v1, vcc
	v_cvt_pk_bf16_f32 v38, v11, v8
	v_cvt_pk_bf16_f32 v39, v15, v18
	global_store_dwordx4 v[2:3], v[36:39], off offset:2048 sc1 nt
	s_nop 1
	v_cvt_pk_bf16_f32 v36, v12, v4
	v_cvt_pk_bf16_f32 v37, v6, v7
	global_store_dwordx4 v[0:1], v[34:37], off sc1 nt
	s_nop 1
	v_cvt_pk_bf16_f32 v34, v13, v5
	v_cvt_pk_bf16_f32 v35, v16, v19
	global_store_dwordx4 v[0:1], v[32:35], off offset:2048 sc1 nt
	s_and_b64 vcc, exec, s[8:9]
	s_mov_b64 s[8:9], -1
	s_cbranch_vccnz .LBB0_189
	s_xor_b32 s8, s15, 0x1000
	s_add_i32 s15, s8, 0
	s_add_i32 s15, s15, 0x24010
	s_and_saveexec_b64 s[8:9], s[2:3]
	s_cbranch_execz .LBB0_211
	v_add3_u32 v0, s15, v161, v146
	s_waitcnt vmcnt(8)
	ds_write_b128 v0, v[48:51]

.LBB0_286:
	ds_read_b128 v[128:131], v162
	ds_read_b128 v[148:151], v162 offset:1024
	ds_read_b128 v[152:155], v162 offset:2048
	ds_read_b128 v[166:169], v162 offset:3072
	s_add_u32 s36, s34, 0xfffc0080
	s_addc_u32 s37, s35, -1
	s_cmp_eq_u32 s59, 12
	s_cselect_b32 s39, s23, s37
	s_cselect_b32 s38, s55, s36
	s_cselect_b32 s37, s21, s58
	s_cselect_b32 s36, s56, s57
	v_lshl_add_u64 v[156:157], s[34:35], 0, v[140:141]
	s_add_i32 m0, s31, 0xc000
	ds_read_b128 v[170:173], v163
	ds_read_b128 v[174:177], v163 offset:1024
	ds_read_b128 v[178:181], v163 offset:2048
	ds_read_b128 v[182:185], v163 offset:3072
	ds_read_b128 v[190:193], v163 offset:4096
	ds_read_b128 v[194:197], v163 offset:5120
	ds_read_b128 v[198:201], v163 offset:6144
	ds_read_b128 v[202:205], v163 offset:7168
	global_load_lds_dwordx4 v[156:157], off
	v_lshl_add_u64 v[156:157], s[34:35], 0, v[142:143]
	s_add_i32 m0, s31, 0xe000
	s_nop 0
	global_load_lds_dwordx4 v[156:157], off
	s_waitcnt lgkmcnt(8)
	s_barrier
	s_waitcnt lgkmcnt(0)
	s_setprio 1
	s_waitcnt lgkmcnt(0)
	v_mfma_f32_16x16x32_bf16 v[124:127], v[128:131], v[170:173], v[124:127]
	v_mfma_f32_16x16x32_bf16 v[120:123], v[152:155], v[170:173], v[120:123]
	v_mfma_f32_16x16x32_bf16 v[108:111], v[128:131], v[178:181], v[108:111]
	v_mfma_f32_16x16x32_bf16 v[104:107], v[152:155], v[178:181], v[104:107]
	v_mfma_f32_16x16x32_bf16 v[92:95], v[128:131], v[190:193], v[92:95]
	v_mfma_f32_16x16x32_bf16 v[88:91], v[152:155], v[190:193], v[88:91]
	v_mfma_f32_16x16x32_bf16 v[76:79], v[128:131], v[198:201], v[76:79]
	v_mfma_f32_16x16x32_bf16 v[72:75], v[152:155], v[198:201], v[72:75]
	v_mfma_f32_16x16x32_bf16 v[124:127], v[148:151], v[174:177], v[124:127]
	v_mfma_f32_16x16x32_bf16 v[120:123], v[166:169], v[174:177], v[120:123]
	v_mfma_f32_16x16x32_bf16 v[108:111], v[148:151], v[182:185], v[108:111]
	v_mfma_f32_16x16x32_bf16 v[104:107], v[166:169], v[182:185], v[104:107]
	v_mfma_f32_16x16x32_bf16 v[92:95], v[148:151], v[194:197], v[92:95]
	v_mfma_f32_16x16x32_bf16 v[88:91], v[166:169], v[194:197], v[88:91]
	v_mfma_f32_16x16x32_bf16 v[76:79], v[148:151], v[202:205], v[76:79]
	v_mfma_f32_16x16x32_bf16 v[72:75], v[166:169], v[202:205], v[72:75]
	s_setprio 0
	s_barrier
	s_add_i32 s60, s52, s44
	v_lshl_add_u64 v[156:157], s[36:37], 0, v[134:135]
	s_mov_b32 m0, s60
	ds_read_b128 v[206:209], v164
	ds_read_b128 v[210:213], v164 offset:1024
	ds_read_b128 v[214:217], v164 offset:2048
	ds_read_b128 v[218:221], v164 offset:3072
	global_load_lds_dwordx4 v[156:157], off
	v_lshl_add_u64 v[186:187], s[36:37], 0, v[138:139]
	s_add_i32 m0, s60, 0x2000
	s_nop 0
	global_load_lds_dwordx4 v[186:187], off
	s_barrier
	s_waitcnt lgkmcnt(0)
	s_setprio 1
	s_waitcnt lgkmcnt(0)
	v_mfma_f32_16x16x32_bf16 v[116:119], v[206:209], v[170:173], v[116:119]
	v_mfma_f32_16x16x32_bf16 v[112:115], v[214:217], v[170:173], v[112:115]
	v_mfma_f32_16x16x32_bf16 v[100:103], v[206:209], v[178:181], v[100:103]
	v_mfma_f32_16x16x32_bf16 v[96:99], v[214:217], v[178:181], v[96:99]
	v_mfma_f32_16x16x32_bf16 v[84:87], v[206:209], v[190:193], v[84:87]
	v_mfma_f32_16x16x32_bf16 v[80:83], v[214:217], v[190:193], v[80:83]
	v_mfma_f32_16x16x32_bf16 v[68:71], v[206:209], v[198:201], v[68:71]
	v_mfma_f32_16x16x32_bf16 v[64:67], v[214:217], v[198:201], v[64:67]
	v_mfma_f32_16x16x32_bf16 v[116:119], v[210:213], v[174:177], v[116:119]
	v_mfma_f32_16x16x32_bf16 v[112:115], v[218:221], v[174:177], v[112:115]
	v_mfma_f32_16x16x32_bf16 v[100:103], v[210:213], v[182:185], v[100:103]
	v_mfma_f32_16x16x32_bf16 v[96:99], v[218:221], v[182:185], v[96:99]
	v_mfma_f32_16x16x32_bf16 v[84:87], v[210:213], v[194:197], v[84:87]
	v_mfma_f32_16x16x32_bf16 v[80:83], v[218:221], v[194:197], v[80:83]
	v_mfma_f32_16x16x32_bf16 v[68:71], v[210:213], v[202:205], v[68:71]
	v_mfma_f32_16x16x32_bf16 v[64:67], v[218:221], v[202:205], v[64:67]
	s_setprio 0
	s_mov_b32 m0, s31
	v_lshl_add_u64 v[222:223], s[38:39], 0, v[132:133]
	s_barrier
	ds_read_b128 v[170:173], v163 offset:16384
	ds_read_b128 v[174:177], v163 offset:17408
	ds_read_b128 v[178:181], v163 offset:18432
	ds_read_b128 v[182:185], v163 offset:19456
	ds_read_b128 v[190:193], v163 offset:20480
	ds_read_b128 v[194:197], v163 offset:21504
	ds_read_b128 v[198:201], v163 offset:22528
	ds_read_b128 v[202:205], v163 offset:23552
	global_load_lds_dwordx4 v[222:223], off
	v_lshl_add_u64 v[224:225], s[38:39], 0, v[136:137]
	s_mov_b32 m0, s45
	s_nop 0
	global_load_lds_dwordx4 v[224:225], off
	s_barrier
	s_waitcnt lgkmcnt(0)
	s_setprio 1
	s_waitcnt lgkmcnt(0)
	v_mfma_f32_16x16x32_bf16 v[60:63], v[128:131], v[170:173], v[60:63]
	v_mfma_f32_16x16x32_bf16 v[56:59], v[152:155], v[170:173], v[56:59]
	v_mfma_f32_16x16x32_bf16 v[44:47], v[128:131], v[178:181], v[44:47]
	v_mfma_f32_16x16x32_bf16 v[40:43], v[152:155], v[178:181], v[40:43]
	v_mfma_f32_16x16x32_bf16 v[28:31], v[128:131], v[190:193], v[28:31]
	v_mfma_f32_16x16x32_bf16 v[24:27], v[152:155], v[190:193], v[24:27]
	v_mfma_f32_16x16x32_bf16 v[12:15], v[128:131], v[198:201], v[12:15]
	v_mfma_f32_16x16x32_bf16 v[8:11], v[152:155], v[198:201], v[8:11]
	v_mfma_f32_16x16x32_bf16 v[60:63], v[148:151], v[174:177], v[60:63]
	v_mfma_f32_16x16x32_bf16 v[56:59], v[166:169], v[174:177], v[56:59]
	v_mfma_f32_16x16x32_bf16 v[44:47], v[148:151], v[182:185], v[44:47]
	v_mfma_f32_16x16x32_bf16 v[40:43], v[166:169], v[182:185], v[40:43]
	v_mfma_f32_16x16x32_bf16 v[28:31], v[148:151], v[194:197], v[28:31]
	v_mfma_f32_16x16x32_bf16 v[24:27], v[166:169], v[194:197], v[24:27]
	v_mfma_f32_16x16x32_bf16 v[12:15], v[148:151], v[202:205], v[12:15]
	v_mfma_f32_16x16x32_bf16 v[8:11], v[166:169], v[202:205], v[8:11]
	s_setprio 0
	s_barrier
	s_add_u32 s60, s36, 0x40000
	s_addc_u32 s61, s37, 0
	s_add_i32 s62, s53, s44
	v_lshl_add_u64 v[128:129], s[60:61], 0, v[134:135]
	s_mov_b32 m0, s62
	s_nop 0
	global_load_lds_dwordx4 v[128:129], off
	v_lshl_add_u64 v[128:129], s[60:61], 0, v[138:139]
	s_add_i32 m0, s62, 0x2000
	s_nop 0
	global_load_lds_dwordx4 v[128:129], off
	s_waitcnt vmcnt(6)
	s_barrier
	s_setprio 1
	v_mfma_f32_16x16x32_bf16 v[52:55], v[206:209], v[170:173], v[52:55]
	v_mfma_f32_16x16x32_bf16 v[48:51], v[214:217], v[170:173], v[48:51]
	v_mfma_f32_16x16x32_bf16 v[36:39], v[206:209], v[178:181], v[36:39]
	v_mfma_f32_16x16x32_bf16 v[32:35], v[214:217], v[178:181], v[32:35]
	v_mfma_f32_16x16x32_bf16 v[20:23], v[206:209], v[190:193], v[20:23]
	v_mfma_f32_16x16x32_bf16 v[16:19], v[214:217], v[190:193], v[16:19]
	v_mfma_f32_16x16x32_bf16 v[4:7], v[206:209], v[198:201], v[4:7]
	v_mfma_f32_16x16x32_bf16 v[0:3], v[214:217], v[198:201], v[0:3]
	v_mfma_f32_16x16x32_bf16 v[52:55], v[210:213], v[174:177], v[52:55]
	v_mfma_f32_16x16x32_bf16 v[48:51], v[218:221], v[174:177], v[48:51]
	v_mfma_f32_16x16x32_bf16 v[36:39], v[210:213], v[182:185], v[36:39]
	v_mfma_f32_16x16x32_bf16 v[32:35], v[218:221], v[182:185], v[32:35]
	v_mfma_f32_16x16x32_bf16 v[20:23], v[210:213], v[194:197], v[20:23]
	v_mfma_f32_16x16x32_bf16 v[16:19], v[218:221], v[194:197], v[16:19]
	v_mfma_f32_16x16x32_bf16 v[4:7], v[210:213], v[202:205], v[4:7]
	v_mfma_f32_16x16x32_bf16 v[0:3], v[218:221], v[202:205], v[0:3]
	s_setprio 0
	s_add_i32 s60, 0, 0x18000
	v_add_u32_e32 v158, s60, v160
	s_barrier
	ds_read_b128 v[128:131], v158
	ds_read_b128 v[148:151], v158 offset:1024
	ds_read_b128 v[152:155], v158 offset:2048
	ds_read_b128 v[166:169], v158 offset:3072
	s_add_u32 s38, s38, 0x40000
	s_addc_u32 s39, s39, 0
	s_mov_b32 m0, s46
	v_lshl_add_u64 v[206:207], s[38:39], 0, v[132:133]
	ds_read_b128 v[170:173], v163 offset:32768
	ds_read_b128 v[174:177], v163 offset:33792
	ds_read_b128 v[178:181], v163 offset:34816
	ds_read_b128 v[182:185], v163 offset:35840
	ds_read_b128 v[190:193], v163 offset:36864
	ds_read_b128 v[194:197], v163 offset:37888
	ds_read_b128 v[198:201], v163 offset:38912
	ds_read_b128 v[202:205], v163 offset:39936
	global_load_lds_dwordx4 v[206:207], off
	v_lshl_add_u64 v[206:207], s[38:39], 0, v[136:137]
	s_mov_b32 m0, s47
	s_nop 0
	global_load_lds_dwordx4 v[206:207], off
	s_waitcnt lgkmcnt(8)
	s_barrier
	s_waitcnt lgkmcnt(0)
	s_setprio 1
	s_waitcnt lgkmcnt(0)
	v_mfma_f32_16x16x32_bf16 v[124:127], v[128:131], v[170:173], v[124:127]
	v_mfma_f32_16x16x32_bf16 v[120:123], v[152:155], v[170:173], v[120:123]
	v_mfma_f32_16x16x32_bf16 v[108:111], v[128:131], v[178:181], v[108:111]
	v_mfma_f32_16x16x32_bf16 v[104:107], v[152:155], v[178:181], v[104:107]
	v_mfma_f32_16x16x32_bf16 v[92:95], v[128:131], v[190:193], v[92:95]
	v_mfma_f32_16x16x32_bf16 v[88:91], v[152:155], v[190:193], v[88:91]
	v_mfma_f32_16x16x32_bf16 v[76:79], v[128:131], v[198:201], v[76:79]
	v_mfma_f32_16x16x32_bf16 v[72:75], v[152:155], v[198:201], v[72:75]
	v_mfma_f32_16x16x32_bf16 v[124:127], v[148:151], v[174:177], v[124:127]
	v_mfma_f32_16x16x32_bf16 v[120:123], v[166:169], v[174:177], v[120:123]
	v_mfma_f32_16x16x32_bf16 v[108:111], v[148:151], v[182:185], v[108:111]
	v_mfma_f32_16x16x32_bf16 v[104:107], v[166:169], v[182:185], v[104:107]
	v_mfma_f32_16x16x32_bf16 v[92:95], v[148:151], v[194:197], v[92:95]
	v_mfma_f32_16x16x32_bf16 v[88:91], v[166:169], v[194:197], v[88:91]
	v_mfma_f32_16x16x32_bf16 v[76:79], v[148:151], v[202:205], v[76:79]
	v_mfma_f32_16x16x32_bf16 v[72:75], v[166:169], v[202:205], v[72:75]
	s_setprio 0
	s_barrier
	s_add_i32 s38, 0, 0x1c000
	s_add_i32 s39, s60, s44
	v_add_u32_e32 v158, s38, v160
	v_lshl_add_u64 v[156:157], v[156:157], 0, s[8:9]
	s_mov_b32 m0, s39
	ds_read_b128 v[206:209], v158
	ds_read_b128 v[210:213], v158 offset:1024
	ds_read_b128 v[214:217], v158 offset:2048
	ds_read_b128 v[218:221], v158 offset:3072
	global_load_lds_dwordx4 v[156:157], off
	v_lshl_add_u64 v[156:157], v[186:187], 0, s[8:9]
	s_add_i32 m0, s39, 0x2000
	s_nop 0
	global_load_lds_dwordx4 v[156:157], off
	s_barrier
	s_waitcnt lgkmcnt(0)
	s_setprio 1
	s_waitcnt lgkmcnt(0)
	v_mfma_f32_16x16x32_bf16 v[116:119], v[206:209], v[170:173], v[116:119]
	v_mfma_f32_16x16x32_bf16 v[112:115], v[214:217], v[170:173], v[112:115]
	v_mfma_f32_16x16x32_bf16 v[100:103], v[206:209], v[178:181], v[100:103]
	v_mfma_f32_16x16x32_bf16 v[96:99], v[214:217], v[178:181], v[96:99]
	v_mfma_f32_16x16x32_bf16 v[84:87], v[206:209], v[190:193], v[84:87]
	v_mfma_f32_16x16x32_bf16 v[80:83], v[214:217], v[190:193], v[80:83]
	v_mfma_f32_16x16x32_bf16 v[68:71], v[206:209], v[198:201], v[68:71]
	v_mfma_f32_16x16x32_bf16 v[64:67], v[214:217], v[198:201], v[64:67]
	v_mfma_f32_16x16x32_bf16 v[116:119], v[210:213], v[174:177], v[116:119]
	v_mfma_f32_16x16x32_bf16 v[112:115], v[218:221], v[174:177], v[112:115]
	v_mfma_f32_16x16x32_bf16 v[100:103], v[210:213], v[182:185], v[100:103]
	v_mfma_f32_16x16x32_bf16 v[96:99], v[218:221], v[182:185], v[96:99]
	v_mfma_f32_16x16x32_bf16 v[84:87], v[210:213], v[194:197], v[84:87]
	v_mfma_f32_16x16x32_bf16 v[80:83], v[218:221], v[194:197], v[80:83]
	v_mfma_f32_16x16x32_bf16 v[68:71], v[210:213], v[202:205], v[68:71]
	v_mfma_f32_16x16x32_bf16 v[64:67], v[218:221], v[202:205], v[64:67]
	s_setprio 0
	s_mov_b32 m0, s49
	v_lshl_add_u64 v[156:157], v[222:223], 0, s[8:9]
	s_barrier
	ds_read_b128 v[170:173], v163 offset:49152
	ds_read_b128 v[174:177], v163 offset:50176
	ds_read_b128 v[178:181], v163 offset:51200
	ds_read_b128 v[182:185], v163 offset:52224
	ds_read_b128 v[190:193], v163 offset:53248
	ds_read_b128 v[194:197], v163 offset:54272
	ds_read_b128 v[198:201], v163 offset:55296
	ds_read_b128 v[202:205], v163 offset:56320
	global_load_lds_dwordx4 v[156:157], off
	v_lshl_add_u64 v[156:157], v[224:225], 0, s[8:9]
	s_mov_b32 m0, s50
	s_nop 0
	global_load_lds_dwordx4 v[156:157], off
	s_barrier
	s_waitcnt lgkmcnt(0)
	s_setprio 1
	s_waitcnt lgkmcnt(0)
	v_mfma_f32_16x16x32_bf16 v[60:63], v[128:131], v[170:173], v[60:63]
	v_mfma_f32_16x16x32_bf16 v[56:59], v[152:155], v[170:173], v[56:59]
	v_mfma_f32_16x16x32_bf16 v[44:47], v[128:131], v[178:181], v[44:47]
	v_mfma_f32_16x16x32_bf16 v[40:43], v[152:155], v[178:181], v[40:43]
	v_mfma_f32_16x16x32_bf16 v[28:31], v[128:131], v[190:193], v[28:31]
	v_mfma_f32_16x16x32_bf16 v[24:27], v[152:155], v[190:193], v[24:27]
	v_mfma_f32_16x16x32_bf16 v[12:15], v[128:131], v[198:201], v[12:15]
	v_mfma_f32_16x16x32_bf16 v[8:11], v[152:155], v[198:201], v[8:11]
	v_mfma_f32_16x16x32_bf16 v[60:63], v[148:151], v[174:177], v[60:63]
	v_mfma_f32_16x16x32_bf16 v[56:59], v[166:169], v[174:177], v[56:59]
	v_mfma_f32_16x16x32_bf16 v[44:47], v[148:151], v[182:185], v[44:47]
	v_mfma_f32_16x16x32_bf16 v[40:43], v[166:169], v[182:185], v[40:43]
	v_mfma_f32_16x16x32_bf16 v[28:31], v[148:151], v[194:197], v[28:31]
	v_mfma_f32_16x16x32_bf16 v[24:27], v[166:169], v[194:197], v[24:27]
	v_mfma_f32_16x16x32_bf16 v[12:15], v[148:151], v[202:205], v[12:15]
	v_mfma_f32_16x16x32_bf16 v[8:11], v[166:169], v[202:205], v[8:11]
	s_setprio 0
	s_barrier
	s_add_u32 s36, s36, 0x40080
	s_addc_u32 s37, s37, 0
	s_add_i32 s38, s38, s44
	v_lshl_add_u64 v[128:129], s[36:37], 0, v[134:135]
	s_mov_b32 m0, s38
	s_nop 0
	global_load_lds_dwordx4 v[128:129], off
	v_lshl_add_u64 v[128:129], s[36:37], 0, v[138:139]
	s_add_i32 m0, s38, 0x2000
	s_nop 0
	global_load_lds_dwordx4 v[128:129], off
	s_waitcnt vmcnt(6)
	s_barrier
	s_setprio 1
	v_mfma_f32_16x16x32_bf16 v[52:55], v[206:209], v[170:173], v[52:55]
	v_mfma_f32_16x16x32_bf16 v[48:51], v[214:217], v[170:173], v[48:51]
	v_mfma_f32_16x16x32_bf16 v[36:39], v[206:209], v[178:181], v[36:39]
	v_mfma_f32_16x16x32_bf16 v[32:35], v[214:217], v[178:181], v[32:35]
	v_mfma_f32_16x16x32_bf16 v[20:23], v[206:209], v[190:193], v[20:23]
	v_mfma_f32_16x16x32_bf16 v[16:19], v[214:217], v[190:193], v[16:19]
	v_mfma_f32_16x16x32_bf16 v[4:7], v[206:209], v[198:201], v[4:7]
	v_mfma_f32_16x16x32_bf16 v[0:3], v[214:217], v[198:201], v[0:3]
	v_mfma_f32_16x16x32_bf16 v[52:55], v[210:213], v[174:177], v[52:55]
	v_mfma_f32_16x16x32_bf16 v[48:51], v[218:221], v[174:177], v[48:51]
	v_mfma_f32_16x16x32_bf16 v[36:39], v[210:213], v[182:185], v[36:39]
	v_mfma_f32_16x16x32_bf16 v[32:35], v[218:221], v[182:185], v[32:35]
	v_mfma_f32_16x16x32_bf16 v[20:23], v[210:213], v[194:197], v[20:23]
	v_mfma_f32_16x16x32_bf16 v[16:19], v[218:221], v[194:197], v[16:19]
	v_mfma_f32_16x16x32_bf16 v[4:7], v[210:213], v[202:205], v[4:7]
	v_mfma_f32_16x16x32_bf16 v[0:3], v[218:221], v[202:205], v[0:3]
	s_setprio 0
	s_add_i32 s59, s59, 2
	s_add_u32 s34, s34, 0x100
	s_addc_u32 s35, s35, 0
	s_add_u32 s57, s57, 0x100
	s_addc_u32 s58, s58, 0
	s_cmp_gt_u32 s59, 13
	s_barrier
	s_cbranch_scc0 .LBB0_286
	v_lshl_add_u32 v128, s30, 8, v159
	v_or_b32_e32 v156, 16, v128
	v_lshl_or_b32 v130, s54, 8, v161
	v_ashrrev_i32_e32 v129, 31, v128
	v_ashrrev_i32_e32 v157, 31, v156
	v_ashrrev_i32_e32 v131, 31, v130
	v_lshl_add_u64 v[152:153], v[128:129], 2, s[10:11]
	v_lshlrev_b64 v[154:155], 11, v[128:129]
	v_lshl_add_u64 v[170:171], v[156:157], 2, s[10:11]
	v_lshlrev_b64 v[186:187], 11, v[156:157]
	v_or_b32_e32 v156, 32, v128
	v_or_b32_e32 v128, 48, v128
	v_lshlrev_b64 v[148:149], 1, v[130:131]
	v_ashrrev_i32_e32 v157, 31, v156
	v_ashrrev_i32_e32 v129, 31, v128
	v_lshl_add_u64 v[150:151], s[0:1], 0, v[148:149]
	v_lshl_add_u64 v[182:183], v[156:157], 2, s[10:11]
	v_lshlrev_b64 v[198:199], 11, v[156:157]
	v_lshlrev_b64 v[156:157], 11, v[128:129]
	v_lshl_add_u64 v[130:131], v[150:151], 0, v[154:155]
	v_lshl_add_u64 v[178:179], v[150:151], 0, v[186:187]
	v_lshl_add_u64 v[190:191], v[150:151], 0, v[198:199]
	v_lshl_add_u64 v[192:193], v[128:129], 2, s[10:11]
	v_lshl_add_u64 v[128:129], v[150:151], 0, v[156:157]
	global_load_dword v200, v[152:153], off
	global_load_dwordx4 v[166:169], v[130:131], off
	global_load_dword v202, v[170:171], off
	s_nop 0
	global_load_dwordx4 v[170:173], v[130:131], off offset:256
	global_load_dwordx4 v[174:177], v[178:179], off
	s_nop 0
	global_load_dwordx4 v[178:181], v[178:179], off offset:256
	s_nop 0
	global_load_dword v204, v[182:183], off
	s_nop 0
	global_load_dwordx4 v[182:185], v[190:191], off
	global_load_dword v158, v[192:193], off
	s_nop 0
	global_load_dwordx4 v[190:193], v[190:191], off offset:256
	s_nop 0
	global_load_dwordx4 v[194:197], v[128:129], off
	s_nop 0
	global_load_dwordx4 v[128:131], v[128:129], off offset:256
	global_load_dword v216, v[152:153], off offset:512
	global_load_dword v218, v[152:153], off offset:576
	global_load_dword v220, v[152:153], off offset:640
	v_lshl_add_u64 v[252:253], v[154:155], 0, s[6:7]
	v_lshl_add_u64 v[252:253], v[150:151], 0, v[252:253]
	global_load_dwordx4 v[236:239], v[252:253], off
	global_load_dwordx4 v[240:243], v[252:253], off offset:256
	v_lshl_add_u64 v[252:253], v[154:155], 0, s[12:13]
	v_lshl_add_u64 v[252:253], v[150:151], 0, v[252:253]
	global_load_dwordx4 v[244:247], v[252:253], off
	global_load_dwordx4 v[248:251], v[252:253], off offset:256
	v_lshl_add_u64 v[252:253], v[154:155], 0, s[14:15]
	v_lshl_add_u64 v[252:253], v[150:151], 0, v[252:253]
	global_load_dwordx4 v[208:211], v[252:253], off
	global_load_dwordx4 v[212:215], v[252:253], off offset:256
	global_load_dword v252, v[152:153], off offset:704
	s_waitcnt vmcnt(10)
	v_pk_mul_f32 v[124:125], v[124:125], v[200:201] op_sel_hi:[1,0]
	v_pk_mul_f32 v[206:207], v[122:123], v[200:201] op_sel_hi:[1,0]
	v_pk_mul_f32 v[122:123], v[120:121], v[200:201] op_sel_hi:[1,0]
	v_lshlrev_b32_e32 v120, 16, v166
	v_and_b32_e32 v121, 0xffff0000, v166
	v_mul_f32_e32 v120, v124, v120
	v_mul_f32_e32 v121, v125, v121
	v_pk_mul_f32 v[126:127], v[126:127], v[200:201] op_sel_hi:[1,0]
	v_cvt_pk_bf16_f32 v120, v120, v121
	v_lshlrev_b32_e32 v121, 16, v167
	v_and_b32_e32 v124, 0xffff0000, v167
	v_mul_f32_e32 v121, v126, v121
	v_mul_f32_e32 v124, v127, v124
	v_cvt_pk_bf16_f32 v121, v121, v124
	v_lshlrev_b32_e32 v124, 16, v168
	v_mul_f32_e32 v122, v122, v124
	v_and_b32_e32 v124, 0xffff0000, v168
	v_mul_f32_e32 v123, v123, v124
	v_cvt_pk_bf16_f32 v122, v122, v123
	v_lshlrev_b32_e32 v123, 16, v169
	v_and_b32_e32 v124, 0xffff0000, v169
	v_mul_f32_e32 v123, v206, v123
	v_mul_f32_e32 v124, v207, v124
	v_cvt_pk_bf16_f32 v123, v123, v124
	v_lshl_add_u64 v[124:125], s[26:27], 0, v[154:155]
	v_lshl_add_u64 v[124:125], v[124:125], 0, v[148:149]
	global_store_dwordx4 v[124:125], v[120:123], off sc1
	v_pk_mul_f32 v[116:117], v[116:117], v[200:201] op_sel_hi:[1,0]
	v_pk_mul_f32 v[118:119], v[118:119], v[200:201] op_sel_hi:[1,0]
	v_pk_mul_f32 v[120:121], v[114:115], v[200:201] op_sel_hi:[1,0]
	v_pk_mul_f32 v[114:115], v[112:113], v[200:201] op_sel_hi:[1,0]
	v_lshlrev_b32_e32 v112, 16, v170
	v_and_b32_e32 v113, 0xffff0000, v170
	v_mul_f32_e32 v112, v116, v112
	v_mul_f32_e32 v113, v117, v113
	v_cvt_pk_bf16_f32 v112, v112, v113
	v_lshlrev_b32_e32 v113, 16, v171
	v_and_b32_e32 v116, 0xffff0000, v171
	v_mul_f32_e32 v113, v118, v113
	v_mul_f32_e32 v116, v119, v116
	v_cvt_pk_bf16_f32 v113, v113, v116
	v_lshlrev_b32_e32 v116, 16, v172
	v_mul_f32_e32 v114, v114, v116
	v_and_b32_e32 v116, 0xffff0000, v172
	v_mul_f32_e32 v115, v115, v116
	v_cvt_pk_bf16_f32 v114, v114, v115
	v_lshlrev_b32_e32 v115, 16, v173
	v_mul_f32_e32 v115, v120, v115
	v_and_b32_e32 v116, 0xffff0000, v173
	v_mul_f32_e32 v116, v121, v116
	v_cvt_pk_bf16_f32 v115, v115, v116
	global_store_dwordx4 v[124:125], v[112:115], off offset:256 sc1
	v_pk_mul_f32 v[108:109], v[108:109], v[202:203] op_sel_hi:[1,0]
	v_pk_mul_f32 v[110:111], v[110:111], v[202:203] op_sel_hi:[1,0]
	v_pk_mul_f32 v[112:113], v[106:107], v[202:203] op_sel_hi:[1,0]
	v_pk_mul_f32 v[106:107], v[104:105], v[202:203] op_sel_hi:[1,0]
	v_lshlrev_b32_e32 v104, 16, v174
	v_and_b32_e32 v105, 0xffff0000, v174
	v_mul_f32_e32 v104, v108, v104
	v_mul_f32_e32 v105, v109, v105
	v_cvt_pk_bf16_f32 v104, v104, v105
	v_lshlrev_b32_e32 v105, 16, v175
	v_and_b32_e32 v108, 0xffff0000, v175
	v_mul_f32_e32 v105, v110, v105
	v_mul_f32_e32 v108, v111, v108
	v_cvt_pk_bf16_f32 v105, v105, v108
	v_lshlrev_b32_e32 v108, 16, v176
	v_mul_f32_e32 v106, v106, v108
	v_and_b32_e32 v108, 0xffff0000, v176
	v_mul_f32_e32 v107, v107, v108
	v_cvt_pk_bf16_f32 v106, v106, v107
	v_lshlrev_b32_e32 v107, 16, v177
	v_and_b32_e32 v108, 0xffff0000, v177
	v_mul_f32_e32 v107, v112, v107
	v_mul_f32_e32 v108, v113, v108
	v_cvt_pk_bf16_f32 v107, v107, v108
	v_lshl_add_u64 v[108:109], s[26:27], 0, v[186:187]
	v_lshl_add_u64 v[108:109], v[108:109], 0, v[148:149]
	global_store_dwordx4 v[108:109], v[104:107], off sc1
	v_pk_mul_f32 v[100:101], v[100:101], v[202:203] op_sel_hi:[1,0]
	v_pk_mul_f32 v[102:103], v[102:103], v[202:203] op_sel_hi:[1,0]
	v_pk_mul_f32 v[104:105], v[98:99], v[202:203] op_sel_hi:[1,0]
	v_pk_mul_f32 v[98:99], v[96:97], v[202:203] op_sel_hi:[1,0]
	v_lshlrev_b32_e32 v96, 16, v178
	v_and_b32_e32 v97, 0xffff0000, v178
	v_mul_f32_e32 v96, v100, v96
	v_mul_f32_e32 v97, v101, v97
	v_cvt_pk_bf16_f32 v96, v96, v97
	v_lshlrev_b32_e32 v97, 16, v179
	v_and_b32_e32 v100, 0xffff0000, v179
	v_mul_f32_e32 v97, v102, v97
	v_mul_f32_e32 v100, v103, v100
	v_cvt_pk_bf16_f32 v97, v97, v100
	v_lshlrev_b32_e32 v100, 16, v180
	v_mul_f32_e32 v98, v98, v100
	v_and_b32_e32 v100, 0xffff0000, v180
	v_mul_f32_e32 v99, v99, v100
	v_cvt_pk_bf16_f32 v98, v98, v99
	v_lshlrev_b32_e32 v99, 16, v181
	v_mul_f32_e32 v99, v104, v99
	v_and_b32_e32 v100, 0xffff0000, v181
	v_mul_f32_e32 v100, v105, v100
	v_cvt_pk_bf16_f32 v99, v99, v100
	global_store_dwordx4 v[108:109], v[96:99], off offset:256 sc1
	v_pk_mul_f32 v[92:93], v[92:93], v[204:205] op_sel_hi:[1,0]
	v_pk_mul_f32 v[94:95], v[94:95], v[204:205] op_sel_hi:[1,0]
	v_pk_mul_f32 v[96:97], v[90:91], v[204:205] op_sel_hi:[1,0]
	v_pk_mul_f32 v[90:91], v[88:89], v[204:205] op_sel_hi:[1,0]
	v_lshlrev_b32_e32 v88, 16, v182
	v_and_b32_e32 v89, 0xffff0000, v182
	v_mul_f32_e32 v88, v92, v88
	v_mul_f32_e32 v89, v93, v89
	v_cvt_pk_bf16_f32 v88, v88, v89
	v_lshlrev_b32_e32 v89, 16, v183
	v_and_b32_e32 v92, 0xffff0000, v183
	v_mul_f32_e32 v89, v94, v89
	v_mul_f32_e32 v92, v95, v92
	v_cvt_pk_bf16_f32 v89, v89, v92
	v_lshlrev_b32_e32 v92, 16, v184
	v_mul_f32_e32 v90, v90, v92
	v_and_b32_e32 v92, 0xffff0000, v184
	v_mul_f32_e32 v91, v91, v92
	v_cvt_pk_bf16_f32 v90, v90, v91
	v_lshlrev_b32_e32 v91, 16, v185
	v_and_b32_e32 v92, 0xffff0000, v185
	v_mul_f32_e32 v91, v96, v91
	v_mul_f32_e32 v92, v97, v92
	v_cvt_pk_bf16_f32 v91, v91, v92
	v_lshl_add_u64 v[92:93], s[26:27], 0, v[198:199]
	v_lshl_add_u64 v[92:93], v[92:93], 0, v[148:149]
	global_store_dwordx4 v[92:93], v[88:91], off sc1
	v_pk_mul_f32 v[84:85], v[84:85], v[204:205] op_sel_hi:[1,0]
	v_pk_mul_f32 v[86:87], v[86:87], v[204:205] op_sel_hi:[1,0]
	v_pk_mul_f32 v[88:89], v[82:83], v[204:205] op_sel_hi:[1,0]
	v_pk_mul_f32 v[82:83], v[80:81], v[204:205] op_sel_hi:[1,0]
	v_lshlrev_b32_e32 v80, 16, v190
	v_and_b32_e32 v81, 0xffff0000, v190
	v_mul_f32_e32 v80, v84, v80
	v_mul_f32_e32 v81, v85, v81
	v_cvt_pk_bf16_f32 v80, v80, v81
	v_lshlrev_b32_e32 v81, 16, v191
	v_and_b32_e32 v84, 0xffff0000, v191
	v_mul_f32_e32 v81, v86, v81
	v_mul_f32_e32 v84, v87, v84
	v_cvt_pk_bf16_f32 v81, v81, v84
	v_lshlrev_b32_e32 v84, 16, v192
	v_mul_f32_e32 v82, v82, v84
	v_and_b32_e32 v84, 0xffff0000, v192
	v_mul_f32_e32 v83, v83, v84
	v_cvt_pk_bf16_f32 v82, v82, v83
	v_lshlrev_b32_e32 v83, 16, v193
	v_mul_f32_e32 v83, v88, v83
	v_and_b32_e32 v84, 0xffff0000, v193
	v_mul_f32_e32 v84, v89, v84
	v_cvt_pk_bf16_f32 v83, v83, v84
	global_store_dwordx4 v[92:93], v[80:83], off offset:256 sc1
	v_pk_mul_f32 v[76:77], v[76:77], v[158:159] op_sel_hi:[1,0]
	v_pk_mul_f32 v[78:79], v[78:79], v[158:159] op_sel_hi:[1,0]
	v_pk_mul_f32 v[80:81], v[74:75], v[158:159] op_sel_hi:[1,0]
	v_pk_mul_f32 v[74:75], v[72:73], v[158:159] op_sel_hi:[1,0]
	v_lshlrev_b32_e32 v72, 16, v194
	v_and_b32_e32 v73, 0xffff0000, v194
	v_mul_f32_e32 v72, v76, v72
	v_mul_f32_e32 v73, v77, v73
	v_cvt_pk_bf16_f32 v72, v72, v73
	v_lshlrev_b32_e32 v73, 16, v195
	v_and_b32_e32 v76, 0xffff0000, v195
	v_mul_f32_e32 v73, v78, v73
	v_mul_f32_e32 v76, v79, v76
	v_cvt_pk_bf16_f32 v73, v73, v76
	v_lshlrev_b32_e32 v76, 16, v196
	v_mul_f32_e32 v74, v74, v76
	v_and_b32_e32 v76, 0xffff0000, v196
	v_mul_f32_e32 v75, v75, v76
	v_cvt_pk_bf16_f32 v74, v74, v75
	v_lshlrev_b32_e32 v75, 16, v197
	v_and_b32_e32 v76, 0xffff0000, v197
	v_mul_f32_e32 v75, v80, v75
	v_mul_f32_e32 v76, v81, v76
	v_cvt_pk_bf16_f32 v75, v75, v76
	v_lshl_add_u64 v[76:77], s[26:27], 0, v[156:157]
	v_lshl_add_u64 v[76:77], v[76:77], 0, v[148:149]
	global_store_dwordx4 v[76:77], v[72:75], off sc1
	v_pk_mul_f32 v[68:69], v[68:69], v[158:159] op_sel_hi:[1,0]
	v_pk_mul_f32 v[70:71], v[70:71], v[158:159] op_sel_hi:[1,0]
	v_pk_mul_f32 v[72:73], v[66:67], v[158:159] op_sel_hi:[1,0]
	v_pk_mul_f32 v[66:67], v[64:65], v[158:159] op_sel_hi:[1,0]
	v_lshlrev_b32_e32 v64, 16, v128
	v_and_b32_e32 v65, 0xffff0000, v128
	v_mul_f32_e32 v64, v68, v64
	v_mul_f32_e32 v65, v69, v65
	v_cvt_pk_bf16_f32 v64, v64, v65
	v_lshlrev_b32_e32 v65, 16, v129
	v_and_b32_e32 v68, 0xffff0000, v129
	v_mul_f32_e32 v65, v70, v65
	v_mul_f32_e32 v68, v71, v68
	v_cvt_pk_bf16_f32 v65, v65, v68
	v_lshlrev_b32_e32 v68, 16, v130
	v_mul_f32_e32 v66, v66, v68
	v_and_b32_e32 v68, 0xffff0000, v130
	v_mul_f32_e32 v67, v67, v68
	v_cvt_pk_bf16_f32 v66, v66, v67
	v_lshlrev_b32_e32 v67, 16, v131
	v_mul_f32_e32 v67, v72, v67
	v_and_b32_e32 v68, 0xffff0000, v131
	v_mul_f32_e32 v68, v73, v68
	v_cvt_pk_bf16_f32 v67, v67, v68
	v_lshl_add_u64 v[100:101], v[154:155], 0, s[6:7]
	v_lshl_add_u64 v[102:103], v[154:155], 0, s[12:13]
	v_lshl_add_u64 v[104:105], v[154:155], 0, s[14:15]
	global_store_dwordx4 v[76:77], v[64:67], off offset:256 sc1
	v_lshl_add_u64 v[92:93], v[150:151], 0, v[104:105]
	v_lshl_add_u64 v[70:71], v[154:155], 0, s[18:19]
	v_lshl_add_u64 v[64:65], v[150:151], 0, v[100:101]
	v_lshl_add_u64 v[66:67], v[150:151], 0, v[102:103]
	v_lshl_add_u64 v[112:113], v[150:151], 0, v[70:71]
	s_nop 0
	s_nop 0
	global_load_dwordx4 v[96:99], v[112:113], off
	global_load_dwordx4 v[64:67], v[112:113], off offset:256
	s_waitcnt vmcnt(10)
	v_pk_mul_f32 v[60:61], v[60:61], v[216:217] op_sel_hi:[1,0]
	v_pk_mul_f32 v[112:113], v[58:59], v[216:217] op_sel_hi:[1,0]
	v_pk_mul_f32 v[58:59], v[56:57], v[216:217] op_sel_hi:[1,0]
	v_lshlrev_b32_e32 v56, 16, v236
	v_and_b32_e32 v57, 0xffff0000, v236
	v_mul_f32_e32 v56, v60, v56
	v_mul_f32_e32 v57, v61, v57
	v_pk_mul_f32 v[62:63], v[62:63], v[216:217] op_sel_hi:[1,0]
	v_cvt_pk_bf16_f32 v56, v56, v57
	v_lshlrev_b32_e32 v57, 16, v237
	v_and_b32_e32 v60, 0xffff0000, v237
	v_mul_f32_e32 v57, v62, v57
	v_mul_f32_e32 v60, v63, v60
	v_cvt_pk_bf16_f32 v57, v57, v60
	v_lshlrev_b32_e32 v60, 16, v238
	v_mul_f32_e32 v58, v58, v60
	v_and_b32_e32 v60, 0xffff0000, v238
	v_mul_f32_e32 v59, v59, v60
	v_cvt_pk_bf16_f32 v58, v58, v59
	v_lshlrev_b32_e32 v59, 16, v239
	v_and_b32_e32 v60, 0xffff0000, v239
	v_mul_f32_e32 v59, v112, v59
	v_mul_f32_e32 v60, v113, v60
	v_cvt_pk_bf16_f32 v59, v59, v60
	v_lshl_add_u64 v[60:61], s[26:27], 0, v[100:101]
	v_lshl_add_u64 v[60:61], v[60:61], 0, v[148:149]
	global_store_dwordx4 v[60:61], v[56:59], off sc1
	v_pk_mul_f32 v[52:53], v[52:53], v[216:217] op_sel_hi:[1,0]
	v_pk_mul_f32 v[54:55], v[54:55], v[216:217] op_sel_hi:[1,0]
	v_pk_mul_f32 v[56:57], v[50:51], v[216:217] op_sel_hi:[1,0]
	v_pk_mul_f32 v[50:51], v[48:49], v[216:217] op_sel_hi:[1,0]
	v_lshlrev_b32_e32 v48, 16, v240
	v_and_b32_e32 v49, 0xffff0000, v240
	v_mul_f32_e32 v48, v52, v48
	v_mul_f32_e32 v49, v53, v49
	v_cvt_pk_bf16_f32 v48, v48, v49
	v_lshlrev_b32_e32 v49, 16, v241
	v_and_b32_e32 v52, 0xffff0000, v241
	v_mul_f32_e32 v49, v54, v49
	v_mul_f32_e32 v52, v55, v52
	v_cvt_pk_bf16_f32 v49, v49, v52
	v_lshlrev_b32_e32 v52, 16, v242
	v_mul_f32_e32 v50, v50, v52
	v_and_b32_e32 v52, 0xffff0000, v242
	v_mul_f32_e32 v51, v51, v52
	v_cvt_pk_bf16_f32 v50, v50, v51
	v_lshlrev_b32_e32 v51, 16, v243
	v_mul_f32_e32 v51, v56, v51
	v_and_b32_e32 v52, 0xffff0000, v243
	v_mul_f32_e32 v52, v57, v52
	v_cvt_pk_bf16_f32 v51, v51, v52
	global_store_dwordx4 v[60:61], v[48:51], off offset:256 sc1
	v_pk_mul_f32 v[44:45], v[44:45], v[218:219] op_sel_hi:[1,0]
	v_pk_mul_f32 v[46:47], v[46:47], v[218:219] op_sel_hi:[1,0]
	v_pk_mul_f32 v[48:49], v[42:43], v[218:219] op_sel_hi:[1,0]
	v_pk_mul_f32 v[42:43], v[40:41], v[218:219] op_sel_hi:[1,0]
	v_lshlrev_b32_e32 v40, 16, v244
	v_and_b32_e32 v41, 0xffff0000, v244
	v_mul_f32_e32 v40, v44, v40
	v_mul_f32_e32 v41, v45, v41
	v_cvt_pk_bf16_f32 v40, v40, v41
	v_lshlrev_b32_e32 v41, 16, v245
	v_and_b32_e32 v44, 0xffff0000, v245
	v_mul_f32_e32 v41, v46, v41
	v_mul_f32_e32 v44, v47, v44
	v_cvt_pk_bf16_f32 v41, v41, v44
	v_lshlrev_b32_e32 v44, 16, v246
	v_mul_f32_e32 v42, v42, v44
	v_and_b32_e32 v44, 0xffff0000, v246
	v_mul_f32_e32 v43, v43, v44
	v_cvt_pk_bf16_f32 v42, v42, v43
	v_lshlrev_b32_e32 v43, 16, v247
	v_and_b32_e32 v44, 0xffff0000, v247
	v_mul_f32_e32 v43, v48, v43
	v_mul_f32_e32 v44, v49, v44
	v_cvt_pk_bf16_f32 v43, v43, v44
	v_lshl_add_u64 v[44:45], s[26:27], 0, v[102:103]
	v_lshl_add_u64 v[44:45], v[44:45], 0, v[148:149]
	global_store_dwordx4 v[44:45], v[40:43], off sc1
	v_pk_mul_f32 v[36:37], v[36:37], v[218:219] op_sel_hi:[1,0]
	v_pk_mul_f32 v[38:39], v[38:39], v[218:219] op_sel_hi:[1,0]
	v_pk_mul_f32 v[40:41], v[34:35], v[218:219] op_sel_hi:[1,0]
	v_pk_mul_f32 v[34:35], v[32:33], v[218:219] op_sel_hi:[1,0]
	v_lshlrev_b32_e32 v32, 16, v248
	v_and_b32_e32 v33, 0xffff0000, v248
	v_mul_f32_e32 v32, v36, v32
	v_mul_f32_e32 v33, v37, v33
	v_cvt_pk_bf16_f32 v32, v32, v33
	v_lshlrev_b32_e32 v33, 16, v249
	v_and_b32_e32 v36, 0xffff0000, v249
	v_mul_f32_e32 v33, v38, v33
	v_mul_f32_e32 v36, v39, v36
	v_cvt_pk_bf16_f32 v33, v33, v36
	v_lshlrev_b32_e32 v36, 16, v250
	v_mul_f32_e32 v34, v34, v36
	v_and_b32_e32 v36, 0xffff0000, v250
	v_mul_f32_e32 v35, v35, v36
	v_cvt_pk_bf16_f32 v34, v34, v35
	v_lshlrev_b32_e32 v35, 16, v251
	v_mul_f32_e32 v35, v40, v35
	v_and_b32_e32 v36, 0xffff0000, v251
	v_mul_f32_e32 v36, v41, v36
	v_cvt_pk_bf16_f32 v35, v35, v36
	global_store_dwordx4 v[44:45], v[32:35], off offset:256 sc1
	v_pk_mul_f32 v[28:29], v[28:29], v[220:221] op_sel_hi:[1,0]
	v_pk_mul_f32 v[30:31], v[30:31], v[220:221] op_sel_hi:[1,0]
	v_pk_mul_f32 v[32:33], v[26:27], v[220:221] op_sel_hi:[1,0]
	v_pk_mul_f32 v[26:27], v[24:25], v[220:221] op_sel_hi:[1,0]
	v_lshlrev_b32_e32 v24, 16, v208
	v_and_b32_e32 v25, 0xffff0000, v208
	v_mul_f32_e32 v24, v28, v24
	v_mul_f32_e32 v25, v29, v25
	v_cvt_pk_bf16_f32 v24, v24, v25
	v_lshlrev_b32_e32 v25, 16, v209
	v_and_b32_e32 v28, 0xffff0000, v209
	v_mul_f32_e32 v25, v30, v25
	v_mul_f32_e32 v28, v31, v28
	v_cvt_pk_bf16_f32 v25, v25, v28
	v_lshlrev_b32_e32 v28, 16, v210
	v_mul_f32_e32 v26, v26, v28
	v_and_b32_e32 v28, 0xffff0000, v210
	v_mul_f32_e32 v27, v27, v28
	v_cvt_pk_bf16_f32 v26, v26, v27
	v_lshlrev_b32_e32 v27, 16, v211
	v_and_b32_e32 v28, 0xffff0000, v211
	v_mul_f32_e32 v27, v32, v27
	v_mul_f32_e32 v28, v33, v28
	v_cvt_pk_bf16_f32 v27, v27, v28
	v_lshl_add_u64 v[28:29], s[26:27], 0, v[104:105]
	v_lshl_add_u64 v[28:29], v[28:29], 0, v[148:149]
	global_store_dwordx4 v[28:29], v[24:27], off sc1
	v_pk_mul_f32 v[20:21], v[20:21], v[220:221] op_sel_hi:[1,0]
	v_pk_mul_f32 v[22:23], v[22:23], v[220:221] op_sel_hi:[1,0]
	v_pk_mul_f32 v[24:25], v[18:19], v[220:221] op_sel_hi:[1,0]
	v_pk_mul_f32 v[18:19], v[16:17], v[220:221] op_sel_hi:[1,0]
	v_lshlrev_b32_e32 v16, 16, v212
	v_and_b32_e32 v17, 0xffff0000, v212
	v_mul_f32_e32 v16, v20, v16
	v_mul_f32_e32 v17, v21, v17
	v_cvt_pk_bf16_f32 v16, v16, v17
	v_lshlrev_b32_e32 v17, 16, v213
	v_and_b32_e32 v20, 0xffff0000, v213
	v_mul_f32_e32 v17, v22, v17
	v_mul_f32_e32 v20, v23, v20
	v_cvt_pk_bf16_f32 v17, v17, v20
	v_lshlrev_b32_e32 v20, 16, v214
	v_mul_f32_e32 v18, v18, v20
	v_and_b32_e32 v20, 0xffff0000, v214
	v_mul_f32_e32 v19, v19, v20
	v_cvt_pk_bf16_f32 v18, v18, v19
	v_lshlrev_b32_e32 v19, 16, v215
	v_mul_f32_e32 v19, v24, v19
	v_and_b32_e32 v20, 0xffff0000, v215
	v_mul_f32_e32 v20, v25, v20
	v_cvt_pk_bf16_f32 v19, v19, v20
	global_store_dwordx4 v[28:29], v[16:19], off offset:256 sc1
	s_waitcnt vmcnt(6)
	v_pk_mul_f32 v[12:13], v[12:13], v[252:253] op_sel_hi:[1,0]
	v_pk_mul_f32 v[14:15], v[14:15], v[252:253] op_sel_hi:[1,0]
	v_pk_mul_f32 v[16:17], v[10:11], v[252:253] op_sel_hi:[1,0]
	v_pk_mul_f32 v[10:11], v[8:9], v[252:253] op_sel_hi:[1,0]
	v_lshlrev_b32_e32 v8, 16, v96
	v_and_b32_e32 v9, 0xffff0000, v96
	v_mul_f32_e32 v8, v12, v8
	v_mul_f32_e32 v9, v13, v9
	v_cvt_pk_bf16_f32 v8, v8, v9
	v_lshlrev_b32_e32 v9, 16, v97
	v_and_b32_e32 v12, 0xffff0000, v97
	v_mul_f32_e32 v9, v14, v9
	v_mul_f32_e32 v12, v15, v12
	v_cvt_pk_bf16_f32 v9, v9, v12
	v_lshlrev_b32_e32 v12, 16, v98
	v_mul_f32_e32 v10, v10, v12
	v_and_b32_e32 v12, 0xffff0000, v98
	v_mul_f32_e32 v11, v11, v12
	v_cvt_pk_bf16_f32 v10, v10, v11
	v_lshlrev_b32_e32 v11, 16, v99
	v_and_b32_e32 v12, 0xffff0000, v99
	v_mul_f32_e32 v11, v16, v11
	v_mul_f32_e32 v12, v17, v12
	v_cvt_pk_bf16_f32 v11, v11, v12
	v_lshl_add_u64 v[12:13], s[26:27], 0, v[70:71]
	v_lshl_add_u64 v[12:13], v[12:13], 0, v[148:149]
	global_store_dwordx4 v[12:13], v[8:11], off sc1
	v_pk_mul_f32 v[4:5], v[4:5], v[252:253] op_sel_hi:[1,0]
	v_pk_mul_f32 v[6:7], v[6:7], v[252:253] op_sel_hi:[1,0]
	v_pk_mul_f32 v[8:9], v[2:3], v[252:253] op_sel_hi:[1,0]
	v_pk_mul_f32 v[2:3], v[0:1], v[252:253] op_sel_hi:[1,0]
	v_lshlrev_b32_e32 v0, 16, v64
	v_and_b32_e32 v1, 0xffff0000, v64
	v_mul_f32_e32 v0, v4, v0
	v_mul_f32_e32 v1, v5, v1
	v_cvt_pk_bf16_f32 v0, v0, v1
	v_lshlrev_b32_e32 v1, 16, v65
	v_and_b32_e32 v4, 0xffff0000, v65
	v_mul_f32_e32 v1, v6, v1
	v_mul_f32_e32 v4, v7, v4
	v_cvt_pk_bf16_f32 v1, v1, v4
	v_lshlrev_b32_e32 v4, 16, v66
	v_mul_f32_e32 v2, v2, v4
	v_and_b32_e32 v4, 0xffff0000, v66
	v_mul_f32_e32 v3, v3, v4
	v_cvt_pk_bf16_f32 v2, v2, v3
	v_lshlrev_b32_e32 v3, 16, v67
	v_mul_f32_e32 v3, v8, v3
	v_and_b32_e32 v4, 0xffff0000, v67
	s_and_b64 vcc, exec, s[2:3]
	s_mov_b32 s54, s20
	s_mov_b32 s30, s22
	s_mov_b64 s[36:37], s[28:29]
	s_mov_b64 s[34:35], s[24:25]
	v_mul_f32_e32 v4, v9, v4
	v_cvt_pk_bf16_f32 v3, v3, v4
	global_store_dwordx4 v[12:13], v[0:3], off offset:256 sc1
	s_cbranch_vccz .LBB0_279
	s_waitcnt vmcnt(0)
	s_cmpk_gt_u32 s40, 0xff
	s_cbranch_scc1 .LBB0_290
	s_barrier

.LBB0_364:
	ds_read_b128 v[128:131], v208
	ds_read_b128 v[132:135], v208 offset:1024
	ds_read_b128 v[136:139], v208 offset:2048
	ds_read_b128 v[140:143], v208 offset:3072
	s_add_u32 s24, s22, 0xfffc0080
	s_addc_u32 s25, s23, -1
	s_cmp_eq_u32 s51, 12
	s_cselect_b32 s29, s13, s25
	s_cselect_b32 s28, s21, s24
	s_cselect_b32 s25, s11, s50
	s_cselect_b32 s24, s48, s49
	v_lshl_add_u64 v[194:195], s[22:23], 0, v[184:185]
	s_add_i32 m0, s36, 0xc000
	ds_read_b128 v[144:147], v209
	ds_read_b128 v[148:151], v209 offset:1024
	ds_read_b128 v[152:155], v209 offset:2048
	ds_read_b128 v[156:159], v209 offset:3072
	ds_read_b128 v[160:163], v209 offset:4096
	ds_read_b128 v[164:167], v209 offset:5120
	ds_read_b128 v[168:171], v209 offset:6144
	ds_read_b128 v[172:175], v209 offset:7168
	global_load_lds_dwordx4 v[194:195], off
	v_lshl_add_u64 v[194:195], s[22:23], 0, v[186:187]
	s_add_i32 m0, s36, 0xe000
	s_nop 0
	global_load_lds_dwordx4 v[194:195], off
	s_waitcnt lgkmcnt(8)
	s_barrier
	s_waitcnt lgkmcnt(0)
	s_setprio 1
	s_waitcnt lgkmcnt(0)
	v_mfma_f32_16x16x32_bf16 v[124:127], v[128:131], v[144:147], v[124:127]
	v_mfma_f32_16x16x32_bf16 v[120:123], v[136:139], v[144:147], v[120:123]
	v_mfma_f32_16x16x32_bf16 v[108:111], v[128:131], v[152:155], v[108:111]
	v_mfma_f32_16x16x32_bf16 v[104:107], v[136:139], v[152:155], v[104:107]
	v_mfma_f32_16x16x32_bf16 v[92:95], v[128:131], v[160:163], v[92:95]
	v_mfma_f32_16x16x32_bf16 v[88:91], v[136:139], v[160:163], v[88:91]
	v_mfma_f32_16x16x32_bf16 v[76:79], v[128:131], v[168:171], v[76:79]
	v_mfma_f32_16x16x32_bf16 v[72:75], v[136:139], v[168:171], v[72:75]
	v_mfma_f32_16x16x32_bf16 v[124:127], v[132:135], v[148:151], v[124:127]
	v_mfma_f32_16x16x32_bf16 v[120:123], v[140:143], v[148:151], v[120:123]
	v_mfma_f32_16x16x32_bf16 v[108:111], v[132:135], v[156:159], v[108:111]
	v_mfma_f32_16x16x32_bf16 v[104:107], v[140:143], v[156:159], v[104:107]
	v_mfma_f32_16x16x32_bf16 v[92:95], v[132:135], v[164:167], v[92:95]
	v_mfma_f32_16x16x32_bf16 v[88:91], v[140:143], v[164:167], v[88:91]
	v_mfma_f32_16x16x32_bf16 v[76:79], v[132:135], v[172:175], v[76:79]
	v_mfma_f32_16x16x32_bf16 v[72:75], v[140:143], v[172:175], v[72:75]
	s_setprio 0
	s_barrier
	s_add_i32 s52, s45, s35
	v_lshl_add_u64 v[216:217], s[24:25], 0, v[178:179]
	s_mov_b32 m0, s52
	ds_read_b128 v[194:197], v210
	ds_read_b128 v[198:201], v210 offset:1024
	ds_read_b128 v[202:205], v210 offset:2048
	ds_read_b128 v[212:215], v210 offset:3072
	global_load_lds_dwordx4 v[216:217], off
	v_lshl_add_u64 v[218:219], s[24:25], 0, v[182:183]
	s_add_i32 m0, s52, 0x2000
	s_nop 0
	global_load_lds_dwordx4 v[218:219], off
	s_barrier
	s_waitcnt lgkmcnt(0)
	s_setprio 1
	s_waitcnt lgkmcnt(0)
	v_mfma_f32_16x16x32_bf16 v[116:119], v[194:197], v[144:147], v[116:119]
	v_mfma_f32_16x16x32_bf16 v[112:115], v[202:205], v[144:147], v[112:115]
	v_mfma_f32_16x16x32_bf16 v[100:103], v[194:197], v[152:155], v[100:103]
	v_mfma_f32_16x16x32_bf16 v[96:99], v[202:205], v[152:155], v[96:99]
	v_mfma_f32_16x16x32_bf16 v[84:87], v[194:197], v[160:163], v[84:87]
	v_mfma_f32_16x16x32_bf16 v[80:83], v[202:205], v[160:163], v[80:83]
	v_mfma_f32_16x16x32_bf16 v[68:71], v[194:197], v[168:171], v[68:71]
	v_mfma_f32_16x16x32_bf16 v[64:67], v[202:205], v[168:171], v[64:67]
	v_mfma_f32_16x16x32_bf16 v[116:119], v[198:201], v[148:151], v[116:119]
	v_mfma_f32_16x16x32_bf16 v[112:115], v[212:215], v[148:151], v[112:115]
	v_mfma_f32_16x16x32_bf16 v[100:103], v[198:201], v[156:159], v[100:103]
	v_mfma_f32_16x16x32_bf16 v[96:99], v[212:215], v[156:159], v[96:99]
	v_mfma_f32_16x16x32_bf16 v[84:87], v[198:201], v[164:167], v[84:87]
	v_mfma_f32_16x16x32_bf16 v[80:83], v[212:215], v[164:167], v[80:83]
	v_mfma_f32_16x16x32_bf16 v[68:71], v[198:201], v[172:175], v[68:71]
	v_mfma_f32_16x16x32_bf16 v[64:67], v[212:215], v[172:175], v[64:67]
	s_setprio 0
	s_mov_b32 m0, s36
	v_lshl_add_u64 v[220:221], s[28:29], 0, v[176:177]
	s_barrier
	ds_read_b128 v[144:147], v209 offset:16384
	ds_read_b128 v[148:151], v209 offset:17408
	ds_read_b128 v[152:155], v209 offset:18432
	ds_read_b128 v[156:159], v209 offset:19456
	ds_read_b128 v[160:163], v209 offset:20480
	ds_read_b128 v[164:167], v209 offset:21504
	ds_read_b128 v[168:171], v209 offset:22528
	ds_read_b128 v[172:175], v209 offset:23552
	global_load_lds_dwordx4 v[220:221], off
	v_lshl_add_u64 v[222:223], s[28:29], 0, v[180:181]
	s_mov_b32 m0, s37
	s_nop 0
	global_load_lds_dwordx4 v[222:223], off
	s_barrier
	s_waitcnt lgkmcnt(0)
	s_setprio 1
	s_waitcnt lgkmcnt(0)
	v_mfma_f32_16x16x32_bf16 v[60:63], v[128:131], v[144:147], v[60:63]
	v_mfma_f32_16x16x32_bf16 v[56:59], v[136:139], v[144:147], v[56:59]
	v_mfma_f32_16x16x32_bf16 v[44:47], v[128:131], v[152:155], v[44:47]
	v_mfma_f32_16x16x32_bf16 v[40:43], v[136:139], v[152:155], v[40:43]
	v_mfma_f32_16x16x32_bf16 v[28:31], v[128:131], v[160:163], v[28:31]
	v_mfma_f32_16x16x32_bf16 v[24:27], v[136:139], v[160:163], v[24:27]
	v_mfma_f32_16x16x32_bf16 v[12:15], v[128:131], v[168:171], v[12:15]
	v_mfma_f32_16x16x32_bf16 v[8:11], v[136:139], v[168:171], v[8:11]
	v_mfma_f32_16x16x32_bf16 v[60:63], v[132:135], v[148:151], v[60:63]
	v_mfma_f32_16x16x32_bf16 v[56:59], v[140:143], v[148:151], v[56:59]
	v_mfma_f32_16x16x32_bf16 v[44:47], v[132:135], v[156:159], v[44:47]
	v_mfma_f32_16x16x32_bf16 v[40:43], v[140:143], v[156:159], v[40:43]
	v_mfma_f32_16x16x32_bf16 v[28:31], v[132:135], v[164:167], v[28:31]
	v_mfma_f32_16x16x32_bf16 v[24:27], v[140:143], v[164:167], v[24:27]
	v_mfma_f32_16x16x32_bf16 v[12:15], v[132:135], v[172:175], v[12:15]
	v_mfma_f32_16x16x32_bf16 v[8:11], v[140:143], v[172:175], v[8:11]
	s_setprio 0
	s_barrier
	s_add_u32 s52, s24, 0x40000
	s_addc_u32 s53, s25, 0
	s_add_i32 s54, s46, s35
	v_lshl_add_u64 v[128:129], s[52:53], 0, v[178:179]
	s_mov_b32 m0, s54
	s_nop 0
	global_load_lds_dwordx4 v[128:129], off
	v_lshl_add_u64 v[128:129], s[52:53], 0, v[182:183]
	s_add_i32 m0, s54, 0x2000
	s_nop 0
	global_load_lds_dwordx4 v[128:129], off
	s_waitcnt vmcnt(6)
	s_barrier
	s_setprio 1
	v_mfma_f32_16x16x32_bf16 v[52:55], v[194:197], v[144:147], v[52:55]
	v_mfma_f32_16x16x32_bf16 v[48:51], v[202:205], v[144:147], v[48:51]
	v_mfma_f32_16x16x32_bf16 v[36:39], v[194:197], v[152:155], v[36:39]
	v_mfma_f32_16x16x32_bf16 v[32:35], v[202:205], v[152:155], v[32:35]
	v_mfma_f32_16x16x32_bf16 v[20:23], v[194:197], v[160:163], v[20:23]
	v_mfma_f32_16x16x32_bf16 v[16:19], v[202:205], v[160:163], v[16:19]
	v_mfma_f32_16x16x32_bf16 v[4:7], v[194:197], v[168:171], v[4:7]
	v_mfma_f32_16x16x32_bf16 v[0:3], v[202:205], v[168:171], v[0:3]
	v_mfma_f32_16x16x32_bf16 v[52:55], v[198:201], v[148:151], v[52:55]
	v_mfma_f32_16x16x32_bf16 v[48:51], v[212:215], v[148:151], v[48:51]
	v_mfma_f32_16x16x32_bf16 v[36:39], v[198:201], v[156:159], v[36:39]
	v_mfma_f32_16x16x32_bf16 v[32:35], v[212:215], v[156:159], v[32:35]
	v_mfma_f32_16x16x32_bf16 v[20:23], v[198:201], v[164:167], v[20:23]
	v_mfma_f32_16x16x32_bf16 v[16:19], v[212:215], v[164:167], v[16:19]
	v_mfma_f32_16x16x32_bf16 v[4:7], v[198:201], v[172:175], v[4:7]
	v_mfma_f32_16x16x32_bf16 v[0:3], v[212:215], v[172:175], v[0:3]
	s_setprio 0
	s_add_i32 s52, 0, 0x18000
	v_add_u32_e32 v140, s52, v206
	s_barrier
	ds_read_b128 v[128:131], v140
	ds_read_b128 v[132:135], v140 offset:1024
	ds_read_b128 v[136:139], v140 offset:2048
	ds_read_b128 v[140:143], v140 offset:3072
	s_add_u32 s28, s28, 0x40000
	s_addc_u32 s29, s29, 0
	s_mov_b32 m0, s38
	v_lshl_add_u64 v[194:195], s[28:29], 0, v[176:177]
	ds_read_b128 v[144:147], v209 offset:32768
	ds_read_b128 v[148:151], v209 offset:33792
	ds_read_b128 v[152:155], v209 offset:34816
	ds_read_b128 v[156:159], v209 offset:35840
	ds_read_b128 v[160:163], v209 offset:36864
	ds_read_b128 v[164:167], v209 offset:37888
	ds_read_b128 v[168:171], v209 offset:38912
	ds_read_b128 v[172:175], v209 offset:39936
	global_load_lds_dwordx4 v[194:195], off
	v_lshl_add_u64 v[194:195], s[28:29], 0, v[180:181]
	s_mov_b32 m0, s39
	s_nop 0
	global_load_lds_dwordx4 v[194:195], off
	s_waitcnt lgkmcnt(8)
	s_barrier
	s_waitcnt lgkmcnt(0)
	s_setprio 1
	s_waitcnt lgkmcnt(0)
	v_mfma_f32_16x16x32_bf16 v[124:127], v[128:131], v[144:147], v[124:127]
	v_mfma_f32_16x16x32_bf16 v[120:123], v[136:139], v[144:147], v[120:123]
	v_mfma_f32_16x16x32_bf16 v[108:111], v[128:131], v[152:155], v[108:111]
	v_mfma_f32_16x16x32_bf16 v[104:107], v[136:139], v[152:155], v[104:107]
	v_mfma_f32_16x16x32_bf16 v[92:95], v[128:131], v[160:163], v[92:95]
	v_mfma_f32_16x16x32_bf16 v[88:91], v[136:139], v[160:163], v[88:91]
	v_mfma_f32_16x16x32_bf16 v[76:79], v[128:131], v[168:171], v[76:79]
	v_mfma_f32_16x16x32_bf16 v[72:75], v[136:139], v[168:171], v[72:75]
	v_mfma_f32_16x16x32_bf16 v[124:127], v[132:135], v[148:151], v[124:127]
	v_mfma_f32_16x16x32_bf16 v[120:123], v[140:143], v[148:151], v[120:123]
	v_mfma_f32_16x16x32_bf16 v[108:111], v[132:135], v[156:159], v[108:111]
	v_mfma_f32_16x16x32_bf16 v[104:107], v[140:143], v[156:159], v[104:107]
	v_mfma_f32_16x16x32_bf16 v[92:95], v[132:135], v[164:167], v[92:95]
	v_mfma_f32_16x16x32_bf16 v[88:91], v[140:143], v[164:167], v[88:91]
	v_mfma_f32_16x16x32_bf16 v[76:79], v[132:135], v[172:175], v[76:79]
	v_mfma_f32_16x16x32_bf16 v[72:75], v[140:143], v[172:175], v[72:75]
	s_setprio 0
	s_barrier
	s_add_i32 s28, 0, 0x1c000
	s_add_i32 s29, s52, s35
	v_add_u32_e32 v212, s28, v206
	v_lshl_add_u64 v[216:217], v[216:217], 0, s[8:9]
	s_mov_b32 m0, s29
	ds_read_b128 v[194:197], v212
	ds_read_b128 v[198:201], v212 offset:1024
	ds_read_b128 v[202:205], v212 offset:2048
	ds_read_b128 v[212:215], v212 offset:3072
	global_load_lds_dwordx4 v[216:217], off
	v_lshl_add_u64 v[216:217], v[218:219], 0, s[8:9]
	s_add_i32 m0, s29, 0x2000
	s_nop 0
	global_load_lds_dwordx4 v[216:217], off
	s_barrier
	s_waitcnt lgkmcnt(0)
	s_setprio 1
	s_waitcnt lgkmcnt(0)
	v_mfma_f32_16x16x32_bf16 v[116:119], v[194:197], v[144:147], v[116:119]
	v_mfma_f32_16x16x32_bf16 v[112:115], v[202:205], v[144:147], v[112:115]
	v_mfma_f32_16x16x32_bf16 v[100:103], v[194:197], v[152:155], v[100:103]
	v_mfma_f32_16x16x32_bf16 v[96:99], v[202:205], v[152:155], v[96:99]
	v_mfma_f32_16x16x32_bf16 v[84:87], v[194:197], v[160:163], v[84:87]
	v_mfma_f32_16x16x32_bf16 v[80:83], v[202:205], v[160:163], v[80:83]
	v_mfma_f32_16x16x32_bf16 v[68:71], v[194:197], v[168:171], v[68:71]
	v_mfma_f32_16x16x32_bf16 v[64:67], v[202:205], v[168:171], v[64:67]
	v_mfma_f32_16x16x32_bf16 v[116:119], v[198:201], v[148:151], v[116:119]
	v_mfma_f32_16x16x32_bf16 v[112:115], v[212:215], v[148:151], v[112:115]
	v_mfma_f32_16x16x32_bf16 v[100:103], v[198:201], v[156:159], v[100:103]
	v_mfma_f32_16x16x32_bf16 v[96:99], v[212:215], v[156:159], v[96:99]
	v_mfma_f32_16x16x32_bf16 v[84:87], v[198:201], v[164:167], v[84:87]
	v_mfma_f32_16x16x32_bf16 v[80:83], v[212:215], v[164:167], v[80:83]
	v_mfma_f32_16x16x32_bf16 v[68:71], v[198:201], v[172:175], v[68:71]
	v_mfma_f32_16x16x32_bf16 v[64:67], v[212:215], v[172:175], v[64:67]
	s_setprio 0
	s_mov_b32 m0, s41
	v_lshl_add_u64 v[216:217], v[220:221], 0, s[8:9]
	s_barrier
	ds_read_b128 v[144:147], v209 offset:49152
	ds_read_b128 v[148:151], v209 offset:50176
	ds_read_b128 v[152:155], v209 offset:51200
	ds_read_b128 v[156:159], v209 offset:52224
	ds_read_b128 v[160:163], v209 offset:53248
	ds_read_b128 v[164:167], v209 offset:54272
	ds_read_b128 v[168:171], v209 offset:55296
	ds_read_b128 v[172:175], v209 offset:56320
	global_load_lds_dwordx4 v[216:217], off
	v_lshl_add_u64 v[216:217], v[222:223], 0, s[8:9]
	s_mov_b32 m0, s42
	s_nop 0
	global_load_lds_dwordx4 v[216:217], off
	s_barrier
	s_waitcnt lgkmcnt(0)
	s_setprio 1
	s_waitcnt lgkmcnt(0)
	v_mfma_f32_16x16x32_bf16 v[60:63], v[128:131], v[144:147], v[60:63]
	v_mfma_f32_16x16x32_bf16 v[56:59], v[136:139], v[144:147], v[56:59]
	v_mfma_f32_16x16x32_bf16 v[44:47], v[128:131], v[152:155], v[44:47]
	v_mfma_f32_16x16x32_bf16 v[40:43], v[136:139], v[152:155], v[40:43]
	v_mfma_f32_16x16x32_bf16 v[28:31], v[128:131], v[160:163], v[28:31]
	v_mfma_f32_16x16x32_bf16 v[24:27], v[136:139], v[160:163], v[24:27]
	v_mfma_f32_16x16x32_bf16 v[12:15], v[128:131], v[168:171], v[12:15]
	v_mfma_f32_16x16x32_bf16 v[8:11], v[136:139], v[168:171], v[8:11]
	v_mfma_f32_16x16x32_bf16 v[60:63], v[132:135], v[148:151], v[60:63]
	v_mfma_f32_16x16x32_bf16 v[56:59], v[140:143], v[148:151], v[56:59]
	v_mfma_f32_16x16x32_bf16 v[44:47], v[132:135], v[156:159], v[44:47]
	v_mfma_f32_16x16x32_bf16 v[40:43], v[140:143], v[156:159], v[40:43]
	v_mfma_f32_16x16x32_bf16 v[28:31], v[132:135], v[164:167], v[28:31]
	v_mfma_f32_16x16x32_bf16 v[24:27], v[140:143], v[164:167], v[24:27]
	v_mfma_f32_16x16x32_bf16 v[12:15], v[132:135], v[172:175], v[12:15]
	v_mfma_f32_16x16x32_bf16 v[8:11], v[140:143], v[172:175], v[8:11]
	s_setprio 0
	s_barrier
	s_add_u32 s24, s24, 0x40080
	s_addc_u32 s25, s25, 0
	s_add_i32 s28, s28, s35
	v_lshl_add_u64 v[128:129], s[24:25], 0, v[178:179]
	s_mov_b32 m0, s28
	s_nop 0
	global_load_lds_dwordx4 v[128:129], off
	v_lshl_add_u64 v[128:129], s[24:25], 0, v[182:183]
	s_add_i32 m0, s28, 0x2000
	s_nop 0
	global_load_lds_dwordx4 v[128:129], off
	s_waitcnt vmcnt(6)
	s_barrier
	s_setprio 1
	v_mfma_f32_16x16x32_bf16 v[52:55], v[194:197], v[144:147], v[52:55]
	v_mfma_f32_16x16x32_bf16 v[48:51], v[202:205], v[144:147], v[48:51]
	v_mfma_f32_16x16x32_bf16 v[36:39], v[194:197], v[152:155], v[36:39]
	v_mfma_f32_16x16x32_bf16 v[32:35], v[202:205], v[152:155], v[32:35]
	v_mfma_f32_16x16x32_bf16 v[20:23], v[194:197], v[160:163], v[20:23]
	v_mfma_f32_16x16x32_bf16 v[16:19], v[202:205], v[160:163], v[16:19]
	v_mfma_f32_16x16x32_bf16 v[4:7], v[194:197], v[168:171], v[4:7]
	v_mfma_f32_16x16x32_bf16 v[0:3], v[202:205], v[168:171], v[0:3]
	v_mfma_f32_16x16x32_bf16 v[52:55], v[198:201], v[148:151], v[52:55]
	v_mfma_f32_16x16x32_bf16 v[48:51], v[212:215], v[148:151], v[48:51]
	v_mfma_f32_16x16x32_bf16 v[36:39], v[198:201], v[156:159], v[36:39]
	v_mfma_f32_16x16x32_bf16 v[32:35], v[212:215], v[156:159], v[32:35]
	v_mfma_f32_16x16x32_bf16 v[20:23], v[198:201], v[164:167], v[20:23]
	v_mfma_f32_16x16x32_bf16 v[16:19], v[212:215], v[164:167], v[16:19]
	v_mfma_f32_16x16x32_bf16 v[4:7], v[198:201], v[172:175], v[4:7]
	v_mfma_f32_16x16x32_bf16 v[0:3], v[212:215], v[172:175], v[0:3]
	s_setprio 0
	s_add_i32 s51, s51, 2
	s_add_u32 s22, s22, 0x100
	s_addc_u32 s23, s23, 0
	s_add_u32 s49, s49, 0x100
	s_addc_u32 s50, s50, 0
	s_cmp_gt_u32 s51, 13
	s_barrier
	s_cbranch_scc0 .LBB0_364
	v_lshl_add_u32 v196, s20, 8, v189
	v_lshl_or_b32 v194, s6, 8, v207
	v_readlane_b32 s48, v235, 5
	v_ashrrev_i32_e32 v195, 31, v194
	v_readlane_b32 s49, v235, 6
	v_ashrrev_i32_e32 v197, 31, v196
	v_lshlrev_b64 v[128:129], 12, v[196:197]
	v_lshl_add_u64 v[198:199], v[194:195], 2, s[48:49]
	v_or_b32_e32 v204, 16, v196
	v_lshl_add_u64 v[128:129], v[198:199], 0, v[128:129]
	v_ashrrev_i32_e32 v205, 31, v204
	global_load_dwordx4 v[212:215], v[128:129], off offset:16 nt
	global_load_dwordx4 v[216:219], v[128:129], off nt
	global_load_dwordx4 v[220:223], v[128:129], off offset:528 nt
	global_load_dwordx4 v[224:227], v[128:129], off offset:512 nt
	v_lshlrev_b64 v[128:129], 12, v[204:205]
	v_or_b32_e32 v202, 32, v196
	v_lshl_add_u64 v[128:129], v[198:199], 0, v[128:129]
	v_ashrrev_i32_e32 v203, 31, v202
	global_load_dwordx4 v[168:171], v[128:129], off offset:16 nt
	global_load_dwordx4 v[172:175], v[128:129], off nt
	global_load_dwordx4 v[160:163], v[128:129], off offset:528 nt
	global_load_dwordx4 v[164:167], v[128:129], off offset:512 nt
	v_lshlrev_b64 v[128:129], 12, v[202:203]
	v_or_b32_e32 v200, 48, v196
	v_lshl_add_u64 v[128:129], v[198:199], 0, v[128:129]
	v_ashrrev_i32_e32 v201, 31, v200
	global_load_dwordx4 v[152:155], v[128:129], off offset:16 nt
	global_load_dwordx4 v[156:159], v[128:129], off nt
	global_load_dwordx4 v[144:147], v[128:129], off offset:528 nt
	global_load_dwordx4 v[148:151], v[128:129], off offset:512 nt
	v_lshlrev_b64 v[128:129], 12, v[200:201]
	v_lshl_add_u64 v[132:133], v[198:199], 0, v[128:129]
	global_load_dwordx4 v[136:139], v[132:133], off offset:16 nt
	global_load_dwordx4 v[140:143], v[132:133], off nt
	global_load_dwordx4 v[128:131], v[132:133], off offset:528 nt
	s_nop 0
	global_load_dwordx4 v[132:135], v[132:133], off offset:512 nt
	s_lshl_b32 s20, s6, 2
	s_ashr_i32 s21, s20, 31
	v_readlane_b32 s50, v235, 7
	v_readlane_b32 s51, v235, 8
	v_readlane_b32 s52, v235, 9
	v_readlane_b32 s53, v235, 10
	v_readlane_b32 s54, v235, 11
	v_readlane_b32 s55, v235, 12
	v_readlane_b32 s56, v235, 13
	v_readlane_b32 s57, v235, 14
	v_readlane_b32 s58, v235, 15
	v_readlane_b32 s59, v235, 16
	v_readlane_b32 s60, v235, 17
	v_readlane_b32 s61, v235, 18
	v_readlane_b32 s62, v235, 19
	v_readlane_b32 s63, v235, 20
	s_waitcnt vmcnt(0)
	v_pk_add_f32 v[126:127], v[126:127], v[218:219]
	v_pk_add_f32 v[124:125], v[124:125], v[216:217]
	v_pk_add_f32 v[214:215], v[122:123], v[214:215]
	v_mul_f32_e32 v122, v125, v125
	v_mul_f32_e32 v123, v127, v127
	v_pk_add_f32 v[120:121], v[120:121], v[212:213]
	v_fmac_f32_e32 v122, v124, v124
	v_fmac_f32_e32 v123, v126, v126
	v_add_f32_e32 v122, v122, v123
	v_mul_f32_e32 v123, v121, v121
	v_mul_f32_e32 v212, v215, v215
	v_fmac_f32_e32 v123, v120, v120
	v_fmac_f32_e32 v212, v214, v214
	v_pk_add_f32 v[118:119], v[118:119], v[226:227]
	v_pk_add_f32 v[116:117], v[116:117], v[224:225]
	v_add_f32_e32 v123, v123, v212
	v_pk_add_f32 v[212:213], v[112:113], v[220:221]
	v_mul_f32_e32 v112, v117, v117
	v_mul_f32_e32 v113, v119, v119
	v_add_f32_e32 v216, v122, v123
	v_cvt_pk_bf16_f32 v122, v124, v125
	v_cvt_pk_bf16_f32 v123, v126, v127
	v_pk_add_f32 v[126:127], v[114:115], v[222:223]
	v_fmac_f32_e32 v112, v116, v116
	v_fmac_f32_e32 v113, v118, v118
	v_add_f32_e32 v112, v112, v113
	v_mul_f32_e32 v113, v213, v213
	v_mul_f32_e32 v114, v127, v127
	v_fmac_f32_e32 v113, v212, v212
	v_fmac_f32_e32 v114, v126, v126
	v_add_f32_e32 v113, v113, v114
	v_add_f32_e32 v112, v112, v113
	v_and_b32_e32 v113, 64, v211
	v_cvt_pk_bf16_f32 v124, v120, v121
	v_add_f32_e32 v115, v216, v112
	v_xor_b32_e32 v112, 16, v211
	v_add_u32_e32 v121, 64, v113
	v_cmp_lt_i32_e32 vcc, v112, v121
	v_lshlrev_b64 v[228:229], 11, v[196:197]
	v_cvt_pk_bf16_f32 v125, v214, v215
	s_nop 0
	v_cndmask_b32_e32 v112, v211, v112, vcc
	v_lshlrev_b32_e32 v120, 2, v112
	ds_bpermute_b32 v216, v120, v115
	v_lshl_add_u64 v[112:113], s[64:65], 0, v[228:229]
	v_lshl_add_u64 v[214:215], v[194:195], 1, v[112:113]
	v_xor_b32_e32 v113, 32, v211
	v_cmp_lt_i32_e32 vcc, v113, v121
	s_waitcnt lgkmcnt(0)
	v_add_f32_e32 v112, v115, v216
	global_store_dwordx4 v[214:215], v[122:125], off sc1
	v_cndmask_b32_e32 v113, v211, v113, vcc
	v_lshlrev_b32_e32 v121, 2, v113
	ds_bpermute_b32 v113, v121, v112
	v_cvt_pk_bf16_f32 v114, v116, v117
	v_cvt_pk_bf16_f32 v115, v118, v119
	v_cvt_pk_bf16_f32 v116, v212, v213
	v_cvt_pk_bf16_f32 v117, v126, v127
	global_store_dwordx4 v[214:215], v[114:117], off offset:256 sc1
	s_and_saveexec_b64 s[22:23], s[2:3]
	s_cbranch_execz .LBB0_367
	v_lshlrev_b64 v[114:115], 6, v[196:197]
	v_lshl_add_u64 v[114:115], s[74:75], 0, v[114:115]
	v_lshl_add_u64 v[114:115], s[20:21], 2, v[114:115]
	s_lshl_b32 s6, s40, 2
	v_lshl_add_u64 v[114:115], v[114:115], 0, s[6:7]
	s_waitcnt lgkmcnt(0)
	v_add_f32_e32 v112, v112, v113
	global_store_dword v[114:115], v112, off
.LBB0_367:
	s_or_b64 exec, exec, s[22:23]
	v_pk_add_f32 v[110:111], v[110:111], v[174:175]
	v_pk_add_f32 v[108:109], v[108:109], v[172:173]
	v_pk_add_f32 v[114:115], v[106:107], v[170:171]
	v_pk_add_f32 v[106:107], v[104:105], v[168:169]
	v_mul_f32_e32 v104, v109, v109
	v_mul_f32_e32 v105, v111, v111
	v_fmac_f32_e32 v104, v108, v108
	v_fmac_f32_e32 v105, v110, v110
	v_add_f32_e32 v104, v104, v105
	v_mul_f32_e32 v105, v107, v107
	v_mul_f32_e32 v116, v115, v115
	v_fmac_f32_e32 v105, v106, v106
	v_fmac_f32_e32 v116, v114, v114
	v_add_f32_e32 v105, v105, v116
	v_pk_add_f32 v[102:103], v[102:103], v[166:167]
	v_pk_add_f32 v[100:101], v[100:101], v[164:165]
	v_add_f32_e32 v116, v104, v105
	v_cvt_pk_bf16_f32 v104, v108, v109
	v_cvt_pk_bf16_f32 v105, v110, v111
	v_pk_add_f32 v[110:111], v[96:97], v[160:161]
	v_mul_f32_e32 v96, v101, v101
	v_mul_f32_e32 v97, v103, v103
	v_pk_add_f32 v[108:109], v[98:99], v[162:163]
	v_fmac_f32_e32 v96, v100, v100
	v_fmac_f32_e32 v97, v102, v102
	v_add_f32_e32 v96, v96, v97
	v_mul_f32_e32 v97, v111, v111
	v_mul_f32_e32 v98, v109, v109
	v_fmac_f32_e32 v97, v110, v110
	v_fmac_f32_e32 v98, v108, v108
	v_add_f32_e32 v97, v97, v98
	v_add_f32_e32 v96, v96, v97
	v_add_f32_e32 v99, v116, v96
	v_cvt_pk_bf16_f32 v106, v106, v107
	v_cvt_pk_bf16_f32 v107, v114, v115
	ds_bpermute_b32 v114, v120, v99
	s_waitcnt lgkmcnt(1)
	v_lshlrev_b64 v[112:113], 11, v[204:205]
	v_lshl_add_u64 v[96:97], s[64:65], 0, v[112:113]
	v_lshl_add_u64 v[112:113], v[194:195], 1, v[96:97]
	global_store_dwordx4 v[112:113], v[104:107], off sc1
	s_waitcnt lgkmcnt(0)
	v_add_f32_e32 v96, v99, v114
	ds_bpermute_b32 v97, v121, v96
	v_cvt_pk_bf16_f32 v98, v100, v101
	v_cvt_pk_bf16_f32 v99, v102, v103
	v_cvt_pk_bf16_f32 v100, v110, v111
	v_cvt_pk_bf16_f32 v101, v108, v109
	global_store_dwordx4 v[112:113], v[98:101], off offset:256 sc1
	s_and_saveexec_b64 s[22:23], s[2:3]
	s_cbranch_execz .LBB0_369
	v_lshlrev_b64 v[98:99], 6, v[204:205]
	v_lshl_add_u64 v[98:99], s[74:75], 0, v[98:99]
	v_lshl_add_u64 v[98:99], s[20:21], 2, v[98:99]
	s_lshl_b32 s6, s40, 2
	v_lshl_add_u64 v[98:99], v[98:99], 0, s[6:7]
	s_waitcnt lgkmcnt(0)
	v_add_f32_e32 v96, v96, v97
	global_store_dword v[98:99], v96, off
.LBB0_369:
	s_or_b64 exec, exec, s[22:23]
	v_pk_add_f32 v[94:95], v[94:95], v[158:159]
	v_pk_add_f32 v[92:93], v[92:93], v[156:157]
	v_pk_add_f32 v[98:99], v[90:91], v[154:155]
	v_pk_add_f32 v[90:91], v[88:89], v[152:153]
	v_mul_f32_e32 v88, v93, v93
	v_mul_f32_e32 v89, v95, v95
	v_fmac_f32_e32 v88, v92, v92
	v_fmac_f32_e32 v89, v94, v94
	v_add_f32_e32 v88, v88, v89
	v_mul_f32_e32 v89, v91, v91
	v_mul_f32_e32 v100, v99, v99
	v_fmac_f32_e32 v89, v90, v90
	v_fmac_f32_e32 v100, v98, v98
	v_add_f32_e32 v89, v89, v100
	v_pk_add_f32 v[86:87], v[86:87], v[150:151]
	v_pk_add_f32 v[84:85], v[84:85], v[148:149]
	v_add_f32_e32 v100, v88, v89
	v_cvt_pk_bf16_f32 v88, v92, v93
	v_cvt_pk_bf16_f32 v89, v94, v95
	v_pk_add_f32 v[94:95], v[80:81], v[144:145]
	v_mul_f32_e32 v80, v85, v85
	v_mul_f32_e32 v81, v87, v87
	v_pk_add_f32 v[92:93], v[82:83], v[146:147]
	v_fmac_f32_e32 v80, v84, v84
	v_fmac_f32_e32 v81, v86, v86
	v_add_f32_e32 v80, v80, v81
	v_mul_f32_e32 v81, v95, v95
	v_mul_f32_e32 v82, v93, v93
	v_fmac_f32_e32 v81, v94, v94
	v_fmac_f32_e32 v82, v92, v92
	v_add_f32_e32 v81, v81, v82
	v_add_f32_e32 v80, v80, v81
	v_add_f32_e32 v83, v100, v80
	v_cvt_pk_bf16_f32 v90, v90, v91
	v_cvt_pk_bf16_f32 v91, v98, v99
	ds_bpermute_b32 v98, v120, v83
	s_waitcnt lgkmcnt(1)
	v_lshlrev_b64 v[96:97], 11, v[202:203]
	v_lshl_add_u64 v[80:81], s[64:65], 0, v[96:97]
	v_lshl_add_u64 v[96:97], v[194:195], 1, v[80:81]
	global_store_dwordx4 v[96:97], v[88:91], off sc1
	s_waitcnt lgkmcnt(0)
	v_add_f32_e32 v80, v83, v98
	ds_bpermute_b32 v81, v121, v80
	v_cvt_pk_bf16_f32 v82, v84, v85
	v_cvt_pk_bf16_f32 v83, v86, v87
	v_cvt_pk_bf16_f32 v84, v94, v95
	v_cvt_pk_bf16_f32 v85, v92, v93
	global_store_dwordx4 v[96:97], v[82:85], off offset:256 sc1
	s_and_saveexec_b64 s[22:23], s[2:3]
	s_cbranch_execz .LBB0_371
	v_lshlrev_b64 v[82:83], 6, v[202:203]
	v_lshl_add_u64 v[82:83], s[74:75], 0, v[82:83]
	v_lshl_add_u64 v[82:83], s[20:21], 2, v[82:83]
	s_lshl_b32 s6, s40, 2
	v_lshl_add_u64 v[82:83], v[82:83], 0, s[6:7]
	s_waitcnt lgkmcnt(0)
	v_add_f32_e32 v80, v80, v81
	global_store_dword v[82:83], v80, off
.LBB0_371:
	s_or_b64 exec, exec, s[22:23]
	v_pk_add_f32 v[78:79], v[78:79], v[142:143]
	v_pk_add_f32 v[76:77], v[76:77], v[140:141]
	v_pk_add_f32 v[82:83], v[74:75], v[138:139]
	v_pk_add_f32 v[74:75], v[72:73], v[136:137]
	v_mul_f32_e32 v72, v77, v77
	v_mul_f32_e32 v73, v79, v79
	v_fmac_f32_e32 v72, v76, v76
	v_fmac_f32_e32 v73, v78, v78
	v_add_f32_e32 v72, v72, v73
	v_mul_f32_e32 v73, v75, v75
	v_mul_f32_e32 v84, v83, v83
	v_fmac_f32_e32 v73, v74, v74
	v_fmac_f32_e32 v84, v82, v82
	v_add_f32_e32 v73, v73, v84
	v_pk_add_f32 v[70:71], v[70:71], v[134:135]
	v_pk_add_f32 v[68:69], v[68:69], v[132:133]
	v_add_f32_e32 v84, v72, v73
	v_cvt_pk_bf16_f32 v72, v76, v77
	v_cvt_pk_bf16_f32 v73, v78, v79
	v_pk_add_f32 v[78:79], v[64:65], v[128:129]
	v_mul_f32_e32 v64, v69, v69
	v_mul_f32_e32 v65, v71, v71
	v_pk_add_f32 v[76:77], v[66:67], v[130:131]
	v_fmac_f32_e32 v64, v68, v68
	v_fmac_f32_e32 v65, v70, v70
	v_add_f32_e32 v64, v64, v65
	v_mul_f32_e32 v65, v79, v79
	v_mul_f32_e32 v66, v77, v77
	v_fmac_f32_e32 v65, v78, v78
	v_fmac_f32_e32 v66, v76, v76
	v_add_f32_e32 v65, v65, v66
	v_add_f32_e32 v64, v64, v65
	v_add_f32_e32 v67, v84, v64
	v_cvt_pk_bf16_f32 v74, v74, v75
	v_cvt_pk_bf16_f32 v75, v82, v83
	ds_bpermute_b32 v82, v120, v67
	s_waitcnt lgkmcnt(1)
	v_lshlrev_b64 v[80:81], 11, v[200:201]
	v_lshl_add_u64 v[64:65], s[64:65], 0, v[80:81]
	v_lshl_add_u64 v[80:81], v[194:195], 1, v[64:65]
	global_store_dwordx4 v[80:81], v[72:75], off sc1
	s_waitcnt lgkmcnt(0)
	v_add_f32_e32 v64, v67, v82
	ds_bpermute_b32 v65, v121, v64
	v_cvt_pk_bf16_f32 v66, v68, v69
	v_cvt_pk_bf16_f32 v67, v70, v71
	v_cvt_pk_bf16_f32 v68, v78, v79
	v_cvt_pk_bf16_f32 v69, v76, v77
	global_store_dwordx4 v[80:81], v[66:69], off offset:256 sc1
	s_and_saveexec_b64 s[22:23], s[2:3]
	s_cbranch_execz .LBB0_373
	v_lshlrev_b64 v[66:67], 6, v[200:201]
	v_lshl_add_u64 v[66:67], s[74:75], 0, v[66:67]
	v_lshl_add_u64 v[66:67], s[20:21], 2, v[66:67]
	s_lshl_b32 s6, s40, 2
	v_lshl_add_u64 v[66:67], v[66:67], 0, s[6:7]
	s_waitcnt lgkmcnt(0)
	v_add_f32_e32 v64, v64, v65
	global_store_dword v[66:67], v64, off
.LBB0_373:
	s_or_b64 exec, exec, s[22:23]
	v_add_u32_e32 v118, 0x80, v196
	v_ashrrev_i32_e32 v119, 31, v118
	s_waitcnt lgkmcnt(0)
	v_lshlrev_b64 v[64:65], 12, v[118:119]
	v_add_u32_e32 v116, 0x90, v196
	v_lshl_add_u64 v[64:65], v[198:199], 0, v[64:65]
	v_ashrrev_i32_e32 v117, 31, v116
	global_load_dwordx4 v[122:125], v[64:65], off offset:16 nt
	global_load_dwordx4 v[126:129], v[64:65], off nt
	global_load_dwordx4 v[130:133], v[64:65], off offset:528 nt
	global_load_dwordx4 v[134:137], v[64:65], off offset:512 nt
	v_lshlrev_b64 v[64:65], 12, v[116:117]
	v_add_u32_e32 v114, 0xa0, v196
	v_lshl_add_u64 v[64:65], v[198:199], 0, v[64:65]
	v_ashrrev_i32_e32 v115, 31, v114
	global_load_dwordx4 v[104:107], v[64:65], off offset:16 nt
	global_load_dwordx4 v[108:111], v[64:65], off nt
	global_load_dwordx4 v[96:99], v[64:65], off offset:528 nt
	global_load_dwordx4 v[100:103], v[64:65], off offset:512 nt
	v_lshlrev_b64 v[64:65], 12, v[114:115]
	v_add_u32_e32 v112, 0xb0, v196
	v_lshl_add_u64 v[64:65], v[198:199], 0, v[64:65]
	v_ashrrev_i32_e32 v113, 31, v112
	global_load_dwordx4 v[88:91], v[64:65], off offset:16 nt
	global_load_dwordx4 v[92:95], v[64:65], off nt
	global_load_dwordx4 v[80:83], v[64:65], off offset:528 nt
	global_load_dwordx4 v[84:87], v[64:65], off offset:512 nt
	v_lshlrev_b64 v[64:65], 12, v[112:113]
	v_lshl_add_u64 v[68:69], v[198:199], 0, v[64:65]
	global_load_dwordx4 v[72:75], v[68:69], off offset:16 nt
	global_load_dwordx4 v[76:79], v[68:69], off nt
	global_load_dwordx4 v[64:67], v[68:69], off offset:528 nt
	s_nop 0
	global_load_dwordx4 v[68:71], v[68:69], off offset:512 nt
	s_waitcnt vmcnt(14)
	v_pk_add_f32 v[62:63], v[62:63], v[128:129]
	v_pk_add_f32 v[60:61], v[60:61], v[126:127]
	v_pk_add_f32 v[124:125], v[58:59], v[124:125]
	v_pk_add_f32 v[58:59], v[56:57], v[122:123]
	v_mul_f32_e32 v56, v61, v61
	v_mul_f32_e32 v57, v63, v63
	v_fmac_f32_e32 v56, v60, v60
	v_fmac_f32_e32 v57, v62, v62
	v_add_f32_e32 v56, v56, v57
	v_mul_f32_e32 v57, v59, v59
	v_mul_f32_e32 v122, v125, v125
	v_fmac_f32_e32 v57, v58, v58
	v_fmac_f32_e32 v122, v124, v124
	v_add_f32_e32 v57, v57, v122
	s_waitcnt vmcnt(12)
	v_pk_add_f32 v[54:55], v[54:55], v[136:137]
	v_pk_add_f32 v[52:53], v[52:53], v[134:135]
	v_add_f32_e32 v122, v56, v57
	v_cvt_pk_bf16_f32 v56, v60, v61
	v_cvt_pk_bf16_f32 v57, v62, v63
	v_pk_add_f32 v[62:63], v[48:49], v[130:131]
	v_mul_f32_e32 v48, v53, v53
	v_mul_f32_e32 v49, v55, v55
	v_pk_add_f32 v[60:61], v[50:51], v[132:133]
	v_fmac_f32_e32 v48, v52, v52
	v_fmac_f32_e32 v49, v54, v54
	v_add_f32_e32 v48, v48, v49
	v_mul_f32_e32 v49, v63, v63
	v_mul_f32_e32 v50, v61, v61
	v_fmac_f32_e32 v49, v62, v62
	v_fmac_f32_e32 v50, v60, v60
	v_add_f32_e32 v49, v49, v50
	v_add_f32_e32 v48, v48, v49
	v_add_f32_e32 v51, v122, v48
	v_cvt_pk_bf16_f32 v58, v58, v59
	v_cvt_pk_bf16_f32 v59, v124, v125
	ds_bpermute_b32 v124, v120, v51
	v_lshlrev_b64 v[138:139], 11, v[118:119]
	v_lshl_add_u64 v[48:49], s[64:65], 0, v[138:139]
	v_lshl_add_u64 v[122:123], v[194:195], 1, v[48:49]
	global_store_dwordx4 v[122:123], v[56:59], off sc1
	s_waitcnt lgkmcnt(0)
	v_add_f32_e32 v48, v51, v124
	ds_bpermute_b32 v49, v121, v48
	v_cvt_pk_bf16_f32 v50, v52, v53
	v_cvt_pk_bf16_f32 v51, v54, v55
	v_cvt_pk_bf16_f32 v52, v62, v63
	v_cvt_pk_bf16_f32 v53, v60, v61
	global_store_dwordx4 v[122:123], v[50:53], off offset:256 sc1
	s_and_saveexec_b64 s[22:23], s[2:3]
	s_cbranch_execz .LBB0_375
	v_lshlrev_b64 v[50:51], 6, v[118:119]
	v_lshl_add_u64 v[50:51], s[74:75], 0, v[50:51]
	v_lshl_add_u64 v[50:51], s[20:21], 2, v[50:51]
	s_lshl_b32 s6, s40, 2
	v_lshl_add_u64 v[50:51], v[50:51], 0, s[6:7]
	s_waitcnt lgkmcnt(0)
	v_add_f32_e32 v48, v48, v49
	global_store_dword v[50:51], v48, off
.LBB0_375:
	s_or_b64 exec, exec, s[22:23]
	s_waitcnt vmcnt(12)
	v_pk_add_f32 v[46:47], v[46:47], v[110:111]
	v_pk_add_f32 v[44:45], v[44:45], v[108:109]
	v_pk_add_f32 v[50:51], v[42:43], v[106:107]
	v_pk_add_f32 v[42:43], v[40:41], v[104:105]
	v_mul_f32_e32 v40, v45, v45
	v_mul_f32_e32 v41, v47, v47
	v_fmac_f32_e32 v40, v44, v44
	v_fmac_f32_e32 v41, v46, v46
	v_add_f32_e32 v40, v40, v41
	v_mul_f32_e32 v41, v43, v43
	v_mul_f32_e32 v52, v51, v51
	v_fmac_f32_e32 v41, v42, v42
	v_fmac_f32_e32 v52, v50, v50
	v_add_f32_e32 v41, v41, v52
	s_waitcnt vmcnt(10)
	v_pk_add_f32 v[38:39], v[38:39], v[102:103]
	v_pk_add_f32 v[36:37], v[36:37], v[100:101]
	v_add_f32_e32 v52, v40, v41
	v_cvt_pk_bf16_f32 v40, v44, v45
	v_cvt_pk_bf16_f32 v41, v46, v47
	v_pk_add_f32 v[46:47], v[32:33], v[96:97]
	v_mul_f32_e32 v32, v37, v37
	v_mul_f32_e32 v33, v39, v39
	v_pk_add_f32 v[44:45], v[34:35], v[98:99]
	v_fmac_f32_e32 v32, v36, v36
	v_fmac_f32_e32 v33, v38, v38
	v_add_f32_e32 v32, v32, v33
	v_mul_f32_e32 v33, v47, v47
	v_mul_f32_e32 v34, v45, v45
	v_fmac_f32_e32 v33, v46, v46
	v_fmac_f32_e32 v34, v44, v44
	v_add_f32_e32 v33, v33, v34
	v_add_f32_e32 v32, v32, v33
	v_add_f32_e32 v35, v52, v32
	v_cvt_pk_bf16_f32 v42, v42, v43
	v_cvt_pk_bf16_f32 v43, v50, v51
	ds_bpermute_b32 v50, v120, v35
	s_waitcnt lgkmcnt(1)
	v_lshlrev_b64 v[48:49], 11, v[116:117]
	v_lshl_add_u64 v[32:33], s[64:65], 0, v[48:49]
	v_lshl_add_u64 v[48:49], v[194:195], 1, v[32:33]
	global_store_dwordx4 v[48:49], v[40:43], off sc1
	s_waitcnt lgkmcnt(0)
	v_add_f32_e32 v32, v35, v50
	ds_bpermute_b32 v33, v121, v32
	v_cvt_pk_bf16_f32 v34, v36, v37
	v_cvt_pk_bf16_f32 v35, v38, v39
	v_cvt_pk_bf16_f32 v36, v46, v47
	v_cvt_pk_bf16_f32 v37, v44, v45
	global_store_dwordx4 v[48:49], v[34:37], off offset:256 sc1
	s_and_saveexec_b64 s[22:23], s[2:3]
	s_cbranch_execz .LBB0_377
	v_lshlrev_b64 v[34:35], 6, v[116:117]
	v_lshl_add_u64 v[34:35], s[74:75], 0, v[34:35]
	v_lshl_add_u64 v[34:35], s[20:21], 2, v[34:35]
	s_lshl_b32 s6, s40, 2
	v_lshl_add_u64 v[34:35], v[34:35], 0, s[6:7]
	s_waitcnt lgkmcnt(0)
	v_add_f32_e32 v32, v32, v33
	global_store_dword v[34:35], v32, off
.LBB0_377:
	s_or_b64 exec, exec, s[22:23]
	s_waitcnt vmcnt(10)
	v_pk_add_f32 v[30:31], v[30:31], v[94:95]
	v_pk_add_f32 v[28:29], v[28:29], v[92:93]
	v_pk_add_f32 v[34:35], v[26:27], v[90:91]
	v_pk_add_f32 v[26:27], v[24:25], v[88:89]
	v_mul_f32_e32 v24, v29, v29
	v_mul_f32_e32 v25, v31, v31
	v_fmac_f32_e32 v24, v28, v28
	v_fmac_f32_e32 v25, v30, v30
	v_add_f32_e32 v24, v24, v25
	v_mul_f32_e32 v25, v27, v27
	v_mul_f32_e32 v36, v35, v35
	v_fmac_f32_e32 v25, v26, v26
	v_fmac_f32_e32 v36, v34, v34
	v_add_f32_e32 v25, v25, v36
	s_waitcnt vmcnt(8)
	v_pk_add_f32 v[22:23], v[22:23], v[86:87]
	v_pk_add_f32 v[20:21], v[20:21], v[84:85]
	v_add_f32_e32 v36, v24, v25
	v_cvt_pk_bf16_f32 v24, v28, v29
	v_cvt_pk_bf16_f32 v25, v30, v31
	v_pk_add_f32 v[30:31], v[16:17], v[80:81]
	v_mul_f32_e32 v16, v21, v21
	v_mul_f32_e32 v17, v23, v23
	v_pk_add_f32 v[28:29], v[18:19], v[82:83]
	v_fmac_f32_e32 v16, v20, v20
	v_fmac_f32_e32 v17, v22, v22
	v_add_f32_e32 v16, v16, v17
	v_mul_f32_e32 v17, v31, v31
	v_mul_f32_e32 v18, v29, v29
	v_fmac_f32_e32 v17, v30, v30
	v_fmac_f32_e32 v18, v28, v28
	v_add_f32_e32 v17, v17, v18
	v_add_f32_e32 v16, v16, v17
	v_add_f32_e32 v19, v36, v16
	v_cvt_pk_bf16_f32 v26, v26, v27
	v_cvt_pk_bf16_f32 v27, v34, v35
	ds_bpermute_b32 v34, v120, v19
	s_waitcnt lgkmcnt(1)
	v_lshlrev_b64 v[32:33], 11, v[114:115]
	v_lshl_add_u64 v[16:17], s[64:65], 0, v[32:33]
	v_lshl_add_u64 v[32:33], v[194:195], 1, v[16:17]
	global_store_dwordx4 v[32:33], v[24:27], off sc1
	s_waitcnt lgkmcnt(0)
	v_add_f32_e32 v16, v19, v34
	ds_bpermute_b32 v17, v121, v16
	v_cvt_pk_bf16_f32 v18, v20, v21
	v_cvt_pk_bf16_f32 v19, v22, v23
	v_cvt_pk_bf16_f32 v20, v30, v31
	v_cvt_pk_bf16_f32 v21, v28, v29
	global_store_dwordx4 v[32:33], v[18:21], off offset:256 sc1
	s_and_saveexec_b64 s[22:23], s[2:3]
	s_cbranch_execz .LBB0_379
	v_lshlrev_b64 v[18:19], 6, v[114:115]
	v_lshl_add_u64 v[18:19], s[74:75], 0, v[18:19]
	v_lshl_add_u64 v[18:19], s[20:21], 2, v[18:19]
	s_lshl_b32 s6, s40, 2
	v_lshl_add_u64 v[18:19], v[18:19], 0, s[6:7]
	s_waitcnt lgkmcnt(0)
	v_add_f32_e32 v16, v16, v17
	global_store_dword v[18:19], v16, off
.LBB0_379:
	s_or_b64 exec, exec, s[22:23]
	s_waitcnt vmcnt(8)
	v_pk_add_f32 v[14:15], v[14:15], v[78:79]
	v_pk_add_f32 v[12:13], v[12:13], v[76:77]
	v_pk_add_f32 v[18:19], v[10:11], v[74:75]
	v_pk_add_f32 v[10:11], v[8:9], v[72:73]
	v_mul_f32_e32 v8, v13, v13
	v_mul_f32_e32 v9, v15, v15
	v_fmac_f32_e32 v8, v12, v12
	v_fmac_f32_e32 v9, v14, v14
	v_add_f32_e32 v8, v8, v9
	v_mul_f32_e32 v9, v11, v11
	v_mul_f32_e32 v20, v19, v19
	v_fmac_f32_e32 v9, v10, v10
	v_fmac_f32_e32 v20, v18, v18
	v_add_f32_e32 v9, v9, v20
	s_waitcnt vmcnt(6)
	v_pk_add_f32 v[6:7], v[6:7], v[70:71]
	v_pk_add_f32 v[4:5], v[4:5], v[68:69]
	v_add_f32_e32 v20, v8, v9
	v_cvt_pk_bf16_f32 v8, v12, v13
	v_cvt_pk_bf16_f32 v9, v14, v15
	v_pk_add_f32 v[14:15], v[0:1], v[64:65]
	v_mul_f32_e32 v0, v5, v5
	v_mul_f32_e32 v1, v7, v7
	v_pk_add_f32 v[12:13], v[2:3], v[66:67]
	v_fmac_f32_e32 v0, v4, v4
	v_fmac_f32_e32 v1, v6, v6
	v_add_f32_e32 v0, v0, v1
	v_mul_f32_e32 v1, v15, v15
	v_mul_f32_e32 v2, v13, v13
	v_fmac_f32_e32 v1, v14, v14
	v_fmac_f32_e32 v2, v12, v12
	v_add_f32_e32 v1, v1, v2
	v_add_f32_e32 v0, v0, v1
	v_add_f32_e32 v3, v20, v0
	v_cvt_pk_bf16_f32 v10, v10, v11
	v_cvt_pk_bf16_f32 v11, v18, v19
	ds_bpermute_b32 v18, v120, v3
	s_waitcnt lgkmcnt(1)
	v_lshlrev_b64 v[16:17], 11, v[112:113]
	v_lshl_add_u64 v[0:1], s[64:65], 0, v[16:17]
	v_lshl_add_u64 v[16:17], v[194:195], 1, v[0:1]
	global_store_dwordx4 v[16:17], v[8:11], off sc1
	s_waitcnt lgkmcnt(0)
	v_add_f32_e32 v0, v3, v18
	ds_bpermute_b32 v1, v121, v0
	v_cvt_pk_bf16_f32 v2, v4, v5
	v_cvt_pk_bf16_f32 v3, v6, v7
	v_cvt_pk_bf16_f32 v4, v14, v15
	v_cvt_pk_bf16_f32 v5, v12, v13
	global_store_dwordx4 v[16:17], v[2:5], off offset:256 sc1
	s_and_saveexec_b64 s[22:23], s[2:3]
	s_cbranch_execz .LBB0_356
	v_lshlrev_b64 v[2:3], 6, v[112:113]
	v_lshl_add_u64 v[2:3], s[74:75], 0, v[2:3]
	v_lshl_add_u64 v[2:3], s[20:21], 2, v[2:3]
	s_lshl_b32 s6, s40, 2
	v_lshl_add_u64 v[2:3], v[2:3], 0, s[6:7]
	s_waitcnt lgkmcnt(0)
	v_add_f32_e32 v0, v0, v1
	global_store_dword v[2:3], v0, off
	s_branch .LBB0_356

.LBB0_467:
	v_mov_b32_e32 v136, v96
	v_mov_b32_e32 v137, v96
	v_mov_b32_e32 v148, v97
	v_mov_b32_e32 v149, v97
	v_mov_b32_e32 v140, v96
	v_mov_b32_e32 v141, v96
	v_mov_b32_e32 v96, v97
	v_pk_mul_f32 v[138:139], v[42:43], v[140:141]
	v_pk_mul_f32 v[40:41], v[40:41], v[136:137]
	v_pk_mul_f32 v[42:43], v[32:33], v[136:137]
	v_pk_mul_f32 v[136:137], v[38:39], v[96:97]
	v_pk_mul_f32 v[38:39], v[36:37], v[148:149]
	v_mov_b32_dpp v127, v84 row_shr:1 row_mask:0xf bank_mask:0xf
	v_mov_b32_dpp v126, v88 row_shr:1 row_mask:0xf bank_mask:0xf
	s_waitcnt lgkmcnt(0)
	v_mov_b32_e32 v36, v118
	v_mov_b32_e32 v37, v106
	v_pk_mul_f32 v[140:141], v[34:35], v[140:141]
	v_pk_mul_f32 v[30:31], v[30:31], v[96:97]
	v_mov_b32_e32 v96, v42
	v_mov_b32_e32 v97, v40
	v_mov_b32_e32 v34, v122
	v_mov_b32_e32 v35, v110
	v_pk_mul_f32 v[32:33], v[36:37], v[126:127]
	v_pk_mul_f32 v[28:29], v[28:29], v[148:149]
	v_mov_b32_dpp v131, v80 row_shr:1 row_mask:0xf bank_mask:0xf
	v_mov_b32_dpp v130, v92 row_shr:1 row_mask:0xf bank_mask:0xf
	v_pk_fma_f32 v[148:149], v[96:97], v[34:35], v[32:33]
	v_mov_b32_e32 v32, v114
	v_mov_b32_e32 v33, v74
	v_pk_fma_f32 v[130:131], v[32:33], v[130:131], v[148:149]
	v_mov_b32_e32 v148, v28
	v_mul_f32_e32 v28, 0xbfb8aa3b, v131
	v_exp_f32_e32 v28, v28
	v_mov_b32_e32 v149, v38
	v_pk_mul_f32 v[150:151], v[148:149], v[34:35]
	v_mov_b32_dpp v143, v85 row_shr:1 row_mask:0xf bank_mask:0xf
	v_pk_fma_f32 v[150:151], v[96:97], v[36:37], v[150:151]
	v_add_f32_e32 v28, 1.0, v28
	v_pk_fma_f32 v[126:127], v[32:33], v[126:127], v[150:151]
	v_mov_b32_e32 v150, v92
	v_mov_b32_e32 v151, v80
	v_pk_mul_f32 v[152:153], v[150:151], v[34:35]
	v_rcp_f32_e32 v28, v28
	v_mul_f32_e32 v38, 0xbfb8aa3b, v127
	v_pk_fma_f32 v[152:153], v[148:149], v[36:37], v[152:153]
	v_exp_f32_e32 v38, v38
	v_pk_fma_f32 v[96:97], v[96:97], v[32:33], v[152:153]
	v_mov_b32_e32 v152, v88
	v_mov_b32_e32 v153, v84
	v_pk_mul_f32 v[152:153], v[152:153], v[34:35]
	v_mul_f32_e32 v28, v131, v28
	v_pk_fma_f32 v[150:151], v[150:151], v[36:37], v[152:153]
	v_mul_f32_e32 v79, v130, v28
	v_pk_fma_f32 v[148:149], v[148:149], v[32:33], v[150:151]
	v_add_f32_e32 v28, 1.0, v38
	v_mul_f32_e32 v38, 0xbfb8aa3b, v97
	v_exp_f32_e32 v38, v38
	v_mul_f32_e32 v40, 0xbfb8aa3b, v149
	v_exp_f32_e32 v40, v40
	v_rcp_f32_e32 v28, v28
	v_add_f32_e32 v38, 1.0, v38
	v_rcp_f32_e32 v38, v38
	v_add_f32_e32 v40, 1.0, v40
	v_rcp_f32_e32 v40, v40
	v_mul_f32_e32 v28, v127, v28
	v_mul_f32_e32 v114, v126, v28
	v_mul_f32_e32 v28, v97, v38
	v_mov_b32_dpp v142, v89 row_shr:1 row_mask:0xf bank_mask:0xf
	v_mov_b32_e32 v106, v119
	v_mul_f32_e32 v118, v96, v28
	v_mul_f32_e32 v28, v149, v40
	v_mov_b32_e32 v40, v43
	v_mov_b32_e32 v110, v123
	v_pk_mul_f32 v[42:43], v[106:107], v[142:143]
	v_mov_b32_dpp v145, v81 row_shr:1 row_mask:0xf bank_mask:0xf
	v_mov_b32_dpp v144, v93 row_shr:1 row_mask:0xf bank_mask:0xf
	v_pk_fma_f32 v[42:43], v[40:41], v[110:111], v[42:43]
	v_mov_b32_e32 v74, v115
	v_pk_fma_f32 v[42:43], v[74:75], v[144:145], v[42:43]
	v_mov_b32_e32 v38, v29
	v_mul_f32_e32 v84, 0xbfb8aa3b, v43
	v_exp_f32_e32 v88, v84
	v_mul_f32_e32 v122, v148, v28
	v_pk_mul_f32 v[28:29], v[38:39], v[110:111]
	v_mov_b32_e32 v84, v89
	v_pk_fma_f32 v[28:29], v[40:41], v[106:107], v[28:29]
	v_mov_b32_e32 v80, v93
	v_pk_mul_f32 v[84:85], v[84:85], v[110:111]
	v_pk_fma_f32 v[28:29], v[74:75], v[142:143], v[28:29]
	v_pk_mul_f32 v[92:93], v[80:81], v[110:111]
	v_pk_fma_f32 v[80:81], v[80:81], v[106:107], v[84:85]
	v_add_f32_e32 v84, 1.0, v88
	v_rcp_f32_e32 v84, v84
	v_mul_f32_e32 v85, 0xbfb8aa3b, v29
	v_exp_f32_e32 v85, v85
	v_pk_fma_f32 v[92:93], v[38:39], v[106:107], v[92:93]
	v_mul_f32_e32 v43, v43, v84
	v_pk_fma_f32 v[40:41], v[40:41], v[74:75], v[92:93]
	v_pk_fma_f32 v[38:39], v[38:39], v[74:75], v[80:81]
	v_mul_f32_e32 v115, v42, v43
	v_add_f32_e32 v42, 1.0, v85
	v_mul_f32_e32 v43, 0xbfb8aa3b, v41
	v_rcp_f32_e32 v42, v42
	v_exp_f32_e32 v43, v43
	v_mul_f32_e32 v80, 0xbfb8aa3b, v39
	v_exp_f32_e32 v80, v80
	v_mul_f32_e32 v29, v29, v42
	v_add_f32_e32 v42, 1.0, v43
	v_rcp_f32_e32 v42, v42
	v_add_f32_e32 v43, 1.0, v80
	v_rcp_f32_e32 v43, v43
	v_mul_f32_e32 v119, v28, v29
	v_mul_f32_e32 v28, v41, v42
	v_mul_f32_e32 v123, v40, v28
	v_mul_f32_e32 v28, v39, v43
	v_mov_b32_dpp v129, v86 row_shr:1 row_mask:0xf bank_mask:0xf
	v_mov_b32_dpp v128, v90 row_shr:1 row_mask:0xf bank_mask:0xf
	v_mov_b32_e32 v42, v120
	v_mov_b32_e32 v43, v108
	v_mul_f32_e32 v126, v38, v28
	v_mov_b32_e32 v28, v140
	v_mov_b32_e32 v29, v138
	v_mov_b32_e32 v40, v124
	v_mov_b32_e32 v41, v112
	v_pk_mul_f32 v[38:39], v[42:43], v[128:129]
	v_mov_b32_dpp v133, v82 row_shr:1 row_mask:0xf bank_mask:0xf
	v_mov_b32_dpp v132, v94 row_shr:1 row_mask:0xf bank_mask:0xf
	v_pk_fma_f32 v[80:81], v[28:29], v[40:41], v[38:39]
	v_mov_b32_e32 v38, v116
	v_mov_b32_e32 v39, v76
	v_pk_fma_f32 v[80:81], v[38:39], v[132:133], v[80:81]
	v_mov_b32_e32 v84, v30
	v_mul_f32_e32 v30, 0xbfb8aa3b, v81
	v_exp_f32_e32 v30, v30
	v_mov_b32_e32 v85, v136
	v_pk_mul_f32 v[88:89], v[84:85], v[40:41]
	v_mov_b32_e32 v92, v94
	v_pk_fma_f32 v[88:89], v[28:29], v[42:43], v[88:89]
	v_mov_b32_e32 v93, v82
	v_pk_fma_f32 v[88:89], v[38:39], v[128:129], v[88:89]
	v_add_f32_e32 v30, 1.0, v30
	v_pk_mul_f32 v[96:97], v[92:93], v[40:41]
	v_rcp_f32_e32 v30, v30
	v_mul_f32_e32 v76, 0xbfb8aa3b, v89
	v_pk_fma_f32 v[96:97], v[84:85], v[42:43], v[96:97]
	v_exp_f32_e32 v76, v76
	v_pk_fma_f32 v[28:29], v[28:29], v[38:39], v[96:97]
	v_mov_b32_e32 v96, v90
	v_mov_b32_e32 v97, v86
	v_pk_mul_f32 v[96:97], v[96:97], v[40:41]
	v_mul_f32_e32 v30, v81, v30
	v_pk_fma_f32 v[92:93], v[92:93], v[42:43], v[96:97]
	v_mul_f32_e32 v90, v80, v30
	v_pk_fma_f32 v[84:85], v[84:85], v[38:39], v[92:93]
	v_add_f32_e32 v30, 1.0, v76
	v_mul_f32_e32 v76, 0xbfb8aa3b, v29
	v_exp_f32_e32 v76, v76
	v_mul_f32_e32 v80, 0xbfb8aa3b, v85
	v_exp_f32_e32 v80, v80
	v_rcp_f32_e32 v30, v30
	v_add_f32_e32 v76, 1.0, v76
	v_rcp_f32_e32 v76, v76
	v_add_f32_e32 v80, 1.0, v80
	v_rcp_f32_e32 v80, v80
	v_mul_f32_e32 v30, v89, v30
	v_mul_f32_e32 v29, v29, v76
	v_mul_f32_e32 v89, v28, v29
	v_mul_f32_e32 v28, v85, v80
	v_mov_b32_dpp v105, v87 row_shr:1 row_mask:0xf bank_mask:0xf
	v_mov_b32_dpp v104, v91 row_shr:1 row_mask:0xf bank_mask:0xf
	v_mov_b32_e32 v108, v121
	v_mul_f32_e32 v92, v84, v28
	v_mov_b32_e32 v138, v141
	v_mov_b32_e32 v112, v125
	v_pk_mul_f32 v[28:29], v[108:109], v[104:105]
	v_mov_b32_dpp v135, v83 row_shr:1 row_mask:0xf bank_mask:0xf
	v_mov_b32_dpp v134, v95 row_shr:1 row_mask:0xf bank_mask:0xf
	v_pk_fma_f32 v[28:29], v[138:139], v[112:113], v[28:29]
	v_mov_b32_e32 v76, v117
	v_pk_fma_f32 v[28:29], v[76:77], v[134:135], v[28:29]
	v_mov_b32_e32 v136, v31
	v_mul_f32_e32 v84, 0xbfb8aa3b, v29
	v_exp_f32_e32 v93, v84
	v_mul_f32_e32 v88, v88, v30
	v_pk_mul_f32 v[30:31], v[136:137], v[112:113]
	v_mov_b32_e32 v86, v91
	v_pk_fma_f32 v[30:31], v[138:139], v[108:109], v[30:31]
	v_mov_b32_e32 v82, v95
	v_pk_mul_f32 v[84:85], v[86:87], v[112:113]
	v_pk_fma_f32 v[30:31], v[76:77], v[104:105], v[30:31]
	v_pk_mul_f32 v[80:81], v[82:83], v[112:113]
	v_pk_fma_f32 v[82:83], v[82:83], v[108:109], v[84:85]
	v_add_f32_e32 v84, 1.0, v93
	v_rcp_f32_e32 v84, v84
	v_mul_f32_e32 v85, 0xbfb8aa3b, v31
	v_exp_f32_e32 v85, v85
	v_pk_fma_f32 v[80:81], v[136:137], v[108:109], v[80:81]
	v_mul_f32_e32 v29, v29, v84
	v_pk_fma_f32 v[80:81], v[138:139], v[76:77], v[80:81]
	v_pk_fma_f32 v[82:83], v[136:137], v[76:77], v[82:83]
	v_mul_f32_e32 v28, v28, v29
	v_add_f32_e32 v29, 1.0, v85
	v_mul_f32_e32 v84, 0xbfb8aa3b, v81
	v_rcp_f32_e32 v29, v29
	v_exp_f32_e32 v84, v84
	v_mul_f32_e32 v85, 0xbfb8aa3b, v83
	v_exp_f32_e32 v85, v85
	v_mul_f32_e32 v29, v31, v29
	v_add_f32_e32 v31, 1.0, v84
	v_rcp_f32_e32 v31, v31
	v_add_f32_e32 v84, 1.0, v85
	v_rcp_f32_e32 v84, v84
	v_mul_f32_e32 v85, v30, v29
	v_mul_f32_e32 v29, v81, v31
	v_lshl_or_b32 v72, s60, 7, v210
	v_mul_f32_e32 v80, v80, v29
	v_mul_f32_e32 v29, v83, v84
	v_lshl_add_u32 v146, s61, 8, v209
	v_ashrrev_i32_e32 v73, 31, v72
	v_mul_f32_e32 v81, v82, v29
	v_cvt_pk_bf16_f32 v104, v79, v115
	v_cvt_pk_bf16_f32 v105, v90, v28
	v_mov_b64_e32 v[28:29], s[24:25]
	v_mad_i64_i32 v[30:31], s[34:35], v146, s58, v[28:29]
	v_lshlrev_b64 v[82:83], 1, v[72:73]
	v_lshl_add_u64 v[30:31], v[30:31], 0, v[82:83]
	global_store_dwordx4 v[30:31], v[102:105], off sc1 nt
	v_or_b32_e32 v30, 1, v146
	v_mad_i64_i32 v[30:31], s[34:35], v30, s58, v[28:29]
	v_lshl_add_u64 v[30:31], v[30:31], 0, v[82:83]
	v_cvt_pk_bf16_f32 v102, v114, v119
	v_cvt_pk_bf16_f32 v103, v88, v85
	global_store_dwordx4 v[30:31], v[100:103], off sc1 nt
	v_or_b32_e32 v30, 2, v146
	v_mad_i64_i32 v[30:31], s[34:35], v30, s58, v[28:29]
	v_lshl_add_u64 v[30:31], v[30:31], 0, v[82:83]
	v_cvt_pk_bf16_f32 v100, v118, v123
	v_cvt_pk_bf16_f32 v101, v89, v80
	global_store_dwordx4 v[30:31], v[98:101], off sc1 nt
	v_or_b32_e32 v30, 3, v146
	v_mad_i64_i32 v[28:29], s[34:35], v30, s58, v[28:29]
	v_cvt_pk_bf16_f32 v72, v122, v126
	v_cvt_pk_bf16_f32 v73, v92, v81
	v_lshl_add_u64 v[28:29], v[28:29], 0, v[82:83]
	global_store_dwordx4 v[28:29], v[70:73], off sc1 nt
	s_andn2_b64 vcc, exec, s[30:31]
	v_mov_b32_e32 v84, 0
	v_mov_b32_e32 v80, 0
	v_mov_b32_e32 v70, 0
	v_mov_b32_e32 v28, 0
	v_mov_b32_e32 v86, 0
	v_mov_b32_e32 v30, 0
	v_mov_b32_e32 v72, 0
	v_mov_b32_e32 v79, 0
	v_mov_b32_e32 v85, 0
	v_mov_b32_e32 v81, 0
	v_mov_b32_e32 v71, 0
	v_mov_b32_e32 v29, 0
	v_mov_b32_e32 v87, 0
	v_mov_b32_e32 v31, 0
	v_mov_b32_e32 v73, 0
	s_cbranch_vccnz .LBB0_469
	ds_read_b128 v[78:81], v160 offset:1552
	ds_read_b128 v[28:31], v160 offset:528
	ds_read_b128 v[88:91], v160 offset:16
	ds_read_b128 v[92:95], v160 offset:1040
	s_waitcnt lgkmcnt(0)
	v_mov_b32_e32 v84, v79
	v_mov_b32_e32 v70, v81
	v_mov_b32_e32 v86, v29
	v_mov_b32_e32 v72, v31
	v_mov_b32_e32 v79, v92
	v_mov_b32_e32 v85, v93
	v_mov_b32_e32 v81, v94
	v_mov_b32_e32 v71, v95
	v_mov_b32_e32 v29, v88
	v_mov_b32_e32 v87, v89
	v_mov_b32_e32 v31, v90
	v_mov_b32_e32 v73, v91
.LBB0_469:
	v_mov_b32_e32 v88, v68
	v_mov_b32_e32 v89, v68
	v_mov_b32_e32 v92, v68
	v_mov_b32_e32 v93, v68
	v_pk_mul_f32 v[12:13], v[12:13], v[88:89]
	v_pk_mul_f32 v[88:89], v[4:5], v[88:89]
	v_mov_b32_e32 v68, v69
	v_mov_b32_dpp v79, v52 row_shr:1 row_mask:0xf bank_mask:0xf
	v_mov_b32_dpp v78, v56 row_shr:1 row_mask:0xf bank_mask:0xf
	v_mov_b32_e32 v90, v69
	v_mov_b32_e32 v91, v69
	v_pk_mul_f32 v[4:5], v[10:11], v[68:69]
	v_pk_mul_f32 v[2:3], v[2:3], v[68:69]
	v_mov_b32_e32 v10, v88
	v_mov_b32_e32 v11, v12
	v_pk_mul_f32 v[68:69], v[36:37], v[78:79]
	v_mov_b32_dpp v29, v44 row_shr:1 row_mask:0xf bank_mask:0xf
	v_mov_b32_dpp v28, v48 row_shr:1 row_mask:0xf bank_mask:0xf
	v_pk_fma_f32 v[68:69], v[10:11], v[34:35], v[68:69]
	v_pk_mul_f32 v[0:1], v[0:1], v[90:91]
	v_pk_fma_f32 v[28:29], v[32:33], v[28:29], v[68:69]
	v_mov_b32_e32 v68, v0
	v_mul_f32_e32 v0, 0xbfb8aa3b, v29
	v_pk_mul_f32 v[8:9], v[8:9], v[90:91]
	v_exp_f32_e32 v0, v0
	v_mov_b32_e32 v69, v8
	v_pk_mul_f32 v[90:91], v[68:69], v[34:35]
	v_pk_mul_f32 v[14:15], v[14:15], v[92:93]
	v_pk_fma_f32 v[90:91], v[10:11], v[36:37], v[90:91]
	v_add_f32_e32 v0, 1.0, v0
	v_pk_fma_f32 v[78:79], v[32:33], v[78:79], v[90:91]
	v_mov_b32_e32 v90, v48
	v_mov_b32_e32 v91, v44
	v_pk_mul_f32 v[6:7], v[6:7], v[92:93]
	v_pk_mul_f32 v[92:93], v[90:91], v[34:35]
	v_rcp_f32_e32 v0, v0
	v_mul_f32_e32 v8, 0xbfb8aa3b, v79
	v_pk_fma_f32 v[92:93], v[68:69], v[36:37], v[92:93]
	v_exp_f32_e32 v8, v8
	v_pk_fma_f32 v[10:11], v[10:11], v[32:33], v[92:93]
	v_mov_b32_e32 v92, v56
	v_mov_b32_e32 v93, v52
	v_pk_mul_f32 v[34:35], v[92:93], v[34:35]
	v_mul_f32_e32 v0, v29, v0
	v_pk_fma_f32 v[34:35], v[90:91], v[36:37], v[34:35]
	v_mov_b32_dpp v85, v53 row_shr:1 row_mask:0xf bank_mask:0xf
	v_pk_fma_f32 v[32:33], v[68:69], v[32:33], v[34:35]
	v_mul_f32_e32 v34, v28, v0
	v_add_f32_e32 v0, 1.0, v8
	v_mul_f32_e32 v8, 0xbfb8aa3b, v11
	v_exp_f32_e32 v8, v8
	v_mul_f32_e32 v12, 0xbfb8aa3b, v33
	v_exp_f32_e32 v12, v12
	v_rcp_f32_e32 v0, v0
	v_add_f32_e32 v8, 1.0, v8
	v_rcp_f32_e32 v8, v8
	v_add_f32_e32 v12, 1.0, v12
	v_rcp_f32_e32 v12, v12
	v_mul_f32_e32 v0, v79, v0
	v_mul_f32_e32 v35, v78, v0
	v_mul_f32_e32 v0, v11, v8
	v_mov_b32_dpp v84, v57 row_shr:1 row_mask:0xf bank_mask:0xf
	v_mul_f32_e32 v36, v10, v0
	v_mul_f32_e32 v0, v33, v12
	v_mov_b32_e32 v12, v89
	v_pk_mul_f32 v[10:11], v[106:107], v[84:85]
	v_mov_b32_e32 v44, v49
	v_mov_b32_dpp v87, v45 row_shr:1 row_mask:0xf bank_mask:0xf
	v_mov_b32_dpp v86, v49 row_shr:1 row_mask:0xf bank_mask:0xf
	v_pk_fma_f32 v[10:11], v[12:13], v[110:111], v[10:11]
	v_mov_b32_e32 v8, v1
	v_pk_mul_f32 v[28:29], v[44:45], v[110:111]
	v_mul_f32_e32 v32, v32, v0
	v_pk_fma_f32 v[10:11], v[74:75], v[86:87], v[10:11]
	v_pk_mul_f32 v[0:1], v[8:9], v[110:111]
	v_pk_fma_f32 v[28:29], v[8:9], v[106:107], v[28:29]
	v_pk_fma_f32 v[0:1], v[12:13], v[106:107], v[0:1]
	v_pk_fma_f32 v[12:13], v[12:13], v[74:75], v[28:29]
	v_mul_f32_e32 v28, 0xbfb8aa3b, v11
	v_exp_f32_e32 v33, v28
	v_pk_fma_f32 v[0:1], v[74:75], v[84:85], v[0:1]
	v_mov_b32_e32 v52, v57
	v_mul_f32_e32 v37, 0xbfb8aa3b, v1
	v_add_f32_e32 v33, 1.0, v33
	v_rcp_f32_e32 v33, v33
	v_exp_f32_e32 v37, v37
	v_pk_mul_f32 v[28:29], v[52:53], v[110:111]
	v_mov_b32_dpp v81, v54 row_shr:1 row_mask:0xf bank_mask:0xf
	v_pk_fma_f32 v[28:29], v[44:45], v[106:107], v[28:29]
	v_mul_f32_e32 v11, v11, v33
	v_pk_fma_f32 v[8:9], v[8:9], v[74:75], v[28:29]
	v_mul_f32_e32 v33, v10, v11
	v_add_f32_e32 v10, 1.0, v37
	v_mul_f32_e32 v11, 0xbfb8aa3b, v13
	v_rcp_f32_e32 v10, v10
	v_exp_f32_e32 v11, v11
	v_mul_f32_e32 v28, 0xbfb8aa3b, v9
	v_exp_f32_e32 v28, v28
	v_mul_f32_e32 v1, v1, v10
	v_add_f32_e32 v10, 1.0, v11
	v_rcp_f32_e32 v10, v10
	v_add_f32_e32 v11, 1.0, v28
	v_rcp_f32_e32 v11, v11
	v_mul_f32_e32 v37, v0, v1
	v_mul_f32_e32 v0, v13, v10
	v_mul_f32_e32 v44, v12, v0
	v_mul_f32_e32 v0, v9, v11
	v_mov_b32_dpp v80, v58 row_shr:1 row_mask:0xf bank_mask:0xf
	v_mul_f32_e32 v45, v8, v0
	v_mov_b32_e32 v0, v6
	v_mov_b32_e32 v1, v14
	v_pk_mul_f32 v[8:9], v[42:43], v[80:81]
	v_mov_b32_dpp v31, v46 row_shr:1 row_mask:0xf bank_mask:0xf
	v_mov_b32_dpp v30, v50 row_shr:1 row_mask:0xf bank_mask:0xf
	v_pk_fma_f32 v[8:9], v[0:1], v[40:41], v[8:9]
	v_mov_b32_e32 v10, v2
	v_pk_fma_f32 v[8:9], v[38:39], v[30:31], v[8:9]
	v_mov_b32_e32 v11, v4
	v_mul_f32_e32 v2, 0xbfb8aa3b, v9
	v_exp_f32_e32 v2, v2
	v_pk_mul_f32 v[12:13], v[10:11], v[40:41]
	v_mov_b32_e32 v28, v50
	v_pk_fma_f32 v[12:13], v[0:1], v[42:43], v[12:13]
	v_mov_b32_e32 v29, v46
	v_pk_fma_f32 v[12:13], v[38:39], v[80:81], v[12:13]
	v_add_f32_e32 v2, 1.0, v2
	v_pk_mul_f32 v[30:31], v[28:29], v[40:41]
	v_rcp_f32_e32 v2, v2
	v_mul_f32_e32 v4, 0xbfb8aa3b, v13
	v_pk_fma_f32 v[30:31], v[10:11], v[42:43], v[30:31]
	v_exp_f32_e32 v4, v4
	v_pk_fma_f32 v[0:1], v[0:1], v[38:39], v[30:31]
	v_mov_b32_e32 v30, v58
	v_mov_b32_e32 v31, v54
	v_pk_mul_f32 v[30:31], v[30:31], v[40:41]
	v_mul_f32_e32 v2, v9, v2
	v_pk_fma_f32 v[28:29], v[28:29], v[42:43], v[30:31]
	v_mov_b32_dpp v71, v55 row_shr:1 row_mask:0xf bank_mask:0xf
	v_pk_fma_f32 v[10:11], v[10:11], v[38:39], v[28:29]
	v_mul_f32_e32 v28, v8, v2
	v_add_f32_e32 v2, 1.0, v4
	v_mul_f32_e32 v4, 0xbfb8aa3b, v1
	v_exp_f32_e32 v4, v4
	v_mul_f32_e32 v6, 0xbfb8aa3b, v11
	v_exp_f32_e32 v6, v6
	v_rcp_f32_e32 v2, v2
	v_add_f32_e32 v4, 1.0, v4
	v_rcp_f32_e32 v4, v4
	v_add_f32_e32 v6, 1.0, v6
	v_rcp_f32_e32 v6, v6
	v_mul_f32_e32 v2, v13, v2
	v_mul_f32_e32 v1, v1, v4
	v_mul_f32_e32 v13, v0, v1
	v_mul_f32_e32 v0, v11, v6
	v_mov_b32_dpp v70, v59 row_shr:1 row_mask:0xf bank_mask:0xf
	v_mul_f32_e32 v10, v10, v0
	v_mov_b32_e32 v14, v7
	v_pk_mul_f32 v[0:1], v[108:109], v[70:71]
	v_mov_b32_dpp v73, v47 row_shr:1 row_mask:0xf bank_mask:0xf
	v_mov_b32_dpp v72, v51 row_shr:1 row_mask:0xf bank_mask:0xf
	v_pk_fma_f32 v[0:1], v[14:15], v[112:113], v[0:1]
	v_mov_b32_e32 v4, v3
	v_pk_fma_f32 v[0:1], v[76:77], v[72:73], v[0:1]
	v_mul_f32_e32 v12, v12, v2
	v_mul_f32_e32 v8, 0xbfb8aa3b, v1
	v_exp_f32_e32 v11, v8
	v_pk_mul_f32 v[2:3], v[4:5], v[112:113]
	v_mov_b32_e32 v46, v51
	v_pk_fma_f32 v[2:3], v[14:15], v[108:109], v[2:3]
	v_pk_mul_f32 v[6:7], v[46:47], v[112:113]
	v_pk_fma_f32 v[2:3], v[76:77], v[70:71], v[2:3]
	v_pk_fma_f32 v[6:7], v[4:5], v[108:109], v[6:7]
	v_add_f32_e32 v11, 1.0, v11
	v_pk_fma_f32 v[6:7], v[14:15], v[76:77], v[6:7]
	v_rcp_f32_e32 v11, v11
	v_mul_f32_e32 v14, 0xbfb8aa3b, v3
	v_exp_f32_e32 v14, v14
	v_mov_b32_e32 v54, v59
	v_pk_mul_f32 v[8:9], v[54:55], v[112:113]
	v_mul_f32_e32 v1, v1, v11
	v_pk_fma_f32 v[8:9], v[46:47], v[108:109], v[8:9]
	v_mul_f32_e32 v0, v0, v1
	v_pk_fma_f32 v[4:5], v[4:5], v[76:77], v[8:9]
	v_add_f32_e32 v1, 1.0, v14
	v_mul_f32_e32 v8, 0xbfb8aa3b, v7
	v_rcp_f32_e32 v1, v1
	v_exp_f32_e32 v8, v8
	v_mul_f32_e32 v9, 0xbfb8aa3b, v5
	v_exp_f32_e32 v9, v9
	v_mul_f32_e32 v1, v3, v1
	v_add_f32_e32 v3, 1.0, v8
	v_rcp_f32_e32 v3, v3
	v_add_f32_e32 v8, 1.0, v9
	v_rcp_f32_e32 v8, v8
	v_mul_f32_e32 v9, v2, v1
	v_mul_f32_e32 v1, v7, v3
	v_mul_f32_e32 v6, v6, v1
	v_mul_f32_e32 v1, v5, v8
	v_add_u32_e32 v94, 0x80, v146
	v_mul_f32_e32 v4, v4, v1
	v_cvt_pk_bf16_f32 v68, v34, v33
	v_cvt_pk_bf16_f32 v69, v28, v0
	v_mov_b64_e32 v[0:1], s[24:25]
	v_mad_i64_i32 v[2:3], s[30:31], v94, s58, v[0:1]
	v_lshl_add_u64 v[2:3], v[2:3], 0, v[82:83]
	global_store_dwordx4 v[2:3], v[66:69], off sc1 nt
	v_add_u32_e32 v2, 0x81, v146
	v_mad_i64_i32 v[2:3], s[30:31], v2, s58, v[0:1]
	v_lshl_add_u64 v[2:3], v[2:3], 0, v[82:83]
	v_cvt_pk_bf16_f32 v66, v35, v37
	v_cvt_pk_bf16_f32 v67, v12, v9
	global_store_dwordx4 v[2:3], v[64:67], off sc1 nt
	v_add_u32_e32 v2, 0x82, v146
	v_mad_i64_i32 v[2:3], s[30:31], v2, s58, v[0:1]
	v_lshl_add_u64 v[2:3], v[2:3], 0, v[82:83]
	v_cvt_pk_bf16_f32 v64, v36, v44
	v_cvt_pk_bf16_f32 v65, v13, v6
	global_store_dwordx4 v[2:3], v[62:65], off sc1 nt
	v_add_u32_e32 v2, 0x83, v146
	v_mad_i64_i32 v[0:1], s[30:31], v2, s58, v[0:1]
	v_lshl_add_u64 v[0:1], v[0:1], 0, v[82:83]
	v_cvt_pk_bf16_f32 v62, v32, v45
	v_cvt_pk_bf16_f32 v63, v10, v4
	global_store_dwordx4 v[0:1], v[60:63], off sc1 nt
	s_and_b64 vcc, exec, s[8:9]
	s_mov_b64 s[8:9], -1
	s_cbranch_vccnz .LBB0_450
	s_xor_b32 s8, s11, 0x1000
	s_add_i32 s11, s8, 0
	s_add_i32 s11, s11, 0x24010
	s_and_saveexec_b64 s[8:9], s[2:3]
	s_cbranch_execz .LBB0_472
	v_add3_u32 v0, s11, v215, v190
	s_waitcnt vmcnt(8)
	ds_write_b128 v0, v[16:19]

.LBB0_554:
	ds_read_b128 v[128:131], v190
	ds_read_b128 v[132:135], v190 offset:1024
	ds_read_b128 v[136:139], v190 offset:2048
	ds_read_b128 v[140:143], v190 offset:3072
	s_add_u32 s18, s14, 0x100
	s_addc_u32 s19, s15, 0
	s_cmp_eq_u32 s51, 40
	s_cselect_b32 s23, s1, s19
	s_cselect_b32 s22, s0, s18
	s_cselect_b32 s21, s7, s50
	s_cselect_b32 s20, s6, s49
	v_lshl_add_u64 v[184:185], s[14:15], 0, v[160:161]
	s_add_i32 m0, s34, 0xc000
	ds_read_b128 v[144:147], v191
	ds_read_b128 v[148:151], v191 offset:1024
	ds_read_b128 v[168:171], v191 offset:2048
	ds_read_b128 v[172:175], v191 offset:3072
	ds_read_b128 v[176:179], v191 offset:4096
	ds_read_b128 v[180:183], v191 offset:5120
	ds_read_b128 v[194:197], v191 offset:6144
	ds_read_b128 v[198:201], v191 offset:7168
	global_load_lds_dwordx4 v[184:185], off
	v_lshl_add_u64 v[184:185], s[14:15], 0, v[162:163]
	s_add_i32 m0, s34, 0xe000
	s_nop 0
	global_load_lds_dwordx4 v[184:185], off
	s_waitcnt lgkmcnt(8)
	s_barrier
	s_waitcnt lgkmcnt(0)
	s_setprio 1
	s_waitcnt lgkmcnt(0)
	v_mfma_f32_16x16x32_bf16 v[124:127], v[128:131], v[144:147], v[124:127]
	v_mfma_f32_16x16x32_bf16 v[120:123], v[136:139], v[144:147], v[120:123]
	v_mfma_f32_16x16x32_bf16 v[108:111], v[128:131], v[168:171], v[108:111]
	v_mfma_f32_16x16x32_bf16 v[104:107], v[136:139], v[168:171], v[104:107]
	v_mfma_f32_16x16x32_bf16 v[92:95], v[128:131], v[176:179], v[92:95]
	v_mfma_f32_16x16x32_bf16 v[88:91], v[136:139], v[176:179], v[88:91]
	v_mfma_f32_16x16x32_bf16 v[76:79], v[128:131], v[194:197], v[76:79]
	v_mfma_f32_16x16x32_bf16 v[72:75], v[136:139], v[194:197], v[72:75]
	v_mfma_f32_16x16x32_bf16 v[124:127], v[132:135], v[148:151], v[124:127]
	v_mfma_f32_16x16x32_bf16 v[120:123], v[140:143], v[148:151], v[120:123]
	v_mfma_f32_16x16x32_bf16 v[108:111], v[132:135], v[172:175], v[108:111]
	v_mfma_f32_16x16x32_bf16 v[104:107], v[140:143], v[172:175], v[104:107]
	v_mfma_f32_16x16x32_bf16 v[92:95], v[132:135], v[180:183], v[92:95]
	v_mfma_f32_16x16x32_bf16 v[88:91], v[140:143], v[180:183], v[88:91]
	v_mfma_f32_16x16x32_bf16 v[76:79], v[132:135], v[198:201], v[76:79]
	v_mfma_f32_16x16x32_bf16 v[72:75], v[140:143], v[198:201], v[72:75]
	s_setprio 0
	s_barrier
	s_add_i32 s14, s43, s31
	v_lshl_add_u64 v[184:185], s[20:21], 0, v[154:155]
	s_mov_b32 m0, s14
	ds_read_b128 v[202:205], v192
	ds_read_b128 v[206:209], v192 offset:1024
	ds_read_b128 v[210:213], v192 offset:2048
	ds_read_b128 v[214:217], v192 offset:3072
	global_load_lds_dwordx4 v[184:185], off
	v_lshl_add_u64 v[218:219], s[20:21], 0, v[158:159]
	s_add_i32 m0, s14, 0x2000
	s_nop 0
	global_load_lds_dwordx4 v[218:219], off
	s_barrier
	s_waitcnt lgkmcnt(0)
	s_setprio 1
	s_waitcnt lgkmcnt(0)
	v_mfma_f32_16x16x32_bf16 v[116:119], v[202:205], v[144:147], v[116:119]
	v_mfma_f32_16x16x32_bf16 v[112:115], v[210:213], v[144:147], v[112:115]
	v_mfma_f32_16x16x32_bf16 v[100:103], v[202:205], v[168:171], v[100:103]
	v_mfma_f32_16x16x32_bf16 v[96:99], v[210:213], v[168:171], v[96:99]
	v_mfma_f32_16x16x32_bf16 v[84:87], v[202:205], v[176:179], v[84:87]
	v_mfma_f32_16x16x32_bf16 v[80:83], v[210:213], v[176:179], v[80:83]
	v_mfma_f32_16x16x32_bf16 v[68:71], v[202:205], v[194:197], v[68:71]
	v_mfma_f32_16x16x32_bf16 v[64:67], v[210:213], v[194:197], v[64:67]
	v_mfma_f32_16x16x32_bf16 v[116:119], v[206:209], v[148:151], v[116:119]
	v_mfma_f32_16x16x32_bf16 v[112:115], v[214:217], v[148:151], v[112:115]
	v_mfma_f32_16x16x32_bf16 v[100:103], v[206:209], v[172:175], v[100:103]
	v_mfma_f32_16x16x32_bf16 v[96:99], v[214:217], v[172:175], v[96:99]
	v_mfma_f32_16x16x32_bf16 v[84:87], v[206:209], v[180:183], v[84:87]
	v_mfma_f32_16x16x32_bf16 v[80:83], v[214:217], v[180:183], v[80:83]
	v_mfma_f32_16x16x32_bf16 v[68:71], v[206:209], v[198:201], v[68:71]
	v_mfma_f32_16x16x32_bf16 v[64:67], v[214:217], v[198:201], v[64:67]
	s_setprio 0
	s_mov_b32 m0, s34
	v_lshl_add_u64 v[220:221], s[22:23], 0, v[152:153]
	s_barrier
	ds_read_b128 v[144:147], v191 offset:16384
	ds_read_b128 v[148:151], v191 offset:17408
	ds_read_b128 v[168:171], v191 offset:18432
	ds_read_b128 v[172:175], v191 offset:19456
	ds_read_b128 v[176:179], v191 offset:20480
	ds_read_b128 v[180:183], v191 offset:21504
	ds_read_b128 v[194:197], v191 offset:22528
	ds_read_b128 v[198:201], v191 offset:23552
	global_load_lds_dwordx4 v[220:221], off
	v_lshl_add_u64 v[222:223], s[22:23], 0, v[156:157]
	s_mov_b32 m0, s35
	s_nop 0
	global_load_lds_dwordx4 v[222:223], off
	s_barrier
	s_waitcnt lgkmcnt(0)
	s_setprio 1
	s_waitcnt lgkmcnt(0)
	v_mfma_f32_16x16x32_bf16 v[60:63], v[128:131], v[144:147], v[60:63]
	v_mfma_f32_16x16x32_bf16 v[56:59], v[136:139], v[144:147], v[56:59]
	v_mfma_f32_16x16x32_bf16 v[44:47], v[128:131], v[168:171], v[44:47]
	v_mfma_f32_16x16x32_bf16 v[40:43], v[136:139], v[168:171], v[40:43]
	v_mfma_f32_16x16x32_bf16 v[28:31], v[128:131], v[176:179], v[28:31]
	v_mfma_f32_16x16x32_bf16 v[24:27], v[136:139], v[176:179], v[24:27]
	v_mfma_f32_16x16x32_bf16 v[12:15], v[128:131], v[194:197], v[12:15]
	v_mfma_f32_16x16x32_bf16 v[8:11], v[136:139], v[194:197], v[8:11]
	v_mfma_f32_16x16x32_bf16 v[60:63], v[132:135], v[148:151], v[60:63]
	v_mfma_f32_16x16x32_bf16 v[56:59], v[140:143], v[148:151], v[56:59]
	v_mfma_f32_16x16x32_bf16 v[44:47], v[132:135], v[172:175], v[44:47]
	v_mfma_f32_16x16x32_bf16 v[40:43], v[140:143], v[172:175], v[40:43]
	v_mfma_f32_16x16x32_bf16 v[28:31], v[132:135], v[180:183], v[28:31]
	v_mfma_f32_16x16x32_bf16 v[24:27], v[140:143], v[180:183], v[24:27]
	v_mfma_f32_16x16x32_bf16 v[12:15], v[132:135], v[198:201], v[12:15]
	v_mfma_f32_16x16x32_bf16 v[8:11], v[140:143], v[198:201], v[8:11]
	s_setprio 0
	s_barrier
	s_add_u32 s14, s20, 0xb0000
	s_addc_u32 s15, s21, 0
	s_add_i32 s52, s44, s31
	v_lshl_add_u64 v[128:129], s[14:15], 0, v[154:155]
	s_mov_b32 m0, s52
	s_nop 0
	global_load_lds_dwordx4 v[128:129], off
	v_lshl_add_u64 v[128:129], s[14:15], 0, v[158:159]
	s_add_i32 m0, s52, 0x2000
	s_nop 0
	global_load_lds_dwordx4 v[128:129], off
	s_waitcnt vmcnt(6)
	s_barrier
	s_setprio 1
	v_mfma_f32_16x16x32_bf16 v[52:55], v[202:205], v[144:147], v[52:55]
	v_mfma_f32_16x16x32_bf16 v[48:51], v[210:213], v[144:147], v[48:51]
	v_mfma_f32_16x16x32_bf16 v[36:39], v[202:205], v[168:171], v[36:39]
	v_mfma_f32_16x16x32_bf16 v[32:35], v[210:213], v[168:171], v[32:35]
	v_mfma_f32_16x16x32_bf16 v[20:23], v[202:205], v[176:179], v[20:23]
	v_mfma_f32_16x16x32_bf16 v[16:19], v[210:213], v[176:179], v[16:19]
	v_mfma_f32_16x16x32_bf16 v[4:7], v[202:205], v[194:197], v[4:7]
	v_mfma_f32_16x16x32_bf16 v[0:3], v[210:213], v[194:197], v[0:3]
	v_mfma_f32_16x16x32_bf16 v[52:55], v[206:209], v[148:151], v[52:55]
	v_mfma_f32_16x16x32_bf16 v[48:51], v[214:217], v[148:151], v[48:51]
	v_mfma_f32_16x16x32_bf16 v[36:39], v[206:209], v[172:175], v[36:39]
	v_mfma_f32_16x16x32_bf16 v[32:35], v[214:217], v[172:175], v[32:35]
	v_mfma_f32_16x16x32_bf16 v[20:23], v[206:209], v[180:183], v[20:23]
	v_mfma_f32_16x16x32_bf16 v[16:19], v[214:217], v[180:183], v[16:19]
	v_mfma_f32_16x16x32_bf16 v[4:7], v[206:209], v[198:201], v[4:7]
	v_mfma_f32_16x16x32_bf16 v[0:3], v[214:217], v[198:201], v[0:3]
	s_setprio 0
	s_add_i32 s52, 0, 0x18000
	v_add_u32_e32 v140, s52, v187
	s_barrier
	ds_read_b128 v[128:131], v140
	ds_read_b128 v[132:135], v140 offset:1024
	ds_read_b128 v[136:139], v140 offset:2048
	ds_read_b128 v[140:143], v140 offset:3072
	s_add_u32 s14, s22, 0xb0000
	s_addc_u32 s15, s23, 0
	s_mov_b32 m0, s36
	v_lshl_add_u64 v[202:203], s[14:15], 0, v[152:153]
	ds_read_b128 v[144:147], v191 offset:32768
	ds_read_b128 v[148:151], v191 offset:33792
	ds_read_b128 v[168:171], v191 offset:34816
	ds_read_b128 v[172:175], v191 offset:35840
	ds_read_b128 v[176:179], v191 offset:36864
	ds_read_b128 v[180:183], v191 offset:37888
	ds_read_b128 v[194:197], v191 offset:38912
	ds_read_b128 v[198:201], v191 offset:39936
	global_load_lds_dwordx4 v[202:203], off
	v_lshl_add_u64 v[202:203], s[14:15], 0, v[156:157]
	s_mov_b32 m0, s37
	s_nop 0
	global_load_lds_dwordx4 v[202:203], off
	s_waitcnt lgkmcnt(8)
	s_barrier
	s_waitcnt lgkmcnt(0)
	s_setprio 1
	s_waitcnt lgkmcnt(0)
	v_mfma_f32_16x16x32_bf16 v[124:127], v[128:131], v[144:147], v[124:127]
	v_mfma_f32_16x16x32_bf16 v[120:123], v[136:139], v[144:147], v[120:123]
	v_mfma_f32_16x16x32_bf16 v[108:111], v[128:131], v[168:171], v[108:111]
	v_mfma_f32_16x16x32_bf16 v[104:107], v[136:139], v[168:171], v[104:107]
	v_mfma_f32_16x16x32_bf16 v[92:95], v[128:131], v[176:179], v[92:95]
	v_mfma_f32_16x16x32_bf16 v[88:91], v[136:139], v[176:179], v[88:91]
	v_mfma_f32_16x16x32_bf16 v[76:79], v[128:131], v[194:197], v[76:79]
	v_mfma_f32_16x16x32_bf16 v[72:75], v[136:139], v[194:197], v[72:75]
	v_mfma_f32_16x16x32_bf16 v[124:127], v[132:135], v[148:151], v[124:127]
	v_mfma_f32_16x16x32_bf16 v[120:123], v[140:143], v[148:151], v[120:123]
	v_mfma_f32_16x16x32_bf16 v[108:111], v[132:135], v[172:175], v[108:111]
	v_mfma_f32_16x16x32_bf16 v[104:107], v[140:143], v[172:175], v[104:107]
	v_mfma_f32_16x16x32_bf16 v[92:95], v[132:135], v[180:183], v[92:95]
	v_mfma_f32_16x16x32_bf16 v[88:91], v[140:143], v[180:183], v[88:91]
	v_mfma_f32_16x16x32_bf16 v[76:79], v[132:135], v[198:201], v[76:79]
	v_mfma_f32_16x16x32_bf16 v[72:75], v[140:143], v[198:201], v[72:75]
	s_setprio 0
	s_barrier
	s_add_i32 s22, 0, 0x1c000
	s_add_i32 s14, s52, s31
	v_add_u32_e32 v214, s22, v187
	v_lshl_add_u64 v[184:185], v[184:185], 0, s[12:13]
	s_mov_b32 m0, s14
	ds_read_b128 v[202:205], v214
	ds_read_b128 v[206:209], v214 offset:1024
	ds_read_b128 v[210:213], v214 offset:2048
	ds_read_b128 v[214:217], v214 offset:3072
	global_load_lds_dwordx4 v[184:185], off
	v_lshl_add_u64 v[184:185], v[218:219], 0, s[12:13]
	s_add_i32 m0, s14, 0x2000
	s_nop 0
	global_load_lds_dwordx4 v[184:185], off
	s_barrier
	s_waitcnt lgkmcnt(0)
	s_setprio 1
	s_waitcnt lgkmcnt(0)
	v_mfma_f32_16x16x32_bf16 v[116:119], v[202:205], v[144:147], v[116:119]
	v_mfma_f32_16x16x32_bf16 v[112:115], v[210:213], v[144:147], v[112:115]
	v_mfma_f32_16x16x32_bf16 v[100:103], v[202:205], v[168:171], v[100:103]
	v_mfma_f32_16x16x32_bf16 v[96:99], v[210:213], v[168:171], v[96:99]
	v_mfma_f32_16x16x32_bf16 v[84:87], v[202:205], v[176:179], v[84:87]
	v_mfma_f32_16x16x32_bf16 v[80:83], v[210:213], v[176:179], v[80:83]
	v_mfma_f32_16x16x32_bf16 v[68:71], v[202:205], v[194:197], v[68:71]
	v_mfma_f32_16x16x32_bf16 v[64:67], v[210:213], v[194:197], v[64:67]
	v_mfma_f32_16x16x32_bf16 v[116:119], v[206:209], v[148:151], v[116:119]
	v_mfma_f32_16x16x32_bf16 v[112:115], v[214:217], v[148:151], v[112:115]
	v_mfma_f32_16x16x32_bf16 v[100:103], v[206:209], v[172:175], v[100:103]
	v_mfma_f32_16x16x32_bf16 v[96:99], v[214:217], v[172:175], v[96:99]
	v_mfma_f32_16x16x32_bf16 v[84:87], v[206:209], v[180:183], v[84:87]
	v_mfma_f32_16x16x32_bf16 v[80:83], v[214:217], v[180:183], v[80:83]
	v_mfma_f32_16x16x32_bf16 v[68:71], v[206:209], v[198:201], v[68:71]
	v_mfma_f32_16x16x32_bf16 v[64:67], v[214:217], v[198:201], v[64:67]
	s_setprio 0
	s_mov_b32 m0, s39
	v_lshl_add_u64 v[184:185], v[220:221], 0, s[12:13]
	s_barrier
	ds_read_b128 v[144:147], v191 offset:49152
	ds_read_b128 v[148:151], v191 offset:50176
	ds_read_b128 v[168:171], v191 offset:51200
	ds_read_b128 v[172:175], v191 offset:52224
	ds_read_b128 v[176:179], v191 offset:53248
	ds_read_b128 v[180:183], v191 offset:54272
	ds_read_b128 v[194:197], v191 offset:55296
	ds_read_b128 v[198:201], v191 offset:56320
	global_load_lds_dwordx4 v[184:185], off
	v_lshl_add_u64 v[184:185], v[222:223], 0, s[12:13]
	s_mov_b32 m0, s40
	s_nop 0
	global_load_lds_dwordx4 v[184:185], off
	s_barrier
	s_waitcnt lgkmcnt(0)
	s_setprio 1
	s_waitcnt lgkmcnt(0)
	v_mfma_f32_16x16x32_bf16 v[60:63], v[128:131], v[144:147], v[60:63]
	v_mfma_f32_16x16x32_bf16 v[56:59], v[136:139], v[144:147], v[56:59]
	v_mfma_f32_16x16x32_bf16 v[44:47], v[128:131], v[168:171], v[44:47]
	v_mfma_f32_16x16x32_bf16 v[40:43], v[136:139], v[168:171], v[40:43]
	v_mfma_f32_16x16x32_bf16 v[28:31], v[128:131], v[176:179], v[28:31]
	v_mfma_f32_16x16x32_bf16 v[24:27], v[136:139], v[176:179], v[24:27]
	v_mfma_f32_16x16x32_bf16 v[12:15], v[128:131], v[194:197], v[12:15]
	v_mfma_f32_16x16x32_bf16 v[8:11], v[136:139], v[194:197], v[8:11]
	v_mfma_f32_16x16x32_bf16 v[60:63], v[132:135], v[148:151], v[60:63]
	v_mfma_f32_16x16x32_bf16 v[56:59], v[140:143], v[148:151], v[56:59]
	v_mfma_f32_16x16x32_bf16 v[44:47], v[132:135], v[172:175], v[44:47]
	v_mfma_f32_16x16x32_bf16 v[40:43], v[140:143], v[172:175], v[40:43]
	v_mfma_f32_16x16x32_bf16 v[28:31], v[132:135], v[180:183], v[28:31]
	v_mfma_f32_16x16x32_bf16 v[24:27], v[140:143], v[180:183], v[24:27]
	v_mfma_f32_16x16x32_bf16 v[12:15], v[132:135], v[198:201], v[12:15]
	v_mfma_f32_16x16x32_bf16 v[8:11], v[140:143], v[198:201], v[8:11]
	s_setprio 0
	s_barrier
	s_add_u32 s14, s20, 0xb0080
	s_addc_u32 s15, s21, 0
	s_add_i32 s20, s22, s31
	v_lshl_add_u64 v[128:129], s[14:15], 0, v[154:155]
	s_mov_b32 m0, s20
	s_nop 0
	global_load_lds_dwordx4 v[128:129], off
	v_lshl_add_u64 v[128:129], s[14:15], 0, v[158:159]
	s_add_i32 m0, s20, 0x2000
	s_nop 0
	global_load_lds_dwordx4 v[128:129], off
	s_waitcnt vmcnt(6)
	s_barrier
	s_setprio 1
	v_mfma_f32_16x16x32_bf16 v[52:55], v[202:205], v[144:147], v[52:55]
	v_mfma_f32_16x16x32_bf16 v[48:51], v[210:213], v[144:147], v[48:51]
	v_mfma_f32_16x16x32_bf16 v[36:39], v[202:205], v[168:171], v[36:39]
	v_mfma_f32_16x16x32_bf16 v[32:35], v[210:213], v[168:171], v[32:35]
	v_mfma_f32_16x16x32_bf16 v[20:23], v[202:205], v[176:179], v[20:23]
	v_mfma_f32_16x16x32_bf16 v[16:19], v[210:213], v[176:179], v[16:19]
	v_mfma_f32_16x16x32_bf16 v[4:7], v[202:205], v[194:197], v[4:7]
	v_mfma_f32_16x16x32_bf16 v[0:3], v[210:213], v[194:197], v[0:3]
	v_mfma_f32_16x16x32_bf16 v[52:55], v[206:209], v[148:151], v[52:55]
	v_mfma_f32_16x16x32_bf16 v[48:51], v[214:217], v[148:151], v[48:51]
	v_mfma_f32_16x16x32_bf16 v[36:39], v[206:209], v[172:175], v[36:39]
	v_mfma_f32_16x16x32_bf16 v[32:35], v[214:217], v[172:175], v[32:35]
	v_mfma_f32_16x16x32_bf16 v[20:23], v[206:209], v[180:183], v[20:23]
	v_mfma_f32_16x16x32_bf16 v[16:19], v[214:217], v[180:183], v[16:19]
	v_mfma_f32_16x16x32_bf16 v[4:7], v[206:209], v[198:201], v[4:7]
	v_mfma_f32_16x16x32_bf16 v[0:3], v[214:217], v[198:201], v[0:3]
	s_setprio 0
	s_add_i32 s51, s51, 2
	s_add_u32 s49, s49, 0x100
	s_addc_u32 s50, s50, 0
	s_cmp_gt_u32 s51, 41
	s_mov_b64 s[14:15], s[18:19]
	s_barrier
	s_cbranch_scc0 .LBB0_554
	v_lshl_or_b32 v168, s10, 8, v189
	v_lshl_add_u32 v170, s48, 8, v186
	v_ashrrev_i32_e32 v169, 31, v168
	v_lshlrev_b64 v[202:203], 1, v[168:169]
	v_ashrrev_i32_e32 v171, 31, v170
	v_or_b32_e32 v182, 16, v170
	v_lshl_add_u64 v[172:173], s[64:65], 0, v[202:203]
	v_lshlrev_b64 v[204:205], 11, v[170:171]
	v_ashrrev_i32_e32 v183, 31, v182
	v_or_b32_e32 v178, 32, v170
	v_lshl_add_u64 v[128:129], v[172:173], 0, v[204:205]
	v_lshlrev_b64 v[184:185], 11, v[182:183]
	v_ashrrev_i32_e32 v179, 31, v178
	v_or_b32_e32 v174, 48, v170
	global_load_dwordx4 v[194:197], v[128:129], off
	global_load_dwordx4 v[198:201], v[128:129], off offset:256
	v_lshl_add_u64 v[128:129], v[172:173], 0, v[184:185]
	v_lshlrev_b64 v[180:181], 11, v[178:179]
	v_ashrrev_i32_e32 v175, 31, v174
	global_load_dwordx4 v[148:151], v[128:129], off
	global_load_dwordx4 v[144:147], v[128:129], off offset:256
	v_lshl_add_u64 v[128:129], v[172:173], 0, v[180:181]
	v_lshlrev_b64 v[176:177], 11, v[174:175]
	global_load_dwordx4 v[140:143], v[128:129], off
	global_load_dwordx4 v[136:139], v[128:129], off offset:256
	v_lshl_add_u64 v[128:129], v[172:173], 0, v[176:177]
	global_load_dwordx4 v[132:135], v[128:129], off
	s_nop 0
	global_load_dwordx4 v[128:131], v[128:129], off offset:256
	s_lshl_b32 s14, s10, 2
	s_ashr_i32 s15, s14, 31
	v_add_u32_e32 v252, 0x80, v170
	v_ashrrev_i32_e32 v253, 31, v252
	v_lshlrev_b64 v[252:253], 11, v[252:253]
	v_lshl_add_u64 v[252:253], v[172:173], 0, v[252:253]
	global_load_dwordx4 v[236:239], v[252:253], off
	global_load_dwordx4 v[240:243], v[252:253], off offset:256
	v_add_u32_e32 v252, 0x90, v170
	v_ashrrev_i32_e32 v253, 31, v252
	v_lshlrev_b64 v[252:253], 11, v[252:253]
	v_lshl_add_u64 v[252:253], v[172:173], 0, v[252:253]
	global_load_dwordx4 v[244:247], v[252:253], off
	global_load_dwordx4 v[248:251], v[252:253], off offset:256
	v_add_u32_e32 v252, 0xa0, v170
	v_ashrrev_i32_e32 v253, 31, v252
	v_lshlrev_b64 v[252:253], 11, v[252:253]
	v_lshl_add_u64 v[252:253], v[172:173], 0, v[252:253]
	global_load_dwordx4 v[210:213], v[252:253], off
	global_load_dwordx4 v[214:217], v[252:253], off offset:256
	s_waitcnt vmcnt(6)
	v_lshlrev_b32_e32 v206, 16, v194
	v_and_b32_e32 v207, 0xffff0000, v194
	v_lshlrev_b32_e32 v194, 16, v195
	v_and_b32_e32 v195, 0xffff0000, v195
	v_lshlrev_b32_e32 v208, 16, v196
	v_and_b32_e32 v209, 0xffff0000, v196
	v_lshlrev_b32_e32 v196, 16, v197
	v_and_b32_e32 v197, 0xffff0000, v197
	v_pk_add_f32 v[126:127], v[126:127], v[194:195]
	v_pk_add_f32 v[124:125], v[124:125], v[206:207]
	v_pk_add_f32 v[194:195], v[122:123], v[196:197]
	v_pk_add_f32 v[122:123], v[120:121], v[208:209]
	v_mul_f32_e32 v120, v125, v125
	v_mul_f32_e32 v121, v127, v127
	v_fmac_f32_e32 v120, v124, v124
	v_fmac_f32_e32 v121, v126, v126
	v_add_f32_e32 v120, v120, v121
	v_mul_f32_e32 v121, v123, v123
	v_mul_f32_e32 v196, v195, v195
	v_fmac_f32_e32 v121, v122, v122
	v_fmac_f32_e32 v196, v194, v194
	v_add_f32_e32 v121, v121, v196
	v_add_f32_e32 v206, v120, v121
	v_cvt_pk_bf16_f32 v120, v124, v125
	v_cvt_pk_bf16_f32 v121, v126, v127
	v_lshlrev_b32_e32 v124, 16, v198
	v_and_b32_e32 v125, 0xffff0000, v198
	v_lshlrev_b32_e32 v126, 16, v199
	v_and_b32_e32 v127, 0xffff0000, v199
	v_cvt_pk_bf16_f32 v122, v122, v123
	v_cvt_pk_bf16_f32 v123, v194, v195
	v_lshlrev_b32_e32 v194, 16, v200
	v_and_b32_e32 v195, 0xffff0000, v200
	v_pk_add_f32 v[118:119], v[118:119], v[126:127]
	v_pk_add_f32 v[116:117], v[116:117], v[124:125]
	v_lshlrev_b32_e32 v196, 16, v201
	v_and_b32_e32 v197, 0xffff0000, v201
	v_pk_add_f32 v[126:127], v[112:113], v[194:195]
	v_mul_f32_e32 v112, v117, v117
	v_mul_f32_e32 v113, v119, v119
	v_pk_add_f32 v[124:125], v[114:115], v[196:197]
	v_fmac_f32_e32 v112, v116, v116
	v_fmac_f32_e32 v113, v118, v118
	v_add_f32_e32 v112, v112, v113
	v_mul_f32_e32 v113, v127, v127
	v_mul_f32_e32 v114, v125, v125
	v_fmac_f32_e32 v113, v126, v126
	v_fmac_f32_e32 v114, v124, v124
	v_add_f32_e32 v113, v113, v114
	v_add_f32_e32 v112, v112, v113
	v_and_b32_e32 v114, 64, v193
	v_add_f32_e32 v113, v206, v112
	v_xor_b32_e32 v112, 16, v193
	v_add_u32_e32 v196, 64, v114
	v_cmp_lt_i32_e32 vcc, v112, v196
	v_lshl_add_u64 v[114:115], s[64:65], 0, v[204:205]
	v_lshl_add_u64 v[194:195], v[114:115], 0, v[202:203]
	v_cndmask_b32_e32 v112, v193, v112, vcc
	v_lshlrev_b32_e32 v112, 2, v112
	ds_bpermute_b32 v197, v112, v113
	global_store_dwordx4 v[194:195], v[120:123], off sc1
	v_cvt_pk_bf16_f32 v116, v116, v117
	v_cvt_pk_bf16_f32 v117, v118, v119
	v_cvt_pk_bf16_f32 v118, v126, v127
	s_waitcnt lgkmcnt(0)
	v_add_f32_e32 v114, v113, v197
	v_xor_b32_e32 v113, 32, v193
	v_cmp_lt_i32_e32 vcc, v113, v196
	v_cvt_pk_bf16_f32 v119, v124, v125
	global_store_dwordx4 v[194:195], v[116:119], off offset:256 sc1
	s_nop 0
	v_cndmask_b32_e32 v113, v193, v113, vcc
	v_lshlrev_b32_e32 v113, 2, v113
	ds_bpermute_b32 v115, v113, v114
	s_and_saveexec_b64 s[18:19], s[2:3]
	s_cbranch_execz .LBB0_557
	s_waitcnt lgkmcnt(0)
	v_add_f32_e32 v116, v114, v115
	v_lshlrev_b64 v[114:115], 6, v[170:171]
	v_lshl_add_u64 v[114:115], s[74:75], 0, v[114:115]
	v_lshl_add_u64 v[114:115], s[14:15], 2, v[114:115]
	s_lshl_b32 s10, s38, 2
	v_lshl_add_u64 v[114:115], v[114:115], 0, s[10:11]
	global_store_dword v[114:115], v116, off
.LBB0_557:
	s_or_b64 exec, exec, s[18:19]
	v_lshlrev_b32_e32 v114, 16, v148
	s_waitcnt lgkmcnt(0)
	v_and_b32_e32 v115, 0xffff0000, v148
	v_lshlrev_b32_e32 v116, 16, v149
	v_and_b32_e32 v117, 0xffff0000, v149
	v_lshlrev_b32_e32 v118, 16, v150
	v_and_b32_e32 v119, 0xffff0000, v150
	v_lshlrev_b32_e32 v120, 16, v151
	v_and_b32_e32 v121, 0xffff0000, v151
	v_pk_add_f32 v[110:111], v[110:111], v[116:117]
	v_pk_add_f32 v[108:109], v[108:109], v[114:115]
	v_pk_add_f32 v[114:115], v[106:107], v[120:121]
	v_pk_add_f32 v[106:107], v[104:105], v[118:119]
	v_mul_f32_e32 v104, v109, v109
	v_mul_f32_e32 v105, v111, v111
	v_fmac_f32_e32 v104, v108, v108
	v_fmac_f32_e32 v105, v110, v110
	v_add_f32_e32 v104, v104, v105
	v_mul_f32_e32 v105, v107, v107
	v_mul_f32_e32 v116, v115, v115
	v_fmac_f32_e32 v105, v106, v106
	v_fmac_f32_e32 v116, v114, v114
	v_add_f32_e32 v105, v105, v116
	v_add_f32_e32 v118, v104, v105
	v_cvt_pk_bf16_f32 v104, v108, v109
	v_cvt_pk_bf16_f32 v105, v110, v111
	v_lshlrev_b32_e32 v108, 16, v144
	v_and_b32_e32 v109, 0xffff0000, v144
	v_lshlrev_b32_e32 v110, 16, v145
	v_and_b32_e32 v111, 0xffff0000, v145
	v_cvt_pk_bf16_f32 v106, v106, v107
	v_cvt_pk_bf16_f32 v107, v114, v115
	v_lshlrev_b32_e32 v114, 16, v146
	v_and_b32_e32 v115, 0xffff0000, v146
	v_pk_add_f32 v[102:103], v[102:103], v[110:111]
	v_pk_add_f32 v[100:101], v[100:101], v[108:109]
	v_lshlrev_b32_e32 v116, 16, v147
	v_and_b32_e32 v117, 0xffff0000, v147
	v_pk_add_f32 v[110:111], v[96:97], v[114:115]
	v_mul_f32_e32 v96, v101, v101
	v_mul_f32_e32 v97, v103, v103
	v_pk_add_f32 v[108:109], v[98:99], v[116:117]
	v_fmac_f32_e32 v96, v100, v100
	v_fmac_f32_e32 v97, v102, v102
	v_add_f32_e32 v96, v96, v97
	v_mul_f32_e32 v97, v111, v111
	v_mul_f32_e32 v98, v109, v109
	v_fmac_f32_e32 v97, v110, v110
	v_fmac_f32_e32 v98, v108, v108
	v_add_f32_e32 v97, v97, v98
	v_add_f32_e32 v96, v96, v97
	v_add_f32_e32 v99, v118, v96
	ds_bpermute_b32 v116, v112, v99
	v_lshl_add_u64 v[96:97], s[64:65], 0, v[184:185]
	v_lshl_add_u64 v[114:115], v[168:169], 1, v[96:97]
	global_store_dwordx4 v[114:115], v[104:107], off sc1
	v_cvt_pk_bf16_f32 v98, v100, v101
	s_waitcnt lgkmcnt(0)
	v_add_f32_e32 v96, v99, v116
	ds_bpermute_b32 v97, v113, v96
	v_cvt_pk_bf16_f32 v99, v102, v103
	v_cvt_pk_bf16_f32 v100, v110, v111
	v_cvt_pk_bf16_f32 v101, v108, v109
	global_store_dwordx4 v[114:115], v[98:101], off offset:256 sc1
	s_and_saveexec_b64 s[18:19], s[2:3]
	s_cbranch_execz .LBB0_559
	s_waitcnt lgkmcnt(0)
	v_add_f32_e32 v98, v96, v97
	v_lshlrev_b64 v[96:97], 6, v[182:183]
	v_lshl_add_u64 v[96:97], s[74:75], 0, v[96:97]
	v_lshl_add_u64 v[96:97], s[14:15], 2, v[96:97]
	s_lshl_b32 s10, s38, 2
	v_lshl_add_u64 v[96:97], v[96:97], 0, s[10:11]
	global_store_dword v[96:97], v98, off
.LBB0_559:
	s_or_b64 exec, exec, s[18:19]
	v_lshlrev_b32_e32 v96, 16, v140
	s_waitcnt lgkmcnt(0)
	v_and_b32_e32 v97, 0xffff0000, v140
	v_lshlrev_b32_e32 v98, 16, v141
	v_and_b32_e32 v99, 0xffff0000, v141
	v_lshlrev_b32_e32 v100, 16, v142
	v_and_b32_e32 v101, 0xffff0000, v142
	v_lshlrev_b32_e32 v102, 16, v143
	v_and_b32_e32 v103, 0xffff0000, v143
	v_pk_add_f32 v[94:95], v[94:95], v[98:99]
	v_pk_add_f32 v[92:93], v[92:93], v[96:97]
	v_pk_add_f32 v[96:97], v[90:91], v[102:103]
	v_pk_add_f32 v[90:91], v[88:89], v[100:101]
	v_mul_f32_e32 v88, v93, v93
	v_mul_f32_e32 v89, v95, v95
	v_fmac_f32_e32 v88, v92, v92
	v_fmac_f32_e32 v89, v94, v94
	v_add_f32_e32 v88, v88, v89
	v_mul_f32_e32 v89, v91, v91
	v_mul_f32_e32 v98, v97, v97
	v_fmac_f32_e32 v89, v90, v90
	v_fmac_f32_e32 v98, v96, v96
	v_add_f32_e32 v89, v89, v98
	v_add_f32_e32 v100, v88, v89
	v_cvt_pk_bf16_f32 v88, v92, v93
	v_cvt_pk_bf16_f32 v89, v94, v95
	v_lshlrev_b32_e32 v92, 16, v136
	v_and_b32_e32 v93, 0xffff0000, v136
	v_lshlrev_b32_e32 v94, 16, v137
	v_and_b32_e32 v95, 0xffff0000, v137
	v_cvt_pk_bf16_f32 v90, v90, v91
	v_cvt_pk_bf16_f32 v91, v96, v97
	v_lshlrev_b32_e32 v96, 16, v138
	v_and_b32_e32 v97, 0xffff0000, v138
	v_pk_add_f32 v[86:87], v[86:87], v[94:95]
	v_pk_add_f32 v[84:85], v[84:85], v[92:93]
	v_lshlrev_b32_e32 v98, 16, v139
	v_and_b32_e32 v99, 0xffff0000, v139
	v_pk_add_f32 v[94:95], v[80:81], v[96:97]
	v_mul_f32_e32 v80, v85, v85
	v_mul_f32_e32 v81, v87, v87
	v_pk_add_f32 v[92:93], v[82:83], v[98:99]
	v_fmac_f32_e32 v80, v84, v84
	v_fmac_f32_e32 v81, v86, v86
	v_add_f32_e32 v80, v80, v81
	v_mul_f32_e32 v81, v95, v95
	v_mul_f32_e32 v82, v93, v93
	v_fmac_f32_e32 v81, v94, v94
	v_fmac_f32_e32 v82, v92, v92
	v_add_f32_e32 v81, v81, v82
	v_add_f32_e32 v80, v80, v81
	v_add_f32_e32 v83, v100, v80
	ds_bpermute_b32 v98, v112, v83
	v_lshl_add_u64 v[80:81], s[64:65], 0, v[180:181]
	v_lshl_add_u64 v[96:97], v[168:169], 1, v[80:81]
	global_store_dwordx4 v[96:97], v[88:91], off sc1
	v_cvt_pk_bf16_f32 v82, v84, v85
	s_waitcnt lgkmcnt(0)
	v_add_f32_e32 v80, v83, v98
	ds_bpermute_b32 v81, v113, v80
	v_cvt_pk_bf16_f32 v83, v86, v87
	v_cvt_pk_bf16_f32 v84, v94, v95
	v_cvt_pk_bf16_f32 v85, v92, v93
	global_store_dwordx4 v[96:97], v[82:85], off offset:256 sc1
	s_and_saveexec_b64 s[18:19], s[2:3]
	s_cbranch_execz .LBB0_561
	s_waitcnt lgkmcnt(0)
	v_add_f32_e32 v82, v80, v81
	v_lshlrev_b64 v[80:81], 6, v[178:179]
	v_lshl_add_u64 v[80:81], s[74:75], 0, v[80:81]
	v_lshl_add_u64 v[80:81], s[14:15], 2, v[80:81]
	s_lshl_b32 s10, s38, 2
	v_lshl_add_u64 v[80:81], v[80:81], 0, s[10:11]
	global_store_dword v[80:81], v82, off
.LBB0_561:
	s_or_b64 exec, exec, s[18:19]
	v_lshlrev_b32_e32 v80, 16, v132
	s_waitcnt lgkmcnt(0)
	v_and_b32_e32 v81, 0xffff0000, v132
	v_lshlrev_b32_e32 v82, 16, v133
	v_and_b32_e32 v83, 0xffff0000, v133
	v_lshlrev_b32_e32 v84, 16, v134
	v_and_b32_e32 v85, 0xffff0000, v134
	v_lshlrev_b32_e32 v86, 16, v135
	v_and_b32_e32 v87, 0xffff0000, v135
	v_pk_add_f32 v[78:79], v[78:79], v[82:83]
	v_pk_add_f32 v[76:77], v[76:77], v[80:81]
	v_pk_add_f32 v[80:81], v[74:75], v[86:87]
	v_pk_add_f32 v[74:75], v[72:73], v[84:85]
	v_mul_f32_e32 v72, v77, v77
	v_mul_f32_e32 v73, v79, v79
	v_fmac_f32_e32 v72, v76, v76
	v_fmac_f32_e32 v73, v78, v78
	v_add_f32_e32 v72, v72, v73
	v_mul_f32_e32 v73, v75, v75
	v_mul_f32_e32 v82, v81, v81
	v_fmac_f32_e32 v73, v74, v74
	v_fmac_f32_e32 v82, v80, v80
	v_add_f32_e32 v73, v73, v82
	v_add_f32_e32 v84, v72, v73
	v_cvt_pk_bf16_f32 v72, v76, v77
	v_cvt_pk_bf16_f32 v73, v78, v79
	v_lshlrev_b32_e32 v76, 16, v128
	v_and_b32_e32 v77, 0xffff0000, v128
	v_lshlrev_b32_e32 v78, 16, v129
	v_and_b32_e32 v79, 0xffff0000, v129
	v_cvt_pk_bf16_f32 v74, v74, v75
	v_cvt_pk_bf16_f32 v75, v80, v81
	v_lshlrev_b32_e32 v80, 16, v130
	v_and_b32_e32 v81, 0xffff0000, v130
	v_pk_add_f32 v[70:71], v[70:71], v[78:79]
	v_pk_add_f32 v[68:69], v[68:69], v[76:77]
	v_lshlrev_b32_e32 v82, 16, v131
	v_and_b32_e32 v83, 0xffff0000, v131
	v_pk_add_f32 v[78:79], v[64:65], v[80:81]
	v_mul_f32_e32 v64, v69, v69
	v_mul_f32_e32 v65, v71, v71
	v_pk_add_f32 v[76:77], v[66:67], v[82:83]
	v_fmac_f32_e32 v64, v68, v68
	v_fmac_f32_e32 v65, v70, v70
	v_add_f32_e32 v64, v64, v65
	v_mul_f32_e32 v65, v79, v79
	v_mul_f32_e32 v66, v77, v77
	v_fmac_f32_e32 v65, v78, v78
	v_fmac_f32_e32 v66, v76, v76
	v_add_f32_e32 v65, v65, v66
	v_add_f32_e32 v64, v64, v65
	v_add_f32_e32 v67, v84, v64
	ds_bpermute_b32 v82, v112, v67
	v_lshl_add_u64 v[64:65], s[64:65], 0, v[176:177]
	v_lshl_add_u64 v[80:81], v[168:169], 1, v[64:65]
	global_store_dwordx4 v[80:81], v[72:75], off sc1
	v_cvt_pk_bf16_f32 v66, v68, v69
	s_waitcnt lgkmcnt(0)
	v_add_f32_e32 v64, v67, v82
	ds_bpermute_b32 v65, v113, v64
	v_cvt_pk_bf16_f32 v67, v70, v71
	v_cvt_pk_bf16_f32 v68, v78, v79
	v_cvt_pk_bf16_f32 v69, v76, v77
	global_store_dwordx4 v[80:81], v[66:69], off offset:256 sc1
	s_and_saveexec_b64 s[18:19], s[2:3]
	s_cbranch_execz .LBB0_563
	s_waitcnt lgkmcnt(0)
	v_add_f32_e32 v66, v64, v65
	v_lshlrev_b64 v[64:65], 6, v[174:175]
	v_lshl_add_u64 v[64:65], s[74:75], 0, v[64:65]
	v_lshl_add_u64 v[64:65], s[14:15], 2, v[64:65]
	s_lshl_b32 s10, s38, 2
	v_lshl_add_u64 v[64:65], v[64:65], 0, s[10:11]
	global_store_dword v[64:65], v66, off
.LBB0_563:
	s_or_b64 exec, exec, s[18:19]
	v_add_u32_e32 v100, 0x80, v170
	v_ashrrev_i32_e32 v101, 31, v100
	v_add_u32_e32 v96, 0x90, v170
	v_lshlrev_b64 v[110:111], 11, v[100:101]
	v_ashrrev_i32_e32 v97, 31, v96
	v_add_u32_e32 v92, 0xa0, v170
	s_waitcnt lgkmcnt(0)
	v_lshl_add_u64 v[64:65], v[172:173], 0, v[110:111]
	v_lshlrev_b64 v[98:99], 11, v[96:97]
	v_ashrrev_i32_e32 v93, 31, v92
	v_add_u32_e32 v88, 0xb0, v170
	v_lshl_add_u64 v[64:65], v[172:173], 0, v[98:99]
	v_lshlrev_b64 v[94:95], 11, v[92:93]
	v_ashrrev_i32_e32 v89, 31, v88
	v_lshl_add_u64 v[64:65], v[172:173], 0, v[94:95]
	v_lshlrev_b64 v[90:91], 11, v[88:89]
	v_lshl_add_u64 v[64:65], v[172:173], 0, v[90:91]
	global_load_dwordx4 v[68:71], v[64:65], off
	s_nop 0
	global_load_dwordx4 v[64:67], v[64:65], off offset:256
	s_waitcnt vmcnt(15)
	v_lshlrev_b32_e32 v114, 16, v236
	v_and_b32_e32 v115, 0xffff0000, v236
	v_lshlrev_b32_e32 v236, 16, v237
	v_and_b32_e32 v237, 0xffff0000, v237
	v_lshlrev_b32_e32 v116, 16, v238
	v_and_b32_e32 v117, 0xffff0000, v238
	v_lshlrev_b32_e32 v238, 16, v239
	v_and_b32_e32 v239, 0xffff0000, v239
	v_pk_add_f32 v[62:63], v[62:63], v[236:237]
	v_pk_add_f32 v[60:61], v[60:61], v[114:115]
	v_pk_add_f32 v[236:237], v[58:59], v[238:239]
	v_pk_add_f32 v[58:59], v[56:57], v[116:117]
	v_mul_f32_e32 v56, v61, v61
	v_mul_f32_e32 v57, v63, v63
	v_fmac_f32_e32 v56, v60, v60
	v_fmac_f32_e32 v57, v62, v62
	v_add_f32_e32 v56, v56, v57
	v_mul_f32_e32 v57, v59, v59
	v_mul_f32_e32 v238, v237, v237
	v_fmac_f32_e32 v57, v58, v58
	v_fmac_f32_e32 v238, v236, v236
	v_add_f32_e32 v57, v57, v238
	v_add_f32_e32 v114, v56, v57
	v_cvt_pk_bf16_f32 v56, v60, v61
	v_cvt_pk_bf16_f32 v57, v62, v63
	s_waitcnt vmcnt(14)
	v_lshlrev_b32_e32 v60, 16, v240
	v_and_b32_e32 v61, 0xffff0000, v240
	v_lshlrev_b32_e32 v62, 16, v241
	v_and_b32_e32 v63, 0xffff0000, v241
	v_cvt_pk_bf16_f32 v58, v58, v59
	v_cvt_pk_bf16_f32 v59, v236, v237
	v_lshlrev_b32_e32 v236, 16, v242
	v_and_b32_e32 v237, 0xffff0000, v242
	v_pk_add_f32 v[54:55], v[54:55], v[62:63]
	v_pk_add_f32 v[52:53], v[52:53], v[60:61]
	v_lshlrev_b32_e32 v238, 16, v243
	v_and_b32_e32 v239, 0xffff0000, v243
	v_pk_add_f32 v[62:63], v[48:49], v[236:237]
	v_mul_f32_e32 v48, v53, v53
	v_mul_f32_e32 v49, v55, v55
	v_pk_add_f32 v[60:61], v[50:51], v[238:239]
	v_fmac_f32_e32 v48, v52, v52
	v_fmac_f32_e32 v49, v54, v54
	v_add_f32_e32 v48, v48, v49
	v_mul_f32_e32 v49, v63, v63
	v_mul_f32_e32 v50, v61, v61
	v_fmac_f32_e32 v49, v62, v62
	v_fmac_f32_e32 v50, v60, v60
	v_add_f32_e32 v49, v49, v50
	v_add_f32_e32 v48, v48, v49
	v_add_f32_e32 v51, v114, v48
	ds_bpermute_b32 v238, v112, v51
	v_lshl_add_u64 v[48:49], s[64:65], 0, v[110:111]
	v_lshl_add_u64 v[236:237], v[168:169], 1, v[48:49]
	global_store_dwordx4 v[236:237], v[56:59], off sc1
	v_cvt_pk_bf16_f32 v50, v52, v53
	s_waitcnt lgkmcnt(0)
	v_add_f32_e32 v48, v51, v238
	ds_bpermute_b32 v49, v113, v48
	v_cvt_pk_bf16_f32 v51, v54, v55
	v_cvt_pk_bf16_f32 v52, v62, v63
	v_cvt_pk_bf16_f32 v53, v60, v61
	global_store_dwordx4 v[236:237], v[50:53], off offset:256 sc1
	s_and_saveexec_b64 s[18:19], s[2:3]
	s_cbranch_execz .LBB0_565
	s_waitcnt lgkmcnt(0)
	v_add_f32_e32 v50, v48, v49
	v_lshlrev_b64 v[48:49], 6, v[100:101]
	v_lshl_add_u64 v[48:49], s[74:75], 0, v[48:49]
	v_lshl_add_u64 v[48:49], s[14:15], 2, v[48:49]
	s_lshl_b32 s10, s38, 2
	v_lshl_add_u64 v[48:49], v[48:49], 0, s[10:11]
	global_store_dword v[48:49], v50, off
.LBB0_565:
	s_or_b64 exec, exec, s[18:19]
	s_waitcnt vmcnt(15)
	v_lshlrev_b32_e32 v48, 16, v244
	s_waitcnt lgkmcnt(0)
	v_and_b32_e32 v49, 0xffff0000, v244
	v_lshlrev_b32_e32 v50, 16, v245
	v_and_b32_e32 v51, 0xffff0000, v245
	v_lshlrev_b32_e32 v52, 16, v246
	v_and_b32_e32 v53, 0xffff0000, v246
	v_lshlrev_b32_e32 v54, 16, v247
	v_and_b32_e32 v55, 0xffff0000, v247
	v_pk_add_f32 v[46:47], v[46:47], v[50:51]
	v_pk_add_f32 v[44:45], v[44:45], v[48:49]
	v_pk_add_f32 v[48:49], v[42:43], v[54:55]
	v_pk_add_f32 v[42:43], v[40:41], v[52:53]
	v_mul_f32_e32 v40, v45, v45
	v_mul_f32_e32 v41, v47, v47
	v_fmac_f32_e32 v40, v44, v44
	v_fmac_f32_e32 v41, v46, v46
	v_add_f32_e32 v40, v40, v41
	v_mul_f32_e32 v41, v43, v43
	v_mul_f32_e32 v50, v49, v49
	v_fmac_f32_e32 v41, v42, v42
	v_fmac_f32_e32 v50, v48, v48
	v_add_f32_e32 v41, v41, v50
	v_add_f32_e32 v52, v40, v41
	v_cvt_pk_bf16_f32 v40, v44, v45
	v_cvt_pk_bf16_f32 v41, v46, v47
	s_waitcnt vmcnt(14)
	v_lshlrev_b32_e32 v44, 16, v248
	v_and_b32_e32 v45, 0xffff0000, v248
	v_lshlrev_b32_e32 v46, 16, v249
	v_and_b32_e32 v47, 0xffff0000, v249
	v_cvt_pk_bf16_f32 v42, v42, v43
	v_cvt_pk_bf16_f32 v43, v48, v49
	v_lshlrev_b32_e32 v48, 16, v250
	v_and_b32_e32 v49, 0xffff0000, v250
	v_pk_add_f32 v[38:39], v[38:39], v[46:47]
	v_pk_add_f32 v[36:37], v[36:37], v[44:45]
	v_lshlrev_b32_e32 v50, 16, v251
	v_and_b32_e32 v51, 0xffff0000, v251
	v_pk_add_f32 v[46:47], v[32:33], v[48:49]
	v_mul_f32_e32 v32, v37, v37
	v_mul_f32_e32 v33, v39, v39
	v_pk_add_f32 v[44:45], v[34:35], v[50:51]
	v_fmac_f32_e32 v32, v36, v36
	v_fmac_f32_e32 v33, v38, v38
	v_add_f32_e32 v32, v32, v33
	v_mul_f32_e32 v33, v47, v47
	v_mul_f32_e32 v34, v45, v45
	v_fmac_f32_e32 v33, v46, v46
	v_fmac_f32_e32 v34, v44, v44
	v_add_f32_e32 v33, v33, v34
	v_add_f32_e32 v32, v32, v33
	v_add_f32_e32 v35, v52, v32
	ds_bpermute_b32 v50, v112, v35
	v_lshl_add_u64 v[32:33], s[64:65], 0, v[98:99]
	v_lshl_add_u64 v[48:49], v[168:169], 1, v[32:33]
	global_store_dwordx4 v[48:49], v[40:43], off sc1
	v_cvt_pk_bf16_f32 v34, v36, v37
	s_waitcnt lgkmcnt(0)
	v_add_f32_e32 v32, v35, v50
	ds_bpermute_b32 v33, v113, v32
	v_cvt_pk_bf16_f32 v35, v38, v39
	v_cvt_pk_bf16_f32 v36, v46, v47
	v_cvt_pk_bf16_f32 v37, v44, v45
	global_store_dwordx4 v[48:49], v[34:37], off offset:256 sc1
	s_and_saveexec_b64 s[18:19], s[2:3]
	s_cbranch_execz .LBB0_567
	s_waitcnt lgkmcnt(0)
	v_add_f32_e32 v34, v32, v33
	v_lshlrev_b64 v[32:33], 6, v[96:97]
	v_lshl_add_u64 v[32:33], s[74:75], 0, v[32:33]
	v_lshl_add_u64 v[32:33], s[14:15], 2, v[32:33]
	s_lshl_b32 s10, s38, 2
	v_lshl_add_u64 v[32:33], v[32:33], 0, s[10:11]
	global_store_dword v[32:33], v34, off
.LBB0_567:
	s_or_b64 exec, exec, s[18:19]
	s_waitcnt vmcnt(15)
	v_lshlrev_b32_e32 v32, 16, v210
	s_waitcnt lgkmcnt(0)
	v_and_b32_e32 v33, 0xffff0000, v210
	v_lshlrev_b32_e32 v34, 16, v211
	v_and_b32_e32 v35, 0xffff0000, v211
	v_lshlrev_b32_e32 v36, 16, v212
	v_and_b32_e32 v37, 0xffff0000, v212
	v_lshlrev_b32_e32 v38, 16, v213
	v_and_b32_e32 v39, 0xffff0000, v213
	v_pk_add_f32 v[30:31], v[30:31], v[34:35]
	v_pk_add_f32 v[28:29], v[28:29], v[32:33]
	v_pk_add_f32 v[32:33], v[26:27], v[38:39]
	v_pk_add_f32 v[26:27], v[24:25], v[36:37]
	v_mul_f32_e32 v24, v29, v29
	v_mul_f32_e32 v25, v31, v31
	v_fmac_f32_e32 v24, v28, v28
	v_fmac_f32_e32 v25, v30, v30
	v_add_f32_e32 v24, v24, v25
	v_mul_f32_e32 v25, v27, v27
	v_mul_f32_e32 v34, v33, v33
	v_fmac_f32_e32 v25, v26, v26
	v_fmac_f32_e32 v34, v32, v32
	v_add_f32_e32 v25, v25, v34
	v_add_f32_e32 v36, v24, v25
	v_cvt_pk_bf16_f32 v24, v28, v29
	v_cvt_pk_bf16_f32 v25, v30, v31
	s_waitcnt vmcnt(14)
	v_lshlrev_b32_e32 v28, 16, v214
	v_and_b32_e32 v29, 0xffff0000, v214
	v_lshlrev_b32_e32 v30, 16, v215
	v_and_b32_e32 v31, 0xffff0000, v215
	v_cvt_pk_bf16_f32 v26, v26, v27
	v_cvt_pk_bf16_f32 v27, v32, v33
	v_lshlrev_b32_e32 v32, 16, v216
	v_and_b32_e32 v33, 0xffff0000, v216
	v_pk_add_f32 v[22:23], v[22:23], v[30:31]
	v_pk_add_f32 v[20:21], v[20:21], v[28:29]
	v_lshlrev_b32_e32 v34, 16, v217
	v_and_b32_e32 v35, 0xffff0000, v217
	v_pk_add_f32 v[30:31], v[16:17], v[32:33]
	v_mul_f32_e32 v16, v21, v21
	v_mul_f32_e32 v17, v23, v23
	v_pk_add_f32 v[28:29], v[18:19], v[34:35]
	v_fmac_f32_e32 v16, v20, v20
	v_fmac_f32_e32 v17, v22, v22
	v_add_f32_e32 v16, v16, v17
	v_mul_f32_e32 v17, v31, v31
	v_mul_f32_e32 v18, v29, v29
	v_fmac_f32_e32 v17, v30, v30
	v_fmac_f32_e32 v18, v28, v28
	v_add_f32_e32 v17, v17, v18
	v_add_f32_e32 v16, v16, v17
	v_add_f32_e32 v19, v36, v16
	ds_bpermute_b32 v34, v112, v19
	v_lshl_add_u64 v[16:17], s[64:65], 0, v[94:95]
	v_lshl_add_u64 v[32:33], v[168:169], 1, v[16:17]
	global_store_dwordx4 v[32:33], v[24:27], off sc1
	v_cvt_pk_bf16_f32 v18, v20, v21
	s_waitcnt lgkmcnt(0)
	v_add_f32_e32 v16, v19, v34
	ds_bpermute_b32 v17, v113, v16
	v_cvt_pk_bf16_f32 v19, v22, v23
	v_cvt_pk_bf16_f32 v20, v30, v31
	v_cvt_pk_bf16_f32 v21, v28, v29
	global_store_dwordx4 v[32:33], v[18:21], off offset:256 sc1
	s_and_saveexec_b64 s[18:19], s[2:3]
	s_cbranch_execz .LBB0_569
	s_waitcnt lgkmcnt(0)
	v_add_f32_e32 v18, v16, v17
	v_lshlrev_b64 v[16:17], 6, v[92:93]
	v_lshl_add_u64 v[16:17], s[74:75], 0, v[16:17]
	v_lshl_add_u64 v[16:17], s[14:15], 2, v[16:17]
	s_lshl_b32 s10, s38, 2
	v_lshl_add_u64 v[16:17], v[16:17], 0, s[10:11]
	global_store_dword v[16:17], v18, off
.LBB0_569:
	s_or_b64 exec, exec, s[18:19]
	s_waitcnt vmcnt(7)
	v_lshlrev_b32_e32 v16, 16, v68
	s_waitcnt lgkmcnt(0)
	v_and_b32_e32 v17, 0xffff0000, v68
	v_lshlrev_b32_e32 v18, 16, v69
	v_and_b32_e32 v19, 0xffff0000, v69
	v_lshlrev_b32_e32 v20, 16, v70
	v_and_b32_e32 v21, 0xffff0000, v70
	v_lshlrev_b32_e32 v22, 16, v71
	v_and_b32_e32 v23, 0xffff0000, v71
	v_pk_add_f32 v[14:15], v[14:15], v[18:19]
	v_pk_add_f32 v[12:13], v[12:13], v[16:17]
	v_pk_add_f32 v[16:17], v[10:11], v[22:23]
	v_pk_add_f32 v[10:11], v[8:9], v[20:21]
	v_mul_f32_e32 v8, v13, v13
	v_mul_f32_e32 v9, v15, v15
	v_fmac_f32_e32 v8, v12, v12
	v_fmac_f32_e32 v9, v14, v14
	v_add_f32_e32 v8, v8, v9
	v_mul_f32_e32 v9, v11, v11
	v_mul_f32_e32 v18, v17, v17
	v_fmac_f32_e32 v9, v10, v10
	v_fmac_f32_e32 v18, v16, v16
	v_add_f32_e32 v9, v9, v18
	v_add_f32_e32 v20, v8, v9
	v_cvt_pk_bf16_f32 v8, v12, v13
	v_cvt_pk_bf16_f32 v9, v14, v15
	s_waitcnt vmcnt(6)
	v_lshlrev_b32_e32 v12, 16, v64
	v_and_b32_e32 v13, 0xffff0000, v64
	v_lshlrev_b32_e32 v14, 16, v65
	v_and_b32_e32 v15, 0xffff0000, v65
	v_cvt_pk_bf16_f32 v10, v10, v11
	v_cvt_pk_bf16_f32 v11, v16, v17
	v_lshlrev_b32_e32 v16, 16, v66
	v_and_b32_e32 v17, 0xffff0000, v66
	v_pk_add_f32 v[6:7], v[6:7], v[14:15]
	v_pk_add_f32 v[4:5], v[4:5], v[12:13]
	v_lshlrev_b32_e32 v18, 16, v67
	v_and_b32_e32 v19, 0xffff0000, v67
	v_pk_add_f32 v[14:15], v[0:1], v[16:17]
	v_mul_f32_e32 v0, v5, v5
	v_mul_f32_e32 v1, v7, v7
	v_pk_add_f32 v[12:13], v[2:3], v[18:19]
	v_fmac_f32_e32 v0, v4, v4
	v_fmac_f32_e32 v1, v6, v6
	v_add_f32_e32 v0, v0, v1
	v_mul_f32_e32 v1, v15, v15
	v_mul_f32_e32 v2, v13, v13
	v_fmac_f32_e32 v1, v14, v14
	v_fmac_f32_e32 v2, v12, v12
	v_add_f32_e32 v1, v1, v2
	v_add_f32_e32 v0, v0, v1
	v_add_f32_e32 v3, v20, v0
	ds_bpermute_b32 v18, v112, v3
	v_lshl_add_u64 v[0:1], s[64:65], 0, v[90:91]
	v_lshl_add_u64 v[16:17], v[168:169], 1, v[0:1]
	global_store_dwordx4 v[16:17], v[8:11], off sc1
	v_cvt_pk_bf16_f32 v2, v4, v5
	s_waitcnt lgkmcnt(0)
	v_add_f32_e32 v0, v3, v18
	ds_bpermute_b32 v1, v113, v0
	v_cvt_pk_bf16_f32 v3, v6, v7
	v_cvt_pk_bf16_f32 v4, v14, v15
	v_cvt_pk_bf16_f32 v5, v12, v13
	global_store_dwordx4 v[16:17], v[2:5], off offset:256 sc1
	s_and_saveexec_b64 s[18:19], s[2:3]
	s_cbranch_execz .LBB0_542
	s_waitcnt lgkmcnt(0)
	v_add_f32_e32 v2, v0, v1
	v_lshlrev_b64 v[0:1], 6, v[88:89]
	v_lshl_add_u64 v[0:1], s[74:75], 0, v[0:1]
	v_lshl_add_u64 v[0:1], s[14:15], 2, v[0:1]
	s_lshl_b32 s10, s38, 2
	v_lshl_add_u64 v[0:1], v[0:1], 0, s[10:11]
	global_store_dword v[0:1], v2, off
	s_branch .LBB0_542

.LBB0_645:
	s_lshl_b32 s8, s37, 12
	s_and_b32 s23, s8, 0x1000
	v_add_u32_e32 v138, s23, v176
	v_add_u32_e32 v138, 0xc00, v138
	s_cmp_gt_i32 s14, 5
	v_lshl_add_u32 v162, s36, 8, v174
	ds_read2_b32 v[168:169], v138 offset1:16
	ds_read2_b32 v[166:167], v138 offset0:32 offset1:48
	ds_read2_b32 v[164:165], v138 offset0:128 offset1:144
	ds_read2_b32 v[160:161], v138 offset0:160 offset1:176
	s_cselect_b64 s[42:43], -1, 0
	s_cmp_lt_u32 s14, 10
	s_cselect_b64 s[36:37], -1, 0
	s_cmp_gt_u32 s14, 9
	v_ashrrev_i32_e32 v163, 31, v162
	s_cselect_b64 s[40:41], -1, 0
	s_lshl_b32 s14, s14, 8
	v_lshlrev_b64 v[170:171], 11, v[162:163]
	s_waitcnt lgkmcnt(0)
	v_pk_mul_f32 v[134:135], v[134:135], v[168:169] op_sel_hi:[1,0]
	v_pk_mul_f32 v[132:133], v[132:133], v[168:169] op_sel_hi:[1,0]
	v_pk_mul_f32 v[130:131], v[130:131], v[168:169] op_sel_hi:[1,0]
	v_pk_mul_f32 v[128:129], v[128:129], v[168:169] op_sel_hi:[1,0]
	s_mov_b64 s[8:9], -1
	s_and_b64 vcc, exec, s[42:43]
	s_cbranch_vccz .LBB0_653
	s_and_b64 vcc, exec, s[40:41]
	s_cbranch_vccz .LBB0_650
	s_and_saveexec_b64 s[8:9], s[4:5]
	s_cbranch_execz .LBB0_649
	v_mul_f32_e32 v163, 0xbfb8aa3b, v134
	v_exp_f32_e32 v182, v163
	v_mul_f32_e32 v163, 0xbfb8aa3b, v135
	v_exp_f32_e32 v183, v163
	v_mul_f32_e32 v138, 0xbfb8aa3b, v132
	v_exp_f32_e32 v172, v138
	v_mul_f32_e32 v138, 0xbfb8aa3b, v128
	v_exp_f32_e32 v186, v138
	v_mul_f32_e32 v138, 0xbfb8aa3b, v133
	v_exp_f32_e32 v173, v138
	v_mul_f32_e32 v138, 0xbfb8aa3b, v129
	v_pk_add_f32 v[182:183], v[182:183], 1.0 op_sel_hi:[1,0]
	v_exp_f32_e32 v187, v138
	v_div_scale_f32 v138, s[38:39], v183, v183, 1.0
	v_rcp_f32_e32 v163, v138
	v_mul_f32_e32 v184, 0xbfb8aa3b, v130
	v_exp_f32_e32 v190, v184
	v_pk_add_f32 v[172:173], v[172:173], 1.0 op_sel_hi:[1,0]
	v_fma_f32 v184, -v138, v163, 1.0
	v_fmac_f32_e32 v163, v184, v163
	v_div_scale_f32 v184, vcc, 1.0, v183, 1.0
	v_mul_f32_e32 v185, v184, v163
	v_fma_f32 v189, -v138, v185, v184
	v_fmac_f32_e32 v185, v189, v163
	v_fma_f32 v138, -v138, v185, v184
	v_div_scale_f32 v184, s[38:39], v182, v182, 1.0
	v_rcp_f32_e32 v189, v184
	v_div_fmas_f32 v138, v138, v163, v185
	v_div_fixup_f32 v185, v138, v183, 1.0
	v_fma_f32 v138, -v184, v189, 1.0
	v_fmac_f32_e32 v189, v138, v189
	v_div_scale_f32 v138, vcc, 1.0, v182, 1.0
	v_mul_f32_e32 v163, v138, v189
	v_fma_f32 v183, -v184, v163, v138
	v_fmac_f32_e32 v163, v183, v189
	v_div_scale_f32 v183, s[38:39], v173, v173, 1.0
	v_rcp_f32_e32 v191, v183
	v_fma_f32 v138, -v184, v163, v138
	v_div_fmas_f32 v138, v138, v189, v163
	v_div_fixup_f32 v184, v138, v182, 1.0
	v_fma_f32 v138, -v183, v191, 1.0
	v_fmac_f32_e32 v191, v138, v191
	v_div_scale_f32 v138, vcc, 1.0, v173, 1.0
	v_mul_f32_e32 v163, v138, v191
	v_fma_f32 v182, -v183, v163, v138
	v_fmac_f32_e32 v163, v182, v191
	v_fma_f32 v138, -v183, v163, v138
	v_div_scale_f32 v182, s[38:39], v172, v172, 1.0
	v_div_fmas_f32 v138, v138, v191, v163
	v_rcp_f32_e32 v189, v182
	v_div_fixup_f32 v183, v138, v173, 1.0
	v_mul_f32_e32 v173, 0xbfb8aa3b, v131
	v_exp_f32_e32 v191, v173
	v_fma_f32 v138, -v182, v189, 1.0
	v_fmac_f32_e32 v189, v138, v189
	v_div_scale_f32 v138, vcc, 1.0, v172, 1.0
	v_pk_add_f32 v[190:191], v[190:191], 1.0 op_sel_hi:[1,0]
	v_mul_f32_e32 v163, v138, v189
	v_div_scale_f32 v192, s[38:39], v191, v191, 1.0
	v_fma_f32 v173, -v182, v163, v138
	v_rcp_f32_e32 v193, v192
	v_fmac_f32_e32 v163, v173, v189
	v_fma_f32 v138, -v182, v163, v138
	v_div_fmas_f32 v138, v138, v189, v163
	v_div_fixup_f32 v182, v138, v172, 1.0
	v_fma_f32 v138, -v192, v193, 1.0
	v_fmac_f32_e32 v193, v138, v193
	v_div_scale_f32 v138, vcc, 1.0, v191, 1.0
	v_mul_f32_e32 v163, v138, v193
	v_pk_add_f32 v[172:173], v[186:187], 1.0 op_sel_hi:[1,0]
	v_fma_f32 v186, -v192, v163, v138
	v_fmac_f32_e32 v163, v186, v193
	v_div_scale_f32 v186, s[38:39], v190, v190, 1.0
	v_rcp_f32_e32 v187, v186
	v_fma_f32 v138, -v192, v163, v138
	v_div_fmas_f32 v138, v138, v193, v163
	v_div_fixup_f32 v193, v138, v191, 1.0
	v_fma_f32 v138, -v186, v187, 1.0
	v_fmac_f32_e32 v187, v138, v187
	v_div_scale_f32 v138, vcc, 1.0, v190, 1.0
	v_mul_f32_e32 v163, v138, v187
	v_fma_f32 v189, -v186, v163, v138
	v_fmac_f32_e32 v163, v189, v187
	v_fma_f32 v138, -v186, v163, v138
	v_div_scale_f32 v186, s[38:39], v173, v173, 1.0
	v_rcp_f32_e32 v189, v186
	v_div_fmas_f32 v138, v138, v187, v163
	v_div_fixup_f32 v192, v138, v190, 1.0
	v_fma_f32 v138, -v186, v189, 1.0
	v_fmac_f32_e32 v189, v138, v189
	v_div_scale_f32 v138, vcc, 1.0, v173, 1.0
	v_mul_f32_e32 v163, v138, v189
	v_fma_f32 v187, -v186, v163, v138
	v_fmac_f32_e32 v163, v187, v189
	v_fma_f32 v138, -v186, v163, v138
	v_div_scale_f32 v186, s[38:39], v172, v172, 1.0
	v_rcp_f32_e32 v187, v186
	v_div_fmas_f32 v138, v138, v189, v163
	v_div_fixup_f32 v191, v138, v173, 1.0
	v_fma_f32 v138, -v186, v187, 1.0
	v_fmac_f32_e32 v187, v138, v187
	v_div_scale_f32 v138, vcc, 1.0, v172, 1.0
	v_mul_f32_e32 v163, v138, v187
	v_fma_f32 v173, -v186, v163, v138
	v_fmac_f32_e32 v163, v173, v187
	v_fma_f32 v138, -v186, v163, v138
	v_div_fmas_f32 v138, v138, v187, v163
	v_div_fixup_f32 v190, v138, v172, 1.0
	v_mad_i64_i32 v[172:173], s[38:39], v162, s53, v[150:151]
	global_store_dwordx4 v[172:173], v[182:185], off sc1
	global_store_dwordx4 v[172:173], v[190:193], off offset:16 sc1

.LBB0_650:
	s_andn2_b64 vcc, exec, s[8:9]
	s_cbranch_vccnz .LBB0_652
	v_pk_mul_f32 v[172:173], v[134:135], s[18:19] op_sel_hi:[1,0]
	v_pk_mul_f32 v[182:183], v[132:133], s[18:19] op_sel_hi:[1,0]
	v_lshlrev_b32_e32 v138, 1, v146
	v_cvt_pk_bf16_f32 v182, v182, v183
	v_cvt_pk_bf16_f32 v183, v172, v173
	v_lshl_add_u64 v[172:173], s[10:11], 0, v[170:171]
	v_lshl_add_u64 v[172:173], s[14:15], 1, v[172:173]
	v_pk_mul_f32 v[184:185], v[128:129], s[18:19] op_sel_hi:[1,0]
	v_lshl_add_u64 v[172:173], v[172:173], 0, v[138:139]
	v_pk_mul_f32 v[186:187], v[130:131], s[18:19] op_sel_hi:[1,0]
	v_cvt_pk_bf16_f32 v184, v184, v185
	s_nop 0
	v_cvt_pk_bf16_f32 v185, v186, v187
	global_store_dwordx4 v[172:173], v[182:185], off offset:-3072 sc1

.LBB0_653:
	s_ashr_i32 s39, s14, 31
	s_mov_b32 s38, s14
	s_andn2_b64 vcc, exec, s[8:9]
	v_mad_i64_i32 v[172:173], s[8:9], v162, s61, 0
	s_cbranch_vccnz .LBB0_655
	v_cvt_pk_bf16_f32 v132, v132, v133
	v_cvt_pk_bf16_f32 v133, v134, v135
	v_cvt_pk_bf16_f32 v134, v128, v129
	v_lshl_add_u64 v[128:129], s[24:25], 0, v[172:173]
	v_lshl_add_u64 v[128:129], s[38:39], 1, v[128:129]
	v_lshlrev_b32_e32 v138, 1, v146
	v_lshl_add_u64 v[128:129], v[128:129], 0, v[138:139]
	v_cvt_pk_bf16_f32 v135, v130, v131
	global_store_dwordx4 v[128:129], v[132:135], off sc1

.LBB0_662:
	v_lshlrev_b32_e32 v138, 1, v146
	v_lshl_add_u64 v[124:125], v[132:133], 0, v[138:139]
	global_store_dwordx4 v[124:125], v[120:123], off offset:256 sc1
.LBB0_663:
	s_nop 1
	v_or_b32_e32 v122, 16, v162
	v_ashrrev_i32_e32 v123, 31, v122
	v_mov_b32_e32 v124, v169
	v_lshlrev_b64 v[120:121], 11, v[122:123]
	v_pk_mul_f32 v[118:119], v[118:119], v[124:125] op_sel_hi:[1,0]
	v_pk_mul_f32 v[116:117], v[116:117], v[124:125] op_sel_hi:[1,0]
	v_pk_mul_f32 v[114:115], v[114:115], v[124:125] op_sel_hi:[1,0]
	v_pk_mul_f32 v[112:113], v[112:113], v[124:125] op_sel_hi:[1,0]
	s_and_b64 vcc, exec, s[8:9]
	s_mov_b64 s[42:43], -1
	s_cbranch_vccnz .LBB0_671
	s_andn2_b64 vcc, exec, s[40:41]
	s_cbranch_vccnz .LBB0_668
	s_and_saveexec_b64 s[42:43], s[4:5]
	s_cbranch_execz .LBB0_667
	v_mul_f32_e32 v125, 0xbfb8aa3b, v118
	v_exp_f32_e32 v126, v125
	v_mul_f32_e32 v125, 0xbfb8aa3b, v119
	v_exp_f32_e32 v127, v125
	v_mul_f32_e32 v123, 0xbfb8aa3b, v116
	v_exp_f32_e32 v124, v123
	v_mul_f32_e32 v123, 0xbfb8aa3b, v112
	v_exp_f32_e32 v128, v123
	v_mul_f32_e32 v123, 0xbfb8aa3b, v117
	v_exp_f32_e32 v125, v123
	v_mul_f32_e32 v123, 0xbfb8aa3b, v113
	v_pk_add_f32 v[126:127], v[126:127], 1.0 op_sel_hi:[1,0]
	v_exp_f32_e32 v129, v123
	v_div_scale_f32 v123, s[44:45], v127, v127, 1.0
	v_rcp_f32_e32 v131, v123
	v_pk_add_f32 v[124:125], v[124:125], 1.0 op_sel_hi:[1,0]
	v_mul_f32_e32 v130, 0xbfb8aa3b, v114
	v_exp_f32_e32 v130, v130
	v_fma_f32 v132, -v123, v131, 1.0
	v_fmac_f32_e32 v131, v132, v131
	v_div_scale_f32 v132, vcc, 1.0, v127, 1.0
	v_mul_f32_e32 v133, v132, v131
	v_fma_f32 v134, -v123, v133, v132
	v_fmac_f32_e32 v133, v134, v131
	v_fma_f32 v123, -v123, v133, v132
	v_div_scale_f32 v132, s[44:45], v126, v126, 1.0
	v_rcp_f32_e32 v134, v132
	v_div_fmas_f32 v123, v123, v131, v133
	v_div_fixup_f32 v127, v123, v127, 1.0
	v_pk_add_f32 v[128:129], v[128:129], 1.0 op_sel_hi:[1,0]
	v_fma_f32 v123, -v132, v134, 1.0
	v_fmac_f32_e32 v134, v123, v134
	v_div_scale_f32 v123, vcc, 1.0, v126, 1.0
	v_mul_f32_e32 v131, v123, v134
	v_fma_f32 v133, -v132, v131, v123
	v_fmac_f32_e32 v131, v133, v134
	v_fma_f32 v123, -v132, v131, v123
	v_div_scale_f32 v132, s[44:45], v125, v125, 1.0
	v_rcp_f32_e32 v133, v132
	v_div_fmas_f32 v123, v123, v134, v131
	v_div_fixup_f32 v126, v123, v126, 1.0
	v_fma_f32 v123, -v132, v133, 1.0
	v_fmac_f32_e32 v133, v123, v133
	v_div_scale_f32 v123, vcc, 1.0, v125, 1.0
	v_mul_f32_e32 v131, v123, v133
	v_fma_f32 v134, -v132, v131, v123
	v_fmac_f32_e32 v131, v134, v133
	v_fma_f32 v123, -v132, v131, v123
	v_div_scale_f32 v132, s[44:45], v124, v124, 1.0
	v_rcp_f32_e32 v134, v132
	v_div_fmas_f32 v123, v123, v133, v131
	v_mul_f32_e32 v131, 0xbfb8aa3b, v115
	v_div_fixup_f32 v125, v123, v125, 1.0
	v_fma_f32 v123, -v132, v134, 1.0
	v_exp_f32_e32 v131, v131
	v_fmac_f32_e32 v134, v123, v134
	v_div_scale_f32 v123, vcc, 1.0, v124, 1.0
	v_mul_f32_e32 v133, v123, v134
	v_fma_f32 v135, -v132, v133, v123
	v_fmac_f32_e32 v133, v135, v134
	v_pk_add_f32 v[130:131], v[130:131], 1.0 op_sel_hi:[1,0]
	v_fma_f32 v123, -v132, v133, v123
	v_div_scale_f32 v132, s[44:45], v131, v131, 1.0
	v_rcp_f32_e32 v135, v132
	v_div_fmas_f32 v123, v123, v134, v133
	v_div_fixup_f32 v124, v123, v124, 1.0
	v_fma_f32 v123, -v132, v135, 1.0
	v_fmac_f32_e32 v135, v123, v135
	v_div_scale_f32 v123, vcc, 1.0, v131, 1.0
	v_mul_f32_e32 v133, v123, v135
	v_fma_f32 v134, -v132, v133, v123
	v_fmac_f32_e32 v133, v134, v135
	v_fma_f32 v123, -v132, v133, v123
	v_div_scale_f32 v132, s[44:45], v130, v130, 1.0
	v_rcp_f32_e32 v134, v132
	v_div_fmas_f32 v123, v123, v135, v133
	v_div_fixup_f32 v131, v123, v131, 1.0
	v_fma_f32 v123, -v132, v134, 1.0
	v_fmac_f32_e32 v134, v123, v134
	v_div_scale_f32 v123, vcc, 1.0, v130, 1.0
	v_mul_f32_e32 v133, v123, v134
	v_fma_f32 v135, -v132, v133, v123
	v_fmac_f32_e32 v133, v135, v134
	v_fma_f32 v123, -v132, v133, v123
	v_div_scale_f32 v132, s[44:45], v129, v129, 1.0
	v_rcp_f32_e32 v135, v132
	v_div_fmas_f32 v123, v123, v134, v133
	v_div_fixup_f32 v130, v123, v130, 1.0
	v_fma_f32 v123, -v132, v135, 1.0
	v_fmac_f32_e32 v135, v123, v135
	v_div_scale_f32 v123, vcc, 1.0, v129, 1.0
	v_mul_f32_e32 v133, v123, v135
	v_fma_f32 v134, -v132, v133, v123
	v_fmac_f32_e32 v133, v134, v135
	v_fma_f32 v123, -v132, v133, v123
	v_div_scale_f32 v132, s[44:45], v128, v128, 1.0
	v_rcp_f32_e32 v134, v132
	v_div_fmas_f32 v123, v123, v135, v133
	v_div_fixup_f32 v129, v123, v129, 1.0
	v_fma_f32 v123, -v132, v134, 1.0
	v_fmac_f32_e32 v134, v123, v134
	v_div_scale_f32 v123, vcc, 1.0, v128, 1.0
	v_mul_f32_e32 v133, v123, v134
	v_fma_f32 v135, -v132, v133, v123
	v_fmac_f32_e32 v133, v135, v134
	v_fma_f32 v123, -v132, v133, v123
	v_div_fmas_f32 v123, v123, v134, v133
	v_mad_i64_i32 v[132:133], s[44:45], v122, s53, v[150:151]
	v_div_fixup_f32 v128, v123, v128, 1.0
	global_store_dwordx4 v[132:133], v[124:127], off sc1
	global_store_dwordx4 v[132:133], v[128:131], off offset:16 sc1

.LBB0_668:
	s_andn2_b64 vcc, exec, s[42:43]
	s_cbranch_vccnz .LBB0_670
	v_pk_mul_f32 v[126:127], v[118:119], s[18:19] op_sel_hi:[1,0]
	v_pk_mul_f32 v[124:125], v[116:117], s[18:19] op_sel_hi:[1,0]
	v_pk_mul_f32 v[128:129], v[114:115], s[18:19] op_sel_hi:[1,0]
	v_pk_mul_f32 v[130:131], v[112:113], s[18:19] op_sel_hi:[1,0]
	v_cvt_pk_bf16_f32 v124, v124, v125
	v_cvt_pk_bf16_f32 v125, v126, v127
	v_lshlrev_b32_e32 v138, 1, v146
	v_cvt_pk_bf16_f32 v126, v130, v131
	v_cvt_pk_bf16_f32 v127, v128, v129
	v_lshl_add_u64 v[128:129], s[10:11], 0, v[120:121]
	v_lshl_add_u64 v[128:129], s[14:15], 1, v[128:129]
	v_lshl_add_u64 v[128:129], v[128:129], 0, v[138:139]
	global_store_dwordx4 v[128:129], v[124:127], off offset:-3072 sc1

.LBB0_671:
	s_andn2_b64 vcc, exec, s[42:43]
	v_mad_i64_i32 v[122:123], s[42:43], v122, s61, 0
	s_cbranch_vccnz .LBB0_673
	v_cvt_pk_bf16_f32 v116, v116, v117
	v_cvt_pk_bf16_f32 v117, v118, v119
	v_cvt_pk_bf16_f32 v118, v112, v113
	v_lshl_add_u64 v[112:113], s[24:25], 0, v[122:123]
	v_lshl_add_u64 v[112:113], s[38:39], 1, v[112:113]
	v_lshlrev_b32_e32 v138, 1, v146
	v_lshl_add_u64 v[112:113], v[112:113], 0, v[138:139]
	v_cvt_pk_bf16_f32 v119, v114, v115
	global_store_dwordx4 v[112:113], v[116:119], off sc1

.LBB0_679:
	s_andn2_b64 vcc, exec, s[44:45]
	s_cbranch_vccnz .LBB0_681
	v_lshlrev_b32_e32 v138, 1, v146
	v_lshl_add_u64 v[108:109], v[116:117], 0, v[138:139]
	global_store_dwordx4 v[108:109], v[104:107], off offset:256 sc1
.LBB0_681:
	s_nop 1
	v_or_b32_e32 v106, 32, v162
	v_ashrrev_i32_e32 v107, 31, v106
	v_lshlrev_b64 v[104:105], 11, v[106:107]
	v_pk_mul_f32 v[102:103], v[102:103], v[166:167] op_sel_hi:[1,0]
	v_pk_mul_f32 v[100:101], v[100:101], v[166:167] op_sel_hi:[1,0]
	v_pk_mul_f32 v[98:99], v[98:99], v[166:167] op_sel_hi:[1,0]
	v_pk_mul_f32 v[96:97], v[96:97], v[166:167] op_sel_hi:[1,0]
	s_and_b64 vcc, exec, s[8:9]
	s_mov_b64 s[42:43], -1
	s_cbranch_vccnz .LBB0_689
	s_andn2_b64 vcc, exec, s[40:41]
	s_cbranch_vccnz .LBB0_686
	s_and_saveexec_b64 s[42:43], s[4:5]
	s_cbranch_execz .LBB0_685
	v_mul_f32_e32 v109, 0xbfb8aa3b, v102
	v_exp_f32_e32 v110, v109
	v_mul_f32_e32 v109, 0xbfb8aa3b, v103
	v_exp_f32_e32 v111, v109
	v_mul_f32_e32 v107, 0xbfb8aa3b, v100
	v_exp_f32_e32 v108, v107
	v_mul_f32_e32 v107, 0xbfb8aa3b, v96
	v_exp_f32_e32 v112, v107
	v_mul_f32_e32 v107, 0xbfb8aa3b, v101
	v_exp_f32_e32 v109, v107
	v_mul_f32_e32 v107, 0xbfb8aa3b, v97
	v_pk_add_f32 v[110:111], v[110:111], 1.0 op_sel_hi:[1,0]
	v_exp_f32_e32 v113, v107
	v_div_scale_f32 v107, s[44:45], v111, v111, 1.0
	v_rcp_f32_e32 v115, v107
	v_pk_add_f32 v[108:109], v[108:109], 1.0 op_sel_hi:[1,0]
	v_mul_f32_e32 v114, 0xbfb8aa3b, v98
	v_exp_f32_e32 v114, v114
	v_fma_f32 v116, -v107, v115, 1.0
	v_fmac_f32_e32 v115, v116, v115
	v_div_scale_f32 v116, vcc, 1.0, v111, 1.0
	v_mul_f32_e32 v117, v116, v115
	v_fma_f32 v118, -v107, v117, v116
	v_fmac_f32_e32 v117, v118, v115
	v_fma_f32 v107, -v107, v117, v116
	v_div_scale_f32 v116, s[44:45], v110, v110, 1.0
	v_rcp_f32_e32 v118, v116
	v_div_fmas_f32 v107, v107, v115, v117
	v_div_fixup_f32 v111, v107, v111, 1.0
	v_pk_add_f32 v[112:113], v[112:113], 1.0 op_sel_hi:[1,0]
	v_fma_f32 v107, -v116, v118, 1.0
	v_fmac_f32_e32 v118, v107, v118
	v_div_scale_f32 v107, vcc, 1.0, v110, 1.0
	v_mul_f32_e32 v115, v107, v118
	v_fma_f32 v117, -v116, v115, v107
	v_fmac_f32_e32 v115, v117, v118
	v_fma_f32 v107, -v116, v115, v107
	v_div_scale_f32 v116, s[44:45], v109, v109, 1.0
	v_rcp_f32_e32 v117, v116
	v_div_fmas_f32 v107, v107, v118, v115
	v_div_fixup_f32 v110, v107, v110, 1.0
	v_fma_f32 v107, -v116, v117, 1.0
	v_fmac_f32_e32 v117, v107, v117
	v_div_scale_f32 v107, vcc, 1.0, v109, 1.0
	v_mul_f32_e32 v115, v107, v117
	v_fma_f32 v118, -v116, v115, v107
	v_fmac_f32_e32 v115, v118, v117
	v_fma_f32 v107, -v116, v115, v107
	v_div_scale_f32 v116, s[44:45], v108, v108, 1.0
	v_rcp_f32_e32 v118, v116
	v_div_fmas_f32 v107, v107, v117, v115
	v_mul_f32_e32 v115, 0xbfb8aa3b, v99
	v_div_fixup_f32 v109, v107, v109, 1.0
	v_fma_f32 v107, -v116, v118, 1.0
	v_exp_f32_e32 v115, v115
	v_fmac_f32_e32 v118, v107, v118
	v_div_scale_f32 v107, vcc, 1.0, v108, 1.0
	v_mul_f32_e32 v117, v107, v118
	v_fma_f32 v119, -v116, v117, v107
	v_fmac_f32_e32 v117, v119, v118
	v_pk_add_f32 v[114:115], v[114:115], 1.0 op_sel_hi:[1,0]
	v_fma_f32 v107, -v116, v117, v107
	v_div_scale_f32 v116, s[44:45], v115, v115, 1.0
	v_rcp_f32_e32 v119, v116
	v_div_fmas_f32 v107, v107, v118, v117
	v_div_fixup_f32 v108, v107, v108, 1.0
	v_fma_f32 v107, -v116, v119, 1.0
	v_fmac_f32_e32 v119, v107, v119
	v_div_scale_f32 v107, vcc, 1.0, v115, 1.0
	v_mul_f32_e32 v117, v107, v119
	v_fma_f32 v118, -v116, v117, v107
	v_fmac_f32_e32 v117, v118, v119
	v_fma_f32 v107, -v116, v117, v107
	v_div_scale_f32 v116, s[44:45], v114, v114, 1.0
	v_rcp_f32_e32 v118, v116
	v_div_fmas_f32 v107, v107, v119, v117
	v_div_fixup_f32 v115, v107, v115, 1.0
	v_fma_f32 v107, -v116, v118, 1.0
	v_fmac_f32_e32 v118, v107, v118
	v_div_scale_f32 v107, vcc, 1.0, v114, 1.0
	v_mul_f32_e32 v117, v107, v118
	v_fma_f32 v119, -v116, v117, v107
	v_fmac_f32_e32 v117, v119, v118
	v_fma_f32 v107, -v116, v117, v107
	v_div_scale_f32 v116, s[44:45], v113, v113, 1.0
	v_rcp_f32_e32 v119, v116
	v_div_fmas_f32 v107, v107, v118, v117
	v_div_fixup_f32 v114, v107, v114, 1.0
	v_fma_f32 v107, -v116, v119, 1.0
	v_fmac_f32_e32 v119, v107, v119
	v_div_scale_f32 v107, vcc, 1.0, v113, 1.0
	v_mul_f32_e32 v117, v107, v119
	v_fma_f32 v118, -v116, v117, v107
	v_fmac_f32_e32 v117, v118, v119
	v_fma_f32 v107, -v116, v117, v107
	v_div_scale_f32 v116, s[44:45], v112, v112, 1.0
	v_rcp_f32_e32 v118, v116
	v_div_fmas_f32 v107, v107, v119, v117
	v_div_fixup_f32 v113, v107, v113, 1.0
	v_fma_f32 v107, -v116, v118, 1.0
	v_fmac_f32_e32 v118, v107, v118
	v_div_scale_f32 v107, vcc, 1.0, v112, 1.0
	v_mul_f32_e32 v117, v107, v118
	v_fma_f32 v119, -v116, v117, v107
	v_fmac_f32_e32 v117, v119, v118
	v_fma_f32 v107, -v116, v117, v107
	v_div_fmas_f32 v107, v107, v118, v117
	v_mad_i64_i32 v[116:117], s[44:45], v106, s53, v[150:151]
	v_div_fixup_f32 v112, v107, v112, 1.0
	global_store_dwordx4 v[116:117], v[108:111], off sc1
	global_store_dwordx4 v[116:117], v[112:115], off offset:16 sc1

.LBB0_686:
	s_andn2_b64 vcc, exec, s[42:43]
	s_cbranch_vccnz .LBB0_688
	v_pk_mul_f32 v[110:111], v[102:103], s[18:19] op_sel_hi:[1,0]
	v_pk_mul_f32 v[108:109], v[100:101], s[18:19] op_sel_hi:[1,0]
	v_pk_mul_f32 v[112:113], v[98:99], s[18:19] op_sel_hi:[1,0]
	v_pk_mul_f32 v[114:115], v[96:97], s[18:19] op_sel_hi:[1,0]
	v_cvt_pk_bf16_f32 v108, v108, v109
	v_cvt_pk_bf16_f32 v109, v110, v111
	v_lshlrev_b32_e32 v138, 1, v146
	v_cvt_pk_bf16_f32 v110, v114, v115
	v_cvt_pk_bf16_f32 v111, v112, v113
	v_lshl_add_u64 v[112:113], s[10:11], 0, v[104:105]
	v_lshl_add_u64 v[112:113], s[14:15], 1, v[112:113]
	v_lshl_add_u64 v[112:113], v[112:113], 0, v[138:139]
	global_store_dwordx4 v[112:113], v[108:111], off offset:-3072 sc1

.LBB0_689:
	s_andn2_b64 vcc, exec, s[42:43]
	v_mad_i64_i32 v[106:107], s[42:43], v106, s61, 0
	s_cbranch_vccnz .LBB0_691
	v_cvt_pk_bf16_f32 v100, v100, v101
	v_cvt_pk_bf16_f32 v101, v102, v103
	v_cvt_pk_bf16_f32 v102, v96, v97
	v_lshl_add_u64 v[96:97], s[24:25], 0, v[106:107]
	v_lshl_add_u64 v[96:97], s[38:39], 1, v[96:97]
	v_lshlrev_b32_e32 v138, 1, v146
	v_lshl_add_u64 v[96:97], v[96:97], 0, v[138:139]
	v_cvt_pk_bf16_f32 v103, v98, v99
	global_store_dwordx4 v[96:97], v[100:103], off sc1

.LBB0_697:
	s_andn2_b64 vcc, exec, s[44:45]
	s_cbranch_vccnz .LBB0_699
	v_lshlrev_b32_e32 v138, 1, v146
	v_lshl_add_u64 v[92:93], v[100:101], 0, v[138:139]
	global_store_dwordx4 v[92:93], v[88:91], off offset:256 sc1
.LBB0_699:
	s_nop 1
	v_or_b32_e32 v90, 48, v162
	v_ashrrev_i32_e32 v91, 31, v90
	v_mov_b32_e32 v92, v167
	v_lshlrev_b64 v[88:89], 11, v[90:91]
	v_pk_mul_f32 v[86:87], v[86:87], v[92:93] op_sel_hi:[1,0]
	v_pk_mul_f32 v[84:85], v[84:85], v[92:93] op_sel_hi:[1,0]
	v_pk_mul_f32 v[82:83], v[82:83], v[92:93] op_sel_hi:[1,0]
	v_pk_mul_f32 v[80:81], v[80:81], v[92:93] op_sel_hi:[1,0]
	s_and_b64 vcc, exec, s[8:9]
	s_mov_b64 s[42:43], -1
	s_cbranch_vccnz .LBB0_707
	s_andn2_b64 vcc, exec, s[40:41]
	s_cbranch_vccnz .LBB0_704
	s_and_saveexec_b64 s[42:43], s[4:5]
	s_cbranch_execz .LBB0_703
	v_mul_f32_e32 v93, 0xbfb8aa3b, v86
	v_exp_f32_e32 v94, v93
	v_mul_f32_e32 v93, 0xbfb8aa3b, v87
	v_exp_f32_e32 v95, v93
	v_mul_f32_e32 v91, 0xbfb8aa3b, v84
	v_exp_f32_e32 v92, v91
	v_mul_f32_e32 v91, 0xbfb8aa3b, v80
	v_exp_f32_e32 v96, v91
	v_mul_f32_e32 v91, 0xbfb8aa3b, v85
	v_exp_f32_e32 v93, v91
	v_mul_f32_e32 v91, 0xbfb8aa3b, v81
	v_pk_add_f32 v[94:95], v[94:95], 1.0 op_sel_hi:[1,0]
	v_exp_f32_e32 v97, v91
	v_div_scale_f32 v91, s[44:45], v95, v95, 1.0
	v_rcp_f32_e32 v99, v91
	v_pk_add_f32 v[92:93], v[92:93], 1.0 op_sel_hi:[1,0]
	v_mul_f32_e32 v98, 0xbfb8aa3b, v82
	v_exp_f32_e32 v98, v98
	v_fma_f32 v100, -v91, v99, 1.0
	v_fmac_f32_e32 v99, v100, v99
	v_div_scale_f32 v100, vcc, 1.0, v95, 1.0
	v_mul_f32_e32 v101, v100, v99
	v_fma_f32 v102, -v91, v101, v100
	v_fmac_f32_e32 v101, v102, v99
	v_fma_f32 v91, -v91, v101, v100
	v_div_scale_f32 v100, s[44:45], v94, v94, 1.0
	v_rcp_f32_e32 v102, v100
	v_div_fmas_f32 v91, v91, v99, v101
	v_div_fixup_f32 v95, v91, v95, 1.0
	v_pk_add_f32 v[96:97], v[96:97], 1.0 op_sel_hi:[1,0]
	v_fma_f32 v91, -v100, v102, 1.0
	v_fmac_f32_e32 v102, v91, v102
	v_div_scale_f32 v91, vcc, 1.0, v94, 1.0
	v_mul_f32_e32 v99, v91, v102
	v_fma_f32 v101, -v100, v99, v91
	v_fmac_f32_e32 v99, v101, v102
	v_fma_f32 v91, -v100, v99, v91
	v_div_scale_f32 v100, s[44:45], v93, v93, 1.0
	v_rcp_f32_e32 v101, v100
	v_div_fmas_f32 v91, v91, v102, v99
	v_div_fixup_f32 v94, v91, v94, 1.0
	v_fma_f32 v91, -v100, v101, 1.0
	v_fmac_f32_e32 v101, v91, v101
	v_div_scale_f32 v91, vcc, 1.0, v93, 1.0
	v_mul_f32_e32 v99, v91, v101
	v_fma_f32 v102, -v100, v99, v91
	v_fmac_f32_e32 v99, v102, v101
	v_fma_f32 v91, -v100, v99, v91
	v_div_scale_f32 v100, s[44:45], v92, v92, 1.0
	v_rcp_f32_e32 v102, v100
	v_div_fmas_f32 v91, v91, v101, v99
	v_mul_f32_e32 v99, 0xbfb8aa3b, v83
	v_div_fixup_f32 v93, v91, v93, 1.0
	v_fma_f32 v91, -v100, v102, 1.0
	v_exp_f32_e32 v99, v99
	v_fmac_f32_e32 v102, v91, v102
	v_div_scale_f32 v91, vcc, 1.0, v92, 1.0
	v_mul_f32_e32 v101, v91, v102
	v_fma_f32 v103, -v100, v101, v91
	v_fmac_f32_e32 v101, v103, v102
	v_pk_add_f32 v[98:99], v[98:99], 1.0 op_sel_hi:[1,0]
	v_fma_f32 v91, -v100, v101, v91
	v_div_scale_f32 v100, s[44:45], v99, v99, 1.0
	v_rcp_f32_e32 v103, v100
	v_div_fmas_f32 v91, v91, v102, v101
	v_div_fixup_f32 v92, v91, v92, 1.0
	v_fma_f32 v91, -v100, v103, 1.0
	v_fmac_f32_e32 v103, v91, v103
	v_div_scale_f32 v91, vcc, 1.0, v99, 1.0
	v_mul_f32_e32 v101, v91, v103
	v_fma_f32 v102, -v100, v101, v91
	v_fmac_f32_e32 v101, v102, v103
	v_fma_f32 v91, -v100, v101, v91
	v_div_scale_f32 v100, s[44:45], v98, v98, 1.0
	v_rcp_f32_e32 v102, v100
	v_div_fmas_f32 v91, v91, v103, v101
	v_div_fixup_f32 v99, v91, v99, 1.0
	v_fma_f32 v91, -v100, v102, 1.0
	v_fmac_f32_e32 v102, v91, v102
	v_div_scale_f32 v91, vcc, 1.0, v98, 1.0
	v_mul_f32_e32 v101, v91, v102
	v_fma_f32 v103, -v100, v101, v91
	v_fmac_f32_e32 v101, v103, v102
	v_fma_f32 v91, -v100, v101, v91
	v_div_scale_f32 v100, s[44:45], v97, v97, 1.0
	v_rcp_f32_e32 v103, v100
	v_div_fmas_f32 v91, v91, v102, v101
	v_div_fixup_f32 v98, v91, v98, 1.0
	v_fma_f32 v91, -v100, v103, 1.0
	v_fmac_f32_e32 v103, v91, v103
	v_div_scale_f32 v91, vcc, 1.0, v97, 1.0
	v_mul_f32_e32 v101, v91, v103
	v_fma_f32 v102, -v100, v101, v91
	v_fmac_f32_e32 v101, v102, v103
	v_fma_f32 v91, -v100, v101, v91
	v_div_scale_f32 v100, s[44:45], v96, v96, 1.0
	v_rcp_f32_e32 v102, v100
	v_div_fmas_f32 v91, v91, v103, v101
	v_div_fixup_f32 v97, v91, v97, 1.0
	v_fma_f32 v91, -v100, v102, 1.0
	v_fmac_f32_e32 v102, v91, v102
	v_div_scale_f32 v91, vcc, 1.0, v96, 1.0
	v_mul_f32_e32 v101, v91, v102
	v_fma_f32 v103, -v100, v101, v91
	v_fmac_f32_e32 v101, v103, v102
	v_fma_f32 v91, -v100, v101, v91
	v_div_fmas_f32 v91, v91, v102, v101
	v_mad_i64_i32 v[100:101], s[44:45], v90, s53, v[150:151]
	v_div_fixup_f32 v96, v91, v96, 1.0
	global_store_dwordx4 v[100:101], v[92:95], off sc1
	global_store_dwordx4 v[100:101], v[96:99], off offset:16 sc1

.LBB0_704:
	s_andn2_b64 vcc, exec, s[42:43]
	s_cbranch_vccnz .LBB0_706
	v_pk_mul_f32 v[94:95], v[86:87], s[18:19] op_sel_hi:[1,0]
	v_pk_mul_f32 v[92:93], v[84:85], s[18:19] op_sel_hi:[1,0]
	v_pk_mul_f32 v[96:97], v[82:83], s[18:19] op_sel_hi:[1,0]
	v_pk_mul_f32 v[98:99], v[80:81], s[18:19] op_sel_hi:[1,0]
	v_cvt_pk_bf16_f32 v92, v92, v93
	v_cvt_pk_bf16_f32 v93, v94, v95
	v_lshlrev_b32_e32 v138, 1, v146
	v_cvt_pk_bf16_f32 v94, v98, v99
	v_cvt_pk_bf16_f32 v95, v96, v97
	v_lshl_add_u64 v[96:97], s[10:11], 0, v[88:89]
	v_lshl_add_u64 v[96:97], s[14:15], 1, v[96:97]
	v_lshl_add_u64 v[96:97], v[96:97], 0, v[138:139]
	global_store_dwordx4 v[96:97], v[92:95], off offset:-3072 sc1

.LBB0_707:
	s_andn2_b64 vcc, exec, s[42:43]
	v_mad_i64_i32 v[90:91], s[42:43], v90, s61, 0
	s_cbranch_vccnz .LBB0_709
	v_cvt_pk_bf16_f32 v84, v84, v85
	v_cvt_pk_bf16_f32 v85, v86, v87
	v_cvt_pk_bf16_f32 v86, v80, v81
	v_lshl_add_u64 v[80:81], s[24:25], 0, v[90:91]
	v_lshl_add_u64 v[80:81], s[38:39], 1, v[80:81]
	v_lshlrev_b32_e32 v138, 1, v146
	v_lshl_add_u64 v[80:81], v[80:81], 0, v[138:139]
	v_cvt_pk_bf16_f32 v87, v82, v83
	global_store_dwordx4 v[80:81], v[84:87], off sc1

.LBB0_715:
	s_andn2_b64 vcc, exec, s[44:45]
	s_cbranch_vccnz .LBB0_717
	v_lshlrev_b32_e32 v138, 1, v146
	v_lshl_add_u64 v[76:77], v[84:85], 0, v[138:139]
	global_store_dwordx4 v[76:77], v[72:75], off offset:256 sc1
.LBB0_717:
	s_nop 1
	v_add_u32_e32 v74, 0x80, v162
	v_ashrrev_i32_e32 v75, 31, v74
	v_lshlrev_b64 v[72:73], 11, v[74:75]
	v_pk_mul_f32 v[70:71], v[70:71], v[164:165] op_sel_hi:[1,0]
	v_pk_mul_f32 v[68:69], v[68:69], v[164:165] op_sel_hi:[1,0]
	v_pk_mul_f32 v[66:67], v[66:67], v[164:165] op_sel_hi:[1,0]
	v_pk_mul_f32 v[64:65], v[64:65], v[164:165] op_sel_hi:[1,0]
	s_and_b64 vcc, exec, s[8:9]
	s_mov_b64 s[42:43], -1
	s_cbranch_vccnz .LBB0_725
	s_andn2_b64 vcc, exec, s[40:41]
	s_cbranch_vccnz .LBB0_722
	s_and_saveexec_b64 s[42:43], s[4:5]
	s_cbranch_execz .LBB0_721
	v_mul_f32_e32 v77, 0xbfb8aa3b, v70
	v_exp_f32_e32 v78, v77
	v_mul_f32_e32 v77, 0xbfb8aa3b, v71
	v_exp_f32_e32 v79, v77
	v_mul_f32_e32 v75, 0xbfb8aa3b, v68
	v_exp_f32_e32 v76, v75
	v_mul_f32_e32 v75, 0xbfb8aa3b, v64
	v_exp_f32_e32 v80, v75
	v_mul_f32_e32 v75, 0xbfb8aa3b, v69
	v_exp_f32_e32 v77, v75
	v_mul_f32_e32 v75, 0xbfb8aa3b, v65
	v_pk_add_f32 v[78:79], v[78:79], 1.0 op_sel_hi:[1,0]
	v_exp_f32_e32 v81, v75
	v_div_scale_f32 v75, s[44:45], v79, v79, 1.0
	v_rcp_f32_e32 v83, v75
	v_pk_add_f32 v[76:77], v[76:77], 1.0 op_sel_hi:[1,0]
	v_mul_f32_e32 v82, 0xbfb8aa3b, v66
	v_exp_f32_e32 v82, v82
	v_fma_f32 v84, -v75, v83, 1.0
	v_fmac_f32_e32 v83, v84, v83
	v_div_scale_f32 v84, vcc, 1.0, v79, 1.0
	v_mul_f32_e32 v85, v84, v83
	v_fma_f32 v86, -v75, v85, v84
	v_fmac_f32_e32 v85, v86, v83
	v_fma_f32 v75, -v75, v85, v84
	v_div_scale_f32 v84, s[44:45], v78, v78, 1.0
	v_rcp_f32_e32 v86, v84
	v_div_fmas_f32 v75, v75, v83, v85
	v_div_fixup_f32 v79, v75, v79, 1.0
	v_pk_add_f32 v[80:81], v[80:81], 1.0 op_sel_hi:[1,0]
	v_fma_f32 v75, -v84, v86, 1.0
	v_fmac_f32_e32 v86, v75, v86
	v_div_scale_f32 v75, vcc, 1.0, v78, 1.0
	v_mul_f32_e32 v83, v75, v86
	v_fma_f32 v85, -v84, v83, v75
	v_fmac_f32_e32 v83, v85, v86
	v_fma_f32 v75, -v84, v83, v75
	v_div_scale_f32 v84, s[44:45], v77, v77, 1.0
	v_rcp_f32_e32 v85, v84
	v_div_fmas_f32 v75, v75, v86, v83
	v_div_fixup_f32 v78, v75, v78, 1.0
	v_fma_f32 v75, -v84, v85, 1.0
	v_fmac_f32_e32 v85, v75, v85
	v_div_scale_f32 v75, vcc, 1.0, v77, 1.0
	v_mul_f32_e32 v83, v75, v85
	v_fma_f32 v86, -v84, v83, v75
	v_fmac_f32_e32 v83, v86, v85
	v_fma_f32 v75, -v84, v83, v75
	v_div_scale_f32 v84, s[44:45], v76, v76, 1.0
	v_rcp_f32_e32 v86, v84
	v_div_fmas_f32 v75, v75, v85, v83
	v_mul_f32_e32 v83, 0xbfb8aa3b, v67
	v_div_fixup_f32 v77, v75, v77, 1.0
	v_fma_f32 v75, -v84, v86, 1.0
	v_exp_f32_e32 v83, v83
	v_fmac_f32_e32 v86, v75, v86
	v_div_scale_f32 v75, vcc, 1.0, v76, 1.0
	v_mul_f32_e32 v85, v75, v86
	v_fma_f32 v87, -v84, v85, v75
	v_fmac_f32_e32 v85, v87, v86
	v_pk_add_f32 v[82:83], v[82:83], 1.0 op_sel_hi:[1,0]
	v_fma_f32 v75, -v84, v85, v75
	v_div_scale_f32 v84, s[44:45], v83, v83, 1.0
	v_rcp_f32_e32 v87, v84
	v_div_fmas_f32 v75, v75, v86, v85
	v_div_fixup_f32 v76, v75, v76, 1.0
	v_fma_f32 v75, -v84, v87, 1.0
	v_fmac_f32_e32 v87, v75, v87
	v_div_scale_f32 v75, vcc, 1.0, v83, 1.0
	v_mul_f32_e32 v85, v75, v87
	v_fma_f32 v86, -v84, v85, v75
	v_fmac_f32_e32 v85, v86, v87
	v_fma_f32 v75, -v84, v85, v75
	v_div_scale_f32 v84, s[44:45], v82, v82, 1.0
	v_rcp_f32_e32 v86, v84
	v_div_fmas_f32 v75, v75, v87, v85
	v_div_fixup_f32 v83, v75, v83, 1.0
	v_fma_f32 v75, -v84, v86, 1.0
	v_fmac_f32_e32 v86, v75, v86
	v_div_scale_f32 v75, vcc, 1.0, v82, 1.0
	v_mul_f32_e32 v85, v75, v86
	v_fma_f32 v87, -v84, v85, v75
	v_fmac_f32_e32 v85, v87, v86
	v_fma_f32 v75, -v84, v85, v75
	v_div_scale_f32 v84, s[44:45], v81, v81, 1.0
	v_rcp_f32_e32 v87, v84
	v_div_fmas_f32 v75, v75, v86, v85
	v_div_fixup_f32 v82, v75, v82, 1.0
	v_fma_f32 v75, -v84, v87, 1.0
	v_fmac_f32_e32 v87, v75, v87
	v_div_scale_f32 v75, vcc, 1.0, v81, 1.0
	v_mul_f32_e32 v85, v75, v87
	v_fma_f32 v86, -v84, v85, v75
	v_fmac_f32_e32 v85, v86, v87
	v_fma_f32 v75, -v84, v85, v75
	v_div_scale_f32 v84, s[44:45], v80, v80, 1.0
	v_rcp_f32_e32 v86, v84
	v_div_fmas_f32 v75, v75, v87, v85
	v_div_fixup_f32 v81, v75, v81, 1.0
	v_fma_f32 v75, -v84, v86, 1.0
	v_fmac_f32_e32 v86, v75, v86
	v_div_scale_f32 v75, vcc, 1.0, v80, 1.0
	v_mul_f32_e32 v85, v75, v86
	v_fma_f32 v87, -v84, v85, v75
	v_fmac_f32_e32 v85, v87, v86
	v_fma_f32 v75, -v84, v85, v75
	v_div_fmas_f32 v75, v75, v86, v85
	v_mad_i64_i32 v[84:85], s[44:45], v74, s53, v[150:151]
	v_div_fixup_f32 v80, v75, v80, 1.0
	global_store_dwordx4 v[84:85], v[76:79], off sc1
	global_store_dwordx4 v[84:85], v[80:83], off offset:16 sc1

.LBB0_722:
	s_andn2_b64 vcc, exec, s[42:43]
	s_cbranch_vccnz .LBB0_724
	v_pk_mul_f32 v[78:79], v[70:71], s[18:19] op_sel_hi:[1,0]
	v_pk_mul_f32 v[76:77], v[68:69], s[18:19] op_sel_hi:[1,0]
	v_pk_mul_f32 v[80:81], v[66:67], s[18:19] op_sel_hi:[1,0]
	v_pk_mul_f32 v[82:83], v[64:65], s[18:19] op_sel_hi:[1,0]
	v_cvt_pk_bf16_f32 v76, v76, v77
	v_cvt_pk_bf16_f32 v77, v78, v79
	v_lshlrev_b32_e32 v138, 1, v146
	v_cvt_pk_bf16_f32 v78, v82, v83
	v_cvt_pk_bf16_f32 v79, v80, v81
	v_lshl_add_u64 v[80:81], s[10:11], 0, v[72:73]
	v_lshl_add_u64 v[80:81], s[14:15], 1, v[80:81]
	v_lshl_add_u64 v[80:81], v[80:81], 0, v[138:139]
	global_store_dwordx4 v[80:81], v[76:79], off offset:-3072 sc1

.LBB0_725:
	s_andn2_b64 vcc, exec, s[42:43]
	v_mad_i64_i32 v[74:75], s[42:43], v74, s61, 0
	s_cbranch_vccnz .LBB0_727
	v_cvt_pk_bf16_f32 v68, v68, v69
	v_cvt_pk_bf16_f32 v69, v70, v71
	v_cvt_pk_bf16_f32 v70, v64, v65
	v_lshl_add_u64 v[64:65], s[24:25], 0, v[74:75]
	v_lshl_add_u64 v[64:65], s[38:39], 1, v[64:65]
	v_lshlrev_b32_e32 v138, 1, v146
	v_lshl_add_u64 v[64:65], v[64:65], 0, v[138:139]
	v_cvt_pk_bf16_f32 v71, v66, v67
	global_store_dwordx4 v[64:65], v[68:71], off sc1

.LBB0_733:
	s_andn2_b64 vcc, exec, s[44:45]
	s_cbranch_vccnz .LBB0_735
	v_lshlrev_b32_e32 v138, 1, v146
	v_lshl_add_u64 v[60:61], v[68:69], 0, v[138:139]
	global_store_dwordx4 v[60:61], v[56:59], off offset:256 sc1
.LBB0_735:
	s_nop 1
	v_add_u32_e32 v58, 0x90, v162
	v_ashrrev_i32_e32 v59, 31, v58
	v_mov_b32_e32 v60, v165
	v_lshlrev_b64 v[56:57], 11, v[58:59]
	v_pk_mul_f32 v[54:55], v[54:55], v[60:61] op_sel_hi:[1,0]
	v_pk_mul_f32 v[52:53], v[52:53], v[60:61] op_sel_hi:[1,0]
	v_pk_mul_f32 v[50:51], v[50:51], v[60:61] op_sel_hi:[1,0]
	v_pk_mul_f32 v[48:49], v[48:49], v[60:61] op_sel_hi:[1,0]
	s_and_b64 vcc, exec, s[8:9]
	s_mov_b64 s[42:43], -1
	s_cbranch_vccnz .LBB0_743
	s_andn2_b64 vcc, exec, s[40:41]
	s_cbranch_vccnz .LBB0_740
	s_and_saveexec_b64 s[42:43], s[4:5]
	s_cbranch_execz .LBB0_739
	v_mul_f32_e32 v61, 0xbfb8aa3b, v54
	v_exp_f32_e32 v62, v61
	v_mul_f32_e32 v61, 0xbfb8aa3b, v55
	v_exp_f32_e32 v63, v61
	v_mul_f32_e32 v59, 0xbfb8aa3b, v52
	v_exp_f32_e32 v60, v59
	v_mul_f32_e32 v59, 0xbfb8aa3b, v48
	v_exp_f32_e32 v64, v59
	v_mul_f32_e32 v59, 0xbfb8aa3b, v53
	v_exp_f32_e32 v61, v59
	v_mul_f32_e32 v59, 0xbfb8aa3b, v49
	v_pk_add_f32 v[62:63], v[62:63], 1.0 op_sel_hi:[1,0]
	v_exp_f32_e32 v65, v59
	v_div_scale_f32 v59, s[44:45], v63, v63, 1.0
	v_rcp_f32_e32 v67, v59
	v_pk_add_f32 v[60:61], v[60:61], 1.0 op_sel_hi:[1,0]
	v_mul_f32_e32 v66, 0xbfb8aa3b, v50
	v_exp_f32_e32 v66, v66
	v_fma_f32 v68, -v59, v67, 1.0
	v_fmac_f32_e32 v67, v68, v67
	v_div_scale_f32 v68, vcc, 1.0, v63, 1.0
	v_mul_f32_e32 v69, v68, v67
	v_fma_f32 v70, -v59, v69, v68
	v_fmac_f32_e32 v69, v70, v67
	v_fma_f32 v59, -v59, v69, v68
	v_div_scale_f32 v68, s[44:45], v62, v62, 1.0
	v_rcp_f32_e32 v70, v68
	v_div_fmas_f32 v59, v59, v67, v69
	v_div_fixup_f32 v63, v59, v63, 1.0
	v_pk_add_f32 v[64:65], v[64:65], 1.0 op_sel_hi:[1,0]
	v_fma_f32 v59, -v68, v70, 1.0
	v_fmac_f32_e32 v70, v59, v70
	v_div_scale_f32 v59, vcc, 1.0, v62, 1.0
	v_mul_f32_e32 v67, v59, v70
	v_fma_f32 v69, -v68, v67, v59
	v_fmac_f32_e32 v67, v69, v70
	v_fma_f32 v59, -v68, v67, v59
	v_div_scale_f32 v68, s[44:45], v61, v61, 1.0
	v_rcp_f32_e32 v69, v68
	v_div_fmas_f32 v59, v59, v70, v67
	v_div_fixup_f32 v62, v59, v62, 1.0
	v_fma_f32 v59, -v68, v69, 1.0
	v_fmac_f32_e32 v69, v59, v69
	v_div_scale_f32 v59, vcc, 1.0, v61, 1.0
	v_mul_f32_e32 v67, v59, v69
	v_fma_f32 v70, -v68, v67, v59
	v_fmac_f32_e32 v67, v70, v69
	v_fma_f32 v59, -v68, v67, v59
	v_div_scale_f32 v68, s[44:45], v60, v60, 1.0
	v_rcp_f32_e32 v70, v68
	v_div_fmas_f32 v59, v59, v69, v67
	v_mul_f32_e32 v67, 0xbfb8aa3b, v51
	v_div_fixup_f32 v61, v59, v61, 1.0
	v_fma_f32 v59, -v68, v70, 1.0
	v_exp_f32_e32 v67, v67
	v_fmac_f32_e32 v70, v59, v70
	v_div_scale_f32 v59, vcc, 1.0, v60, 1.0
	v_mul_f32_e32 v69, v59, v70
	v_fma_f32 v71, -v68, v69, v59
	v_fmac_f32_e32 v69, v71, v70
	v_pk_add_f32 v[66:67], v[66:67], 1.0 op_sel_hi:[1,0]
	v_fma_f32 v59, -v68, v69, v59
	v_div_scale_f32 v68, s[44:45], v67, v67, 1.0
	v_rcp_f32_e32 v71, v68
	v_div_fmas_f32 v59, v59, v70, v69
	v_div_fixup_f32 v60, v59, v60, 1.0
	v_fma_f32 v59, -v68, v71, 1.0
	v_fmac_f32_e32 v71, v59, v71
	v_div_scale_f32 v59, vcc, 1.0, v67, 1.0
	v_mul_f32_e32 v69, v59, v71
	v_fma_f32 v70, -v68, v69, v59
	v_fmac_f32_e32 v69, v70, v71
	v_fma_f32 v59, -v68, v69, v59
	v_div_scale_f32 v68, s[44:45], v66, v66, 1.0
	v_rcp_f32_e32 v70, v68
	v_div_fmas_f32 v59, v59, v71, v69
	v_div_fixup_f32 v67, v59, v67, 1.0
	v_fma_f32 v59, -v68, v70, 1.0
	v_fmac_f32_e32 v70, v59, v70
	v_div_scale_f32 v59, vcc, 1.0, v66, 1.0
	v_mul_f32_e32 v69, v59, v70
	v_fma_f32 v71, -v68, v69, v59
	v_fmac_f32_e32 v69, v71, v70
	v_fma_f32 v59, -v68, v69, v59
	v_div_scale_f32 v68, s[44:45], v65, v65, 1.0
	v_rcp_f32_e32 v71, v68
	v_div_fmas_f32 v59, v59, v70, v69
	v_div_fixup_f32 v66, v59, v66, 1.0
	v_fma_f32 v59, -v68, v71, 1.0
	v_fmac_f32_e32 v71, v59, v71
	v_div_scale_f32 v59, vcc, 1.0, v65, 1.0
	v_mul_f32_e32 v69, v59, v71
	v_fma_f32 v70, -v68, v69, v59
	v_fmac_f32_e32 v69, v70, v71
	v_fma_f32 v59, -v68, v69, v59
	v_div_scale_f32 v68, s[44:45], v64, v64, 1.0
	v_rcp_f32_e32 v70, v68
	v_div_fmas_f32 v59, v59, v71, v69
	v_div_fixup_f32 v65, v59, v65, 1.0
	v_fma_f32 v59, -v68, v70, 1.0
	v_fmac_f32_e32 v70, v59, v70
	v_div_scale_f32 v59, vcc, 1.0, v64, 1.0
	v_mul_f32_e32 v69, v59, v70
	v_fma_f32 v71, -v68, v69, v59
	v_fmac_f32_e32 v69, v71, v70
	v_fma_f32 v59, -v68, v69, v59
	v_div_fmas_f32 v59, v59, v70, v69
	v_mad_i64_i32 v[68:69], s[44:45], v58, s53, v[150:151]
	v_div_fixup_f32 v64, v59, v64, 1.0
	global_store_dwordx4 v[68:69], v[60:63], off sc1
	global_store_dwordx4 v[68:69], v[64:67], off offset:16 sc1

.LBB0_740:
	s_andn2_b64 vcc, exec, s[42:43]
	s_cbranch_vccnz .LBB0_742
	v_pk_mul_f32 v[62:63], v[54:55], s[18:19] op_sel_hi:[1,0]
	v_pk_mul_f32 v[60:61], v[52:53], s[18:19] op_sel_hi:[1,0]
	v_pk_mul_f32 v[64:65], v[50:51], s[18:19] op_sel_hi:[1,0]
	v_pk_mul_f32 v[66:67], v[48:49], s[18:19] op_sel_hi:[1,0]
	v_cvt_pk_bf16_f32 v60, v60, v61
	v_cvt_pk_bf16_f32 v61, v62, v63
	v_lshlrev_b32_e32 v138, 1, v146
	v_cvt_pk_bf16_f32 v62, v66, v67
	v_cvt_pk_bf16_f32 v63, v64, v65
	v_lshl_add_u64 v[64:65], s[10:11], 0, v[56:57]
	v_lshl_add_u64 v[64:65], s[14:15], 1, v[64:65]
	v_lshl_add_u64 v[64:65], v[64:65], 0, v[138:139]
	global_store_dwordx4 v[64:65], v[60:63], off offset:-3072 sc1

.LBB0_743:
	s_andn2_b64 vcc, exec, s[42:43]
	v_mad_i64_i32 v[58:59], s[42:43], v58, s61, 0
	s_cbranch_vccnz .LBB0_745
	v_cvt_pk_bf16_f32 v52, v52, v53
	v_cvt_pk_bf16_f32 v53, v54, v55
	v_cvt_pk_bf16_f32 v54, v48, v49
	v_lshl_add_u64 v[48:49], s[24:25], 0, v[58:59]
	v_lshl_add_u64 v[48:49], s[38:39], 1, v[48:49]
	v_lshlrev_b32_e32 v138, 1, v146
	v_lshl_add_u64 v[48:49], v[48:49], 0, v[138:139]
	v_cvt_pk_bf16_f32 v55, v50, v51
	global_store_dwordx4 v[48:49], v[52:55], off sc1

.LBB0_751:
	s_andn2_b64 vcc, exec, s[44:45]
	s_cbranch_vccnz .LBB0_753
	v_lshlrev_b32_e32 v138, 1, v146
	v_lshl_add_u64 v[44:45], v[52:53], 0, v[138:139]
	global_store_dwordx4 v[44:45], v[40:43], off offset:256 sc1
.LBB0_753:
	s_nop 1
	v_add_u32_e32 v42, 0xa0, v162
	v_ashrrev_i32_e32 v43, 31, v42
	v_lshlrev_b64 v[40:41], 11, v[42:43]
	v_pk_mul_f32 v[38:39], v[38:39], v[160:161] op_sel_hi:[1,0]
	v_pk_mul_f32 v[36:37], v[36:37], v[160:161] op_sel_hi:[1,0]
	v_pk_mul_f32 v[34:35], v[34:35], v[160:161] op_sel_hi:[1,0]
	v_pk_mul_f32 v[32:33], v[32:33], v[160:161] op_sel_hi:[1,0]
	s_and_b64 vcc, exec, s[8:9]
	s_mov_b64 s[42:43], -1
	s_cbranch_vccnz .LBB0_761
	s_andn2_b64 vcc, exec, s[40:41]
	s_cbranch_vccnz .LBB0_758
	s_and_saveexec_b64 s[42:43], s[4:5]
	s_cbranch_execz .LBB0_757
	v_mul_f32_e32 v45, 0xbfb8aa3b, v38
	v_exp_f32_e32 v46, v45
	v_mul_f32_e32 v45, 0xbfb8aa3b, v39
	v_exp_f32_e32 v47, v45
	v_mul_f32_e32 v43, 0xbfb8aa3b, v36
	v_exp_f32_e32 v44, v43
	v_mul_f32_e32 v43, 0xbfb8aa3b, v32
	v_exp_f32_e32 v48, v43
	v_mul_f32_e32 v43, 0xbfb8aa3b, v37
	v_exp_f32_e32 v45, v43
	v_mul_f32_e32 v43, 0xbfb8aa3b, v33
	v_pk_add_f32 v[46:47], v[46:47], 1.0 op_sel_hi:[1,0]
	v_exp_f32_e32 v49, v43
	v_div_scale_f32 v43, s[44:45], v47, v47, 1.0
	v_rcp_f32_e32 v51, v43
	v_pk_add_f32 v[44:45], v[44:45], 1.0 op_sel_hi:[1,0]
	v_mul_f32_e32 v50, 0xbfb8aa3b, v34
	v_exp_f32_e32 v50, v50
	v_fma_f32 v52, -v43, v51, 1.0
	v_fmac_f32_e32 v51, v52, v51
	v_div_scale_f32 v52, vcc, 1.0, v47, 1.0
	v_mul_f32_e32 v53, v52, v51
	v_fma_f32 v54, -v43, v53, v52
	v_fmac_f32_e32 v53, v54, v51
	v_fma_f32 v43, -v43, v53, v52
	v_div_scale_f32 v52, s[44:45], v46, v46, 1.0
	v_rcp_f32_e32 v54, v52
	v_div_fmas_f32 v43, v43, v51, v53
	v_div_fixup_f32 v47, v43, v47, 1.0
	v_pk_add_f32 v[48:49], v[48:49], 1.0 op_sel_hi:[1,0]
	v_fma_f32 v43, -v52, v54, 1.0
	v_fmac_f32_e32 v54, v43, v54
	v_div_scale_f32 v43, vcc, 1.0, v46, 1.0
	v_mul_f32_e32 v51, v43, v54
	v_fma_f32 v53, -v52, v51, v43
	v_fmac_f32_e32 v51, v53, v54
	v_fma_f32 v43, -v52, v51, v43
	v_div_scale_f32 v52, s[44:45], v45, v45, 1.0
	v_rcp_f32_e32 v53, v52
	v_div_fmas_f32 v43, v43, v54, v51
	v_div_fixup_f32 v46, v43, v46, 1.0
	v_fma_f32 v43, -v52, v53, 1.0
	v_fmac_f32_e32 v53, v43, v53
	v_div_scale_f32 v43, vcc, 1.0, v45, 1.0
	v_mul_f32_e32 v51, v43, v53
	v_fma_f32 v54, -v52, v51, v43
	v_fmac_f32_e32 v51, v54, v53
	v_fma_f32 v43, -v52, v51, v43
	v_div_scale_f32 v52, s[44:45], v44, v44, 1.0
	v_rcp_f32_e32 v54, v52
	v_div_fmas_f32 v43, v43, v53, v51
	v_mul_f32_e32 v51, 0xbfb8aa3b, v35
	v_div_fixup_f32 v45, v43, v45, 1.0
	v_fma_f32 v43, -v52, v54, 1.0
	v_exp_f32_e32 v51, v51
	v_fmac_f32_e32 v54, v43, v54
	v_div_scale_f32 v43, vcc, 1.0, v44, 1.0
	v_mul_f32_e32 v53, v43, v54
	v_fma_f32 v55, -v52, v53, v43
	v_fmac_f32_e32 v53, v55, v54
	v_pk_add_f32 v[50:51], v[50:51], 1.0 op_sel_hi:[1,0]
	v_fma_f32 v43, -v52, v53, v43
	v_div_scale_f32 v52, s[44:45], v51, v51, 1.0
	v_rcp_f32_e32 v55, v52
	v_div_fmas_f32 v43, v43, v54, v53
	v_div_fixup_f32 v44, v43, v44, 1.0
	v_fma_f32 v43, -v52, v55, 1.0
	v_fmac_f32_e32 v55, v43, v55
	v_div_scale_f32 v43, vcc, 1.0, v51, 1.0
	v_mul_f32_e32 v53, v43, v55
	v_fma_f32 v54, -v52, v53, v43
	v_fmac_f32_e32 v53, v54, v55
	v_fma_f32 v43, -v52, v53, v43
	v_div_scale_f32 v52, s[44:45], v50, v50, 1.0
	v_rcp_f32_e32 v54, v52
	v_div_fmas_f32 v43, v43, v55, v53
	v_div_fixup_f32 v51, v43, v51, 1.0
	v_fma_f32 v43, -v52, v54, 1.0
	v_fmac_f32_e32 v54, v43, v54
	v_div_scale_f32 v43, vcc, 1.0, v50, 1.0
	v_mul_f32_e32 v53, v43, v54
	v_fma_f32 v55, -v52, v53, v43
	v_fmac_f32_e32 v53, v55, v54
	v_fma_f32 v43, -v52, v53, v43
	v_div_scale_f32 v52, s[44:45], v49, v49, 1.0
	v_rcp_f32_e32 v55, v52
	v_div_fmas_f32 v43, v43, v54, v53
	v_div_fixup_f32 v50, v43, v50, 1.0
	v_fma_f32 v43, -v52, v55, 1.0
	v_fmac_f32_e32 v55, v43, v55
	v_div_scale_f32 v43, vcc, 1.0, v49, 1.0
	v_mul_f32_e32 v53, v43, v55
	v_fma_f32 v54, -v52, v53, v43
	v_fmac_f32_e32 v53, v54, v55
	v_fma_f32 v43, -v52, v53, v43
	v_div_scale_f32 v52, s[44:45], v48, v48, 1.0
	v_rcp_f32_e32 v54, v52
	v_div_fmas_f32 v43, v43, v55, v53
	v_div_fixup_f32 v49, v43, v49, 1.0
	v_fma_f32 v43, -v52, v54, 1.0
	v_fmac_f32_e32 v54, v43, v54
	v_div_scale_f32 v43, vcc, 1.0, v48, 1.0
	v_mul_f32_e32 v53, v43, v54
	v_fma_f32 v55, -v52, v53, v43
	v_fmac_f32_e32 v53, v55, v54
	v_fma_f32 v43, -v52, v53, v43
	v_div_fmas_f32 v43, v43, v54, v53
	v_mad_i64_i32 v[52:53], s[44:45], v42, s53, v[150:151]
	v_div_fixup_f32 v48, v43, v48, 1.0
	global_store_dwordx4 v[52:53], v[44:47], off sc1
	global_store_dwordx4 v[52:53], v[48:51], off offset:16 sc1

.LBB0_758:
	s_andn2_b64 vcc, exec, s[42:43]
	s_cbranch_vccnz .LBB0_760
	v_pk_mul_f32 v[46:47], v[38:39], s[18:19] op_sel_hi:[1,0]
	v_pk_mul_f32 v[44:45], v[36:37], s[18:19] op_sel_hi:[1,0]
	v_pk_mul_f32 v[48:49], v[34:35], s[18:19] op_sel_hi:[1,0]
	v_pk_mul_f32 v[50:51], v[32:33], s[18:19] op_sel_hi:[1,0]
	v_cvt_pk_bf16_f32 v44, v44, v45
	v_cvt_pk_bf16_f32 v45, v46, v47
	v_lshlrev_b32_e32 v138, 1, v146
	v_cvt_pk_bf16_f32 v46, v50, v51
	v_cvt_pk_bf16_f32 v47, v48, v49
	v_lshl_add_u64 v[48:49], s[10:11], 0, v[40:41]
	v_lshl_add_u64 v[48:49], s[14:15], 1, v[48:49]
	v_lshl_add_u64 v[48:49], v[48:49], 0, v[138:139]
	global_store_dwordx4 v[48:49], v[44:47], off offset:-3072 sc1

.LBB0_761:
	s_andn2_b64 vcc, exec, s[42:43]
	v_mad_i64_i32 v[42:43], s[42:43], v42, s61, 0
	s_cbranch_vccnz .LBB0_763
	v_cvt_pk_bf16_f32 v36, v36, v37
	v_cvt_pk_bf16_f32 v37, v38, v39
	v_cvt_pk_bf16_f32 v38, v32, v33
	v_lshl_add_u64 v[32:33], s[24:25], 0, v[42:43]
	v_lshl_add_u64 v[32:33], s[38:39], 1, v[32:33]
	v_lshlrev_b32_e32 v138, 1, v146
	v_lshl_add_u64 v[32:33], v[32:33], 0, v[138:139]
	v_cvt_pk_bf16_f32 v39, v34, v35
	global_store_dwordx4 v[32:33], v[36:39], off sc1

.LBB0_769:
	s_andn2_b64 vcc, exec, s[44:45]
	s_cbranch_vccnz .LBB0_771
	v_lshlrev_b32_e32 v138, 1, v146
	v_lshl_add_u64 v[20:21], v[36:37], 0, v[138:139]
	global_store_dwordx4 v[20:21], v[16:19], off offset:256 sc1
.LBB0_771:
	s_nop 1
	v_add_u32_e32 v18, 0xb0, v162
	v_ashrrev_i32_e32 v19, 31, v18
	v_mov_b32_e32 v20, v161
	v_lshlrev_b64 v[16:17], 11, v[18:19]
	v_pk_mul_f32 v[14:15], v[14:15], v[20:21] op_sel_hi:[1,0]
	v_pk_mul_f32 v[12:13], v[12:13], v[20:21] op_sel_hi:[1,0]
	v_pk_mul_f32 v[10:11], v[10:11], v[20:21] op_sel_hi:[1,0]
	v_pk_mul_f32 v[8:9], v[8:9], v[20:21] op_sel_hi:[1,0]
	s_and_b64 vcc, exec, s[8:9]
	s_mov_b64 s[42:43], -1
	s_cbranch_vccnz .LBB0_779
	s_andn2_b64 vcc, exec, s[40:41]
	s_mov_b64 s[40:41], -1
	s_cbranch_vccnz .LBB0_776
	s_and_saveexec_b64 s[40:41], s[4:5]
	s_cbranch_execz .LBB0_775
	v_mul_f32_e32 v21, 0xbfb8aa3b, v14
	v_exp_f32_e32 v22, v21
	v_mul_f32_e32 v21, 0xbfb8aa3b, v15
	v_exp_f32_e32 v23, v21
	v_mul_f32_e32 v19, 0xbfb8aa3b, v12
	v_exp_f32_e32 v20, v19
	v_mul_f32_e32 v19, 0xbfb8aa3b, v8
	v_exp_f32_e32 v32, v19
	v_mul_f32_e32 v19, 0xbfb8aa3b, v13
	v_exp_f32_e32 v21, v19
	v_mul_f32_e32 v19, 0xbfb8aa3b, v9
	v_pk_add_f32 v[22:23], v[22:23], 1.0 op_sel_hi:[1,0]
	v_exp_f32_e32 v33, v19
	v_div_scale_f32 v19, s[42:43], v23, v23, 1.0
	v_rcp_f32_e32 v35, v19
	v_pk_add_f32 v[20:21], v[20:21], 1.0 op_sel_hi:[1,0]
	v_mul_f32_e32 v34, 0xbfb8aa3b, v10
	v_exp_f32_e32 v34, v34
	v_fma_f32 v36, -v19, v35, 1.0
	v_fmac_f32_e32 v35, v36, v35
	v_div_scale_f32 v36, vcc, 1.0, v23, 1.0
	v_mul_f32_e32 v37, v36, v35
	v_fma_f32 v38, -v19, v37, v36
	v_fmac_f32_e32 v37, v38, v35
	v_fma_f32 v19, -v19, v37, v36
	v_div_scale_f32 v36, s[42:43], v22, v22, 1.0
	v_rcp_f32_e32 v38, v36
	v_div_fmas_f32 v19, v19, v35, v37
	v_div_fixup_f32 v23, v19, v23, 1.0
	v_pk_add_f32 v[32:33], v[32:33], 1.0 op_sel_hi:[1,0]
	v_fma_f32 v19, -v36, v38, 1.0
	v_fmac_f32_e32 v38, v19, v38
	v_div_scale_f32 v19, vcc, 1.0, v22, 1.0
	v_mul_f32_e32 v35, v19, v38
	v_fma_f32 v37, -v36, v35, v19
	v_fmac_f32_e32 v35, v37, v38
	v_fma_f32 v19, -v36, v35, v19
	v_div_scale_f32 v36, s[42:43], v21, v21, 1.0
	v_rcp_f32_e32 v37, v36
	v_div_fmas_f32 v19, v19, v38, v35
	v_div_fixup_f32 v22, v19, v22, 1.0
	v_fma_f32 v19, -v36, v37, 1.0
	v_fmac_f32_e32 v37, v19, v37
	v_div_scale_f32 v19, vcc, 1.0, v21, 1.0
	v_mul_f32_e32 v35, v19, v37
	v_fma_f32 v38, -v36, v35, v19
	v_fmac_f32_e32 v35, v38, v37
	v_fma_f32 v19, -v36, v35, v19
	v_div_scale_f32 v36, s[42:43], v20, v20, 1.0
	v_rcp_f32_e32 v38, v36
	v_div_fmas_f32 v19, v19, v37, v35
	v_mul_f32_e32 v35, 0xbfb8aa3b, v11
	v_div_fixup_f32 v21, v19, v21, 1.0
	v_fma_f32 v19, -v36, v38, 1.0
	v_exp_f32_e32 v35, v35
	v_fmac_f32_e32 v38, v19, v38
	v_div_scale_f32 v19, vcc, 1.0, v20, 1.0
	v_mul_f32_e32 v37, v19, v38
	v_fma_f32 v39, -v36, v37, v19
	v_fmac_f32_e32 v37, v39, v38
	v_pk_add_f32 v[34:35], v[34:35], 1.0 op_sel_hi:[1,0]
	v_fma_f32 v19, -v36, v37, v19
	v_div_scale_f32 v36, s[42:43], v35, v35, 1.0
	v_rcp_f32_e32 v39, v36
	v_div_fmas_f32 v19, v19, v38, v37
	v_div_fixup_f32 v20, v19, v20, 1.0
	v_fma_f32 v19, -v36, v39, 1.0
	v_fmac_f32_e32 v39, v19, v39
	v_div_scale_f32 v19, vcc, 1.0, v35, 1.0
	v_mul_f32_e32 v37, v19, v39
	v_fma_f32 v38, -v36, v37, v19
	v_fmac_f32_e32 v37, v38, v39
	v_fma_f32 v19, -v36, v37, v19
	v_div_scale_f32 v36, s[42:43], v34, v34, 1.0
	v_rcp_f32_e32 v38, v36
	v_div_fmas_f32 v19, v19, v39, v37
	v_div_fixup_f32 v35, v19, v35, 1.0
	v_fma_f32 v19, -v36, v38, 1.0
	v_fmac_f32_e32 v38, v19, v38
	v_div_scale_f32 v19, vcc, 1.0, v34, 1.0
	v_mul_f32_e32 v37, v19, v38
	v_fma_f32 v39, -v36, v37, v19
	v_fmac_f32_e32 v37, v39, v38
	v_fma_f32 v19, -v36, v37, v19
	v_div_scale_f32 v36, s[42:43], v33, v33, 1.0
	v_rcp_f32_e32 v39, v36
	v_div_fmas_f32 v19, v19, v38, v37
	v_div_fixup_f32 v34, v19, v34, 1.0
	v_fma_f32 v19, -v36, v39, 1.0
	v_fmac_f32_e32 v39, v19, v39
	v_div_scale_f32 v19, vcc, 1.0, v33, 1.0
	v_mul_f32_e32 v37, v19, v39
	v_fma_f32 v38, -v36, v37, v19
	v_fmac_f32_e32 v37, v38, v39
	v_fma_f32 v19, -v36, v37, v19
	v_div_scale_f32 v36, s[42:43], v32, v32, 1.0
	v_rcp_f32_e32 v38, v36
	v_div_fmas_f32 v19, v19, v39, v37
	v_div_fixup_f32 v33, v19, v33, 1.0
	v_fma_f32 v19, -v36, v38, 1.0
	v_fmac_f32_e32 v38, v19, v38
	v_div_scale_f32 v19, vcc, 1.0, v32, 1.0
	v_mul_f32_e32 v37, v19, v38
	v_fma_f32 v39, -v36, v37, v19
	v_fmac_f32_e32 v37, v39, v38
	v_fma_f32 v19, -v36, v37, v19
	v_div_fmas_f32 v19, v19, v38, v37
	v_mad_i64_i32 v[36:37], s[42:43], v18, s53, v[150:151]
	v_div_fixup_f32 v32, v19, v32, 1.0
	global_store_dwordx4 v[36:37], v[20:23], off sc1
	global_store_dwordx4 v[36:37], v[32:35], off offset:16 sc1

.LBB0_776:
	s_andn2_b64 vcc, exec, s[40:41]
	s_cbranch_vccnz .LBB0_778
	v_pk_mul_f32 v[22:23], v[14:15], s[18:19] op_sel_hi:[1,0]
	v_pk_mul_f32 v[20:21], v[12:13], s[18:19] op_sel_hi:[1,0]
	v_pk_mul_f32 v[32:33], v[10:11], s[18:19] op_sel_hi:[1,0]
	v_pk_mul_f32 v[34:35], v[8:9], s[18:19] op_sel_hi:[1,0]
	v_cvt_pk_bf16_f32 v20, v20, v21
	v_cvt_pk_bf16_f32 v21, v22, v23
	v_lshlrev_b32_e32 v138, 1, v146
	v_cvt_pk_bf16_f32 v22, v34, v35
	v_cvt_pk_bf16_f32 v23, v32, v33
	v_lshl_add_u64 v[32:33], s[10:11], 0, v[16:17]
	v_lshl_add_u64 v[32:33], s[14:15], 1, v[32:33]
	v_lshl_add_u64 v[32:33], v[32:33], 0, v[138:139]
	global_store_dwordx4 v[32:33], v[20:23], off offset:-3072 sc1

.LBB0_779:
	s_andn2_b64 vcc, exec, s[42:43]
	v_mad_i64_i32 v[18:19], s[40:41], v18, s61, 0
	s_cbranch_vccnz .LBB0_781
	v_cvt_pk_bf16_f32 v12, v12, v13
	v_cvt_pk_bf16_f32 v13, v14, v15
	v_cvt_pk_bf16_f32 v14, v8, v9
	v_lshl_add_u64 v[8:9], s[24:25], 0, v[18:19]
	v_lshl_add_u64 v[8:9], s[38:39], 1, v[8:9]
	v_lshlrev_b32_e32 v138, 1, v146
	v_lshl_add_u64 v[8:9], v[8:9], 0, v[138:139]
	v_cvt_pk_bf16_f32 v15, v10, v11
	global_store_dwordx4 v[8:9], v[12:15], off sc1

.LBB0_789:
	v_lshlrev_b32_e32 v138, 1, v146
	v_lshl_add_u64 v[4:5], v[12:13], 0, v[138:139]
	global_store_dwordx4 v[4:5], v[0:3], off offset:256 sc1
	s_and_b64 vcc, exec, s[6:7]
	s_mov_b64 s[6:7], -1
	s_cbranch_vccnz .LBB0_638

.LBB0_860:
	s_or_b64 exec, exec, s[30:31]
	v_bfi_b32 v11, s68, v11, v10
	v_bfi_b32 v10, s68, v9, v8
	v_bfi_b32 v15, s68, v15, v14
	v_bfi_b32 v14, s68, v13, v12
	v_pk_mul_f32 v[0:1], v[0:1], 0.5 op_sel_hi:[1,0]
	v_pk_add_f32 v[8:9], v[10:11], 1.0 op_sel_hi:[1,0]
	v_pk_mul_f32 v[4:5], v[4:5], 0.5 op_sel_hi:[1,0]
	v_pk_add_f32 v[12:13], v[14:15], 1.0 op_sel_hi:[1,0]
	v_pk_mul_f32 v[0:1], v[0:1], v[8:9]
	v_lshlrev_b64 v[8:9], 9, v[64:65]
	v_pk_mul_f32 v[4:5], v[4:5], v[12:13]
	v_bfi_b32 v13, s68, v23, v22
	v_bfi_b32 v12, s68, v19, v18
	v_lshl_add_u64 v[8:9], s[0:1], 0, v[8:9]
	v_pk_mul_f32 v[2:3], v[2:3], 0.5 op_sel_hi:[1,0]
	v_pk_add_f32 v[10:11], v[12:13], 1.0 op_sel_hi:[1,0]
	v_lshl_add_u64 v[8:9], v[8:9], 0, v[80:81]
	v_bfi_b32 v21, s68, v21, v20
	v_bfi_b32 v20, s68, v17, v16
	v_pk_mul_f32 v[2:3], v[2:3], v[10:11]
	v_lshl_add_u64 v[10:11], v[8:9], 0, s[18:19]
	v_add_co_u32_e32 v8, vcc, 0x16000, v8
	v_pk_mul_f32 v[6:7], v[6:7], 0.5 op_sel_hi:[1,0]
	v_pk_add_f32 v[14:15], v[20:21], 1.0 op_sel_hi:[1,0]
	v_addc_co_u32_e32 v9, vcc, 0, v9, vcc
	v_pk_mul_f32 v[6:7], v[6:7], v[14:15]
	s_and_b64 vcc, exec, s[2:3]
	s_mov_b32 s30, s20
	s_mov_b32 s70, s69
	s_mov_b64 s[36:37], s[28:29]
	s_mov_b64 s[34:35], s[22:23]
	global_store_dwordx4 v[8:9], v[4:7], off sc1
	global_store_dwordx4 v[10:11], v[0:3], off offset:16 sc1
	s_cbranch_vccnz .LBB0_1131

.LBB0_905:
	s_andn2_saveexec_b64 s[0:1], s[0:1]
	v_mul_f32_e32 v112, v111, v111
	v_fmamk_f32 v113, v112, 0xbbbac73d, v96
	v_fmaak_f32 v113, v112, v113, 0xbd5c1c4e
	v_fmaak_f32 v113, v112, v113, 0x3e088382
	v_fmaak_f32 v113, v112, v113, 0xbeaaaa99
	v_mul_f32_e64 v113, |v111|, v113
	v_fma_f32 v112, v112, v113, |v111|
	s_or_b64 exec, exec, s[0:1]
	v_bfi_b32 v80, s68, v98, v80
	v_mul_f32_e32 v68, 0.5, v68
	v_add_f32_e32 v80, 1.0, v80
	v_mul_f32_e32 v68, v68, v80
	v_bfi_b32 v80, s68, v102, v101
	v_mul_f32_e32 v69, 0.5, v69
	v_add_f32_e32 v80, 1.0, v80
	v_mul_f32_e32 v69, v69, v80
	v_bfi_b32 v80, s68, v106, v105
	v_mul_f32_e32 v70, 0.5, v70
	v_add_f32_e32 v80, 1.0, v80
	v_mul_f32_e32 v70, v70, v80
	v_bfi_b32 v80, s68, v110, v109
	v_mul_f32_e32 v71, 0.5, v71
	v_add_f32_e32 v80, 1.0, v80
	v_mul_f32_e32 v71, v71, v80
	v_bfi_b32 v80, s68, v100, v99
	v_mul_f32_e32 v64, 0.5, v64
	v_add_f32_e32 v80, 1.0, v80
	v_mul_f32_e32 v98, v64, v80
	v_mul_f32_e32 v64, 0.5, v65
	v_bfi_b32 v65, s68, v104, v103
	v_add_f32_e32 v65, 1.0, v65
	v_mul_f32_e32 v99, v64, v65
	v_bfi_b32 v65, s68, v108, v107
	v_mul_f32_e32 v64, 0.5, v66
	v_add_f32_e32 v65, 1.0, v65
	s_ashr_i32 s31, s30, 31
	v_bfi_b32 v66, s68, v112, v111
	v_mul_f32_e32 v100, v64, v65
	v_lshl_add_u32 v64, s70, 8, v83
	s_lshl_b64 s[0:1], s[30:31], 23
	v_mul_f32_e32 v65, 0.5, v67
	v_add_f32_e32 v66, 1.0, v66
	v_mul_f32_e32 v101, v65, v66
	v_ashrrev_i32_e32 v65, 31, v64
	s_add_u32 s0, s52, s0
	s_addc_u32 s1, s53, s1
	v_lshlrev_b64 v[66:67], 9, v[64:65]
	v_lshl_add_u64 v[66:67], s[0:1], 0, v[66:67]
	v_lshlrev_b32_e32 v80, 2, v82
	v_lshl_add_u64 v[66:67], v[66:67], 0, v[80:81]
	v_pk_add_f32 v[60:61], v[60:61], v[16:17]
	global_store_dwordx4 v[66:67], v[68:71], off sc1
	global_store_dwordx4 v[66:67], v[98:101], off offset:16 sc1
	v_mul_f32_e32 v66, 0x3d372713, v60
	v_mul_f32_e32 v66, v60, v66
	v_fma_f32 v66, v60, v66, v60
	v_mul_f32_e32 v66, 0x3f4c422a, v66
	v_cmp_nlt_f32_e64 s[30:31], |v66|, s61
	s_and_saveexec_b64 s[34:35], s[30:31]
	s_xor_b64 s[30:31], exec, s[34:35]
	s_cbranch_execz .LBB0_909
	v_add_f32_e64 v67, |v66|, |v66|
	v_mul_f32_e32 v68, 0x3fb8aa3b, v67
	v_rndne_f32_e32 v69, v68
	v_sub_f32_e32 v70, v68, v69
	v_fma_f32 v68, v67, s62, -v68
	v_fmac_f32_e32 v68, 0x32a5705f, v67
	v_add_f32_e32 v68, v70, v68
	v_cvt_i32_f32_e32 v69, v69
	v_exp_f32_e32 v68, v68
	v_cmp_ngt_f32_e32 vcc, s63, v67
	v_ldexp_f32 v68, v68, v69
	s_nop 0
	v_cndmask_b32_e32 v68, 0, v68, vcc
	v_cmp_nlt_f32_e32 vcc, s67, v67
	s_nop 1
	v_cndmask_b32_e32 v67, v97, v68, vcc
	v_add_f32_e32 v67, 1.0, v67
	v_rcp_f32_e32 v67, v67
	s_nop 0
	v_fma_f32 v67, v67, -2.0, 1.0

.LBB0_937:
	s_andn2_saveexec_b64 s[30:31], s[30:31]
	v_mul_f32_e32 v107, v106, v106
	v_fmamk_f32 v108, v107, 0xbbbac73d, v96
	v_fmaak_f32 v108, v107, v108, 0xbd5c1c4e
	v_fmaak_f32 v108, v107, v108, 0x3e088382
	v_fmaak_f32 v108, v107, v108, 0xbeaaaa99
	v_mul_f32_e64 v108, |v106|, v108
	v_fma_f32 v107, v107, v108, |v106|
	s_or_b64 exec, exec, s[30:31]
	v_bfi_b32 v66, s68, v67, v66
	v_mul_f32_e32 v60, 0.5, v60
	v_add_f32_e32 v66, 1.0, v66
	v_mul_f32_e32 v60, v60, v66
	v_bfi_b32 v66, s68, v71, v70
	v_mul_f32_e32 v61, 0.5, v61
	v_add_f32_e32 v66, 1.0, v66
	v_mul_f32_e32 v61, v61, v66
	v_bfi_b32 v66, s68, v101, v100
	v_mul_f32_e32 v62, 0.5, v62
	v_add_f32_e32 v66, 1.0, v66
	v_mul_f32_e32 v62, v62, v66
	v_bfi_b32 v66, s68, v105, v104
	v_mul_f32_e32 v63, 0.5, v63
	v_add_f32_e32 v66, 1.0, v66
	v_mul_f32_e32 v63, v63, v66
	v_bfi_b32 v66, s68, v69, v68
	v_mul_f32_e32 v56, 0.5, v56
	v_add_f32_e32 v66, 1.0, v66
	v_mul_f32_e32 v56, v56, v66
	v_bfi_b32 v66, s68, v99, v98
	v_mul_f32_e32 v57, 0.5, v57
	v_add_f32_e32 v66, 1.0, v66
	v_mul_f32_e32 v57, v57, v66
	v_bfi_b32 v66, s68, v103, v102
	v_mul_f32_e32 v58, 0.5, v58
	v_add_f32_e32 v66, 1.0, v66
	v_mul_f32_e32 v58, v58, v66
	v_bfi_b32 v66, s68, v107, v106
	v_mul_f32_e32 v59, 0.5, v59
	v_add_f32_e32 v66, 1.0, v66
	v_mul_f32_e32 v59, v59, v66
	v_or_b32_e32 v66, 16, v64
	v_ashrrev_i32_e32 v67, 31, v66
	v_lshlrev_b64 v[66:67], 9, v[66:67]
	v_lshl_add_u64 v[66:67], s[0:1], 0, v[66:67]
	v_lshl_add_u64 v[66:67], v[66:67], 0, v[80:81]
	v_pk_add_f32 v[52:53], v[52:53], v[16:17]
	global_store_dwordx4 v[66:67], v[60:63], off sc1
	global_store_dwordx4 v[66:67], v[56:59], off offset:16 sc1
	s_nop 1
	v_mul_f32_e32 v56, 0x3d372713, v52
	v_mul_f32_e32 v56, v52, v56
	v_fma_f32 v56, v52, v56, v52
	v_mul_f32_e32 v56, 0x3f4c422a, v56
	v_cmp_nlt_f32_e64 s[30:31], |v56|, s61
	s_and_saveexec_b64 s[34:35], s[30:31]
	s_xor_b64 s[30:31], exec, s[34:35]
	s_cbranch_execz .LBB0_941
	v_add_f32_e64 v57, |v56|, |v56|
	v_mul_f32_e32 v58, 0x3fb8aa3b, v57
	v_rndne_f32_e32 v59, v58
	v_sub_f32_e32 v60, v58, v59
	v_fma_f32 v58, v57, s62, -v58
	v_fmac_f32_e32 v58, 0x32a5705f, v57
	v_add_f32_e32 v58, v60, v58
	v_cvt_i32_f32_e32 v59, v59
	v_exp_f32_e32 v58, v58
	v_cmp_ngt_f32_e32 vcc, s63, v57
	v_ldexp_f32 v58, v58, v59
	s_nop 0
	v_cndmask_b32_e32 v58, 0, v58, vcc
	v_cmp_nlt_f32_e32 vcc, s67, v57
	s_nop 1
	v_cndmask_b32_e32 v57, v97, v58, vcc
	v_add_f32_e32 v57, 1.0, v57
	v_rcp_f32_e32 v57, v57
	s_nop 0
	v_fma_f32 v57, v57, -2.0, 1.0

.LBB0_969:
	s_andn2_saveexec_b64 s[30:31], s[30:31]
	v_mul_f32_e32 v99, v98, v98
	v_fmamk_f32 v100, v99, 0xbbbac73d, v96
	v_fmaak_f32 v100, v99, v100, 0xbd5c1c4e
	v_fmaak_f32 v100, v99, v100, 0x3e088382
	v_fmaak_f32 v100, v99, v100, 0xbeaaaa99
	v_mul_f32_e64 v100, |v98|, v100
	v_fma_f32 v99, v99, v100, |v98|
	s_or_b64 exec, exec, s[30:31]
	v_bfi_b32 v56, s68, v57, v56
	v_mul_f32_e32 v52, 0.5, v52
	v_add_f32_e32 v56, 1.0, v56
	v_mul_f32_e32 v52, v52, v56
	v_bfi_b32 v56, s68, v61, v60
	v_mul_f32_e32 v53, 0.5, v53
	v_add_f32_e32 v56, 1.0, v56
	v_mul_f32_e32 v53, v53, v56
	v_bfi_b32 v56, s68, v67, v66
	v_mul_f32_e32 v54, 0.5, v54
	v_add_f32_e32 v56, 1.0, v56
	v_mul_f32_e32 v54, v54, v56
	v_bfi_b32 v56, s68, v71, v70
	v_mul_f32_e32 v55, 0.5, v55
	v_add_f32_e32 v56, 1.0, v56
	v_mul_f32_e32 v55, v55, v56
	v_bfi_b32 v56, s68, v59, v58
	v_mul_f32_e32 v48, 0.5, v48
	v_add_f32_e32 v56, 1.0, v56
	v_mul_f32_e32 v48, v48, v56
	v_bfi_b32 v56, s68, v63, v62
	v_mul_f32_e32 v49, 0.5, v49
	v_add_f32_e32 v56, 1.0, v56
	v_mul_f32_e32 v49, v49, v56
	v_bfi_b32 v56, s68, v69, v68
	v_mul_f32_e32 v50, 0.5, v50
	v_add_f32_e32 v56, 1.0, v56
	v_mul_f32_e32 v50, v50, v56
	v_bfi_b32 v56, s68, v99, v98
	v_mul_f32_e32 v51, 0.5, v51
	v_add_f32_e32 v56, 1.0, v56
	v_mul_f32_e32 v51, v51, v56
	v_or_b32_e32 v56, 32, v64
	v_ashrrev_i32_e32 v57, 31, v56
	v_lshlrev_b64 v[56:57], 9, v[56:57]
	v_lshl_add_u64 v[56:57], s[0:1], 0, v[56:57]
	v_lshl_add_u64 v[56:57], v[56:57], 0, v[80:81]
	v_pk_add_f32 v[44:45], v[44:45], v[16:17]
	global_store_dwordx4 v[56:57], v[52:55], off sc1
	global_store_dwordx4 v[56:57], v[48:51], off offset:16 sc1
	s_nop 1
	v_mul_f32_e32 v48, 0x3d372713, v44
	v_mul_f32_e32 v48, v44, v48
	v_fma_f32 v48, v44, v48, v44
	v_mul_f32_e32 v48, 0x3f4c422a, v48
	v_cmp_nlt_f32_e64 s[30:31], |v48|, s61
	s_and_saveexec_b64 s[34:35], s[30:31]
	s_xor_b64 s[30:31], exec, s[34:35]
	s_cbranch_execz .LBB0_973
	v_add_f32_e64 v49, |v48|, |v48|
	v_mul_f32_e32 v50, 0x3fb8aa3b, v49
	v_rndne_f32_e32 v51, v50
	v_sub_f32_e32 v52, v50, v51
	v_fma_f32 v50, v49, s62, -v50
	v_fmac_f32_e32 v50, 0x32a5705f, v49
	v_add_f32_e32 v50, v52, v50
	v_cvt_i32_f32_e32 v51, v51
	v_exp_f32_e32 v50, v50
	v_cmp_ngt_f32_e32 vcc, s63, v49
	v_ldexp_f32 v50, v50, v51
	s_nop 0
	v_cndmask_b32_e32 v50, 0, v50, vcc
	v_cmp_nlt_f32_e32 vcc, s67, v49
	s_nop 1
	v_cndmask_b32_e32 v49, v97, v50, vcc
	v_add_f32_e32 v49, 1.0, v49
	v_rcp_f32_e32 v49, v49
	s_nop 0
	v_fma_f32 v49, v49, -2.0, 1.0

.LBB0_1001:
	s_andn2_saveexec_b64 s[30:31], s[30:31]
	v_mul_f32_e32 v63, v62, v62
	v_fmamk_f32 v66, v63, 0xbbbac73d, v96
	v_fmaak_f32 v66, v63, v66, 0xbd5c1c4e
	v_fmaak_f32 v66, v63, v66, 0x3e088382
	v_fmaak_f32 v66, v63, v66, 0xbeaaaa99
	v_mul_f32_e64 v66, |v62|, v66
	v_fma_f32 v63, v63, v66, |v62|
	s_or_b64 exec, exec, s[30:31]
	v_bfi_b32 v48, s68, v49, v48
	v_mul_f32_e32 v44, 0.5, v44
	v_add_f32_e32 v48, 1.0, v48
	v_mul_f32_e32 v44, v44, v48
	v_bfi_b32 v48, s68, v53, v52
	v_mul_f32_e32 v45, 0.5, v45
	v_add_f32_e32 v48, 1.0, v48
	v_mul_f32_e32 v45, v45, v48
	v_bfi_b32 v48, s68, v57, v56
	v_mul_f32_e32 v46, 0.5, v46
	v_add_f32_e32 v48, 1.0, v48
	v_mul_f32_e32 v46, v46, v48
	v_bfi_b32 v48, s68, v61, v60
	v_mul_f32_e32 v47, 0.5, v47
	v_add_f32_e32 v48, 1.0, v48
	v_mul_f32_e32 v47, v47, v48
	v_bfi_b32 v48, s68, v51, v50
	v_mul_f32_e32 v40, 0.5, v40
	v_add_f32_e32 v48, 1.0, v48
	v_mul_f32_e32 v40, v40, v48
	v_bfi_b32 v48, s68, v55, v54
	v_mul_f32_e32 v41, 0.5, v41
	v_add_f32_e32 v48, 1.0, v48
	v_mul_f32_e32 v41, v41, v48
	v_bfi_b32 v48, s68, v59, v58
	v_mul_f32_e32 v42, 0.5, v42
	v_add_f32_e32 v48, 1.0, v48
	v_mul_f32_e32 v42, v42, v48
	v_bfi_b32 v48, s68, v63, v62
	v_mul_f32_e32 v43, 0.5, v43
	v_add_f32_e32 v48, 1.0, v48
	v_mul_f32_e32 v43, v43, v48
	v_or_b32_e32 v48, 48, v64
	v_ashrrev_i32_e32 v49, 31, v48
	v_lshlrev_b64 v[48:49], 9, v[48:49]
	v_lshl_add_u64 v[48:49], s[0:1], 0, v[48:49]
	v_lshl_add_u64 v[48:49], v[48:49], 0, v[80:81]
	v_pk_add_f32 v[36:37], v[36:37], v[16:17]
	global_store_dwordx4 v[48:49], v[44:47], off sc1
	global_store_dwordx4 v[48:49], v[40:43], off offset:16 sc1
	s_nop 1
	v_mul_f32_e32 v40, 0x3d372713, v36
	v_mul_f32_e32 v40, v36, v40
	v_fma_f32 v40, v36, v40, v36
	v_mul_f32_e32 v40, 0x3f4c422a, v40
	v_cmp_nlt_f32_e64 s[30:31], |v40|, s61
	s_and_saveexec_b64 s[34:35], s[30:31]
	s_xor_b64 s[30:31], exec, s[34:35]
	s_cbranch_execz .LBB0_1005
	v_add_f32_e64 v41, |v40|, |v40|
	v_mul_f32_e32 v42, 0x3fb8aa3b, v41
	v_rndne_f32_e32 v43, v42
	v_sub_f32_e32 v44, v42, v43
	v_fma_f32 v42, v41, s62, -v42
	v_fmac_f32_e32 v42, 0x32a5705f, v41
	v_add_f32_e32 v42, v44, v42
	v_cvt_i32_f32_e32 v43, v43
	v_exp_f32_e32 v42, v42
	v_cmp_ngt_f32_e32 vcc, s63, v41
	v_ldexp_f32 v42, v42, v43
	s_nop 0
	v_cndmask_b32_e32 v42, 0, v42, vcc
	v_cmp_nlt_f32_e32 vcc, s67, v41
	s_nop 1
	v_cndmask_b32_e32 v41, v97, v42, vcc
	v_add_f32_e32 v41, 1.0, v41
	v_rcp_f32_e32 v41, v41
	s_nop 0
	v_fma_f32 v41, v41, -2.0, 1.0

.LBB0_1033:
	s_andn2_saveexec_b64 s[30:31], s[30:31]
	v_mul_f32_e32 v55, v54, v54
	v_fmamk_f32 v56, v55, 0xbbbac73d, v96
	v_fmaak_f32 v56, v55, v56, 0xbd5c1c4e
	v_fmaak_f32 v56, v55, v56, 0x3e088382
	v_fmaak_f32 v56, v55, v56, 0xbeaaaa99
	v_mul_f32_e64 v56, |v54|, v56
	v_fma_f32 v55, v55, v56, |v54|
	s_or_b64 exec, exec, s[30:31]
	v_bfi_b32 v40, s68, v41, v40
	v_mul_f32_e32 v36, 0.5, v36
	v_add_f32_e32 v40, 1.0, v40
	v_mul_f32_e32 v36, v36, v40
	v_bfi_b32 v40, s68, v45, v44
	v_mul_f32_e32 v37, 0.5, v37
	v_add_f32_e32 v40, 1.0, v40
	v_mul_f32_e32 v37, v37, v40
	v_bfi_b32 v40, s68, v49, v48
	v_mul_f32_e32 v38, 0.5, v38
	v_add_f32_e32 v40, 1.0, v40
	v_mul_f32_e32 v38, v38, v40
	v_bfi_b32 v40, s68, v53, v52
	v_mul_f32_e32 v39, 0.5, v39
	v_add_f32_e32 v40, 1.0, v40
	v_mul_f32_e32 v39, v39, v40
	v_bfi_b32 v40, s68, v43, v42
	v_mul_f32_e32 v32, 0.5, v32
	v_add_f32_e32 v40, 1.0, v40
	v_mul_f32_e32 v32, v32, v40
	v_bfi_b32 v40, s68, v47, v46
	v_mul_f32_e32 v33, 0.5, v33
	v_add_f32_e32 v40, 1.0, v40
	v_mul_f32_e32 v33, v33, v40
	v_bfi_b32 v40, s68, v51, v50
	v_mul_f32_e32 v34, 0.5, v34
	v_add_f32_e32 v40, 1.0, v40
	v_mul_f32_e32 v34, v34, v40
	v_bfi_b32 v40, s68, v55, v54
	v_mul_f32_e32 v35, 0.5, v35
	v_add_f32_e32 v40, 1.0, v40
	v_mul_f32_e32 v35, v35, v40
	v_lshlrev_b64 v[40:41], 9, v[64:65]
	v_lshl_add_u64 v[40:41], s[0:1], 0, v[40:41]
	v_lshl_add_u64 v[40:41], v[40:41], 0, v[80:81]
	v_lshl_add_u64 v[42:43], v[40:41], 0, s[10:11]
	v_add_co_u32_e32 v40, vcc, s49, v40
	v_pk_add_f32 v[28:29], v[28:29], v[16:17]
	s_nop 0
	v_addc_co_u32_e32 v41, vcc, 0, v41, vcc
	global_store_dwordx4 v[40:41], v[36:39], off sc1
	global_store_dwordx4 v[42:43], v[32:35], off offset:16 sc1
	s_nop 1
	v_mul_f32_e32 v32, 0x3d372713, v28
	v_mul_f32_e32 v32, v28, v32
	v_fma_f32 v32, v28, v32, v28
	v_mul_f32_e32 v32, 0x3f4c422a, v32
	v_cmp_nlt_f32_e64 s[30:31], |v32|, s61
	s_and_saveexec_b64 s[34:35], s[30:31]
	s_xor_b64 s[30:31], exec, s[34:35]
	s_cbranch_execz .LBB0_1037
	v_add_f32_e64 v33, |v32|, |v32|
	v_mul_f32_e32 v34, 0x3fb8aa3b, v33
	v_rndne_f32_e32 v35, v34
	v_sub_f32_e32 v36, v34, v35
	v_fma_f32 v34, v33, s62, -v34
	v_fmac_f32_e32 v34, 0x32a5705f, v33
	v_add_f32_e32 v34, v36, v34
	v_cvt_i32_f32_e32 v35, v35
	v_exp_f32_e32 v34, v34
	v_cmp_ngt_f32_e32 vcc, s63, v33
	v_ldexp_f32 v34, v34, v35
	s_nop 0
	v_cndmask_b32_e32 v34, 0, v34, vcc
	v_cmp_nlt_f32_e32 vcc, s67, v33
	s_nop 1
	v_cndmask_b32_e32 v33, v97, v34, vcc
	v_add_f32_e32 v33, 1.0, v33
	v_rcp_f32_e32 v33, v33
	s_nop 0
	v_fma_f32 v33, v33, -2.0, 1.0

.LBB0_1065:
	s_andn2_saveexec_b64 s[30:31], s[30:31]
	v_mul_f32_e32 v47, v46, v46
	v_fmamk_f32 v48, v47, 0xbbbac73d, v96
	v_fmaak_f32 v48, v47, v48, 0xbd5c1c4e
	v_fmaak_f32 v48, v47, v48, 0x3e088382
	v_fmaak_f32 v48, v47, v48, 0xbeaaaa99
	v_mul_f32_e64 v48, |v46|, v48
	v_fma_f32 v47, v47, v48, |v46|
	s_or_b64 exec, exec, s[30:31]
	v_bfi_b32 v32, s68, v33, v32
	v_mul_f32_e32 v28, 0.5, v28
	v_add_f32_e32 v32, 1.0, v32
	v_mul_f32_e32 v28, v28, v32
	v_bfi_b32 v32, s68, v37, v36
	v_mul_f32_e32 v29, 0.5, v29
	v_add_f32_e32 v32, 1.0, v32
	v_mul_f32_e32 v29, v29, v32
	v_bfi_b32 v32, s68, v41, v40
	v_mul_f32_e32 v30, 0.5, v30
	v_add_f32_e32 v32, 1.0, v32
	v_mul_f32_e32 v30, v30, v32
	v_bfi_b32 v32, s68, v45, v44
	v_mul_f32_e32 v31, 0.5, v31
	v_add_f32_e32 v32, 1.0, v32
	v_mul_f32_e32 v31, v31, v32
	v_bfi_b32 v32, s68, v35, v34
	v_mul_f32_e32 v24, 0.5, v24
	v_add_f32_e32 v32, 1.0, v32
	v_mul_f32_e32 v24, v24, v32
	v_bfi_b32 v32, s68, v39, v38
	v_mul_f32_e32 v25, 0.5, v25
	v_add_f32_e32 v32, 1.0, v32
	v_mul_f32_e32 v25, v25, v32
	v_bfi_b32 v32, s68, v43, v42
	v_mul_f32_e32 v26, 0.5, v26
	v_add_f32_e32 v32, 1.0, v32
	v_mul_f32_e32 v26, v26, v32
	v_bfi_b32 v32, s68, v47, v46
	v_mul_f32_e32 v27, 0.5, v27
	v_add_f32_e32 v32, 1.0, v32
	v_mul_f32_e32 v27, v27, v32
	v_lshlrev_b64 v[32:33], 9, v[64:65]
	v_lshl_add_u64 v[32:33], s[0:1], 0, v[32:33]
	v_lshl_add_u64 v[32:33], v[32:33], 0, v[80:81]
	v_lshl_add_u64 v[34:35], v[32:33], 0, s[12:13]
	v_add_co_u32_e32 v32, vcc, s50, v32
	v_pk_add_f32 v[20:21], v[20:21], v[16:17]
	s_nop 0
	v_addc_co_u32_e32 v33, vcc, 0, v33, vcc
	global_store_dwordx4 v[32:33], v[28:31], off sc1
	global_store_dwordx4 v[34:35], v[24:27], off offset:16 sc1
	s_nop 1
	v_mul_f32_e32 v24, 0x3d372713, v20
	v_mul_f32_e32 v24, v20, v24
	v_fma_f32 v24, v20, v24, v20
	v_mul_f32_e32 v24, 0x3f4c422a, v24
	v_cmp_nlt_f32_e64 s[30:31], |v24|, s61
	s_and_saveexec_b64 s[34:35], s[30:31]
	s_xor_b64 s[30:31], exec, s[34:35]
	s_cbranch_execz .LBB0_1069
	v_add_f32_e64 v25, |v24|, |v24|
	v_mul_f32_e32 v26, 0x3fb8aa3b, v25
	v_rndne_f32_e32 v27, v26
	v_sub_f32_e32 v28, v26, v27
	v_fma_f32 v26, v25, s62, -v26
	v_fmac_f32_e32 v26, 0x32a5705f, v25
	v_add_f32_e32 v26, v28, v26
	v_cvt_i32_f32_e32 v27, v27
	v_exp_f32_e32 v26, v26
	v_cmp_ngt_f32_e32 vcc, s63, v25
	v_ldexp_f32 v26, v26, v27
	s_nop 0
	v_cndmask_b32_e32 v26, 0, v26, vcc
	v_cmp_nlt_f32_e32 vcc, s67, v25
	s_nop 1
	v_cndmask_b32_e32 v25, v97, v26, vcc
	v_add_f32_e32 v25, 1.0, v25
	v_rcp_f32_e32 v25, v25
	s_nop 0
	v_fma_f32 v25, v25, -2.0, 1.0

.LBB0_1097:
	s_andn2_saveexec_b64 s[30:31], s[30:31]
	v_mul_f32_e32 v39, v38, v38
	v_fmamk_f32 v40, v39, 0xbbbac73d, v96
	v_fmaak_f32 v40, v39, v40, 0xbd5c1c4e
	v_fmaak_f32 v40, v39, v40, 0x3e088382
	v_fmaak_f32 v40, v39, v40, 0xbeaaaa99
	v_mul_f32_e64 v40, |v38|, v40
	v_fma_f32 v39, v39, v40, |v38|
	s_or_b64 exec, exec, s[30:31]
	v_bfi_b32 v24, s68, v25, v24
	v_mul_f32_e32 v20, 0.5, v20
	v_add_f32_e32 v24, 1.0, v24
	v_mul_f32_e32 v20, v20, v24
	v_bfi_b32 v24, s68, v29, v28
	v_mul_f32_e32 v21, 0.5, v21
	v_add_f32_e32 v24, 1.0, v24
	v_mul_f32_e32 v21, v21, v24
	v_bfi_b32 v24, s68, v33, v32
	v_mul_f32_e32 v22, 0.5, v22
	v_add_f32_e32 v24, 1.0, v24
	v_mul_f32_e32 v22, v22, v24
	v_bfi_b32 v24, s68, v37, v36
	v_mul_f32_e32 v23, 0.5, v23
	v_add_f32_e32 v24, 1.0, v24
	v_mul_f32_e32 v23, v23, v24
	v_bfi_b32 v24, s68, v27, v26
	v_mul_f32_e32 v12, 0.5, v12
	v_add_f32_e32 v24, 1.0, v24
	v_mul_f32_e32 v12, v12, v24
	v_bfi_b32 v24, s68, v31, v30
	v_mul_f32_e32 v13, 0.5, v13
	v_add_f32_e32 v24, 1.0, v24
	v_mul_f32_e32 v13, v13, v24
	v_bfi_b32 v24, s68, v35, v34
	v_mul_f32_e32 v14, 0.5, v14
	v_add_f32_e32 v24, 1.0, v24
	v_mul_f32_e32 v14, v14, v24
	v_bfi_b32 v24, s68, v39, v38
	v_mul_f32_e32 v15, 0.5, v15
	v_add_f32_e32 v24, 1.0, v24
	v_mul_f32_e32 v15, v15, v24
	v_lshlrev_b64 v[24:25], 9, v[64:65]
	v_lshl_add_u64 v[24:25], s[0:1], 0, v[24:25]
	v_lshl_add_u64 v[24:25], v[24:25], 0, v[80:81]
	v_lshl_add_u64 v[26:27], v[24:25], 0, s[14:15]
	v_add_co_u32_e32 v24, vcc, s51, v24
	v_pk_add_f32 v[4:5], v[4:5], v[16:17]
	s_nop 0
	v_addc_co_u32_e32 v25, vcc, 0, v25, vcc
	global_store_dwordx4 v[24:25], v[20:23], off sc1
	global_store_dwordx4 v[26:27], v[12:15], off offset:16 sc1
	s_nop 1
	v_mul_f32_e32 v12, 0x3d372713, v4
	v_mul_f32_e32 v12, v4, v12
	v_fma_f32 v12, v4, v12, v4
	v_mul_f32_e32 v12, 0x3f4c422a, v12
	v_cmp_nlt_f32_e64 s[30:31], |v12|, s61
	s_and_saveexec_b64 s[34:35], s[30:31]
	s_xor_b64 s[30:31], exec, s[34:35]
	s_cbranch_execz .LBB0_1101
	v_add_f32_e64 v13, |v12|, |v12|
	v_mul_f32_e32 v14, 0x3fb8aa3b, v13
	v_rndne_f32_e32 v15, v14
	v_sub_f32_e32 v16, v14, v15
	v_fma_f32 v14, v13, s62, -v14
	v_fmac_f32_e32 v14, 0x32a5705f, v13
	v_add_f32_e32 v14, v16, v14
	v_cvt_i32_f32_e32 v15, v15
	v_exp_f32_e32 v14, v14
	v_cmp_ngt_f32_e32 vcc, s63, v13
	v_ldexp_f32 v14, v14, v15
	s_nop 0
	v_cndmask_b32_e32 v14, 0, v14, vcc
	v_cmp_nlt_f32_e32 vcc, s67, v13
	s_nop 1
	v_cndmask_b32_e32 v13, v97, v14, vcc
	v_add_f32_e32 v13, 1.0, v13
	v_rcp_f32_e32 v13, v13
	s_nop 0
	v_fma_f32 v13, v13, -2.0, 1.0

.LBB0_1269:
	ds_bpermute_b32 v0, v155, v121
	v_mov_b32_e32 v123, v32
	v_mov_b32_e32 v125, v32
	v_mov_b32_e32 v127, v32
	v_mov_b32_e32 v129, v32
	s_waitcnt lgkmcnt(0)
	v_add_f32_e32 v0, v121, v0
	v_div_scale_f32 v1, s[0:1], v0, v0, v106
	v_rcp_f32_e32 v2, v1
	s_ashr_i32 s1, s39, 31
	s_add_u32 s0, s46, s39
	s_addc_u32 s1, s47, s1
	v_fma_f32 v3, -v1, v2, 1.0
	v_fmac_f32_e32 v2, v3, v2
	v_div_scale_f32 v3, vcc, v106, v0, v106
	v_mul_f32_e32 v4, v3, v2
	v_fma_f32 v5, -v1, v4, v3
	v_fmac_f32_e32 v4, v5, v2
	v_fma_f32 v1, -v1, v4, v3
	v_div_fmas_f32 v1, v1, v2, v4
	ds_read_b128 v[2:5], v210
	v_div_fixup_f32 v0, v1, v0, v106
	s_or_b64 s[0:1], s[0:1], s[60:61]
	s_lshl_b64 s[0:1], s[0:1], 11
	s_add_u32 s2, s26, s0
	s_waitcnt lgkmcnt(0)
	v_pk_fma_f32 v[2:3], v[64:65], v[0:1], v[2:3] op_sel_hi:[1,0,1]
	v_pk_fma_f32 v[4:5], v[66:67], v[0:1], v[4:5] op_sel_hi:[1,0,1]
	v_cvt_pk_bf16_f32 v2, v2, v3
	v_cvt_pk_bf16_f32 v3, v4, v5
	ds_read_b128 v[4:7], v210 offset:1024
	s_addc_u32 s3, s27, s1
	s_lshl_b64 s[0:1], s[48:49], 1
	s_add_u32 s0, s2, s0
	s_addc_u32 s1, s3, s1
	s_waitcnt lgkmcnt(0)
	v_pk_fma_f32 v[4:5], v[68:69], v[0:1], v[4:5] op_sel_hi:[1,0,1]
	v_mov_b32_e32 v121, v32
	v_cvt_pk_bf16_f32 v8, v4, v5
	v_pk_fma_f32 v[4:5], v[70:71], v[0:1], v[6:7] op_sel_hi:[1,0,1]
	s_add_i32 s38, s38, 1
	v_cvt_pk_bf16_f32 v9, v4, v5
	ds_read_b128 v[4:7], v210 offset:2048
	s_cmp_eq_u32 s38, s72
	s_waitcnt lgkmcnt(0)
	v_pk_fma_f32 v[4:5], v[72:73], v[0:1], v[4:5] op_sel_hi:[1,0,1]
	s_nop 0
	v_cvt_pk_bf16_f32 v10, v4, v5
	v_pk_fma_f32 v[4:5], v[74:75], v[0:1], v[6:7] op_sel_hi:[1,0,1]
	s_nop 0
	v_cvt_pk_bf16_f32 v11, v4, v5
	ds_read_b128 v[4:7], v210 offset:3072
	s_waitcnt lgkmcnt(0)
	v_pk_fma_f32 v[4:5], v[76:77], v[0:1], v[4:5] op_sel_hi:[1,0,1]
	s_nop 0
	v_cvt_pk_bf16_f32 v12, v4, v5
	v_pk_fma_f32 v[4:5], v[78:79], v[0:1], v[6:7] op_sel_hi:[1,0,1]
	s_nop 0
	v_cvt_pk_bf16_f32 v13, v4, v5
	ds_read_b128 v[4:7], v210 offset:4096
	s_waitcnt lgkmcnt(0)
	v_pk_fma_f32 v[4:5], v[48:49], v[0:1], v[4:5] op_sel_hi:[1,0,1]
	s_nop 0
	v_cvt_pk_bf16_f32 v14, v4, v5
	v_pk_fma_f32 v[4:5], v[50:51], v[0:1], v[6:7] op_sel_hi:[1,0,1]
	s_nop 0
	v_cvt_pk_bf16_f32 v15, v4, v5
	ds_read_b128 v[4:7], v210 offset:5120
	s_waitcnt lgkmcnt(0)
	v_pk_fma_f32 v[4:5], v[52:53], v[0:1], v[4:5] op_sel_hi:[1,0,1]
	s_nop 0
	v_cvt_pk_bf16_f32 v16, v4, v5
	v_pk_fma_f32 v[4:5], v[54:55], v[0:1], v[6:7] op_sel_hi:[1,0,1]
	s_nop 0
	v_cvt_pk_bf16_f32 v17, v4, v5
	ds_read_b128 v[4:7], v210 offset:6144
	s_waitcnt lgkmcnt(0)
	v_pk_fma_f32 v[4:5], v[56:57], v[0:1], v[4:5] op_sel_hi:[1,0,1]
	s_nop 0
	v_cvt_pk_bf16_f32 v18, v4, v5
	v_pk_fma_f32 v[4:5], v[58:59], v[0:1], v[6:7] op_sel_hi:[1,0,1]
	s_nop 0
	v_cvt_pk_bf16_f32 v19, v4, v5
	ds_read_b128 v[4:7], v210 offset:7168
	s_waitcnt lgkmcnt(0)
	v_pk_fma_f32 v[4:5], v[60:61], v[0:1], v[4:5] op_sel_hi:[1,0,1]
	v_pk_fma_f32 v[0:1], v[62:63], v[0:1], v[6:7] op_sel_hi:[1,0,1]
	v_cvt_pk_bf16_f32 v4, v4, v5
	v_cvt_pk_bf16_f32 v5, v0, v1
	ds_write2_b64 v206, v[2:3], v[8:9] offset1:2
	ds_write2_b64 v206, v[10:11], v[12:13] offset0:4 offset1:6
	ds_write2_b64 v206, v[14:15], v[16:17] offset0:8 offset1:10
	ds_write2_b64 v206, v[18:19], v[4:5] offset0:12 offset1:14
	s_waitcnt lgkmcnt(0)
	ds_read_b128 v[0:3], v207
	v_lshl_add_u64 v[4:5], s[0:1], 0, v[120:121]
	v_lshl_add_u64 v[6:7], v[4:5], 0, v[122:123]
	s_waitcnt lgkmcnt(0)
	global_store_dwordx4 v[6:7], v[0:3], off sc1
	ds_read_b128 v[0:3], v208
	v_lshl_add_u64 v[6:7], v[4:5], 0, v[124:125]
	s_waitcnt lgkmcnt(0)
	global_store_dwordx4 v[6:7], v[0:3], off sc1
	ds_read_b128 v[0:3], v208 offset:1152
	v_lshl_add_u64 v[6:7], v[4:5], 0, v[126:127]
	v_lshl_add_u64 v[4:5], v[4:5], 0, v[128:129]
	s_waitcnt lgkmcnt(0)
	global_store_dwordx4 v[6:7], v[0:3], off sc1
	ds_read_b128 v[0:3], v208 offset:2304
	s_waitcnt lgkmcnt(0)
	global_store_dwordx4 v[4:5], v[0:3], off sc1
	s_cbranch_scc1 .LBB0_1476

.LBB0_1551:
	ds_read_b128 v[128:131], v190
	ds_read_b128 v[132:135], v190 offset:1024
	ds_read_b128 v[136:139], v190 offset:2048
	ds_read_b128 v[140:143], v190 offset:3072
	s_add_u32 s22, s20, 0xfffc0080
	s_addc_u32 s23, s21, -1
	s_cmp_eq_u32 s51, 12
	s_cselect_b32 s29, s13, s23
	s_cselect_b32 s28, s19, s22
	s_cselect_b32 s23, s11, s50
	s_cselect_b32 s22, s48, s49
	v_lshl_add_u64 v[184:185], s[20:21], 0, v[160:161]
	s_add_i32 m0, s36, 0xc000
	ds_read_b128 v[144:147], v191
	ds_read_b128 v[148:151], v191 offset:1024
	ds_read_b128 v[168:171], v191 offset:2048
	ds_read_b128 v[172:175], v191 offset:3072
	ds_read_b128 v[176:179], v191 offset:4096
	ds_read_b128 v[180:183], v191 offset:5120
	ds_read_b128 v[194:197], v191 offset:6144
	ds_read_b128 v[198:201], v191 offset:7168
	global_load_lds_dwordx4 v[184:185], off
	v_lshl_add_u64 v[184:185], s[20:21], 0, v[162:163]
	s_add_i32 m0, s36, 0xe000
	s_nop 0
	global_load_lds_dwordx4 v[184:185], off
	s_waitcnt lgkmcnt(8)
	s_barrier
	s_waitcnt lgkmcnt(0)
	s_setprio 1
	s_waitcnt lgkmcnt(0)
	v_mfma_f32_16x16x32_bf16 v[124:127], v[128:131], v[144:147], v[124:127]
	v_mfma_f32_16x16x32_bf16 v[120:123], v[136:139], v[144:147], v[120:123]
	v_mfma_f32_16x16x32_bf16 v[108:111], v[128:131], v[168:171], v[108:111]
	v_mfma_f32_16x16x32_bf16 v[104:107], v[136:139], v[168:171], v[104:107]
	v_mfma_f32_16x16x32_bf16 v[92:95], v[128:131], v[176:179], v[92:95]
	v_mfma_f32_16x16x32_bf16 v[88:91], v[136:139], v[176:179], v[88:91]
	v_mfma_f32_16x16x32_bf16 v[76:79], v[128:131], v[194:197], v[76:79]
	v_mfma_f32_16x16x32_bf16 v[72:75], v[136:139], v[194:197], v[72:75]
	v_mfma_f32_16x16x32_bf16 v[124:127], v[132:135], v[148:151], v[124:127]
	v_mfma_f32_16x16x32_bf16 v[120:123], v[140:143], v[148:151], v[120:123]
	v_mfma_f32_16x16x32_bf16 v[108:111], v[132:135], v[172:175], v[108:111]
	v_mfma_f32_16x16x32_bf16 v[104:107], v[140:143], v[172:175], v[104:107]
	v_mfma_f32_16x16x32_bf16 v[92:95], v[132:135], v[180:183], v[92:95]
	v_mfma_f32_16x16x32_bf16 v[88:91], v[140:143], v[180:183], v[88:91]
	v_mfma_f32_16x16x32_bf16 v[76:79], v[132:135], v[198:201], v[76:79]
	v_mfma_f32_16x16x32_bf16 v[72:75], v[140:143], v[198:201], v[72:75]
	s_setprio 0
	s_barrier
	s_add_i32 s52, s45, s35
	v_lshl_add_u64 v[184:185], s[22:23], 0, v[154:155]
	s_mov_b32 m0, s52
	ds_read_b128 v[202:205], v192
	ds_read_b128 v[206:209], v192 offset:1024
	ds_read_b128 v[210:213], v192 offset:2048
	ds_read_b128 v[214:217], v192 offset:3072
	global_load_lds_dwordx4 v[184:185], off
	v_lshl_add_u64 v[218:219], s[22:23], 0, v[158:159]
	s_add_i32 m0, s52, 0x2000
	s_nop 0
	global_load_lds_dwordx4 v[218:219], off
	s_barrier
	s_waitcnt lgkmcnt(0)
	s_setprio 1
	s_waitcnt lgkmcnt(0)
	v_mfma_f32_16x16x32_bf16 v[116:119], v[202:205], v[144:147], v[116:119]
	v_mfma_f32_16x16x32_bf16 v[112:115], v[210:213], v[144:147], v[112:115]
	v_mfma_f32_16x16x32_bf16 v[100:103], v[202:205], v[168:171], v[100:103]
	v_mfma_f32_16x16x32_bf16 v[96:99], v[210:213], v[168:171], v[96:99]
	v_mfma_f32_16x16x32_bf16 v[84:87], v[202:205], v[176:179], v[84:87]
	v_mfma_f32_16x16x32_bf16 v[80:83], v[210:213], v[176:179], v[80:83]
	v_mfma_f32_16x16x32_bf16 v[68:71], v[202:205], v[194:197], v[68:71]
	v_mfma_f32_16x16x32_bf16 v[64:67], v[210:213], v[194:197], v[64:67]
	v_mfma_f32_16x16x32_bf16 v[116:119], v[206:209], v[148:151], v[116:119]
	v_mfma_f32_16x16x32_bf16 v[112:115], v[214:217], v[148:151], v[112:115]
	v_mfma_f32_16x16x32_bf16 v[100:103], v[206:209], v[172:175], v[100:103]
	v_mfma_f32_16x16x32_bf16 v[96:99], v[214:217], v[172:175], v[96:99]
	v_mfma_f32_16x16x32_bf16 v[84:87], v[206:209], v[180:183], v[84:87]
	v_mfma_f32_16x16x32_bf16 v[80:83], v[214:217], v[180:183], v[80:83]
	v_mfma_f32_16x16x32_bf16 v[68:71], v[206:209], v[198:201], v[68:71]
	v_mfma_f32_16x16x32_bf16 v[64:67], v[214:217], v[198:201], v[64:67]
	s_setprio 0
	s_mov_b32 m0, s36
	v_lshl_add_u64 v[220:221], s[28:29], 0, v[152:153]
	s_barrier
	ds_read_b128 v[144:147], v191 offset:16384
	ds_read_b128 v[148:151], v191 offset:17408
	ds_read_b128 v[168:171], v191 offset:18432
	ds_read_b128 v[172:175], v191 offset:19456
	ds_read_b128 v[176:179], v191 offset:20480
	ds_read_b128 v[180:183], v191 offset:21504
	ds_read_b128 v[194:197], v191 offset:22528
	ds_read_b128 v[198:201], v191 offset:23552
	global_load_lds_dwordx4 v[220:221], off
	v_lshl_add_u64 v[222:223], s[28:29], 0, v[156:157]
	s_mov_b32 m0, s37
	s_nop 0
	global_load_lds_dwordx4 v[222:223], off
	s_barrier
	s_waitcnt lgkmcnt(0)
	s_setprio 1
	s_waitcnt lgkmcnt(0)
	v_mfma_f32_16x16x32_bf16 v[60:63], v[128:131], v[144:147], v[60:63]
	v_mfma_f32_16x16x32_bf16 v[56:59], v[136:139], v[144:147], v[56:59]
	v_mfma_f32_16x16x32_bf16 v[44:47], v[128:131], v[168:171], v[44:47]
	v_mfma_f32_16x16x32_bf16 v[40:43], v[136:139], v[168:171], v[40:43]
	v_mfma_f32_16x16x32_bf16 v[28:31], v[128:131], v[176:179], v[28:31]
	v_mfma_f32_16x16x32_bf16 v[24:27], v[136:139], v[176:179], v[24:27]
	v_mfma_f32_16x16x32_bf16 v[12:15], v[128:131], v[194:197], v[12:15]
	v_mfma_f32_16x16x32_bf16 v[8:11], v[136:139], v[194:197], v[8:11]
	v_mfma_f32_16x16x32_bf16 v[60:63], v[132:135], v[148:151], v[60:63]
	v_mfma_f32_16x16x32_bf16 v[56:59], v[140:143], v[148:151], v[56:59]
	v_mfma_f32_16x16x32_bf16 v[44:47], v[132:135], v[172:175], v[44:47]
	v_mfma_f32_16x16x32_bf16 v[40:43], v[140:143], v[172:175], v[40:43]
	v_mfma_f32_16x16x32_bf16 v[28:31], v[132:135], v[180:183], v[28:31]
	v_mfma_f32_16x16x32_bf16 v[24:27], v[140:143], v[180:183], v[24:27]
	v_mfma_f32_16x16x32_bf16 v[12:15], v[132:135], v[198:201], v[12:15]
	v_mfma_f32_16x16x32_bf16 v[8:11], v[140:143], v[198:201], v[8:11]
	s_setprio 0
	s_barrier
	s_add_u32 s52, s22, 0x40000
	s_addc_u32 s53, s23, 0
	s_add_i32 s54, s46, s35
	v_lshl_add_u64 v[128:129], s[52:53], 0, v[154:155]
	s_mov_b32 m0, s54
	s_nop 0
	global_load_lds_dwordx4 v[128:129], off
	v_lshl_add_u64 v[128:129], s[52:53], 0, v[158:159]
	s_add_i32 m0, s54, 0x2000
	s_nop 0
	global_load_lds_dwordx4 v[128:129], off
	s_waitcnt vmcnt(6)
	s_barrier
	s_setprio 1
	v_mfma_f32_16x16x32_bf16 v[52:55], v[202:205], v[144:147], v[52:55]
	v_mfma_f32_16x16x32_bf16 v[48:51], v[210:213], v[144:147], v[48:51]
	v_mfma_f32_16x16x32_bf16 v[36:39], v[202:205], v[168:171], v[36:39]
	v_mfma_f32_16x16x32_bf16 v[32:35], v[210:213], v[168:171], v[32:35]
	v_mfma_f32_16x16x32_bf16 v[20:23], v[202:205], v[176:179], v[20:23]
	v_mfma_f32_16x16x32_bf16 v[16:19], v[210:213], v[176:179], v[16:19]
	v_mfma_f32_16x16x32_bf16 v[4:7], v[202:205], v[194:197], v[4:7]
	v_mfma_f32_16x16x32_bf16 v[0:3], v[210:213], v[194:197], v[0:3]
	v_mfma_f32_16x16x32_bf16 v[52:55], v[206:209], v[148:151], v[52:55]
	v_mfma_f32_16x16x32_bf16 v[48:51], v[214:217], v[148:151], v[48:51]
	v_mfma_f32_16x16x32_bf16 v[36:39], v[206:209], v[172:175], v[36:39]
	v_mfma_f32_16x16x32_bf16 v[32:35], v[214:217], v[172:175], v[32:35]
	v_mfma_f32_16x16x32_bf16 v[20:23], v[206:209], v[180:183], v[20:23]
	v_mfma_f32_16x16x32_bf16 v[16:19], v[214:217], v[180:183], v[16:19]
	v_mfma_f32_16x16x32_bf16 v[4:7], v[206:209], v[198:201], v[4:7]
	v_mfma_f32_16x16x32_bf16 v[0:3], v[214:217], v[198:201], v[0:3]
	s_setprio 0
	s_add_i32 s52, 0, 0x18000
	v_add_u32_e32 v140, s52, v187
	s_barrier
	ds_read_b128 v[128:131], v140
	ds_read_b128 v[132:135], v140 offset:1024
	ds_read_b128 v[136:139], v140 offset:2048
	ds_read_b128 v[140:143], v140 offset:3072
	s_add_u32 s28, s28, 0x40000
	s_addc_u32 s29, s29, 0
	s_mov_b32 m0, s38
	v_lshl_add_u64 v[202:203], s[28:29], 0, v[152:153]
	ds_read_b128 v[144:147], v191 offset:32768
	ds_read_b128 v[148:151], v191 offset:33792
	ds_read_b128 v[168:171], v191 offset:34816
	ds_read_b128 v[172:175], v191 offset:35840
	ds_read_b128 v[176:179], v191 offset:36864
	ds_read_b128 v[180:183], v191 offset:37888
	ds_read_b128 v[194:197], v191 offset:38912
	ds_read_b128 v[198:201], v191 offset:39936
	global_load_lds_dwordx4 v[202:203], off
	v_lshl_add_u64 v[202:203], s[28:29], 0, v[156:157]
	s_mov_b32 m0, s39
	s_nop 0
	global_load_lds_dwordx4 v[202:203], off
	s_waitcnt lgkmcnt(8)
	s_barrier
	s_waitcnt lgkmcnt(0)
	s_setprio 1
	s_waitcnt lgkmcnt(0)
	v_mfma_f32_16x16x32_bf16 v[124:127], v[128:131], v[144:147], v[124:127]
	v_mfma_f32_16x16x32_bf16 v[120:123], v[136:139], v[144:147], v[120:123]
	v_mfma_f32_16x16x32_bf16 v[108:111], v[128:131], v[168:171], v[108:111]
	v_mfma_f32_16x16x32_bf16 v[104:107], v[136:139], v[168:171], v[104:107]
	v_mfma_f32_16x16x32_bf16 v[92:95], v[128:131], v[176:179], v[92:95]
	v_mfma_f32_16x16x32_bf16 v[88:91], v[136:139], v[176:179], v[88:91]
	v_mfma_f32_16x16x32_bf16 v[76:79], v[128:131], v[194:197], v[76:79]
	v_mfma_f32_16x16x32_bf16 v[72:75], v[136:139], v[194:197], v[72:75]
	v_mfma_f32_16x16x32_bf16 v[124:127], v[132:135], v[148:151], v[124:127]
	v_mfma_f32_16x16x32_bf16 v[120:123], v[140:143], v[148:151], v[120:123]
	v_mfma_f32_16x16x32_bf16 v[108:111], v[132:135], v[172:175], v[108:111]
	v_mfma_f32_16x16x32_bf16 v[104:107], v[140:143], v[172:175], v[104:107]
	v_mfma_f32_16x16x32_bf16 v[92:95], v[132:135], v[180:183], v[92:95]
	v_mfma_f32_16x16x32_bf16 v[88:91], v[140:143], v[180:183], v[88:91]
	v_mfma_f32_16x16x32_bf16 v[76:79], v[132:135], v[198:201], v[76:79]
	v_mfma_f32_16x16x32_bf16 v[72:75], v[140:143], v[198:201], v[72:75]
	s_setprio 0
	s_barrier
	s_add_i32 s28, 0, 0x1c000
	s_add_i32 s29, s52, s35
	v_add_u32_e32 v214, s28, v187
	v_lshl_add_u64 v[184:185], v[184:185], 0, s[8:9]
	s_mov_b32 m0, s29
	ds_read_b128 v[202:205], v214
	ds_read_b128 v[206:209], v214 offset:1024
	ds_read_b128 v[210:213], v214 offset:2048
	ds_read_b128 v[214:217], v214 offset:3072
	global_load_lds_dwordx4 v[184:185], off
	v_lshl_add_u64 v[184:185], v[218:219], 0, s[8:9]
	s_add_i32 m0, s29, 0x2000
	s_nop 0
	global_load_lds_dwordx4 v[184:185], off
	s_barrier
	s_waitcnt lgkmcnt(0)
	s_setprio 1
	s_waitcnt lgkmcnt(0)
	v_mfma_f32_16x16x32_bf16 v[116:119], v[202:205], v[144:147], v[116:119]
	v_mfma_f32_16x16x32_bf16 v[112:115], v[210:213], v[144:147], v[112:115]
	v_mfma_f32_16x16x32_bf16 v[100:103], v[202:205], v[168:171], v[100:103]
	v_mfma_f32_16x16x32_bf16 v[96:99], v[210:213], v[168:171], v[96:99]
	v_mfma_f32_16x16x32_bf16 v[84:87], v[202:205], v[176:179], v[84:87]
	v_mfma_f32_16x16x32_bf16 v[80:83], v[210:213], v[176:179], v[80:83]
	v_mfma_f32_16x16x32_bf16 v[68:71], v[202:205], v[194:197], v[68:71]
	v_mfma_f32_16x16x32_bf16 v[64:67], v[210:213], v[194:197], v[64:67]
	v_mfma_f32_16x16x32_bf16 v[116:119], v[206:209], v[148:151], v[116:119]
	v_mfma_f32_16x16x32_bf16 v[112:115], v[214:217], v[148:151], v[112:115]
	v_mfma_f32_16x16x32_bf16 v[100:103], v[206:209], v[172:175], v[100:103]
	v_mfma_f32_16x16x32_bf16 v[96:99], v[214:217], v[172:175], v[96:99]
	v_mfma_f32_16x16x32_bf16 v[84:87], v[206:209], v[180:183], v[84:87]
	v_mfma_f32_16x16x32_bf16 v[80:83], v[214:217], v[180:183], v[80:83]
	v_mfma_f32_16x16x32_bf16 v[68:71], v[206:209], v[198:201], v[68:71]
	v_mfma_f32_16x16x32_bf16 v[64:67], v[214:217], v[198:201], v[64:67]
	s_setprio 0
	s_mov_b32 m0, s41
	v_lshl_add_u64 v[184:185], v[220:221], 0, s[8:9]
	s_barrier
	ds_read_b128 v[144:147], v191 offset:49152
	ds_read_b128 v[148:151], v191 offset:50176
	ds_read_b128 v[168:171], v191 offset:51200
	ds_read_b128 v[172:175], v191 offset:52224
	ds_read_b128 v[176:179], v191 offset:53248
	ds_read_b128 v[180:183], v191 offset:54272
	ds_read_b128 v[194:197], v191 offset:55296
	ds_read_b128 v[198:201], v191 offset:56320
	global_load_lds_dwordx4 v[184:185], off
	v_lshl_add_u64 v[184:185], v[222:223], 0, s[8:9]
	s_mov_b32 m0, s42
	s_nop 0
	global_load_lds_dwordx4 v[184:185], off
	s_barrier
	s_waitcnt lgkmcnt(0)
	s_setprio 1
	s_waitcnt lgkmcnt(0)
	v_mfma_f32_16x16x32_bf16 v[60:63], v[128:131], v[144:147], v[60:63]
	v_mfma_f32_16x16x32_bf16 v[56:59], v[136:139], v[144:147], v[56:59]
	v_mfma_f32_16x16x32_bf16 v[44:47], v[128:131], v[168:171], v[44:47]
	v_mfma_f32_16x16x32_bf16 v[40:43], v[136:139], v[168:171], v[40:43]
	v_mfma_f32_16x16x32_bf16 v[28:31], v[128:131], v[176:179], v[28:31]
	v_mfma_f32_16x16x32_bf16 v[24:27], v[136:139], v[176:179], v[24:27]
	v_mfma_f32_16x16x32_bf16 v[12:15], v[128:131], v[194:197], v[12:15]
	v_mfma_f32_16x16x32_bf16 v[8:11], v[136:139], v[194:197], v[8:11]
	v_mfma_f32_16x16x32_bf16 v[60:63], v[132:135], v[148:151], v[60:63]
	v_mfma_f32_16x16x32_bf16 v[56:59], v[140:143], v[148:151], v[56:59]
	v_mfma_f32_16x16x32_bf16 v[44:47], v[132:135], v[172:175], v[44:47]
	v_mfma_f32_16x16x32_bf16 v[40:43], v[140:143], v[172:175], v[40:43]
	v_mfma_f32_16x16x32_bf16 v[28:31], v[132:135], v[180:183], v[28:31]
	v_mfma_f32_16x16x32_bf16 v[24:27], v[140:143], v[180:183], v[24:27]
	v_mfma_f32_16x16x32_bf16 v[12:15], v[132:135], v[198:201], v[12:15]
	v_mfma_f32_16x16x32_bf16 v[8:11], v[140:143], v[198:201], v[8:11]
	s_setprio 0
	s_barrier
	s_add_u32 s22, s22, 0x40080
	s_addc_u32 s23, s23, 0
	s_add_i32 s28, s28, s35
	v_lshl_add_u64 v[128:129], s[22:23], 0, v[154:155]
	s_mov_b32 m0, s28
	s_nop 0
	global_load_lds_dwordx4 v[128:129], off
	v_lshl_add_u64 v[128:129], s[22:23], 0, v[158:159]
	s_add_i32 m0, s28, 0x2000
	s_nop 0
	global_load_lds_dwordx4 v[128:129], off
	s_waitcnt vmcnt(6)
	s_barrier
	s_setprio 1
	v_mfma_f32_16x16x32_bf16 v[52:55], v[202:205], v[144:147], v[52:55]
	v_mfma_f32_16x16x32_bf16 v[48:51], v[210:213], v[144:147], v[48:51]
	v_mfma_f32_16x16x32_bf16 v[36:39], v[202:205], v[168:171], v[36:39]
	v_mfma_f32_16x16x32_bf16 v[32:35], v[210:213], v[168:171], v[32:35]
	v_mfma_f32_16x16x32_bf16 v[20:23], v[202:205], v[176:179], v[20:23]
	v_mfma_f32_16x16x32_bf16 v[16:19], v[210:213], v[176:179], v[16:19]
	v_mfma_f32_16x16x32_bf16 v[4:7], v[202:205], v[194:197], v[4:7]
	v_mfma_f32_16x16x32_bf16 v[0:3], v[210:213], v[194:197], v[0:3]
	v_mfma_f32_16x16x32_bf16 v[52:55], v[206:209], v[148:151], v[52:55]
	v_mfma_f32_16x16x32_bf16 v[48:51], v[214:217], v[148:151], v[48:51]
	v_mfma_f32_16x16x32_bf16 v[36:39], v[206:209], v[172:175], v[36:39]
	v_mfma_f32_16x16x32_bf16 v[32:35], v[214:217], v[172:175], v[32:35]
	v_mfma_f32_16x16x32_bf16 v[20:23], v[206:209], v[180:183], v[20:23]
	v_mfma_f32_16x16x32_bf16 v[16:19], v[214:217], v[180:183], v[16:19]
	v_mfma_f32_16x16x32_bf16 v[4:7], v[206:209], v[198:201], v[4:7]
	v_mfma_f32_16x16x32_bf16 v[0:3], v[214:217], v[198:201], v[0:3]
	s_setprio 0
	s_add_i32 s51, s51, 2
	s_add_u32 s20, s20, 0x100
	s_addc_u32 s21, s21, 0
	s_add_u32 s49, s49, 0x100
	s_addc_u32 s50, s50, 0
	s_cmp_gt_u32 s51, 13
	s_barrier
	s_cbranch_scc0 .LBB0_1551
	v_lshl_or_b32 v168, s6, 8, v189
	v_lshl_add_u32 v170, s18, 8, v186
	v_ashrrev_i32_e32 v169, 31, v168
	v_lshlrev_b64 v[202:203], 1, v[168:169]
	v_ashrrev_i32_e32 v171, 31, v170
	v_or_b32_e32 v182, 16, v170
	v_lshl_add_u64 v[172:173], s[64:65], 0, v[202:203]
	v_lshlrev_b64 v[204:205], 11, v[170:171]
	v_ashrrev_i32_e32 v183, 31, v182
	v_or_b32_e32 v178, 32, v170
	v_lshl_add_u64 v[128:129], v[172:173], 0, v[204:205]
	v_lshlrev_b64 v[184:185], 11, v[182:183]
	v_ashrrev_i32_e32 v179, 31, v178
	v_or_b32_e32 v174, 48, v170
	global_load_dwordx4 v[194:197], v[128:129], off
	global_load_dwordx4 v[198:201], v[128:129], off offset:256
	v_lshl_add_u64 v[128:129], v[172:173], 0, v[184:185]
	v_lshlrev_b64 v[180:181], 11, v[178:179]
	v_ashrrev_i32_e32 v175, 31, v174
	global_load_dwordx4 v[148:151], v[128:129], off
	global_load_dwordx4 v[144:147], v[128:129], off offset:256
	v_lshl_add_u64 v[128:129], v[172:173], 0, v[180:181]
	v_lshlrev_b64 v[176:177], 11, v[174:175]
	global_load_dwordx4 v[140:143], v[128:129], off
	global_load_dwordx4 v[136:139], v[128:129], off offset:256
	v_lshl_add_u64 v[128:129], v[172:173], 0, v[176:177]
	global_load_dwordx4 v[132:135], v[128:129], off
	s_nop 0
	global_load_dwordx4 v[128:131], v[128:129], off offset:256
	s_lshl_b32 s18, s6, 2
	s_ashr_i32 s19, s18, 31
	v_add_u32_e32 v252, 0x80, v170
	v_ashrrev_i32_e32 v253, 31, v252
	v_lshlrev_b64 v[252:253], 11, v[252:253]
	v_lshl_add_u64 v[252:253], v[172:173], 0, v[252:253]
	global_load_dwordx4 v[236:239], v[252:253], off
	global_load_dwordx4 v[240:243], v[252:253], off offset:256
	v_add_u32_e32 v252, 0x90, v170
	v_ashrrev_i32_e32 v253, 31, v252
	v_lshlrev_b64 v[252:253], 11, v[252:253]
	v_lshl_add_u64 v[252:253], v[172:173], 0, v[252:253]
	global_load_dwordx4 v[244:247], v[252:253], off
	global_load_dwordx4 v[248:251], v[252:253], off offset:256
	v_add_u32_e32 v252, 0xa0, v170
	v_ashrrev_i32_e32 v253, 31, v252
	v_lshlrev_b64 v[252:253], 11, v[252:253]
	v_lshl_add_u64 v[252:253], v[172:173], 0, v[252:253]
	global_load_dwordx4 v[210:213], v[252:253], off
	global_load_dwordx4 v[214:217], v[252:253], off offset:256
	s_waitcnt vmcnt(6)
	v_lshlrev_b32_e32 v206, 16, v194
	v_and_b32_e32 v207, 0xffff0000, v194
	v_lshlrev_b32_e32 v194, 16, v195
	v_and_b32_e32 v195, 0xffff0000, v195
	v_lshlrev_b32_e32 v208, 16, v196
	v_and_b32_e32 v209, 0xffff0000, v196
	v_lshlrev_b32_e32 v196, 16, v197
	v_and_b32_e32 v197, 0xffff0000, v197
	v_pk_add_f32 v[126:127], v[126:127], v[194:195]
	v_pk_add_f32 v[124:125], v[124:125], v[206:207]
	v_pk_add_f32 v[194:195], v[122:123], v[196:197]
	v_pk_add_f32 v[122:123], v[120:121], v[208:209]
	v_mul_f32_e32 v120, v125, v125
	v_mul_f32_e32 v121, v127, v127
	v_fmac_f32_e32 v120, v124, v124
	v_fmac_f32_e32 v121, v126, v126
	v_add_f32_e32 v120, v120, v121
	v_mul_f32_e32 v121, v123, v123
	v_mul_f32_e32 v196, v195, v195
	v_fmac_f32_e32 v121, v122, v122
	v_fmac_f32_e32 v196, v194, v194
	v_add_f32_e32 v121, v121, v196
	v_add_f32_e32 v206, v120, v121
	v_cvt_pk_bf16_f32 v120, v124, v125
	v_cvt_pk_bf16_f32 v121, v126, v127
	v_lshlrev_b32_e32 v124, 16, v198
	v_and_b32_e32 v125, 0xffff0000, v198
	v_lshlrev_b32_e32 v126, 16, v199
	v_and_b32_e32 v127, 0xffff0000, v199
	v_cvt_pk_bf16_f32 v122, v122, v123
	v_cvt_pk_bf16_f32 v123, v194, v195
	v_lshlrev_b32_e32 v194, 16, v200
	v_and_b32_e32 v195, 0xffff0000, v200
	v_pk_add_f32 v[118:119], v[118:119], v[126:127]
	v_pk_add_f32 v[116:117], v[116:117], v[124:125]
	v_lshlrev_b32_e32 v196, 16, v201
	v_and_b32_e32 v197, 0xffff0000, v201
	v_pk_add_f32 v[126:127], v[112:113], v[194:195]
	v_mul_f32_e32 v112, v117, v117
	v_mul_f32_e32 v113, v119, v119
	v_pk_add_f32 v[124:125], v[114:115], v[196:197]
	v_fmac_f32_e32 v112, v116, v116
	v_fmac_f32_e32 v113, v118, v118
	v_add_f32_e32 v112, v112, v113
	v_mul_f32_e32 v113, v127, v127
	v_mul_f32_e32 v114, v125, v125
	v_fmac_f32_e32 v113, v126, v126
	v_fmac_f32_e32 v114, v124, v124
	v_add_f32_e32 v113, v113, v114
	v_add_f32_e32 v112, v112, v113
	v_and_b32_e32 v114, 64, v193
	v_add_f32_e32 v113, v206, v112
	v_xor_b32_e32 v112, 16, v193
	v_add_u32_e32 v196, 64, v114
	v_cmp_lt_i32_e32 vcc, v112, v196
	v_lshl_add_u64 v[114:115], s[64:65], 0, v[204:205]
	v_lshl_add_u64 v[194:195], v[114:115], 0, v[202:203]
	v_cndmask_b32_e32 v112, v193, v112, vcc
	v_lshlrev_b32_e32 v112, 2, v112
	ds_bpermute_b32 v197, v112, v113
	global_store_dwordx4 v[194:195], v[120:123], off sc1
	v_cvt_pk_bf16_f32 v116, v116, v117
	v_cvt_pk_bf16_f32 v117, v118, v119
	v_cvt_pk_bf16_f32 v118, v126, v127
	s_waitcnt lgkmcnt(0)
	v_add_f32_e32 v114, v113, v197
	v_xor_b32_e32 v113, 32, v193
	v_cmp_lt_i32_e32 vcc, v113, v196
	v_cvt_pk_bf16_f32 v119, v124, v125
	global_store_dwordx4 v[194:195], v[116:119], off offset:256 sc1
	s_nop 0
	v_cndmask_b32_e32 v113, v193, v113, vcc
	v_lshlrev_b32_e32 v113, 2, v113
	ds_bpermute_b32 v115, v113, v114
	s_and_saveexec_b64 s[20:21], s[2:3]
	s_cbranch_execz .LBB0_1554
	s_waitcnt lgkmcnt(0)
	v_add_f32_e32 v116, v114, v115
	v_lshlrev_b64 v[114:115], 6, v[170:171]
	v_lshl_add_u64 v[114:115], s[74:75], 0, v[114:115]
	v_lshl_add_u64 v[114:115], s[18:19], 2, v[114:115]
	s_lshl_b32 s6, s40, 2
	v_lshl_add_u64 v[114:115], v[114:115], 0, s[6:7]
	global_store_dword v[114:115], v116, off
.LBB0_1554:
	s_or_b64 exec, exec, s[20:21]
	v_lshlrev_b32_e32 v114, 16, v148
	s_waitcnt lgkmcnt(0)
	v_and_b32_e32 v115, 0xffff0000, v148
	v_lshlrev_b32_e32 v116, 16, v149
	v_and_b32_e32 v117, 0xffff0000, v149
	v_lshlrev_b32_e32 v118, 16, v150
	v_and_b32_e32 v119, 0xffff0000, v150
	v_lshlrev_b32_e32 v120, 16, v151
	v_and_b32_e32 v121, 0xffff0000, v151
	v_pk_add_f32 v[110:111], v[110:111], v[116:117]
	v_pk_add_f32 v[108:109], v[108:109], v[114:115]
	v_pk_add_f32 v[114:115], v[106:107], v[120:121]
	v_pk_add_f32 v[106:107], v[104:105], v[118:119]
	v_mul_f32_e32 v104, v109, v109
	v_mul_f32_e32 v105, v111, v111
	v_fmac_f32_e32 v104, v108, v108
	v_fmac_f32_e32 v105, v110, v110
	v_add_f32_e32 v104, v104, v105
	v_mul_f32_e32 v105, v107, v107
	v_mul_f32_e32 v116, v115, v115
	v_fmac_f32_e32 v105, v106, v106
	v_fmac_f32_e32 v116, v114, v114
	v_add_f32_e32 v105, v105, v116
	v_add_f32_e32 v118, v104, v105
	v_cvt_pk_bf16_f32 v104, v108, v109
	v_cvt_pk_bf16_f32 v105, v110, v111
	v_lshlrev_b32_e32 v108, 16, v144
	v_and_b32_e32 v109, 0xffff0000, v144
	v_lshlrev_b32_e32 v110, 16, v145
	v_and_b32_e32 v111, 0xffff0000, v145
	v_cvt_pk_bf16_f32 v106, v106, v107
	v_cvt_pk_bf16_f32 v107, v114, v115
	v_lshlrev_b32_e32 v114, 16, v146
	v_and_b32_e32 v115, 0xffff0000, v146
	v_pk_add_f32 v[102:103], v[102:103], v[110:111]
	v_pk_add_f32 v[100:101], v[100:101], v[108:109]
	v_lshlrev_b32_e32 v116, 16, v147
	v_and_b32_e32 v117, 0xffff0000, v147
	v_pk_add_f32 v[110:111], v[96:97], v[114:115]
	v_mul_f32_e32 v96, v101, v101
	v_mul_f32_e32 v97, v103, v103
	v_pk_add_f32 v[108:109], v[98:99], v[116:117]
	v_fmac_f32_e32 v96, v100, v100
	v_fmac_f32_e32 v97, v102, v102
	v_add_f32_e32 v96, v96, v97
	v_mul_f32_e32 v97, v111, v111
	v_mul_f32_e32 v98, v109, v109
	v_fmac_f32_e32 v97, v110, v110
	v_fmac_f32_e32 v98, v108, v108
	v_add_f32_e32 v97, v97, v98
	v_add_f32_e32 v96, v96, v97
	v_add_f32_e32 v99, v118, v96
	ds_bpermute_b32 v116, v112, v99
	v_lshl_add_u64 v[96:97], s[64:65], 0, v[184:185]
	v_lshl_add_u64 v[114:115], v[168:169], 1, v[96:97]
	global_store_dwordx4 v[114:115], v[104:107], off sc1
	v_cvt_pk_bf16_f32 v98, v100, v101
	s_waitcnt lgkmcnt(0)
	v_add_f32_e32 v96, v99, v116
	ds_bpermute_b32 v97, v113, v96
	v_cvt_pk_bf16_f32 v99, v102, v103
	v_cvt_pk_bf16_f32 v100, v110, v111
	v_cvt_pk_bf16_f32 v101, v108, v109
	global_store_dwordx4 v[114:115], v[98:101], off offset:256 sc1
	s_and_saveexec_b64 s[20:21], s[2:3]
	s_cbranch_execz .LBB0_1556
	s_waitcnt lgkmcnt(0)
	v_add_f32_e32 v98, v96, v97
	v_lshlrev_b64 v[96:97], 6, v[182:183]
	v_lshl_add_u64 v[96:97], s[74:75], 0, v[96:97]
	v_lshl_add_u64 v[96:97], s[18:19], 2, v[96:97]
	s_lshl_b32 s6, s40, 2
	v_lshl_add_u64 v[96:97], v[96:97], 0, s[6:7]
	global_store_dword v[96:97], v98, off
.LBB0_1556:
	s_or_b64 exec, exec, s[20:21]
	v_lshlrev_b32_e32 v96, 16, v140
	s_waitcnt lgkmcnt(0)
	v_and_b32_e32 v97, 0xffff0000, v140
	v_lshlrev_b32_e32 v98, 16, v141
	v_and_b32_e32 v99, 0xffff0000, v141
	v_lshlrev_b32_e32 v100, 16, v142
	v_and_b32_e32 v101, 0xffff0000, v142
	v_lshlrev_b32_e32 v102, 16, v143
	v_and_b32_e32 v103, 0xffff0000, v143
	v_pk_add_f32 v[94:95], v[94:95], v[98:99]
	v_pk_add_f32 v[92:93], v[92:93], v[96:97]
	v_pk_add_f32 v[96:97], v[90:91], v[102:103]
	v_pk_add_f32 v[90:91], v[88:89], v[100:101]
	v_mul_f32_e32 v88, v93, v93
	v_mul_f32_e32 v89, v95, v95
	v_fmac_f32_e32 v88, v92, v92
	v_fmac_f32_e32 v89, v94, v94
	v_add_f32_e32 v88, v88, v89
	v_mul_f32_e32 v89, v91, v91
	v_mul_f32_e32 v98, v97, v97
	v_fmac_f32_e32 v89, v90, v90
	v_fmac_f32_e32 v98, v96, v96
	v_add_f32_e32 v89, v89, v98
	v_add_f32_e32 v100, v88, v89
	v_cvt_pk_bf16_f32 v88, v92, v93
	v_cvt_pk_bf16_f32 v89, v94, v95
	v_lshlrev_b32_e32 v92, 16, v136
	v_and_b32_e32 v93, 0xffff0000, v136
	v_lshlrev_b32_e32 v94, 16, v137
	v_and_b32_e32 v95, 0xffff0000, v137
	v_cvt_pk_bf16_f32 v90, v90, v91
	v_cvt_pk_bf16_f32 v91, v96, v97
	v_lshlrev_b32_e32 v96, 16, v138
	v_and_b32_e32 v97, 0xffff0000, v138
	v_pk_add_f32 v[86:87], v[86:87], v[94:95]
	v_pk_add_f32 v[84:85], v[84:85], v[92:93]
	v_lshlrev_b32_e32 v98, 16, v139
	v_and_b32_e32 v99, 0xffff0000, v139
	v_pk_add_f32 v[94:95], v[80:81], v[96:97]
	v_mul_f32_e32 v80, v85, v85
	v_mul_f32_e32 v81, v87, v87
	v_pk_add_f32 v[92:93], v[82:83], v[98:99]
	v_fmac_f32_e32 v80, v84, v84
	v_fmac_f32_e32 v81, v86, v86
	v_add_f32_e32 v80, v80, v81
	v_mul_f32_e32 v81, v95, v95
	v_mul_f32_e32 v82, v93, v93
	v_fmac_f32_e32 v81, v94, v94
	v_fmac_f32_e32 v82, v92, v92
	v_add_f32_e32 v81, v81, v82
	v_add_f32_e32 v80, v80, v81
	v_add_f32_e32 v83, v100, v80
	ds_bpermute_b32 v98, v112, v83
	v_lshl_add_u64 v[80:81], s[64:65], 0, v[180:181]
	v_lshl_add_u64 v[96:97], v[168:169], 1, v[80:81]
	global_store_dwordx4 v[96:97], v[88:91], off sc1
	v_cvt_pk_bf16_f32 v82, v84, v85
	s_waitcnt lgkmcnt(0)
	v_add_f32_e32 v80, v83, v98
	ds_bpermute_b32 v81, v113, v80
	v_cvt_pk_bf16_f32 v83, v86, v87
	v_cvt_pk_bf16_f32 v84, v94, v95
	v_cvt_pk_bf16_f32 v85, v92, v93
	global_store_dwordx4 v[96:97], v[82:85], off offset:256 sc1
	s_and_saveexec_b64 s[20:21], s[2:3]
	s_cbranch_execz .LBB0_1558
	s_waitcnt lgkmcnt(0)
	v_add_f32_e32 v82, v80, v81
	v_lshlrev_b64 v[80:81], 6, v[178:179]
	v_lshl_add_u64 v[80:81], s[74:75], 0, v[80:81]
	v_lshl_add_u64 v[80:81], s[18:19], 2, v[80:81]
	s_lshl_b32 s6, s40, 2
	v_lshl_add_u64 v[80:81], v[80:81], 0, s[6:7]
	global_store_dword v[80:81], v82, off
.LBB0_1558:
	s_or_b64 exec, exec, s[20:21]
	v_lshlrev_b32_e32 v80, 16, v132
	s_waitcnt lgkmcnt(0)
	v_and_b32_e32 v81, 0xffff0000, v132
	v_lshlrev_b32_e32 v82, 16, v133
	v_and_b32_e32 v83, 0xffff0000, v133
	v_lshlrev_b32_e32 v84, 16, v134
	v_and_b32_e32 v85, 0xffff0000, v134
	v_lshlrev_b32_e32 v86, 16, v135
	v_and_b32_e32 v87, 0xffff0000, v135
	v_pk_add_f32 v[78:79], v[78:79], v[82:83]
	v_pk_add_f32 v[76:77], v[76:77], v[80:81]
	v_pk_add_f32 v[80:81], v[74:75], v[86:87]
	v_pk_add_f32 v[74:75], v[72:73], v[84:85]
	v_mul_f32_e32 v72, v77, v77
	v_mul_f32_e32 v73, v79, v79
	v_fmac_f32_e32 v72, v76, v76
	v_fmac_f32_e32 v73, v78, v78
	v_add_f32_e32 v72, v72, v73
	v_mul_f32_e32 v73, v75, v75
	v_mul_f32_e32 v82, v81, v81
	v_fmac_f32_e32 v73, v74, v74
	v_fmac_f32_e32 v82, v80, v80
	v_add_f32_e32 v73, v73, v82
	v_add_f32_e32 v84, v72, v73
	v_cvt_pk_bf16_f32 v72, v76, v77
	v_cvt_pk_bf16_f32 v73, v78, v79
	v_lshlrev_b32_e32 v76, 16, v128
	v_and_b32_e32 v77, 0xffff0000, v128
	v_lshlrev_b32_e32 v78, 16, v129
	v_and_b32_e32 v79, 0xffff0000, v129
	v_cvt_pk_bf16_f32 v74, v74, v75
	v_cvt_pk_bf16_f32 v75, v80, v81
	v_lshlrev_b32_e32 v80, 16, v130
	v_and_b32_e32 v81, 0xffff0000, v130
	v_pk_add_f32 v[70:71], v[70:71], v[78:79]
	v_pk_add_f32 v[68:69], v[68:69], v[76:77]
	v_lshlrev_b32_e32 v82, 16, v131
	v_and_b32_e32 v83, 0xffff0000, v131
	v_pk_add_f32 v[78:79], v[64:65], v[80:81]
	v_mul_f32_e32 v64, v69, v69
	v_mul_f32_e32 v65, v71, v71
	v_pk_add_f32 v[76:77], v[66:67], v[82:83]
	v_fmac_f32_e32 v64, v68, v68
	v_fmac_f32_e32 v65, v70, v70
	v_add_f32_e32 v64, v64, v65
	v_mul_f32_e32 v65, v79, v79
	v_mul_f32_e32 v66, v77, v77
	v_fmac_f32_e32 v65, v78, v78
	v_fmac_f32_e32 v66, v76, v76
	v_add_f32_e32 v65, v65, v66
	v_add_f32_e32 v64, v64, v65
	v_add_f32_e32 v67, v84, v64
	ds_bpermute_b32 v82, v112, v67
	v_lshl_add_u64 v[64:65], s[64:65], 0, v[176:177]
	v_lshl_add_u64 v[80:81], v[168:169], 1, v[64:65]
	global_store_dwordx4 v[80:81], v[72:75], off sc1
	v_cvt_pk_bf16_f32 v66, v68, v69
	s_waitcnt lgkmcnt(0)
	v_add_f32_e32 v64, v67, v82
	ds_bpermute_b32 v65, v113, v64
	v_cvt_pk_bf16_f32 v67, v70, v71
	v_cvt_pk_bf16_f32 v68, v78, v79
	v_cvt_pk_bf16_f32 v69, v76, v77
	global_store_dwordx4 v[80:81], v[66:69], off offset:256 sc1
	s_and_saveexec_b64 s[20:21], s[2:3]
	s_cbranch_execz .LBB0_1560
	s_waitcnt lgkmcnt(0)
	v_add_f32_e32 v66, v64, v65
	v_lshlrev_b64 v[64:65], 6, v[174:175]
	v_lshl_add_u64 v[64:65], s[74:75], 0, v[64:65]
	v_lshl_add_u64 v[64:65], s[18:19], 2, v[64:65]
	s_lshl_b32 s6, s40, 2
	v_lshl_add_u64 v[64:65], v[64:65], 0, s[6:7]
	global_store_dword v[64:65], v66, off
.LBB0_1560:
	s_or_b64 exec, exec, s[20:21]
	v_add_u32_e32 v100, 0x80, v170
	v_ashrrev_i32_e32 v101, 31, v100
	v_add_u32_e32 v96, 0x90, v170
	v_lshlrev_b64 v[110:111], 11, v[100:101]
	v_ashrrev_i32_e32 v97, 31, v96
	v_add_u32_e32 v92, 0xa0, v170
	s_waitcnt lgkmcnt(0)
	v_lshl_add_u64 v[64:65], v[172:173], 0, v[110:111]
	v_lshlrev_b64 v[98:99], 11, v[96:97]
	v_ashrrev_i32_e32 v93, 31, v92
	v_add_u32_e32 v88, 0xb0, v170
	v_lshl_add_u64 v[64:65], v[172:173], 0, v[98:99]
	v_lshlrev_b64 v[94:95], 11, v[92:93]
	v_ashrrev_i32_e32 v89, 31, v88
	v_lshl_add_u64 v[64:65], v[172:173], 0, v[94:95]
	v_lshlrev_b64 v[90:91], 11, v[88:89]
	v_lshl_add_u64 v[64:65], v[172:173], 0, v[90:91]
	global_load_dwordx4 v[68:71], v[64:65], off
	s_nop 0
	global_load_dwordx4 v[64:67], v[64:65], off offset:256
	s_waitcnt vmcnt(15)
	v_lshlrev_b32_e32 v114, 16, v236
	v_and_b32_e32 v115, 0xffff0000, v236
	v_lshlrev_b32_e32 v236, 16, v237
	v_and_b32_e32 v237, 0xffff0000, v237
	v_lshlrev_b32_e32 v116, 16, v238
	v_and_b32_e32 v117, 0xffff0000, v238
	v_lshlrev_b32_e32 v238, 16, v239
	v_and_b32_e32 v239, 0xffff0000, v239
	v_pk_add_f32 v[62:63], v[62:63], v[236:237]
	v_pk_add_f32 v[60:61], v[60:61], v[114:115]
	v_pk_add_f32 v[236:237], v[58:59], v[238:239]
	v_pk_add_f32 v[58:59], v[56:57], v[116:117]
	v_mul_f32_e32 v56, v61, v61
	v_mul_f32_e32 v57, v63, v63
	v_fmac_f32_e32 v56, v60, v60
	v_fmac_f32_e32 v57, v62, v62
	v_add_f32_e32 v56, v56, v57
	v_mul_f32_e32 v57, v59, v59
	v_mul_f32_e32 v238, v237, v237
	v_fmac_f32_e32 v57, v58, v58
	v_fmac_f32_e32 v238, v236, v236
	v_add_f32_e32 v57, v57, v238
	v_add_f32_e32 v114, v56, v57
	v_cvt_pk_bf16_f32 v56, v60, v61
	v_cvt_pk_bf16_f32 v57, v62, v63
	s_waitcnt vmcnt(14)
	v_lshlrev_b32_e32 v60, 16, v240
	v_and_b32_e32 v61, 0xffff0000, v240
	v_lshlrev_b32_e32 v62, 16, v241
	v_and_b32_e32 v63, 0xffff0000, v241
	v_cvt_pk_bf16_f32 v58, v58, v59
	v_cvt_pk_bf16_f32 v59, v236, v237
	v_lshlrev_b32_e32 v236, 16, v242
	v_and_b32_e32 v237, 0xffff0000, v242
	v_pk_add_f32 v[54:55], v[54:55], v[62:63]
	v_pk_add_f32 v[52:53], v[52:53], v[60:61]
	v_lshlrev_b32_e32 v238, 16, v243
	v_and_b32_e32 v239, 0xffff0000, v243
	v_pk_add_f32 v[62:63], v[48:49], v[236:237]
	v_mul_f32_e32 v48, v53, v53
	v_mul_f32_e32 v49, v55, v55
	v_pk_add_f32 v[60:61], v[50:51], v[238:239]
	v_fmac_f32_e32 v48, v52, v52
	v_fmac_f32_e32 v49, v54, v54
	v_add_f32_e32 v48, v48, v49
	v_mul_f32_e32 v49, v63, v63
	v_mul_f32_e32 v50, v61, v61
	v_fmac_f32_e32 v49, v62, v62
	v_fmac_f32_e32 v50, v60, v60
	v_add_f32_e32 v49, v49, v50
	v_add_f32_e32 v48, v48, v49
	v_add_f32_e32 v51, v114, v48
	ds_bpermute_b32 v238, v112, v51
	v_lshl_add_u64 v[48:49], s[64:65], 0, v[110:111]
	v_lshl_add_u64 v[236:237], v[168:169], 1, v[48:49]
	global_store_dwordx4 v[236:237], v[56:59], off sc1
	v_cvt_pk_bf16_f32 v50, v52, v53
	s_waitcnt lgkmcnt(0)
	v_add_f32_e32 v48, v51, v238
	ds_bpermute_b32 v49, v113, v48
	v_cvt_pk_bf16_f32 v51, v54, v55
	v_cvt_pk_bf16_f32 v52, v62, v63
	v_cvt_pk_bf16_f32 v53, v60, v61
	global_store_dwordx4 v[236:237], v[50:53], off offset:256 sc1
	s_and_saveexec_b64 s[20:21], s[2:3]
	s_cbranch_execz .LBB0_1562
	s_waitcnt lgkmcnt(0)
	v_add_f32_e32 v50, v48, v49
	v_lshlrev_b64 v[48:49], 6, v[100:101]
	v_lshl_add_u64 v[48:49], s[74:75], 0, v[48:49]
	v_lshl_add_u64 v[48:49], s[18:19], 2, v[48:49]
	s_lshl_b32 s6, s40, 2
	v_lshl_add_u64 v[48:49], v[48:49], 0, s[6:7]
	global_store_dword v[48:49], v50, off
.LBB0_1562:
	s_or_b64 exec, exec, s[20:21]
	s_waitcnt vmcnt(15)
	v_lshlrev_b32_e32 v48, 16, v244
	s_waitcnt lgkmcnt(0)
	v_and_b32_e32 v49, 0xffff0000, v244
	v_lshlrev_b32_e32 v50, 16, v245
	v_and_b32_e32 v51, 0xffff0000, v245
	v_lshlrev_b32_e32 v52, 16, v246
	v_and_b32_e32 v53, 0xffff0000, v246
	v_lshlrev_b32_e32 v54, 16, v247
	v_and_b32_e32 v55, 0xffff0000, v247
	v_pk_add_f32 v[46:47], v[46:47], v[50:51]
	v_pk_add_f32 v[44:45], v[44:45], v[48:49]
	v_pk_add_f32 v[48:49], v[42:43], v[54:55]
	v_pk_add_f32 v[42:43], v[40:41], v[52:53]
	v_mul_f32_e32 v40, v45, v45
	v_mul_f32_e32 v41, v47, v47
	v_fmac_f32_e32 v40, v44, v44
	v_fmac_f32_e32 v41, v46, v46
	v_add_f32_e32 v40, v40, v41
	v_mul_f32_e32 v41, v43, v43
	v_mul_f32_e32 v50, v49, v49
	v_fmac_f32_e32 v41, v42, v42
	v_fmac_f32_e32 v50, v48, v48
	v_add_f32_e32 v41, v41, v50
	v_add_f32_e32 v52, v40, v41
	v_cvt_pk_bf16_f32 v40, v44, v45
	v_cvt_pk_bf16_f32 v41, v46, v47
	s_waitcnt vmcnt(14)
	v_lshlrev_b32_e32 v44, 16, v248
	v_and_b32_e32 v45, 0xffff0000, v248
	v_lshlrev_b32_e32 v46, 16, v249
	v_and_b32_e32 v47, 0xffff0000, v249
	v_cvt_pk_bf16_f32 v42, v42, v43
	v_cvt_pk_bf16_f32 v43, v48, v49
	v_lshlrev_b32_e32 v48, 16, v250
	v_and_b32_e32 v49, 0xffff0000, v250
	v_pk_add_f32 v[38:39], v[38:39], v[46:47]
	v_pk_add_f32 v[36:37], v[36:37], v[44:45]
	v_lshlrev_b32_e32 v50, 16, v251
	v_and_b32_e32 v51, 0xffff0000, v251
	v_pk_add_f32 v[46:47], v[32:33], v[48:49]
	v_mul_f32_e32 v32, v37, v37
	v_mul_f32_e32 v33, v39, v39
	v_pk_add_f32 v[44:45], v[34:35], v[50:51]
	v_fmac_f32_e32 v32, v36, v36
	v_fmac_f32_e32 v33, v38, v38
	v_add_f32_e32 v32, v32, v33
	v_mul_f32_e32 v33, v47, v47
	v_mul_f32_e32 v34, v45, v45
	v_fmac_f32_e32 v33, v46, v46
	v_fmac_f32_e32 v34, v44, v44
	v_add_f32_e32 v33, v33, v34
	v_add_f32_e32 v32, v32, v33
	v_add_f32_e32 v35, v52, v32
	ds_bpermute_b32 v50, v112, v35
	v_lshl_add_u64 v[32:33], s[64:65], 0, v[98:99]
	v_lshl_add_u64 v[48:49], v[168:169], 1, v[32:33]
	global_store_dwordx4 v[48:49], v[40:43], off sc1
	v_cvt_pk_bf16_f32 v34, v36, v37
	s_waitcnt lgkmcnt(0)
	v_add_f32_e32 v32, v35, v50
	ds_bpermute_b32 v33, v113, v32
	v_cvt_pk_bf16_f32 v35, v38, v39
	v_cvt_pk_bf16_f32 v36, v46, v47
	v_cvt_pk_bf16_f32 v37, v44, v45
	global_store_dwordx4 v[48:49], v[34:37], off offset:256 sc1
	s_and_saveexec_b64 s[20:21], s[2:3]
	s_cbranch_execz .LBB0_1564
	s_waitcnt lgkmcnt(0)
	v_add_f32_e32 v34, v32, v33
	v_lshlrev_b64 v[32:33], 6, v[96:97]
	v_lshl_add_u64 v[32:33], s[74:75], 0, v[32:33]
	v_lshl_add_u64 v[32:33], s[18:19], 2, v[32:33]
	s_lshl_b32 s6, s40, 2
	v_lshl_add_u64 v[32:33], v[32:33], 0, s[6:7]
	global_store_dword v[32:33], v34, off
.LBB0_1564:
	s_or_b64 exec, exec, s[20:21]
	s_waitcnt vmcnt(15)
	v_lshlrev_b32_e32 v32, 16, v210
	s_waitcnt lgkmcnt(0)
	v_and_b32_e32 v33, 0xffff0000, v210
	v_lshlrev_b32_e32 v34, 16, v211
	v_and_b32_e32 v35, 0xffff0000, v211
	v_lshlrev_b32_e32 v36, 16, v212
	v_and_b32_e32 v37, 0xffff0000, v212
	v_lshlrev_b32_e32 v38, 16, v213
	v_and_b32_e32 v39, 0xffff0000, v213
	v_pk_add_f32 v[30:31], v[30:31], v[34:35]
	v_pk_add_f32 v[28:29], v[28:29], v[32:33]
	v_pk_add_f32 v[32:33], v[26:27], v[38:39]
	v_pk_add_f32 v[26:27], v[24:25], v[36:37]
	v_mul_f32_e32 v24, v29, v29
	v_mul_f32_e32 v25, v31, v31
	v_fmac_f32_e32 v24, v28, v28
	v_fmac_f32_e32 v25, v30, v30
	v_add_f32_e32 v24, v24, v25
	v_mul_f32_e32 v25, v27, v27
	v_mul_f32_e32 v34, v33, v33
	v_fmac_f32_e32 v25, v26, v26
	v_fmac_f32_e32 v34, v32, v32
	v_add_f32_e32 v25, v25, v34
	v_add_f32_e32 v36, v24, v25
	v_cvt_pk_bf16_f32 v24, v28, v29
	v_cvt_pk_bf16_f32 v25, v30, v31
	s_waitcnt vmcnt(14)
	v_lshlrev_b32_e32 v28, 16, v214
	v_and_b32_e32 v29, 0xffff0000, v214
	v_lshlrev_b32_e32 v30, 16, v215
	v_and_b32_e32 v31, 0xffff0000, v215
	v_cvt_pk_bf16_f32 v26, v26, v27
	v_cvt_pk_bf16_f32 v27, v32, v33
	v_lshlrev_b32_e32 v32, 16, v216
	v_and_b32_e32 v33, 0xffff0000, v216
	v_pk_add_f32 v[22:23], v[22:23], v[30:31]
	v_pk_add_f32 v[20:21], v[20:21], v[28:29]
	v_lshlrev_b32_e32 v34, 16, v217
	v_and_b32_e32 v35, 0xffff0000, v217
	v_pk_add_f32 v[30:31], v[16:17], v[32:33]
	v_mul_f32_e32 v16, v21, v21
	v_mul_f32_e32 v17, v23, v23
	v_pk_add_f32 v[28:29], v[18:19], v[34:35]
	v_fmac_f32_e32 v16, v20, v20
	v_fmac_f32_e32 v17, v22, v22
	v_add_f32_e32 v16, v16, v17
	v_mul_f32_e32 v17, v31, v31
	v_mul_f32_e32 v18, v29, v29
	v_fmac_f32_e32 v17, v30, v30
	v_fmac_f32_e32 v18, v28, v28
	v_add_f32_e32 v17, v17, v18
	v_add_f32_e32 v16, v16, v17
	v_add_f32_e32 v19, v36, v16
	ds_bpermute_b32 v34, v112, v19
	v_lshl_add_u64 v[16:17], s[64:65], 0, v[94:95]
	v_lshl_add_u64 v[32:33], v[168:169], 1, v[16:17]
	global_store_dwordx4 v[32:33], v[24:27], off sc1
	v_cvt_pk_bf16_f32 v18, v20, v21
	s_waitcnt lgkmcnt(0)
	v_add_f32_e32 v16, v19, v34
	ds_bpermute_b32 v17, v113, v16
	v_cvt_pk_bf16_f32 v19, v22, v23
	v_cvt_pk_bf16_f32 v20, v30, v31
	v_cvt_pk_bf16_f32 v21, v28, v29
	global_store_dwordx4 v[32:33], v[18:21], off offset:256 sc1
	s_and_saveexec_b64 s[20:21], s[2:3]
	s_cbranch_execz .LBB0_1566
	s_waitcnt lgkmcnt(0)
	v_add_f32_e32 v18, v16, v17
	v_lshlrev_b64 v[16:17], 6, v[92:93]
	v_lshl_add_u64 v[16:17], s[74:75], 0, v[16:17]
	v_lshl_add_u64 v[16:17], s[18:19], 2, v[16:17]
	s_lshl_b32 s6, s40, 2
	v_lshl_add_u64 v[16:17], v[16:17], 0, s[6:7]
	global_store_dword v[16:17], v18, off
.LBB0_1566:
	s_or_b64 exec, exec, s[20:21]
	s_waitcnt vmcnt(7)
	v_lshlrev_b32_e32 v16, 16, v68
	s_waitcnt lgkmcnt(0)
	v_and_b32_e32 v17, 0xffff0000, v68
	v_lshlrev_b32_e32 v18, 16, v69
	v_and_b32_e32 v19, 0xffff0000, v69
	v_lshlrev_b32_e32 v20, 16, v70
	v_and_b32_e32 v21, 0xffff0000, v70
	v_lshlrev_b32_e32 v22, 16, v71
	v_and_b32_e32 v23, 0xffff0000, v71
	v_pk_add_f32 v[14:15], v[14:15], v[18:19]
	v_pk_add_f32 v[12:13], v[12:13], v[16:17]
	v_pk_add_f32 v[16:17], v[10:11], v[22:23]
	v_pk_add_f32 v[10:11], v[8:9], v[20:21]
	v_mul_f32_e32 v8, v13, v13
	v_mul_f32_e32 v9, v15, v15
	v_fmac_f32_e32 v8, v12, v12
	v_fmac_f32_e32 v9, v14, v14
	v_add_f32_e32 v8, v8, v9
	v_mul_f32_e32 v9, v11, v11
	v_mul_f32_e32 v18, v17, v17
	v_fmac_f32_e32 v9, v10, v10
	v_fmac_f32_e32 v18, v16, v16
	v_add_f32_e32 v9, v9, v18
	v_add_f32_e32 v20, v8, v9
	v_cvt_pk_bf16_f32 v8, v12, v13
	v_cvt_pk_bf16_f32 v9, v14, v15
	s_waitcnt vmcnt(6)
	v_lshlrev_b32_e32 v12, 16, v64
	v_and_b32_e32 v13, 0xffff0000, v64
	v_lshlrev_b32_e32 v14, 16, v65
	v_and_b32_e32 v15, 0xffff0000, v65
	v_cvt_pk_bf16_f32 v10, v10, v11
	v_cvt_pk_bf16_f32 v11, v16, v17
	v_lshlrev_b32_e32 v16, 16, v66
	v_and_b32_e32 v17, 0xffff0000, v66
	v_pk_add_f32 v[6:7], v[6:7], v[14:15]
	v_pk_add_f32 v[4:5], v[4:5], v[12:13]
	v_lshlrev_b32_e32 v18, 16, v67
	v_and_b32_e32 v19, 0xffff0000, v67
	v_pk_add_f32 v[14:15], v[0:1], v[16:17]
	v_mul_f32_e32 v0, v5, v5
	v_mul_f32_e32 v1, v7, v7
	v_pk_add_f32 v[12:13], v[2:3], v[18:19]
	v_fmac_f32_e32 v0, v4, v4
	v_fmac_f32_e32 v1, v6, v6
	v_add_f32_e32 v0, v0, v1
	v_mul_f32_e32 v1, v15, v15
	v_mul_f32_e32 v2, v13, v13
	v_fmac_f32_e32 v1, v14, v14
	v_fmac_f32_e32 v2, v12, v12
	v_add_f32_e32 v1, v1, v2
	v_add_f32_e32 v0, v0, v1
	v_add_f32_e32 v3, v20, v0
	ds_bpermute_b32 v18, v112, v3
	v_lshl_add_u64 v[0:1], s[64:65], 0, v[90:91]
	v_lshl_add_u64 v[16:17], v[168:169], 1, v[0:1]
	global_store_dwordx4 v[16:17], v[8:11], off sc1
	v_cvt_pk_bf16_f32 v2, v4, v5
	s_waitcnt lgkmcnt(0)
	v_add_f32_e32 v0, v3, v18
	ds_bpermute_b32 v1, v113, v0
	v_cvt_pk_bf16_f32 v3, v6, v7
	v_cvt_pk_bf16_f32 v4, v14, v15
	v_cvt_pk_bf16_f32 v5, v12, v13
	global_store_dwordx4 v[16:17], v[2:5], off offset:256 sc1
	s_and_saveexec_b64 s[20:21], s[2:3]
	s_cbranch_execz .LBB0_1543
	s_waitcnt lgkmcnt(0)
	v_add_f32_e32 v2, v0, v1
	v_lshlrev_b64 v[0:1], 6, v[88:89]
	v_lshl_add_u64 v[0:1], s[74:75], 0, v[0:1]
	v_lshl_add_u64 v[0:1], s[18:19], 2, v[0:1]
	s_lshl_b32 s6, s40, 2
	v_lshl_add_u64 v[0:1], v[0:1], 0, s[6:7]
	global_store_dword v[0:1], v2, off
	s_branch .LBB0_1543

.LBB0_1654:
	v_mov_b32_e32 v136, v96
	v_mov_b32_e32 v137, v96
	v_mov_b32_e32 v148, v97
	v_mov_b32_e32 v149, v97
	v_mov_b32_e32 v140, v96
	v_mov_b32_e32 v141, v96
	v_mov_b32_e32 v96, v97
	v_pk_mul_f32 v[138:139], v[42:43], v[140:141]
	v_pk_mul_f32 v[40:41], v[40:41], v[136:137]
	v_pk_mul_f32 v[42:43], v[32:33], v[136:137]
	v_pk_mul_f32 v[136:137], v[38:39], v[96:97]
	v_pk_mul_f32 v[38:39], v[36:37], v[148:149]
	v_mov_b32_dpp v127, v84 row_shr:1 row_mask:0xf bank_mask:0xf
	v_mov_b32_dpp v126, v88 row_shr:1 row_mask:0xf bank_mask:0xf
	s_waitcnt lgkmcnt(0)
	v_mov_b32_e32 v36, v118
	v_mov_b32_e32 v37, v106
	v_pk_mul_f32 v[140:141], v[34:35], v[140:141]
	v_pk_mul_f32 v[30:31], v[30:31], v[96:97]
	v_mov_b32_e32 v96, v42
	v_mov_b32_e32 v97, v40
	v_mov_b32_e32 v34, v122
	v_mov_b32_e32 v35, v110
	v_pk_mul_f32 v[32:33], v[36:37], v[126:127]
	v_pk_mul_f32 v[28:29], v[28:29], v[148:149]
	v_mov_b32_dpp v131, v80 row_shr:1 row_mask:0xf bank_mask:0xf
	v_mov_b32_dpp v130, v92 row_shr:1 row_mask:0xf bank_mask:0xf
	v_pk_fma_f32 v[148:149], v[96:97], v[34:35], v[32:33]
	v_mov_b32_e32 v32, v114
	v_mov_b32_e32 v33, v74
	v_pk_fma_f32 v[130:131], v[32:33], v[130:131], v[148:149]
	v_mov_b32_e32 v148, v28
	v_mul_f32_e32 v28, 0xbfb8aa3b, v131
	v_exp_f32_e32 v28, v28
	v_mov_b32_e32 v149, v38
	v_pk_mul_f32 v[150:151], v[148:149], v[34:35]
	v_mov_b32_dpp v143, v85 row_shr:1 row_mask:0xf bank_mask:0xf
	v_pk_fma_f32 v[150:151], v[96:97], v[36:37], v[150:151]
	v_add_f32_e32 v28, 1.0, v28
	v_pk_fma_f32 v[126:127], v[32:33], v[126:127], v[150:151]
	v_mov_b32_e32 v150, v92
	v_mov_b32_e32 v151, v80
	v_pk_mul_f32 v[152:153], v[150:151], v[34:35]
	v_rcp_f32_e32 v28, v28
	v_mul_f32_e32 v38, 0xbfb8aa3b, v127
	v_pk_fma_f32 v[152:153], v[148:149], v[36:37], v[152:153]
	v_exp_f32_e32 v38, v38
	v_pk_fma_f32 v[96:97], v[96:97], v[32:33], v[152:153]
	v_mov_b32_e32 v152, v88
	v_mov_b32_e32 v153, v84
	v_pk_mul_f32 v[152:153], v[152:153], v[34:35]
	v_mul_f32_e32 v28, v131, v28
	v_pk_fma_f32 v[150:151], v[150:151], v[36:37], v[152:153]
	v_mul_f32_e32 v79, v130, v28
	v_pk_fma_f32 v[148:149], v[148:149], v[32:33], v[150:151]
	v_add_f32_e32 v28, 1.0, v38
	v_mul_f32_e32 v38, 0xbfb8aa3b, v97
	v_exp_f32_e32 v38, v38
	v_mul_f32_e32 v40, 0xbfb8aa3b, v149
	v_exp_f32_e32 v40, v40
	v_rcp_f32_e32 v28, v28
	v_add_f32_e32 v38, 1.0, v38
	v_rcp_f32_e32 v38, v38
	v_add_f32_e32 v40, 1.0, v40
	v_rcp_f32_e32 v40, v40
	v_mul_f32_e32 v28, v127, v28
	v_mul_f32_e32 v114, v126, v28
	v_mul_f32_e32 v28, v97, v38
	v_mov_b32_dpp v142, v89 row_shr:1 row_mask:0xf bank_mask:0xf
	v_mov_b32_e32 v106, v119
	v_mul_f32_e32 v118, v96, v28
	v_mul_f32_e32 v28, v149, v40
	v_mov_b32_e32 v40, v43
	v_mov_b32_e32 v110, v123
	v_pk_mul_f32 v[42:43], v[106:107], v[142:143]
	v_mov_b32_dpp v145, v81 row_shr:1 row_mask:0xf bank_mask:0xf
	v_mov_b32_dpp v144, v93 row_shr:1 row_mask:0xf bank_mask:0xf
	v_pk_fma_f32 v[42:43], v[40:41], v[110:111], v[42:43]
	v_mov_b32_e32 v74, v115
	v_pk_fma_f32 v[42:43], v[74:75], v[144:145], v[42:43]
	v_mov_b32_e32 v38, v29
	v_mul_f32_e32 v84, 0xbfb8aa3b, v43
	v_exp_f32_e32 v88, v84
	v_mul_f32_e32 v122, v148, v28
	v_pk_mul_f32 v[28:29], v[38:39], v[110:111]
	v_mov_b32_e32 v84, v89
	v_pk_fma_f32 v[28:29], v[40:41], v[106:107], v[28:29]
	v_mov_b32_e32 v80, v93
	v_pk_mul_f32 v[84:85], v[84:85], v[110:111]
	v_pk_fma_f32 v[28:29], v[74:75], v[142:143], v[28:29]
	v_pk_mul_f32 v[92:93], v[80:81], v[110:111]
	v_pk_fma_f32 v[80:81], v[80:81], v[106:107], v[84:85]
	v_add_f32_e32 v84, 1.0, v88
	v_rcp_f32_e32 v84, v84
	v_mul_f32_e32 v85, 0xbfb8aa3b, v29
	v_exp_f32_e32 v85, v85
	v_pk_fma_f32 v[92:93], v[38:39], v[106:107], v[92:93]
	v_mul_f32_e32 v43, v43, v84
	v_pk_fma_f32 v[40:41], v[40:41], v[74:75], v[92:93]
	v_pk_fma_f32 v[38:39], v[38:39], v[74:75], v[80:81]
	v_mul_f32_e32 v115, v42, v43
	v_add_f32_e32 v42, 1.0, v85
	v_mul_f32_e32 v43, 0xbfb8aa3b, v41
	v_rcp_f32_e32 v42, v42
	v_exp_f32_e32 v43, v43
	v_mul_f32_e32 v80, 0xbfb8aa3b, v39
	v_exp_f32_e32 v80, v80
	v_mul_f32_e32 v29, v29, v42
	v_add_f32_e32 v42, 1.0, v43
	v_rcp_f32_e32 v42, v42
	v_add_f32_e32 v43, 1.0, v80
	v_rcp_f32_e32 v43, v43
	v_mul_f32_e32 v119, v28, v29
	v_mul_f32_e32 v28, v41, v42
	v_mul_f32_e32 v123, v40, v28
	v_mul_f32_e32 v28, v39, v43
	v_mov_b32_dpp v129, v86 row_shr:1 row_mask:0xf bank_mask:0xf
	v_mov_b32_dpp v128, v90 row_shr:1 row_mask:0xf bank_mask:0xf
	v_mov_b32_e32 v42, v120
	v_mov_b32_e32 v43, v108
	v_mul_f32_e32 v126, v38, v28
	v_mov_b32_e32 v28, v140
	v_mov_b32_e32 v29, v138
	v_mov_b32_e32 v40, v124
	v_mov_b32_e32 v41, v112
	v_pk_mul_f32 v[38:39], v[42:43], v[128:129]
	v_mov_b32_dpp v133, v82 row_shr:1 row_mask:0xf bank_mask:0xf
	v_mov_b32_dpp v132, v94 row_shr:1 row_mask:0xf bank_mask:0xf
	v_pk_fma_f32 v[80:81], v[28:29], v[40:41], v[38:39]
	v_mov_b32_e32 v38, v116
	v_mov_b32_e32 v39, v76
	v_pk_fma_f32 v[80:81], v[38:39], v[132:133], v[80:81]
	v_mov_b32_e32 v84, v30
	v_mul_f32_e32 v30, 0xbfb8aa3b, v81
	v_exp_f32_e32 v30, v30
	v_mov_b32_e32 v85, v136
	v_pk_mul_f32 v[88:89], v[84:85], v[40:41]
	v_mov_b32_e32 v92, v94
	v_pk_fma_f32 v[88:89], v[28:29], v[42:43], v[88:89]
	v_mov_b32_e32 v93, v82
	v_pk_fma_f32 v[88:89], v[38:39], v[128:129], v[88:89]
	v_add_f32_e32 v30, 1.0, v30
	v_pk_mul_f32 v[96:97], v[92:93], v[40:41]
	v_rcp_f32_e32 v30, v30
	v_mul_f32_e32 v76, 0xbfb8aa3b, v89
	v_pk_fma_f32 v[96:97], v[84:85], v[42:43], v[96:97]
	v_exp_f32_e32 v76, v76
	v_pk_fma_f32 v[28:29], v[28:29], v[38:39], v[96:97]
	v_mov_b32_e32 v96, v90
	v_mov_b32_e32 v97, v86
	v_pk_mul_f32 v[96:97], v[96:97], v[40:41]
	v_mul_f32_e32 v30, v81, v30
	v_pk_fma_f32 v[92:93], v[92:93], v[42:43], v[96:97]
	v_mul_f32_e32 v90, v80, v30
	v_pk_fma_f32 v[84:85], v[84:85], v[38:39], v[92:93]
	v_add_f32_e32 v30, 1.0, v76
	v_mul_f32_e32 v76, 0xbfb8aa3b, v29
	v_exp_f32_e32 v76, v76
	v_mul_f32_e32 v80, 0xbfb8aa3b, v85
	v_exp_f32_e32 v80, v80
	v_rcp_f32_e32 v30, v30
	v_add_f32_e32 v76, 1.0, v76
	v_rcp_f32_e32 v76, v76
	v_add_f32_e32 v80, 1.0, v80
	v_rcp_f32_e32 v80, v80
	v_mul_f32_e32 v30, v89, v30
	v_mul_f32_e32 v29, v29, v76
	v_mul_f32_e32 v89, v28, v29
	v_mul_f32_e32 v28, v85, v80
	v_mov_b32_dpp v105, v87 row_shr:1 row_mask:0xf bank_mask:0xf
	v_mov_b32_dpp v104, v91 row_shr:1 row_mask:0xf bank_mask:0xf
	v_mov_b32_e32 v108, v121
	v_mul_f32_e32 v92, v84, v28
	v_mov_b32_e32 v138, v141
	v_mov_b32_e32 v112, v125
	v_pk_mul_f32 v[28:29], v[108:109], v[104:105]
	v_mov_b32_dpp v135, v83 row_shr:1 row_mask:0xf bank_mask:0xf
	v_mov_b32_dpp v134, v95 row_shr:1 row_mask:0xf bank_mask:0xf
	v_pk_fma_f32 v[28:29], v[138:139], v[112:113], v[28:29]
	v_mov_b32_e32 v76, v117
	v_pk_fma_f32 v[28:29], v[76:77], v[134:135], v[28:29]
	v_mov_b32_e32 v136, v31
	v_mul_f32_e32 v84, 0xbfb8aa3b, v29
	v_exp_f32_e32 v93, v84
	v_mul_f32_e32 v88, v88, v30
	v_pk_mul_f32 v[30:31], v[136:137], v[112:113]
	v_mov_b32_e32 v86, v91
	v_pk_fma_f32 v[30:31], v[138:139], v[108:109], v[30:31]
	v_mov_b32_e32 v82, v95
	v_pk_mul_f32 v[84:85], v[86:87], v[112:113]
	v_pk_fma_f32 v[30:31], v[76:77], v[104:105], v[30:31]
	v_pk_mul_f32 v[80:81], v[82:83], v[112:113]
	v_pk_fma_f32 v[82:83], v[82:83], v[108:109], v[84:85]
	v_add_f32_e32 v84, 1.0, v93
	v_rcp_f32_e32 v84, v84
	v_mul_f32_e32 v85, 0xbfb8aa3b, v31
	v_exp_f32_e32 v85, v85
	v_pk_fma_f32 v[80:81], v[136:137], v[108:109], v[80:81]
	v_mul_f32_e32 v29, v29, v84
	v_pk_fma_f32 v[80:81], v[138:139], v[76:77], v[80:81]
	v_pk_fma_f32 v[82:83], v[136:137], v[76:77], v[82:83]
	v_mul_f32_e32 v28, v28, v29
	v_add_f32_e32 v29, 1.0, v85
	v_mul_f32_e32 v84, 0xbfb8aa3b, v81
	v_rcp_f32_e32 v29, v29
	v_exp_f32_e32 v84, v84
	v_mul_f32_e32 v85, 0xbfb8aa3b, v83
	v_exp_f32_e32 v85, v85
	v_mul_f32_e32 v29, v31, v29
	v_add_f32_e32 v31, 1.0, v84
	v_rcp_f32_e32 v31, v31
	v_add_f32_e32 v84, 1.0, v85
	v_rcp_f32_e32 v84, v84
	v_mul_f32_e32 v85, v30, v29
	v_mul_f32_e32 v29, v81, v31
	v_lshl_or_b32 v72, s56, 7, v210
	v_mul_f32_e32 v80, v80, v29
	v_mul_f32_e32 v29, v83, v84
	v_lshl_add_u32 v146, s57, 8, v209
	v_ashrrev_i32_e32 v73, 31, v72
	v_mul_f32_e32 v81, v82, v29
	v_cvt_pk_bf16_f32 v104, v79, v115
	v_cvt_pk_bf16_f32 v105, v90, v28
	v_mov_b64_e32 v[28:29], s[24:25]
	v_mad_i64_i32 v[30:31], s[28:29], v146, s54, v[28:29]
	v_lshlrev_b64 v[82:83], 1, v[72:73]
	v_lshl_add_u64 v[30:31], v[30:31], 0, v[82:83]
	global_store_dwordx4 v[30:31], v[102:105], off sc1 nt
	v_or_b32_e32 v30, 1, v146
	v_mad_i64_i32 v[30:31], s[28:29], v30, s54, v[28:29]
	v_lshl_add_u64 v[30:31], v[30:31], 0, v[82:83]
	v_cvt_pk_bf16_f32 v102, v114, v119
	v_cvt_pk_bf16_f32 v103, v88, v85
	global_store_dwordx4 v[30:31], v[100:103], off sc1 nt
	v_or_b32_e32 v30, 2, v146
	v_mad_i64_i32 v[30:31], s[28:29], v30, s54, v[28:29]
	v_lshl_add_u64 v[30:31], v[30:31], 0, v[82:83]
	v_cvt_pk_bf16_f32 v100, v118, v123
	v_cvt_pk_bf16_f32 v101, v89, v80
	global_store_dwordx4 v[30:31], v[98:101], off sc1 nt
	v_or_b32_e32 v30, 3, v146
	v_mad_i64_i32 v[28:29], s[28:29], v30, s54, v[28:29]
	v_cvt_pk_bf16_f32 v72, v122, v126
	v_cvt_pk_bf16_f32 v73, v92, v81
	v_lshl_add_u64 v[28:29], v[28:29], 0, v[82:83]
	global_store_dwordx4 v[28:29], v[70:73], off sc1 nt
	s_andn2_b64 vcc, exec, s[26:27]
	v_mov_b32_e32 v84, 0
	v_mov_b32_e32 v80, 0
	v_mov_b32_e32 v70, 0
	v_mov_b32_e32 v28, 0
	v_mov_b32_e32 v86, 0
	v_mov_b32_e32 v30, 0
	v_mov_b32_e32 v72, 0
	v_mov_b32_e32 v79, 0
	v_mov_b32_e32 v85, 0
	v_mov_b32_e32 v81, 0
	v_mov_b32_e32 v71, 0
	v_mov_b32_e32 v29, 0
	v_mov_b32_e32 v87, 0
	v_mov_b32_e32 v31, 0
	v_mov_b32_e32 v73, 0
	s_cbranch_vccnz .LBB0_1656
	ds_read_b128 v[78:81], v160 offset:1552
	ds_read_b128 v[28:31], v160 offset:528
	ds_read_b128 v[88:91], v160 offset:16
	ds_read_b128 v[92:95], v160 offset:1040
	s_waitcnt lgkmcnt(0)
	v_mov_b32_e32 v84, v79
	v_mov_b32_e32 v70, v81
	v_mov_b32_e32 v86, v29
	v_mov_b32_e32 v72, v31
	v_mov_b32_e32 v79, v92
	v_mov_b32_e32 v85, v93
	v_mov_b32_e32 v81, v94
	v_mov_b32_e32 v71, v95
	v_mov_b32_e32 v29, v88
	v_mov_b32_e32 v87, v89
	v_mov_b32_e32 v31, v90
	v_mov_b32_e32 v73, v91
.LBB0_1656:
	v_mov_b32_e32 v88, v68
	v_mov_b32_e32 v89, v68
	v_mov_b32_e32 v92, v68
	v_mov_b32_e32 v93, v68
	v_pk_mul_f32 v[12:13], v[12:13], v[88:89]
	v_pk_mul_f32 v[88:89], v[4:5], v[88:89]
	v_mov_b32_e32 v68, v69
	v_mov_b32_dpp v79, v52 row_shr:1 row_mask:0xf bank_mask:0xf
	v_mov_b32_dpp v78, v56 row_shr:1 row_mask:0xf bank_mask:0xf
	v_mov_b32_e32 v90, v69
	v_mov_b32_e32 v91, v69
	v_pk_mul_f32 v[4:5], v[10:11], v[68:69]
	v_pk_mul_f32 v[2:3], v[2:3], v[68:69]
	v_mov_b32_e32 v10, v88
	v_mov_b32_e32 v11, v12
	v_pk_mul_f32 v[68:69], v[36:37], v[78:79]
	v_mov_b32_dpp v29, v44 row_shr:1 row_mask:0xf bank_mask:0xf
	v_mov_b32_dpp v28, v48 row_shr:1 row_mask:0xf bank_mask:0xf
	v_pk_fma_f32 v[68:69], v[10:11], v[34:35], v[68:69]
	v_pk_mul_f32 v[0:1], v[0:1], v[90:91]
	v_pk_fma_f32 v[28:29], v[32:33], v[28:29], v[68:69]
	v_mov_b32_e32 v68, v0
	v_mul_f32_e32 v0, 0xbfb8aa3b, v29
	v_pk_mul_f32 v[8:9], v[8:9], v[90:91]
	v_exp_f32_e32 v0, v0
	v_mov_b32_e32 v69, v8
	v_pk_mul_f32 v[90:91], v[68:69], v[34:35]
	v_pk_mul_f32 v[14:15], v[14:15], v[92:93]
	v_pk_fma_f32 v[90:91], v[10:11], v[36:37], v[90:91]
	v_add_f32_e32 v0, 1.0, v0
	v_pk_fma_f32 v[78:79], v[32:33], v[78:79], v[90:91]
	v_mov_b32_e32 v90, v48
	v_mov_b32_e32 v91, v44
	v_pk_mul_f32 v[6:7], v[6:7], v[92:93]
	v_pk_mul_f32 v[92:93], v[90:91], v[34:35]
	v_rcp_f32_e32 v0, v0
	v_mul_f32_e32 v8, 0xbfb8aa3b, v79
	v_pk_fma_f32 v[92:93], v[68:69], v[36:37], v[92:93]
	v_exp_f32_e32 v8, v8
	v_pk_fma_f32 v[10:11], v[10:11], v[32:33], v[92:93]
	v_mov_b32_e32 v92, v56
	v_mov_b32_e32 v93, v52
	v_pk_mul_f32 v[34:35], v[92:93], v[34:35]
	v_mul_f32_e32 v0, v29, v0
	v_pk_fma_f32 v[34:35], v[90:91], v[36:37], v[34:35]
	v_mov_b32_dpp v85, v53 row_shr:1 row_mask:0xf bank_mask:0xf
	v_pk_fma_f32 v[32:33], v[68:69], v[32:33], v[34:35]
	v_mul_f32_e32 v34, v28, v0
	v_add_f32_e32 v0, 1.0, v8
	v_mul_f32_e32 v8, 0xbfb8aa3b, v11
	v_exp_f32_e32 v8, v8
	v_mul_f32_e32 v12, 0xbfb8aa3b, v33
	v_exp_f32_e32 v12, v12
	v_rcp_f32_e32 v0, v0
	v_add_f32_e32 v8, 1.0, v8
	v_rcp_f32_e32 v8, v8
	v_add_f32_e32 v12, 1.0, v12
	v_rcp_f32_e32 v12, v12
	v_mul_f32_e32 v0, v79, v0
	v_mul_f32_e32 v35, v78, v0
	v_mul_f32_e32 v0, v11, v8
	v_mov_b32_dpp v84, v57 row_shr:1 row_mask:0xf bank_mask:0xf
	v_mul_f32_e32 v36, v10, v0
	v_mul_f32_e32 v0, v33, v12
	v_mov_b32_e32 v12, v89
	v_pk_mul_f32 v[10:11], v[106:107], v[84:85]
	v_mov_b32_e32 v44, v49
	v_mov_b32_dpp v87, v45 row_shr:1 row_mask:0xf bank_mask:0xf
	v_mov_b32_dpp v86, v49 row_shr:1 row_mask:0xf bank_mask:0xf
	v_pk_fma_f32 v[10:11], v[12:13], v[110:111], v[10:11]
	v_mov_b32_e32 v8, v1
	v_pk_mul_f32 v[28:29], v[44:45], v[110:111]
	v_mul_f32_e32 v32, v32, v0
	v_pk_fma_f32 v[10:11], v[74:75], v[86:87], v[10:11]
	v_pk_mul_f32 v[0:1], v[8:9], v[110:111]
	v_pk_fma_f32 v[28:29], v[8:9], v[106:107], v[28:29]
	v_pk_fma_f32 v[0:1], v[12:13], v[106:107], v[0:1]
	v_pk_fma_f32 v[12:13], v[12:13], v[74:75], v[28:29]
	v_mul_f32_e32 v28, 0xbfb8aa3b, v11
	v_exp_f32_e32 v33, v28
	v_pk_fma_f32 v[0:1], v[74:75], v[84:85], v[0:1]
	v_mov_b32_e32 v52, v57
	v_mul_f32_e32 v37, 0xbfb8aa3b, v1
	v_add_f32_e32 v33, 1.0, v33
	v_rcp_f32_e32 v33, v33
	v_exp_f32_e32 v37, v37
	v_pk_mul_f32 v[28:29], v[52:53], v[110:111]
	v_mov_b32_dpp v81, v54 row_shr:1 row_mask:0xf bank_mask:0xf
	v_pk_fma_f32 v[28:29], v[44:45], v[106:107], v[28:29]
	v_mul_f32_e32 v11, v11, v33
	v_pk_fma_f32 v[8:9], v[8:9], v[74:75], v[28:29]
	v_mul_f32_e32 v33, v10, v11
	v_add_f32_e32 v10, 1.0, v37
	v_mul_f32_e32 v11, 0xbfb8aa3b, v13
	v_rcp_f32_e32 v10, v10
	v_exp_f32_e32 v11, v11
	v_mul_f32_e32 v28, 0xbfb8aa3b, v9
	v_exp_f32_e32 v28, v28
	v_mul_f32_e32 v1, v1, v10
	v_add_f32_e32 v10, 1.0, v11
	v_rcp_f32_e32 v10, v10
	v_add_f32_e32 v11, 1.0, v28
	v_rcp_f32_e32 v11, v11
	v_mul_f32_e32 v37, v0, v1
	v_mul_f32_e32 v0, v13, v10
	v_mul_f32_e32 v44, v12, v0
	v_mul_f32_e32 v0, v9, v11
	v_mov_b32_dpp v80, v58 row_shr:1 row_mask:0xf bank_mask:0xf
	v_mul_f32_e32 v45, v8, v0
	v_mov_b32_e32 v0, v6
	v_mov_b32_e32 v1, v14
	v_pk_mul_f32 v[8:9], v[42:43], v[80:81]
	v_mov_b32_dpp v31, v46 row_shr:1 row_mask:0xf bank_mask:0xf
	v_mov_b32_dpp v30, v50 row_shr:1 row_mask:0xf bank_mask:0xf
	v_pk_fma_f32 v[8:9], v[0:1], v[40:41], v[8:9]
	v_mov_b32_e32 v10, v2
	v_pk_fma_f32 v[8:9], v[38:39], v[30:31], v[8:9]
	v_mov_b32_e32 v11, v4
	v_mul_f32_e32 v2, 0xbfb8aa3b, v9
	v_exp_f32_e32 v2, v2
	v_pk_mul_f32 v[12:13], v[10:11], v[40:41]
	v_mov_b32_e32 v28, v50
	v_pk_fma_f32 v[12:13], v[0:1], v[42:43], v[12:13]
	v_mov_b32_e32 v29, v46
	v_pk_fma_f32 v[12:13], v[38:39], v[80:81], v[12:13]
	v_add_f32_e32 v2, 1.0, v2
	v_pk_mul_f32 v[30:31], v[28:29], v[40:41]
	v_rcp_f32_e32 v2, v2
	v_mul_f32_e32 v4, 0xbfb8aa3b, v13
	v_pk_fma_f32 v[30:31], v[10:11], v[42:43], v[30:31]
	v_exp_f32_e32 v4, v4
	v_pk_fma_f32 v[0:1], v[0:1], v[38:39], v[30:31]
	v_mov_b32_e32 v30, v58
	v_mov_b32_e32 v31, v54
	v_pk_mul_f32 v[30:31], v[30:31], v[40:41]
	v_mul_f32_e32 v2, v9, v2
	v_pk_fma_f32 v[28:29], v[28:29], v[42:43], v[30:31]
	v_mov_b32_dpp v71, v55 row_shr:1 row_mask:0xf bank_mask:0xf
	v_pk_fma_f32 v[10:11], v[10:11], v[38:39], v[28:29]
	v_mul_f32_e32 v28, v8, v2
	v_add_f32_e32 v2, 1.0, v4
	v_mul_f32_e32 v4, 0xbfb8aa3b, v1
	v_exp_f32_e32 v4, v4
	v_mul_f32_e32 v6, 0xbfb8aa3b, v11
	v_exp_f32_e32 v6, v6
	v_rcp_f32_e32 v2, v2
	v_add_f32_e32 v4, 1.0, v4
	v_rcp_f32_e32 v4, v4
	v_add_f32_e32 v6, 1.0, v6
	v_rcp_f32_e32 v6, v6
	v_mul_f32_e32 v2, v13, v2
	v_mul_f32_e32 v1, v1, v4
	v_mul_f32_e32 v13, v0, v1
	v_mul_f32_e32 v0, v11, v6
	v_mov_b32_dpp v70, v59 row_shr:1 row_mask:0xf bank_mask:0xf
	v_mul_f32_e32 v10, v10, v0
	v_mov_b32_e32 v14, v7
	v_pk_mul_f32 v[0:1], v[108:109], v[70:71]
	v_mov_b32_dpp v73, v47 row_shr:1 row_mask:0xf bank_mask:0xf
	v_mov_b32_dpp v72, v51 row_shr:1 row_mask:0xf bank_mask:0xf
	v_pk_fma_f32 v[0:1], v[14:15], v[112:113], v[0:1]
	v_mov_b32_e32 v4, v3
	v_pk_fma_f32 v[0:1], v[76:77], v[72:73], v[0:1]
	v_mul_f32_e32 v12, v12, v2
	v_mul_f32_e32 v8, 0xbfb8aa3b, v1
	v_exp_f32_e32 v11, v8
	v_pk_mul_f32 v[2:3], v[4:5], v[112:113]
	v_mov_b32_e32 v46, v51
	v_pk_fma_f32 v[2:3], v[14:15], v[108:109], v[2:3]
	v_pk_mul_f32 v[6:7], v[46:47], v[112:113]
	v_pk_fma_f32 v[2:3], v[76:77], v[70:71], v[2:3]
	v_pk_fma_f32 v[6:7], v[4:5], v[108:109], v[6:7]
	v_add_f32_e32 v11, 1.0, v11
	v_pk_fma_f32 v[6:7], v[14:15], v[76:77], v[6:7]
	v_rcp_f32_e32 v11, v11
	v_mul_f32_e32 v14, 0xbfb8aa3b, v3
	v_exp_f32_e32 v14, v14
	v_mov_b32_e32 v54, v59
	v_pk_mul_f32 v[8:9], v[54:55], v[112:113]
	v_mul_f32_e32 v1, v1, v11
	v_pk_fma_f32 v[8:9], v[46:47], v[108:109], v[8:9]
	v_mul_f32_e32 v0, v0, v1
	v_pk_fma_f32 v[4:5], v[4:5], v[76:77], v[8:9]
	v_add_f32_e32 v1, 1.0, v14
	v_mul_f32_e32 v8, 0xbfb8aa3b, v7
	v_rcp_f32_e32 v1, v1
	v_exp_f32_e32 v8, v8
	v_mul_f32_e32 v9, 0xbfb8aa3b, v5
	v_exp_f32_e32 v9, v9
	v_mul_f32_e32 v1, v3, v1
	v_add_f32_e32 v3, 1.0, v8
	v_rcp_f32_e32 v3, v3
	v_add_f32_e32 v8, 1.0, v9
	v_rcp_f32_e32 v8, v8
	v_mul_f32_e32 v9, v2, v1
	v_mul_f32_e32 v1, v7, v3
	v_mul_f32_e32 v6, v6, v1
	v_mul_f32_e32 v1, v5, v8
	v_add_u32_e32 v94, 0x80, v146
	v_mul_f32_e32 v4, v4, v1
	v_cvt_pk_bf16_f32 v68, v34, v33
	v_cvt_pk_bf16_f32 v69, v28, v0
	v_mov_b64_e32 v[0:1], s[24:25]
	v_mad_i64_i32 v[2:3], s[26:27], v94, s54, v[0:1]
	v_lshl_add_u64 v[2:3], v[2:3], 0, v[82:83]
	global_store_dwordx4 v[2:3], v[66:69], off sc1 nt
	v_add_u32_e32 v2, 0x81, v146
	v_mad_i64_i32 v[2:3], s[26:27], v2, s54, v[0:1]
	v_lshl_add_u64 v[2:3], v[2:3], 0, v[82:83]
	v_cvt_pk_bf16_f32 v66, v35, v37
	v_cvt_pk_bf16_f32 v67, v12, v9
	global_store_dwordx4 v[2:3], v[64:67], off sc1 nt
	v_add_u32_e32 v2, 0x82, v146
	v_mad_i64_i32 v[2:3], s[26:27], v2, s54, v[0:1]
	v_lshl_add_u64 v[2:3], v[2:3], 0, v[82:83]
	v_cvt_pk_bf16_f32 v64, v36, v44
	v_cvt_pk_bf16_f32 v65, v13, v6
	global_store_dwordx4 v[2:3], v[62:65], off sc1 nt
	v_add_u32_e32 v2, 0x83, v146
	v_mad_i64_i32 v[0:1], s[26:27], v2, s54, v[0:1]
	v_lshl_add_u64 v[0:1], v[0:1], 0, v[82:83]
	v_cvt_pk_bf16_f32 v62, v32, v45
	v_cvt_pk_bf16_f32 v63, v10, v4
	global_store_dwordx4 v[0:1], v[60:63], off sc1 nt
	s_and_b64 vcc, exec, s[8:9]
	s_mov_b64 s[8:9], -1
	s_cbranch_vccnz .LBB0_1637
	s_xor_b32 s8, s11, 0x1000
	s_add_i32 s11, s8, 0
	s_add_i32 s11, s11, 0x24010
	s_and_saveexec_b64 s[8:9], s[2:3]
	s_cbranch_execz .LBB0_1659
	v_add3_u32 v0, s11, v215, v190
	s_waitcnt vmcnt(8)
	ds_write_b128 v0, v[16:19]

.LBB0_1741:
	ds_read_b128 v[128:131], v190
	ds_read_b128 v[132:135], v190 offset:1024
	ds_read_b128 v[136:139], v190 offset:2048
	ds_read_b128 v[140:143], v190 offset:3072
	s_add_u32 s16, s14, 0x100
	s_addc_u32 s17, s15, 0
	s_cmp_eq_u32 s47, 40
	s_cselect_b32 s21, s1, s17
	s_cselect_b32 s20, s0, s16
	s_cselect_b32 s19, s7, s46
	s_cselect_b32 s18, s6, s45
	v_lshl_add_u64 v[184:185], s[14:15], 0, v[160:161]
	s_add_i32 m0, s28, 0xc000
	ds_read_b128 v[144:147], v191
	ds_read_b128 v[148:151], v191 offset:1024
	ds_read_b128 v[168:171], v191 offset:2048
	ds_read_b128 v[172:175], v191 offset:3072
	ds_read_b128 v[176:179], v191 offset:4096
	ds_read_b128 v[180:183], v191 offset:5120
	ds_read_b128 v[194:197], v191 offset:6144
	ds_read_b128 v[198:201], v191 offset:7168
	global_load_lds_dwordx4 v[184:185], off
	v_lshl_add_u64 v[184:185], s[14:15], 0, v[162:163]
	s_add_i32 m0, s28, 0xe000
	s_nop 0
	global_load_lds_dwordx4 v[184:185], off
	s_waitcnt lgkmcnt(8)
	s_barrier
	s_waitcnt lgkmcnt(0)
	s_setprio 1
	s_waitcnt lgkmcnt(0)
	v_mfma_f32_16x16x32_bf16 v[124:127], v[128:131], v[144:147], v[124:127]
	v_mfma_f32_16x16x32_bf16 v[120:123], v[136:139], v[144:147], v[120:123]
	v_mfma_f32_16x16x32_bf16 v[108:111], v[128:131], v[168:171], v[108:111]
	v_mfma_f32_16x16x32_bf16 v[104:107], v[136:139], v[168:171], v[104:107]
	v_mfma_f32_16x16x32_bf16 v[92:95], v[128:131], v[176:179], v[92:95]
	v_mfma_f32_16x16x32_bf16 v[88:91], v[136:139], v[176:179], v[88:91]
	v_mfma_f32_16x16x32_bf16 v[76:79], v[128:131], v[194:197], v[76:79]
	v_mfma_f32_16x16x32_bf16 v[72:75], v[136:139], v[194:197], v[72:75]
	v_mfma_f32_16x16x32_bf16 v[124:127], v[132:135], v[148:151], v[124:127]
	v_mfma_f32_16x16x32_bf16 v[120:123], v[140:143], v[148:151], v[120:123]
	v_mfma_f32_16x16x32_bf16 v[108:111], v[132:135], v[172:175], v[108:111]
	v_mfma_f32_16x16x32_bf16 v[104:107], v[140:143], v[172:175], v[104:107]
	v_mfma_f32_16x16x32_bf16 v[92:95], v[132:135], v[180:183], v[92:95]
	v_mfma_f32_16x16x32_bf16 v[88:91], v[140:143], v[180:183], v[88:91]
	v_mfma_f32_16x16x32_bf16 v[76:79], v[132:135], v[198:201], v[76:79]
	v_mfma_f32_16x16x32_bf16 v[72:75], v[140:143], v[198:201], v[72:75]
	s_setprio 0
	s_barrier
	s_add_i32 s14, s39, s27
	v_lshl_add_u64 v[184:185], s[18:19], 0, v[154:155]
	s_mov_b32 m0, s14
	ds_read_b128 v[202:205], v192
	ds_read_b128 v[206:209], v192 offset:1024
	ds_read_b128 v[210:213], v192 offset:2048
	ds_read_b128 v[214:217], v192 offset:3072
	global_load_lds_dwordx4 v[184:185], off
	v_lshl_add_u64 v[218:219], s[18:19], 0, v[158:159]
	s_add_i32 m0, s14, 0x2000
	s_nop 0
	global_load_lds_dwordx4 v[218:219], off
	s_barrier
	s_waitcnt lgkmcnt(0)
	s_setprio 1
	s_waitcnt lgkmcnt(0)
	v_mfma_f32_16x16x32_bf16 v[116:119], v[202:205], v[144:147], v[116:119]
	v_mfma_f32_16x16x32_bf16 v[112:115], v[210:213], v[144:147], v[112:115]
	v_mfma_f32_16x16x32_bf16 v[100:103], v[202:205], v[168:171], v[100:103]
	v_mfma_f32_16x16x32_bf16 v[96:99], v[210:213], v[168:171], v[96:99]
	v_mfma_f32_16x16x32_bf16 v[84:87], v[202:205], v[176:179], v[84:87]
	v_mfma_f32_16x16x32_bf16 v[80:83], v[210:213], v[176:179], v[80:83]
	v_mfma_f32_16x16x32_bf16 v[68:71], v[202:205], v[194:197], v[68:71]
	v_mfma_f32_16x16x32_bf16 v[64:67], v[210:213], v[194:197], v[64:67]
	v_mfma_f32_16x16x32_bf16 v[116:119], v[206:209], v[148:151], v[116:119]
	v_mfma_f32_16x16x32_bf16 v[112:115], v[214:217], v[148:151], v[112:115]
	v_mfma_f32_16x16x32_bf16 v[100:103], v[206:209], v[172:175], v[100:103]
	v_mfma_f32_16x16x32_bf16 v[96:99], v[214:217], v[172:175], v[96:99]
	v_mfma_f32_16x16x32_bf16 v[84:87], v[206:209], v[180:183], v[84:87]
	v_mfma_f32_16x16x32_bf16 v[80:83], v[214:217], v[180:183], v[80:83]
	v_mfma_f32_16x16x32_bf16 v[68:71], v[206:209], v[198:201], v[68:71]
	v_mfma_f32_16x16x32_bf16 v[64:67], v[214:217], v[198:201], v[64:67]
	s_setprio 0
	s_mov_b32 m0, s28
	v_lshl_add_u64 v[220:221], s[20:21], 0, v[152:153]
	s_barrier
	ds_read_b128 v[144:147], v191 offset:16384
	ds_read_b128 v[148:151], v191 offset:17408
	ds_read_b128 v[168:171], v191 offset:18432
	ds_read_b128 v[172:175], v191 offset:19456
	ds_read_b128 v[176:179], v191 offset:20480
	ds_read_b128 v[180:183], v191 offset:21504
	ds_read_b128 v[194:197], v191 offset:22528
	ds_read_b128 v[198:201], v191 offset:23552
	global_load_lds_dwordx4 v[220:221], off
	v_lshl_add_u64 v[222:223], s[20:21], 0, v[156:157]
	s_mov_b32 m0, s29
	s_nop 0
	global_load_lds_dwordx4 v[222:223], off
	s_barrier
	s_waitcnt lgkmcnt(0)
	s_setprio 1
	s_waitcnt lgkmcnt(0)
	v_mfma_f32_16x16x32_bf16 v[60:63], v[128:131], v[144:147], v[60:63]
	v_mfma_f32_16x16x32_bf16 v[56:59], v[136:139], v[144:147], v[56:59]
	v_mfma_f32_16x16x32_bf16 v[44:47], v[128:131], v[168:171], v[44:47]
	v_mfma_f32_16x16x32_bf16 v[40:43], v[136:139], v[168:171], v[40:43]
	v_mfma_f32_16x16x32_bf16 v[28:31], v[128:131], v[176:179], v[28:31]
	v_mfma_f32_16x16x32_bf16 v[24:27], v[136:139], v[176:179], v[24:27]
	v_mfma_f32_16x16x32_bf16 v[12:15], v[128:131], v[194:197], v[12:15]
	v_mfma_f32_16x16x32_bf16 v[8:11], v[136:139], v[194:197], v[8:11]
	v_mfma_f32_16x16x32_bf16 v[60:63], v[132:135], v[148:151], v[60:63]
	v_mfma_f32_16x16x32_bf16 v[56:59], v[140:143], v[148:151], v[56:59]
	v_mfma_f32_16x16x32_bf16 v[44:47], v[132:135], v[172:175], v[44:47]
	v_mfma_f32_16x16x32_bf16 v[40:43], v[140:143], v[172:175], v[40:43]
	v_mfma_f32_16x16x32_bf16 v[28:31], v[132:135], v[180:183], v[28:31]
	v_mfma_f32_16x16x32_bf16 v[24:27], v[140:143], v[180:183], v[24:27]
	v_mfma_f32_16x16x32_bf16 v[12:15], v[132:135], v[198:201], v[12:15]
	v_mfma_f32_16x16x32_bf16 v[8:11], v[140:143], v[198:201], v[8:11]
	s_setprio 0
	s_barrier
	s_add_u32 s14, s18, 0xb0000
	s_addc_u32 s15, s19, 0
	s_add_i32 s48, s40, s27
	v_lshl_add_u64 v[128:129], s[14:15], 0, v[154:155]
	s_mov_b32 m0, s48
	s_nop 0
	global_load_lds_dwordx4 v[128:129], off
	v_lshl_add_u64 v[128:129], s[14:15], 0, v[158:159]
	s_add_i32 m0, s48, 0x2000
	s_nop 0
	global_load_lds_dwordx4 v[128:129], off
	s_waitcnt vmcnt(6)
	s_barrier
	s_setprio 1
	v_mfma_f32_16x16x32_bf16 v[52:55], v[202:205], v[144:147], v[52:55]
	v_mfma_f32_16x16x32_bf16 v[48:51], v[210:213], v[144:147], v[48:51]
	v_mfma_f32_16x16x32_bf16 v[36:39], v[202:205], v[168:171], v[36:39]
	v_mfma_f32_16x16x32_bf16 v[32:35], v[210:213], v[168:171], v[32:35]
	v_mfma_f32_16x16x32_bf16 v[20:23], v[202:205], v[176:179], v[20:23]
	v_mfma_f32_16x16x32_bf16 v[16:19], v[210:213], v[176:179], v[16:19]
	v_mfma_f32_16x16x32_bf16 v[4:7], v[202:205], v[194:197], v[4:7]
	v_mfma_f32_16x16x32_bf16 v[0:3], v[210:213], v[194:197], v[0:3]
	v_mfma_f32_16x16x32_bf16 v[52:55], v[206:209], v[148:151], v[52:55]
	v_mfma_f32_16x16x32_bf16 v[48:51], v[214:217], v[148:151], v[48:51]
	v_mfma_f32_16x16x32_bf16 v[36:39], v[206:209], v[172:175], v[36:39]
	v_mfma_f32_16x16x32_bf16 v[32:35], v[214:217], v[172:175], v[32:35]
	v_mfma_f32_16x16x32_bf16 v[20:23], v[206:209], v[180:183], v[20:23]
	v_mfma_f32_16x16x32_bf16 v[16:19], v[214:217], v[180:183], v[16:19]
	v_mfma_f32_16x16x32_bf16 v[4:7], v[206:209], v[198:201], v[4:7]
	v_mfma_f32_16x16x32_bf16 v[0:3], v[214:217], v[198:201], v[0:3]
	s_setprio 0
	s_add_i32 s48, 0, 0x18000
	v_add_u32_e32 v140, s48, v187
	s_barrier
	ds_read_b128 v[128:131], v140
	ds_read_b128 v[132:135], v140 offset:1024
	ds_read_b128 v[136:139], v140 offset:2048
	ds_read_b128 v[140:143], v140 offset:3072
	s_add_u32 s14, s20, 0xb0000
	s_addc_u32 s15, s21, 0
	s_mov_b32 m0, s30
	v_lshl_add_u64 v[202:203], s[14:15], 0, v[152:153]
	ds_read_b128 v[144:147], v191 offset:32768
	ds_read_b128 v[148:151], v191 offset:33792
	ds_read_b128 v[168:171], v191 offset:34816
	ds_read_b128 v[172:175], v191 offset:35840
	ds_read_b128 v[176:179], v191 offset:36864
	ds_read_b128 v[180:183], v191 offset:37888
	ds_read_b128 v[194:197], v191 offset:38912
	ds_read_b128 v[198:201], v191 offset:39936
	global_load_lds_dwordx4 v[202:203], off
	v_lshl_add_u64 v[202:203], s[14:15], 0, v[156:157]
	s_mov_b32 m0, s31
	s_nop 0
	global_load_lds_dwordx4 v[202:203], off
	s_waitcnt lgkmcnt(8)
	s_barrier
	s_waitcnt lgkmcnt(0)
	s_setprio 1
	s_waitcnt lgkmcnt(0)
	v_mfma_f32_16x16x32_bf16 v[124:127], v[128:131], v[144:147], v[124:127]
	v_mfma_f32_16x16x32_bf16 v[120:123], v[136:139], v[144:147], v[120:123]
	v_mfma_f32_16x16x32_bf16 v[108:111], v[128:131], v[168:171], v[108:111]
	v_mfma_f32_16x16x32_bf16 v[104:107], v[136:139], v[168:171], v[104:107]
	v_mfma_f32_16x16x32_bf16 v[92:95], v[128:131], v[176:179], v[92:95]
	v_mfma_f32_16x16x32_bf16 v[88:91], v[136:139], v[176:179], v[88:91]
	v_mfma_f32_16x16x32_bf16 v[76:79], v[128:131], v[194:197], v[76:79]
	v_mfma_f32_16x16x32_bf16 v[72:75], v[136:139], v[194:197], v[72:75]
	v_mfma_f32_16x16x32_bf16 v[124:127], v[132:135], v[148:151], v[124:127]
	v_mfma_f32_16x16x32_bf16 v[120:123], v[140:143], v[148:151], v[120:123]
	v_mfma_f32_16x16x32_bf16 v[108:111], v[132:135], v[172:175], v[108:111]
	v_mfma_f32_16x16x32_bf16 v[104:107], v[140:143], v[172:175], v[104:107]
	v_mfma_f32_16x16x32_bf16 v[92:95], v[132:135], v[180:183], v[92:95]
	v_mfma_f32_16x16x32_bf16 v[88:91], v[140:143], v[180:183], v[88:91]
	v_mfma_f32_16x16x32_bf16 v[76:79], v[132:135], v[198:201], v[76:79]
	v_mfma_f32_16x16x32_bf16 v[72:75], v[140:143], v[198:201], v[72:75]
	s_setprio 0
	s_barrier
	s_add_i32 s20, 0, 0x1c000
	s_add_i32 s14, s48, s27
	v_add_u32_e32 v214, s20, v187
	v_lshl_add_u64 v[184:185], v[184:185], 0, s[12:13]
	s_mov_b32 m0, s14
	ds_read_b128 v[202:205], v214
	ds_read_b128 v[206:209], v214 offset:1024
	ds_read_b128 v[210:213], v214 offset:2048
	ds_read_b128 v[214:217], v214 offset:3072
	global_load_lds_dwordx4 v[184:185], off
	v_lshl_add_u64 v[184:185], v[218:219], 0, s[12:13]
	s_add_i32 m0, s14, 0x2000
	s_nop 0
	global_load_lds_dwordx4 v[184:185], off
	s_barrier
	s_waitcnt lgkmcnt(0)
	s_setprio 1
	s_waitcnt lgkmcnt(0)
	v_mfma_f32_16x16x32_bf16 v[116:119], v[202:205], v[144:147], v[116:119]
	v_mfma_f32_16x16x32_bf16 v[112:115], v[210:213], v[144:147], v[112:115]
	v_mfma_f32_16x16x32_bf16 v[100:103], v[202:205], v[168:171], v[100:103]
	v_mfma_f32_16x16x32_bf16 v[96:99], v[210:213], v[168:171], v[96:99]
	v_mfma_f32_16x16x32_bf16 v[84:87], v[202:205], v[176:179], v[84:87]
	v_mfma_f32_16x16x32_bf16 v[80:83], v[210:213], v[176:179], v[80:83]
	v_mfma_f32_16x16x32_bf16 v[68:71], v[202:205], v[194:197], v[68:71]
	v_mfma_f32_16x16x32_bf16 v[64:67], v[210:213], v[194:197], v[64:67]
	v_mfma_f32_16x16x32_bf16 v[116:119], v[206:209], v[148:151], v[116:119]
	v_mfma_f32_16x16x32_bf16 v[112:115], v[214:217], v[148:151], v[112:115]
	v_mfma_f32_16x16x32_bf16 v[100:103], v[206:209], v[172:175], v[100:103]
	v_mfma_f32_16x16x32_bf16 v[96:99], v[214:217], v[172:175], v[96:99]
	v_mfma_f32_16x16x32_bf16 v[84:87], v[206:209], v[180:183], v[84:87]
	v_mfma_f32_16x16x32_bf16 v[80:83], v[214:217], v[180:183], v[80:83]
	v_mfma_f32_16x16x32_bf16 v[68:71], v[206:209], v[198:201], v[68:71]
	v_mfma_f32_16x16x32_bf16 v[64:67], v[214:217], v[198:201], v[64:67]
	s_setprio 0
	s_mov_b32 m0, s35
	v_lshl_add_u64 v[184:185], v[220:221], 0, s[12:13]
	s_barrier
	ds_read_b128 v[144:147], v191 offset:49152
	ds_read_b128 v[148:151], v191 offset:50176
	ds_read_b128 v[168:171], v191 offset:51200
	ds_read_b128 v[172:175], v191 offset:52224
	ds_read_b128 v[176:179], v191 offset:53248
	ds_read_b128 v[180:183], v191 offset:54272
	ds_read_b128 v[194:197], v191 offset:55296
	ds_read_b128 v[198:201], v191 offset:56320
	global_load_lds_dwordx4 v[184:185], off
	v_lshl_add_u64 v[184:185], v[222:223], 0, s[12:13]
	s_mov_b32 m0, s36
	s_nop 0
	global_load_lds_dwordx4 v[184:185], off
	s_barrier
	s_waitcnt lgkmcnt(0)
	s_setprio 1
	s_waitcnt lgkmcnt(0)
	v_mfma_f32_16x16x32_bf16 v[60:63], v[128:131], v[144:147], v[60:63]
	v_mfma_f32_16x16x32_bf16 v[56:59], v[136:139], v[144:147], v[56:59]
	v_mfma_f32_16x16x32_bf16 v[44:47], v[128:131], v[168:171], v[44:47]
	v_mfma_f32_16x16x32_bf16 v[40:43], v[136:139], v[168:171], v[40:43]
	v_mfma_f32_16x16x32_bf16 v[28:31], v[128:131], v[176:179], v[28:31]
	v_mfma_f32_16x16x32_bf16 v[24:27], v[136:139], v[176:179], v[24:27]
	v_mfma_f32_16x16x32_bf16 v[12:15], v[128:131], v[194:197], v[12:15]
	v_mfma_f32_16x16x32_bf16 v[8:11], v[136:139], v[194:197], v[8:11]
	v_mfma_f32_16x16x32_bf16 v[60:63], v[132:135], v[148:151], v[60:63]
	v_mfma_f32_16x16x32_bf16 v[56:59], v[140:143], v[148:151], v[56:59]
	v_mfma_f32_16x16x32_bf16 v[44:47], v[132:135], v[172:175], v[44:47]
	v_mfma_f32_16x16x32_bf16 v[40:43], v[140:143], v[172:175], v[40:43]
	v_mfma_f32_16x16x32_bf16 v[28:31], v[132:135], v[180:183], v[28:31]
	v_mfma_f32_16x16x32_bf16 v[24:27], v[140:143], v[180:183], v[24:27]
	v_mfma_f32_16x16x32_bf16 v[12:15], v[132:135], v[198:201], v[12:15]
	v_mfma_f32_16x16x32_bf16 v[8:11], v[140:143], v[198:201], v[8:11]
	s_setprio 0
	s_barrier
	s_add_u32 s14, s18, 0xb0080
	s_addc_u32 s15, s19, 0
	s_add_i32 s18, s20, s27
	v_lshl_add_u64 v[128:129], s[14:15], 0, v[154:155]
	s_mov_b32 m0, s18
	s_nop 0
	global_load_lds_dwordx4 v[128:129], off
	v_lshl_add_u64 v[128:129], s[14:15], 0, v[158:159]
	s_add_i32 m0, s18, 0x2000
	s_nop 0
	global_load_lds_dwordx4 v[128:129], off
	s_waitcnt vmcnt(6)
	s_barrier
	s_setprio 1
	v_mfma_f32_16x16x32_bf16 v[52:55], v[202:205], v[144:147], v[52:55]
	v_mfma_f32_16x16x32_bf16 v[48:51], v[210:213], v[144:147], v[48:51]
	v_mfma_f32_16x16x32_bf16 v[36:39], v[202:205], v[168:171], v[36:39]
	v_mfma_f32_16x16x32_bf16 v[32:35], v[210:213], v[168:171], v[32:35]
	v_mfma_f32_16x16x32_bf16 v[20:23], v[202:205], v[176:179], v[20:23]
	v_mfma_f32_16x16x32_bf16 v[16:19], v[210:213], v[176:179], v[16:19]
	v_mfma_f32_16x16x32_bf16 v[4:7], v[202:205], v[194:197], v[4:7]
	v_mfma_f32_16x16x32_bf16 v[0:3], v[210:213], v[194:197], v[0:3]
	v_mfma_f32_16x16x32_bf16 v[52:55], v[206:209], v[148:151], v[52:55]
	v_mfma_f32_16x16x32_bf16 v[48:51], v[214:217], v[148:151], v[48:51]
	v_mfma_f32_16x16x32_bf16 v[36:39], v[206:209], v[172:175], v[36:39]
	v_mfma_f32_16x16x32_bf16 v[32:35], v[214:217], v[172:175], v[32:35]
	v_mfma_f32_16x16x32_bf16 v[20:23], v[206:209], v[180:183], v[20:23]
	v_mfma_f32_16x16x32_bf16 v[16:19], v[214:217], v[180:183], v[16:19]
	v_mfma_f32_16x16x32_bf16 v[4:7], v[206:209], v[198:201], v[4:7]
	v_mfma_f32_16x16x32_bf16 v[0:3], v[214:217], v[198:201], v[0:3]
	s_setprio 0
	s_add_i32 s47, s47, 2
	s_add_u32 s45, s45, 0x100
	s_addc_u32 s46, s46, 0
	s_cmp_gt_u32 s47, 41
	s_mov_b64 s[14:15], s[16:17]
	s_barrier
	s_cbranch_scc0 .LBB0_1741
	v_lshl_or_b32 v168, s10, 8, v189
	v_lshl_add_u32 v170, s44, 8, v186
	v_ashrrev_i32_e32 v169, 31, v168
	v_lshlrev_b64 v[202:203], 1, v[168:169]
	v_ashrrev_i32_e32 v171, 31, v170
	v_or_b32_e32 v182, 16, v170
	v_lshl_add_u64 v[172:173], s[64:65], 0, v[202:203]
	v_lshlrev_b64 v[204:205], 11, v[170:171]
	v_ashrrev_i32_e32 v183, 31, v182
	v_or_b32_e32 v178, 32, v170
	v_lshl_add_u64 v[128:129], v[172:173], 0, v[204:205]
	v_lshlrev_b64 v[184:185], 11, v[182:183]
	v_ashrrev_i32_e32 v179, 31, v178
	v_or_b32_e32 v174, 48, v170
	global_load_dwordx4 v[194:197], v[128:129], off
	global_load_dwordx4 v[198:201], v[128:129], off offset:256
	v_lshl_add_u64 v[128:129], v[172:173], 0, v[184:185]
	v_lshlrev_b64 v[180:181], 11, v[178:179]
	v_ashrrev_i32_e32 v175, 31, v174
	global_load_dwordx4 v[148:151], v[128:129], off
	global_load_dwordx4 v[144:147], v[128:129], off offset:256
	v_lshl_add_u64 v[128:129], v[172:173], 0, v[180:181]
	v_lshlrev_b64 v[176:177], 11, v[174:175]
	global_load_dwordx4 v[140:143], v[128:129], off
	global_load_dwordx4 v[136:139], v[128:129], off offset:256
	v_lshl_add_u64 v[128:129], v[172:173], 0, v[176:177]
	global_load_dwordx4 v[132:135], v[128:129], off
	s_nop 0
	global_load_dwordx4 v[128:131], v[128:129], off offset:256
	s_lshl_b32 s14, s10, 2
	s_ashr_i32 s15, s14, 31
	v_add_u32_e32 v252, 0x80, v170
	v_ashrrev_i32_e32 v253, 31, v252
	v_lshlrev_b64 v[252:253], 11, v[252:253]
	v_lshl_add_u64 v[252:253], v[172:173], 0, v[252:253]
	global_load_dwordx4 v[236:239], v[252:253], off
	global_load_dwordx4 v[240:243], v[252:253], off offset:256
	v_add_u32_e32 v252, 0x90, v170
	v_ashrrev_i32_e32 v253, 31, v252
	v_lshlrev_b64 v[252:253], 11, v[252:253]
	v_lshl_add_u64 v[252:253], v[172:173], 0, v[252:253]
	global_load_dwordx4 v[244:247], v[252:253], off
	global_load_dwordx4 v[248:251], v[252:253], off offset:256
	v_add_u32_e32 v252, 0xa0, v170
	v_ashrrev_i32_e32 v253, 31, v252
	v_lshlrev_b64 v[252:253], 11, v[252:253]
	v_lshl_add_u64 v[252:253], v[172:173], 0, v[252:253]
	global_load_dwordx4 v[210:213], v[252:253], off
	global_load_dwordx4 v[214:217], v[252:253], off offset:256
	s_waitcnt vmcnt(6)
	v_lshlrev_b32_e32 v206, 16, v194
	v_and_b32_e32 v207, 0xffff0000, v194
	v_lshlrev_b32_e32 v194, 16, v195
	v_and_b32_e32 v195, 0xffff0000, v195
	v_lshlrev_b32_e32 v208, 16, v196
	v_and_b32_e32 v209, 0xffff0000, v196
	v_lshlrev_b32_e32 v196, 16, v197
	v_and_b32_e32 v197, 0xffff0000, v197
	v_pk_add_f32 v[126:127], v[126:127], v[194:195]
	v_pk_add_f32 v[124:125], v[124:125], v[206:207]
	v_pk_add_f32 v[194:195], v[122:123], v[196:197]
	v_pk_add_f32 v[122:123], v[120:121], v[208:209]
	v_mul_f32_e32 v120, v125, v125
	v_mul_f32_e32 v121, v127, v127
	v_fmac_f32_e32 v120, v124, v124
	v_fmac_f32_e32 v121, v126, v126
	v_add_f32_e32 v120, v120, v121
	v_mul_f32_e32 v121, v123, v123
	v_mul_f32_e32 v196, v195, v195
	v_fmac_f32_e32 v121, v122, v122
	v_fmac_f32_e32 v196, v194, v194
	v_add_f32_e32 v121, v121, v196
	v_add_f32_e32 v206, v120, v121
	v_cvt_pk_bf16_f32 v120, v124, v125
	v_cvt_pk_bf16_f32 v121, v126, v127
	v_lshlrev_b32_e32 v124, 16, v198
	v_and_b32_e32 v125, 0xffff0000, v198
	v_lshlrev_b32_e32 v126, 16, v199
	v_and_b32_e32 v127, 0xffff0000, v199
	v_cvt_pk_bf16_f32 v122, v122, v123
	v_cvt_pk_bf16_f32 v123, v194, v195
	v_lshlrev_b32_e32 v194, 16, v200
	v_and_b32_e32 v195, 0xffff0000, v200
	v_pk_add_f32 v[118:119], v[118:119], v[126:127]
	v_pk_add_f32 v[116:117], v[116:117], v[124:125]
	v_lshlrev_b32_e32 v196, 16, v201
	v_and_b32_e32 v197, 0xffff0000, v201
	v_pk_add_f32 v[126:127], v[112:113], v[194:195]
	v_mul_f32_e32 v112, v117, v117
	v_mul_f32_e32 v113, v119, v119
	v_pk_add_f32 v[124:125], v[114:115], v[196:197]
	v_fmac_f32_e32 v112, v116, v116
	v_fmac_f32_e32 v113, v118, v118
	v_add_f32_e32 v112, v112, v113
	v_mul_f32_e32 v113, v127, v127
	v_mul_f32_e32 v114, v125, v125
	v_fmac_f32_e32 v113, v126, v126
	v_fmac_f32_e32 v114, v124, v124
	v_add_f32_e32 v113, v113, v114
	v_add_f32_e32 v112, v112, v113
	v_and_b32_e32 v114, 64, v193
	v_add_f32_e32 v113, v206, v112
	v_xor_b32_e32 v112, 16, v193
	v_add_u32_e32 v196, 64, v114
	v_cmp_lt_i32_e32 vcc, v112, v196
	v_lshl_add_u64 v[114:115], s[64:65], 0, v[204:205]
	v_lshl_add_u64 v[194:195], v[114:115], 0, v[202:203]
	v_cndmask_b32_e32 v112, v193, v112, vcc
	v_lshlrev_b32_e32 v112, 2, v112
	ds_bpermute_b32 v197, v112, v113
	global_store_dwordx4 v[194:195], v[120:123], off sc1
	v_cvt_pk_bf16_f32 v116, v116, v117
	v_cvt_pk_bf16_f32 v117, v118, v119
	v_cvt_pk_bf16_f32 v118, v126, v127
	s_waitcnt lgkmcnt(0)
	v_add_f32_e32 v114, v113, v197
	v_xor_b32_e32 v113, 32, v193
	v_cmp_lt_i32_e32 vcc, v113, v196
	v_cvt_pk_bf16_f32 v119, v124, v125
	global_store_dwordx4 v[194:195], v[116:119], off offset:256 sc1
	s_nop 0
	v_cndmask_b32_e32 v113, v193, v113, vcc
	v_lshlrev_b32_e32 v113, 2, v113
	ds_bpermute_b32 v115, v113, v114
	s_and_saveexec_b64 s[16:17], s[2:3]
	s_cbranch_execz .LBB0_1744
	s_waitcnt lgkmcnt(0)
	v_add_f32_e32 v116, v114, v115
	v_lshlrev_b64 v[114:115], 6, v[170:171]
	v_lshl_add_u64 v[114:115], s[74:75], 0, v[114:115]
	v_lshl_add_u64 v[114:115], s[14:15], 2, v[114:115]
	s_lshl_b32 s10, s34, 2
	v_lshl_add_u64 v[114:115], v[114:115], 0, s[10:11]
	global_store_dword v[114:115], v116, off
.LBB0_1744:
	s_or_b64 exec, exec, s[16:17]
	v_lshlrev_b32_e32 v114, 16, v148
	s_waitcnt lgkmcnt(0)
	v_and_b32_e32 v115, 0xffff0000, v148
	v_lshlrev_b32_e32 v116, 16, v149
	v_and_b32_e32 v117, 0xffff0000, v149
	v_lshlrev_b32_e32 v118, 16, v150
	v_and_b32_e32 v119, 0xffff0000, v150
	v_lshlrev_b32_e32 v120, 16, v151
	v_and_b32_e32 v121, 0xffff0000, v151
	v_pk_add_f32 v[110:111], v[110:111], v[116:117]
	v_pk_add_f32 v[108:109], v[108:109], v[114:115]
	v_pk_add_f32 v[114:115], v[106:107], v[120:121]
	v_pk_add_f32 v[106:107], v[104:105], v[118:119]
	v_mul_f32_e32 v104, v109, v109
	v_mul_f32_e32 v105, v111, v111
	v_fmac_f32_e32 v104, v108, v108
	v_fmac_f32_e32 v105, v110, v110
	v_add_f32_e32 v104, v104, v105
	v_mul_f32_e32 v105, v107, v107
	v_mul_f32_e32 v116, v115, v115
	v_fmac_f32_e32 v105, v106, v106
	v_fmac_f32_e32 v116, v114, v114
	v_add_f32_e32 v105, v105, v116
	v_add_f32_e32 v118, v104, v105
	v_cvt_pk_bf16_f32 v104, v108, v109
	v_cvt_pk_bf16_f32 v105, v110, v111
	v_lshlrev_b32_e32 v108, 16, v144
	v_and_b32_e32 v109, 0xffff0000, v144
	v_lshlrev_b32_e32 v110, 16, v145
	v_and_b32_e32 v111, 0xffff0000, v145
	v_cvt_pk_bf16_f32 v106, v106, v107
	v_cvt_pk_bf16_f32 v107, v114, v115
	v_lshlrev_b32_e32 v114, 16, v146
	v_and_b32_e32 v115, 0xffff0000, v146
	v_pk_add_f32 v[102:103], v[102:103], v[110:111]
	v_pk_add_f32 v[100:101], v[100:101], v[108:109]
	v_lshlrev_b32_e32 v116, 16, v147
	v_and_b32_e32 v117, 0xffff0000, v147
	v_pk_add_f32 v[110:111], v[96:97], v[114:115]
	v_mul_f32_e32 v96, v101, v101
	v_mul_f32_e32 v97, v103, v103
	v_pk_add_f32 v[108:109], v[98:99], v[116:117]
	v_fmac_f32_e32 v96, v100, v100
	v_fmac_f32_e32 v97, v102, v102
	v_add_f32_e32 v96, v96, v97
	v_mul_f32_e32 v97, v111, v111
	v_mul_f32_e32 v98, v109, v109
	v_fmac_f32_e32 v97, v110, v110
	v_fmac_f32_e32 v98, v108, v108
	v_add_f32_e32 v97, v97, v98
	v_add_f32_e32 v96, v96, v97
	v_add_f32_e32 v99, v118, v96
	ds_bpermute_b32 v116, v112, v99
	v_lshl_add_u64 v[96:97], s[64:65], 0, v[184:185]
	v_lshl_add_u64 v[114:115], v[168:169], 1, v[96:97]
	global_store_dwordx4 v[114:115], v[104:107], off sc1
	v_cvt_pk_bf16_f32 v98, v100, v101
	s_waitcnt lgkmcnt(0)
	v_add_f32_e32 v96, v99, v116
	ds_bpermute_b32 v97, v113, v96
	v_cvt_pk_bf16_f32 v99, v102, v103
	v_cvt_pk_bf16_f32 v100, v110, v111
	v_cvt_pk_bf16_f32 v101, v108, v109
	global_store_dwordx4 v[114:115], v[98:101], off offset:256 sc1
	s_and_saveexec_b64 s[16:17], s[2:3]
	s_cbranch_execz .LBB0_1746
	s_waitcnt lgkmcnt(0)
	v_add_f32_e32 v98, v96, v97
	v_lshlrev_b64 v[96:97], 6, v[182:183]
	v_lshl_add_u64 v[96:97], s[74:75], 0, v[96:97]
	v_lshl_add_u64 v[96:97], s[14:15], 2, v[96:97]
	s_lshl_b32 s10, s34, 2
	v_lshl_add_u64 v[96:97], v[96:97], 0, s[10:11]
	global_store_dword v[96:97], v98, off
.LBB0_1746:
	s_or_b64 exec, exec, s[16:17]
	v_lshlrev_b32_e32 v96, 16, v140
	s_waitcnt lgkmcnt(0)
	v_and_b32_e32 v97, 0xffff0000, v140
	v_lshlrev_b32_e32 v98, 16, v141
	v_and_b32_e32 v99, 0xffff0000, v141
	v_lshlrev_b32_e32 v100, 16, v142
	v_and_b32_e32 v101, 0xffff0000, v142
	v_lshlrev_b32_e32 v102, 16, v143
	v_and_b32_e32 v103, 0xffff0000, v143
	v_pk_add_f32 v[94:95], v[94:95], v[98:99]
	v_pk_add_f32 v[92:93], v[92:93], v[96:97]
	v_pk_add_f32 v[96:97], v[90:91], v[102:103]
	v_pk_add_f32 v[90:91], v[88:89], v[100:101]
	v_mul_f32_e32 v88, v93, v93
	v_mul_f32_e32 v89, v95, v95
	v_fmac_f32_e32 v88, v92, v92
	v_fmac_f32_e32 v89, v94, v94
	v_add_f32_e32 v88, v88, v89
	v_mul_f32_e32 v89, v91, v91
	v_mul_f32_e32 v98, v97, v97
	v_fmac_f32_e32 v89, v90, v90
	v_fmac_f32_e32 v98, v96, v96
	v_add_f32_e32 v89, v89, v98
	v_add_f32_e32 v100, v88, v89
	v_cvt_pk_bf16_f32 v88, v92, v93
	v_cvt_pk_bf16_f32 v89, v94, v95
	v_lshlrev_b32_e32 v92, 16, v136
	v_and_b32_e32 v93, 0xffff0000, v136
	v_lshlrev_b32_e32 v94, 16, v137
	v_and_b32_e32 v95, 0xffff0000, v137
	v_cvt_pk_bf16_f32 v90, v90, v91
	v_cvt_pk_bf16_f32 v91, v96, v97
	v_lshlrev_b32_e32 v96, 16, v138
	v_and_b32_e32 v97, 0xffff0000, v138
	v_pk_add_f32 v[86:87], v[86:87], v[94:95]
	v_pk_add_f32 v[84:85], v[84:85], v[92:93]
	v_lshlrev_b32_e32 v98, 16, v139
	v_and_b32_e32 v99, 0xffff0000, v139
	v_pk_add_f32 v[94:95], v[80:81], v[96:97]
	v_mul_f32_e32 v80, v85, v85
	v_mul_f32_e32 v81, v87, v87
	v_pk_add_f32 v[92:93], v[82:83], v[98:99]
	v_fmac_f32_e32 v80, v84, v84
	v_fmac_f32_e32 v81, v86, v86
	v_add_f32_e32 v80, v80, v81
	v_mul_f32_e32 v81, v95, v95
	v_mul_f32_e32 v82, v93, v93
	v_fmac_f32_e32 v81, v94, v94
	v_fmac_f32_e32 v82, v92, v92
	v_add_f32_e32 v81, v81, v82
	v_add_f32_e32 v80, v80, v81
	v_add_f32_e32 v83, v100, v80
	ds_bpermute_b32 v98, v112, v83
	v_lshl_add_u64 v[80:81], s[64:65], 0, v[180:181]
	v_lshl_add_u64 v[96:97], v[168:169], 1, v[80:81]
	global_store_dwordx4 v[96:97], v[88:91], off sc1
	v_cvt_pk_bf16_f32 v82, v84, v85
	s_waitcnt lgkmcnt(0)
	v_add_f32_e32 v80, v83, v98
	ds_bpermute_b32 v81, v113, v80
	v_cvt_pk_bf16_f32 v83, v86, v87
	v_cvt_pk_bf16_f32 v84, v94, v95
	v_cvt_pk_bf16_f32 v85, v92, v93
	global_store_dwordx4 v[96:97], v[82:85], off offset:256 sc1
	s_and_saveexec_b64 s[16:17], s[2:3]
	s_cbranch_execz .LBB0_1748
	s_waitcnt lgkmcnt(0)
	v_add_f32_e32 v82, v80, v81
	v_lshlrev_b64 v[80:81], 6, v[178:179]
	v_lshl_add_u64 v[80:81], s[74:75], 0, v[80:81]
	v_lshl_add_u64 v[80:81], s[14:15], 2, v[80:81]
	s_lshl_b32 s10, s34, 2
	v_lshl_add_u64 v[80:81], v[80:81], 0, s[10:11]
	global_store_dword v[80:81], v82, off
.LBB0_1748:
	s_or_b64 exec, exec, s[16:17]
	v_lshlrev_b32_e32 v80, 16, v132
	s_waitcnt lgkmcnt(0)
	v_and_b32_e32 v81, 0xffff0000, v132
	v_lshlrev_b32_e32 v82, 16, v133
	v_and_b32_e32 v83, 0xffff0000, v133
	v_lshlrev_b32_e32 v84, 16, v134
	v_and_b32_e32 v85, 0xffff0000, v134
	v_lshlrev_b32_e32 v86, 16, v135
	v_and_b32_e32 v87, 0xffff0000, v135
	v_pk_add_f32 v[78:79], v[78:79], v[82:83]
	v_pk_add_f32 v[76:77], v[76:77], v[80:81]
	v_pk_add_f32 v[80:81], v[74:75], v[86:87]
	v_pk_add_f32 v[74:75], v[72:73], v[84:85]
	v_mul_f32_e32 v72, v77, v77
	v_mul_f32_e32 v73, v79, v79
	v_fmac_f32_e32 v72, v76, v76
	v_fmac_f32_e32 v73, v78, v78
	v_add_f32_e32 v72, v72, v73
	v_mul_f32_e32 v73, v75, v75
	v_mul_f32_e32 v82, v81, v81
	v_fmac_f32_e32 v73, v74, v74
	v_fmac_f32_e32 v82, v80, v80
	v_add_f32_e32 v73, v73, v82
	v_add_f32_e32 v84, v72, v73
	v_cvt_pk_bf16_f32 v72, v76, v77
	v_cvt_pk_bf16_f32 v73, v78, v79
	v_lshlrev_b32_e32 v76, 16, v128
	v_and_b32_e32 v77, 0xffff0000, v128
	v_lshlrev_b32_e32 v78, 16, v129
	v_and_b32_e32 v79, 0xffff0000, v129
	v_cvt_pk_bf16_f32 v74, v74, v75
	v_cvt_pk_bf16_f32 v75, v80, v81
	v_lshlrev_b32_e32 v80, 16, v130
	v_and_b32_e32 v81, 0xffff0000, v130
	v_pk_add_f32 v[70:71], v[70:71], v[78:79]
	v_pk_add_f32 v[68:69], v[68:69], v[76:77]
	v_lshlrev_b32_e32 v82, 16, v131
	v_and_b32_e32 v83, 0xffff0000, v131
	v_pk_add_f32 v[78:79], v[64:65], v[80:81]
	v_mul_f32_e32 v64, v69, v69
	v_mul_f32_e32 v65, v71, v71
	v_pk_add_f32 v[76:77], v[66:67], v[82:83]
	v_fmac_f32_e32 v64, v68, v68
	v_fmac_f32_e32 v65, v70, v70
	v_add_f32_e32 v64, v64, v65
	v_mul_f32_e32 v65, v79, v79
	v_mul_f32_e32 v66, v77, v77
	v_fmac_f32_e32 v65, v78, v78
	v_fmac_f32_e32 v66, v76, v76
	v_add_f32_e32 v65, v65, v66
	v_add_f32_e32 v64, v64, v65
	v_add_f32_e32 v67, v84, v64
	ds_bpermute_b32 v82, v112, v67
	v_lshl_add_u64 v[64:65], s[64:65], 0, v[176:177]
	v_lshl_add_u64 v[80:81], v[168:169], 1, v[64:65]
	global_store_dwordx4 v[80:81], v[72:75], off sc1
	v_cvt_pk_bf16_f32 v66, v68, v69
	s_waitcnt lgkmcnt(0)
	v_add_f32_e32 v64, v67, v82
	ds_bpermute_b32 v65, v113, v64
	v_cvt_pk_bf16_f32 v67, v70, v71
	v_cvt_pk_bf16_f32 v68, v78, v79
	v_cvt_pk_bf16_f32 v69, v76, v77
	global_store_dwordx4 v[80:81], v[66:69], off offset:256 sc1
	s_and_saveexec_b64 s[16:17], s[2:3]
	s_cbranch_execz .LBB0_1750
	s_waitcnt lgkmcnt(0)
	v_add_f32_e32 v66, v64, v65
	v_lshlrev_b64 v[64:65], 6, v[174:175]
	v_lshl_add_u64 v[64:65], s[74:75], 0, v[64:65]
	v_lshl_add_u64 v[64:65], s[14:15], 2, v[64:65]
	s_lshl_b32 s10, s34, 2
	v_lshl_add_u64 v[64:65], v[64:65], 0, s[10:11]
	global_store_dword v[64:65], v66, off
.LBB0_1750:
	s_or_b64 exec, exec, s[16:17]
	v_add_u32_e32 v100, 0x80, v170
	v_ashrrev_i32_e32 v101, 31, v100
	v_add_u32_e32 v96, 0x90, v170
	v_lshlrev_b64 v[110:111], 11, v[100:101]
	v_ashrrev_i32_e32 v97, 31, v96
	v_add_u32_e32 v92, 0xa0, v170
	s_waitcnt lgkmcnt(0)
	v_lshl_add_u64 v[64:65], v[172:173], 0, v[110:111]
	v_lshlrev_b64 v[98:99], 11, v[96:97]
	v_ashrrev_i32_e32 v93, 31, v92
	v_add_u32_e32 v88, 0xb0, v170
	v_lshl_add_u64 v[64:65], v[172:173], 0, v[98:99]
	v_lshlrev_b64 v[94:95], 11, v[92:93]
	v_ashrrev_i32_e32 v89, 31, v88
	v_lshl_add_u64 v[64:65], v[172:173], 0, v[94:95]
	v_lshlrev_b64 v[90:91], 11, v[88:89]
	v_lshl_add_u64 v[64:65], v[172:173], 0, v[90:91]
	global_load_dwordx4 v[68:71], v[64:65], off
	s_nop 0
	global_load_dwordx4 v[64:67], v[64:65], off offset:256
	s_waitcnt vmcnt(15)
	v_lshlrev_b32_e32 v114, 16, v236
	v_and_b32_e32 v115, 0xffff0000, v236
	v_lshlrev_b32_e32 v236, 16, v237
	v_and_b32_e32 v237, 0xffff0000, v237
	v_lshlrev_b32_e32 v116, 16, v238
	v_and_b32_e32 v117, 0xffff0000, v238
	v_lshlrev_b32_e32 v238, 16, v239
	v_and_b32_e32 v239, 0xffff0000, v239
	v_pk_add_f32 v[62:63], v[62:63], v[236:237]
	v_pk_add_f32 v[60:61], v[60:61], v[114:115]
	v_pk_add_f32 v[236:237], v[58:59], v[238:239]
	v_pk_add_f32 v[58:59], v[56:57], v[116:117]
	v_mul_f32_e32 v56, v61, v61
	v_mul_f32_e32 v57, v63, v63
	v_fmac_f32_e32 v56, v60, v60
	v_fmac_f32_e32 v57, v62, v62
	v_add_f32_e32 v56, v56, v57
	v_mul_f32_e32 v57, v59, v59
	v_mul_f32_e32 v238, v237, v237
	v_fmac_f32_e32 v57, v58, v58
	v_fmac_f32_e32 v238, v236, v236
	v_add_f32_e32 v57, v57, v238
	v_add_f32_e32 v114, v56, v57
	v_cvt_pk_bf16_f32 v56, v60, v61
	v_cvt_pk_bf16_f32 v57, v62, v63
	s_waitcnt vmcnt(14)
	v_lshlrev_b32_e32 v60, 16, v240
	v_and_b32_e32 v61, 0xffff0000, v240
	v_lshlrev_b32_e32 v62, 16, v241
	v_and_b32_e32 v63, 0xffff0000, v241
	v_cvt_pk_bf16_f32 v58, v58, v59
	v_cvt_pk_bf16_f32 v59, v236, v237
	v_lshlrev_b32_e32 v236, 16, v242
	v_and_b32_e32 v237, 0xffff0000, v242
	v_pk_add_f32 v[54:55], v[54:55], v[62:63]
	v_pk_add_f32 v[52:53], v[52:53], v[60:61]
	v_lshlrev_b32_e32 v238, 16, v243
	v_and_b32_e32 v239, 0xffff0000, v243
	v_pk_add_f32 v[62:63], v[48:49], v[236:237]
	v_mul_f32_e32 v48, v53, v53
	v_mul_f32_e32 v49, v55, v55
	v_pk_add_f32 v[60:61], v[50:51], v[238:239]
	v_fmac_f32_e32 v48, v52, v52
	v_fmac_f32_e32 v49, v54, v54
	v_add_f32_e32 v48, v48, v49
	v_mul_f32_e32 v49, v63, v63
	v_mul_f32_e32 v50, v61, v61
	v_fmac_f32_e32 v49, v62, v62
	v_fmac_f32_e32 v50, v60, v60
	v_add_f32_e32 v49, v49, v50
	v_add_f32_e32 v48, v48, v49
	v_add_f32_e32 v51, v114, v48
	ds_bpermute_b32 v238, v112, v51
	v_lshl_add_u64 v[48:49], s[64:65], 0, v[110:111]
	v_lshl_add_u64 v[236:237], v[168:169], 1, v[48:49]
	global_store_dwordx4 v[236:237], v[56:59], off sc1
	v_cvt_pk_bf16_f32 v50, v52, v53
	s_waitcnt lgkmcnt(0)
	v_add_f32_e32 v48, v51, v238
	ds_bpermute_b32 v49, v113, v48
	v_cvt_pk_bf16_f32 v51, v54, v55
	v_cvt_pk_bf16_f32 v52, v62, v63
	v_cvt_pk_bf16_f32 v53, v60, v61
	global_store_dwordx4 v[236:237], v[50:53], off offset:256 sc1
	s_and_saveexec_b64 s[16:17], s[2:3]
	s_cbranch_execz .LBB0_1752
	s_waitcnt lgkmcnt(0)
	v_add_f32_e32 v50, v48, v49
	v_lshlrev_b64 v[48:49], 6, v[100:101]
	v_lshl_add_u64 v[48:49], s[74:75], 0, v[48:49]
	v_lshl_add_u64 v[48:49], s[14:15], 2, v[48:49]
	s_lshl_b32 s10, s34, 2
	v_lshl_add_u64 v[48:49], v[48:49], 0, s[10:11]
	global_store_dword v[48:49], v50, off
.LBB0_1752:
	s_or_b64 exec, exec, s[16:17]
	s_waitcnt vmcnt(15)
	v_lshlrev_b32_e32 v48, 16, v244
	s_waitcnt lgkmcnt(0)
	v_and_b32_e32 v49, 0xffff0000, v244
	v_lshlrev_b32_e32 v50, 16, v245
	v_and_b32_e32 v51, 0xffff0000, v245
	v_lshlrev_b32_e32 v52, 16, v246
	v_and_b32_e32 v53, 0xffff0000, v246
	v_lshlrev_b32_e32 v54, 16, v247
	v_and_b32_e32 v55, 0xffff0000, v247
	v_pk_add_f32 v[46:47], v[46:47], v[50:51]
	v_pk_add_f32 v[44:45], v[44:45], v[48:49]
	v_pk_add_f32 v[48:49], v[42:43], v[54:55]
	v_pk_add_f32 v[42:43], v[40:41], v[52:53]
	v_mul_f32_e32 v40, v45, v45
	v_mul_f32_e32 v41, v47, v47
	v_fmac_f32_e32 v40, v44, v44
	v_fmac_f32_e32 v41, v46, v46
	v_add_f32_e32 v40, v40, v41
	v_mul_f32_e32 v41, v43, v43
	v_mul_f32_e32 v50, v49, v49
	v_fmac_f32_e32 v41, v42, v42
	v_fmac_f32_e32 v50, v48, v48
	v_add_f32_e32 v41, v41, v50
	v_add_f32_e32 v52, v40, v41
	v_cvt_pk_bf16_f32 v40, v44, v45
	v_cvt_pk_bf16_f32 v41, v46, v47
	s_waitcnt vmcnt(14)
	v_lshlrev_b32_e32 v44, 16, v248
	v_and_b32_e32 v45, 0xffff0000, v248
	v_lshlrev_b32_e32 v46, 16, v249
	v_and_b32_e32 v47, 0xffff0000, v249
	v_cvt_pk_bf16_f32 v42, v42, v43
	v_cvt_pk_bf16_f32 v43, v48, v49
	v_lshlrev_b32_e32 v48, 16, v250
	v_and_b32_e32 v49, 0xffff0000, v250
	v_pk_add_f32 v[38:39], v[38:39], v[46:47]
	v_pk_add_f32 v[36:37], v[36:37], v[44:45]
	v_lshlrev_b32_e32 v50, 16, v251
	v_and_b32_e32 v51, 0xffff0000, v251
	v_pk_add_f32 v[46:47], v[32:33], v[48:49]
	v_mul_f32_e32 v32, v37, v37
	v_mul_f32_e32 v33, v39, v39
	v_pk_add_f32 v[44:45], v[34:35], v[50:51]
	v_fmac_f32_e32 v32, v36, v36
	v_fmac_f32_e32 v33, v38, v38
	v_add_f32_e32 v32, v32, v33
	v_mul_f32_e32 v33, v47, v47
	v_mul_f32_e32 v34, v45, v45
	v_fmac_f32_e32 v33, v46, v46
	v_fmac_f32_e32 v34, v44, v44
	v_add_f32_e32 v33, v33, v34
	v_add_f32_e32 v32, v32, v33
	v_add_f32_e32 v35, v52, v32
	ds_bpermute_b32 v50, v112, v35
	v_lshl_add_u64 v[32:33], s[64:65], 0, v[98:99]
	v_lshl_add_u64 v[48:49], v[168:169], 1, v[32:33]
	global_store_dwordx4 v[48:49], v[40:43], off sc1
	v_cvt_pk_bf16_f32 v34, v36, v37
	s_waitcnt lgkmcnt(0)
	v_add_f32_e32 v32, v35, v50
	ds_bpermute_b32 v33, v113, v32
	v_cvt_pk_bf16_f32 v35, v38, v39
	v_cvt_pk_bf16_f32 v36, v46, v47
	v_cvt_pk_bf16_f32 v37, v44, v45
	global_store_dwordx4 v[48:49], v[34:37], off offset:256 sc1
	s_and_saveexec_b64 s[16:17], s[2:3]
	s_cbranch_execz .LBB0_1754
	s_waitcnt lgkmcnt(0)
	v_add_f32_e32 v34, v32, v33
	v_lshlrev_b64 v[32:33], 6, v[96:97]
	v_lshl_add_u64 v[32:33], s[74:75], 0, v[32:33]
	v_lshl_add_u64 v[32:33], s[14:15], 2, v[32:33]
	s_lshl_b32 s10, s34, 2
	v_lshl_add_u64 v[32:33], v[32:33], 0, s[10:11]
	global_store_dword v[32:33], v34, off
.LBB0_1754:
	s_or_b64 exec, exec, s[16:17]
	s_waitcnt vmcnt(15)
	v_lshlrev_b32_e32 v32, 16, v210
	s_waitcnt lgkmcnt(0)
	v_and_b32_e32 v33, 0xffff0000, v210
	v_lshlrev_b32_e32 v34, 16, v211
	v_and_b32_e32 v35, 0xffff0000, v211
	v_lshlrev_b32_e32 v36, 16, v212
	v_and_b32_e32 v37, 0xffff0000, v212
	v_lshlrev_b32_e32 v38, 16, v213
	v_and_b32_e32 v39, 0xffff0000, v213
	v_pk_add_f32 v[30:31], v[30:31], v[34:35]
	v_pk_add_f32 v[28:29], v[28:29], v[32:33]
	v_pk_add_f32 v[32:33], v[26:27], v[38:39]
	v_pk_add_f32 v[26:27], v[24:25], v[36:37]
	v_mul_f32_e32 v24, v29, v29
	v_mul_f32_e32 v25, v31, v31
	v_fmac_f32_e32 v24, v28, v28
	v_fmac_f32_e32 v25, v30, v30
	v_add_f32_e32 v24, v24, v25
	v_mul_f32_e32 v25, v27, v27
	v_mul_f32_e32 v34, v33, v33
	v_fmac_f32_e32 v25, v26, v26
	v_fmac_f32_e32 v34, v32, v32
	v_add_f32_e32 v25, v25, v34
	v_add_f32_e32 v36, v24, v25
	v_cvt_pk_bf16_f32 v24, v28, v29
	v_cvt_pk_bf16_f32 v25, v30, v31
	s_waitcnt vmcnt(14)
	v_lshlrev_b32_e32 v28, 16, v214
	v_and_b32_e32 v29, 0xffff0000, v214
	v_lshlrev_b32_e32 v30, 16, v215
	v_and_b32_e32 v31, 0xffff0000, v215
	v_cvt_pk_bf16_f32 v26, v26, v27
	v_cvt_pk_bf16_f32 v27, v32, v33
	v_lshlrev_b32_e32 v32, 16, v216
	v_and_b32_e32 v33, 0xffff0000, v216
	v_pk_add_f32 v[22:23], v[22:23], v[30:31]
	v_pk_add_f32 v[20:21], v[20:21], v[28:29]
	v_lshlrev_b32_e32 v34, 16, v217
	v_and_b32_e32 v35, 0xffff0000, v217
	v_pk_add_f32 v[30:31], v[16:17], v[32:33]
	v_mul_f32_e32 v16, v21, v21
	v_mul_f32_e32 v17, v23, v23
	v_pk_add_f32 v[28:29], v[18:19], v[34:35]
	v_fmac_f32_e32 v16, v20, v20
	v_fmac_f32_e32 v17, v22, v22
	v_add_f32_e32 v16, v16, v17
	v_mul_f32_e32 v17, v31, v31
	v_mul_f32_e32 v18, v29, v29
	v_fmac_f32_e32 v17, v30, v30
	v_fmac_f32_e32 v18, v28, v28
	v_add_f32_e32 v17, v17, v18
	v_add_f32_e32 v16, v16, v17
	v_add_f32_e32 v19, v36, v16
	ds_bpermute_b32 v34, v112, v19
	v_lshl_add_u64 v[16:17], s[64:65], 0, v[94:95]
	v_lshl_add_u64 v[32:33], v[168:169], 1, v[16:17]
	global_store_dwordx4 v[32:33], v[24:27], off sc1
	v_cvt_pk_bf16_f32 v18, v20, v21
	s_waitcnt lgkmcnt(0)
	v_add_f32_e32 v16, v19, v34
	ds_bpermute_b32 v17, v113, v16
	v_cvt_pk_bf16_f32 v19, v22, v23
	v_cvt_pk_bf16_f32 v20, v30, v31
	v_cvt_pk_bf16_f32 v21, v28, v29
	global_store_dwordx4 v[32:33], v[18:21], off offset:256 sc1
	s_and_saveexec_b64 s[16:17], s[2:3]
	s_cbranch_execz .LBB0_1756
	s_waitcnt lgkmcnt(0)
	v_add_f32_e32 v18, v16, v17
	v_lshlrev_b64 v[16:17], 6, v[92:93]
	v_lshl_add_u64 v[16:17], s[74:75], 0, v[16:17]
	v_lshl_add_u64 v[16:17], s[14:15], 2, v[16:17]
	s_lshl_b32 s10, s34, 2
	v_lshl_add_u64 v[16:17], v[16:17], 0, s[10:11]
	global_store_dword v[16:17], v18, off
.LBB0_1756:
	s_or_b64 exec, exec, s[16:17]
	s_waitcnt vmcnt(7)
	v_lshlrev_b32_e32 v16, 16, v68
	s_waitcnt lgkmcnt(0)
	v_and_b32_e32 v17, 0xffff0000, v68
	v_lshlrev_b32_e32 v18, 16, v69
	v_and_b32_e32 v19, 0xffff0000, v69
	v_lshlrev_b32_e32 v20, 16, v70
	v_and_b32_e32 v21, 0xffff0000, v70
	v_lshlrev_b32_e32 v22, 16, v71
	v_and_b32_e32 v23, 0xffff0000, v71
	v_pk_add_f32 v[14:15], v[14:15], v[18:19]
	v_pk_add_f32 v[12:13], v[12:13], v[16:17]
	v_pk_add_f32 v[16:17], v[10:11], v[22:23]
	v_pk_add_f32 v[10:11], v[8:9], v[20:21]
	v_mul_f32_e32 v8, v13, v13
	v_mul_f32_e32 v9, v15, v15
	v_fmac_f32_e32 v8, v12, v12
	v_fmac_f32_e32 v9, v14, v14
	v_add_f32_e32 v8, v8, v9
	v_mul_f32_e32 v9, v11, v11
	v_mul_f32_e32 v18, v17, v17
	v_fmac_f32_e32 v9, v10, v10
	v_fmac_f32_e32 v18, v16, v16
	v_add_f32_e32 v9, v9, v18
	v_add_f32_e32 v20, v8, v9
	v_cvt_pk_bf16_f32 v8, v12, v13
	v_cvt_pk_bf16_f32 v9, v14, v15
	s_waitcnt vmcnt(6)
	v_lshlrev_b32_e32 v12, 16, v64
	v_and_b32_e32 v13, 0xffff0000, v64
	v_lshlrev_b32_e32 v14, 16, v65
	v_and_b32_e32 v15, 0xffff0000, v65
	v_cvt_pk_bf16_f32 v10, v10, v11
	v_cvt_pk_bf16_f32 v11, v16, v17
	v_lshlrev_b32_e32 v16, 16, v66
	v_and_b32_e32 v17, 0xffff0000, v66
	v_pk_add_f32 v[6:7], v[6:7], v[14:15]
	v_pk_add_f32 v[4:5], v[4:5], v[12:13]
	v_lshlrev_b32_e32 v18, 16, v67
	v_and_b32_e32 v19, 0xffff0000, v67
	v_pk_add_f32 v[14:15], v[0:1], v[16:17]
	v_mul_f32_e32 v0, v5, v5
	v_mul_f32_e32 v1, v7, v7
	v_pk_add_f32 v[12:13], v[2:3], v[18:19]
	v_fmac_f32_e32 v0, v4, v4
	v_fmac_f32_e32 v1, v6, v6
	v_add_f32_e32 v0, v0, v1
	v_mul_f32_e32 v1, v15, v15
	v_mul_f32_e32 v2, v13, v13
	v_fmac_f32_e32 v1, v14, v14
	v_fmac_f32_e32 v2, v12, v12
	v_add_f32_e32 v1, v1, v2
	v_add_f32_e32 v0, v0, v1
	v_add_f32_e32 v3, v20, v0
	ds_bpermute_b32 v18, v112, v3
	v_lshl_add_u64 v[0:1], s[64:65], 0, v[90:91]
	v_lshl_add_u64 v[16:17], v[168:169], 1, v[0:1]
	global_store_dwordx4 v[16:17], v[8:11], off sc1
	v_cvt_pk_bf16_f32 v2, v4, v5
	s_waitcnt lgkmcnt(0)
	v_add_f32_e32 v0, v3, v18
	ds_bpermute_b32 v1, v113, v0
	v_cvt_pk_bf16_f32 v3, v6, v7
	v_cvt_pk_bf16_f32 v4, v14, v15
	v_cvt_pk_bf16_f32 v5, v12, v13
	global_store_dwordx4 v[16:17], v[2:5], off offset:256 sc1
	s_and_saveexec_b64 s[16:17], s[2:3]
	s_cbranch_execz .LBB0_1729
	s_waitcnt lgkmcnt(0)
	v_add_f32_e32 v2, v0, v1
	v_lshlrev_b64 v[0:1], 6, v[88:89]
	v_lshl_add_u64 v[0:1], s[74:75], 0, v[0:1]
	v_lshl_add_u64 v[0:1], s[14:15], 2, v[0:1]
	s_lshl_b32 s10, s34, 2
	v_lshl_add_u64 v[0:1], v[0:1], 0, s[10:11]
	global_store_dword v[0:1], v2, off
	s_branch .LBB0_1729
